# K-loop LDS-DMA loads with SGPR base + 32-bit lane offset use the saddr form (8 fewer 64-bit VALU adds per iteration)
# speedup vs baseline: 1.0046x; 1.0046x over previous
.LBB0_410:
	ds_read_b128 v[154:157], v149
	ds_read_b128 v[158:161], v149 offset:1024
	ds_read_b128 v[162:165], v149 offset:2048
	ds_read_b128 v[166:169], v149 offset:3072
	ds_read_b128 v[170:173], v150
	ds_read_b128 v[174:177], v150 offset:1024
	ds_read_b128 v[178:181], v150 offset:2048
	ds_read_b128 v[182:185], v150 offset:3072
	s_add_u32 s30, s28, 0xfffc0080
	s_addc_u32 s31, s29, -1
	s_cmp_eq_u32 s71, 12
	s_cselect_b32 s35, s21, s31
	s_cselect_b32 s34, s61, s30
	s_cselect_b32 s31, s19, s70
	s_cselect_b32 s30, s62, s63
	s_add_i32 m0, s27, 0xc000
	ds_read_b128 v[186:189], v151
	ds_read_b128 v[190:193], v151 offset:1024
	ds_read_b128 v[196:199], v151 offset:2048
	ds_read_b128 v[200:203], v151 offset:3072
	ds_read_b128 v[204:207], v151 offset:4096
	ds_read_b128 v[208:211], v151 offset:5120
	ds_read_b128 v[212:215], v151 offset:6144
	ds_read_b128 v[216:219], v151 offset:7168
	global_load_lds_dwordx4 v136, s[28:29]
	s_add_i32 m0, s27, 0xe000
	s_nop 0
	global_load_lds_dwordx4 v138, s[28:29]
	s_waitcnt vmcnt(8)
	s_waitcnt lgkmcnt(0)
	s_barrier
	s_setprio 1
	s_waitcnt lgkmcnt(0)
	v_mfma_f32_16x16x32_bf16 v[116:119], v[154:157], v[186:189], v[116:119]
	v_mfma_f32_16x16x32_bf16 v[112:115], v[162:165], v[186:189], v[112:115]
	v_mfma_f32_16x16x32_bf16 v[100:103], v[154:157], v[196:199], v[100:103]
	v_mfma_f32_16x16x32_bf16 v[96:99], v[162:165], v[196:199], v[96:99]
	v_mfma_f32_16x16x32_bf16 v[84:87], v[154:157], v[204:207], v[84:87]
	v_mfma_f32_16x16x32_bf16 v[80:83], v[162:165], v[204:207], v[80:83]
	v_mfma_f32_16x16x32_bf16 v[68:71], v[154:157], v[212:215], v[68:71]
	v_mfma_f32_16x16x32_bf16 v[64:67], v[162:165], v[212:215], v[64:67]
	v_mfma_f32_16x16x32_bf16 v[116:119], v[158:161], v[190:193], v[116:119]
	v_mfma_f32_16x16x32_bf16 v[112:115], v[166:169], v[190:193], v[112:115]
	v_mfma_f32_16x16x32_bf16 v[100:103], v[158:161], v[200:203], v[100:103]
	v_mfma_f32_16x16x32_bf16 v[96:99], v[166:169], v[200:203], v[96:99]
	v_mfma_f32_16x16x32_bf16 v[84:87], v[158:161], v[208:211], v[84:87]
	v_mfma_f32_16x16x32_bf16 v[80:83], v[166:169], v[208:211], v[80:83]
	v_mfma_f32_16x16x32_bf16 v[68:71], v[158:161], v[216:219], v[68:71]
	v_mfma_f32_16x16x32_bf16 v[64:67], v[166:169], v[216:219], v[64:67]
	s_setprio 0
	s_setprio 1
	v_mfma_f32_16x16x32_bf16 v[124:127], v[170:173], v[186:189], v[124:127]
	v_mfma_f32_16x16x32_bf16 v[120:123], v[178:181], v[186:189], v[120:123]
	v_mfma_f32_16x16x32_bf16 v[108:111], v[170:173], v[196:199], v[108:111]
	v_mfma_f32_16x16x32_bf16 v[104:107], v[178:181], v[196:199], v[104:107]
	v_mfma_f32_16x16x32_bf16 v[92:95], v[170:173], v[204:207], v[92:95]
	v_mfma_f32_16x16x32_bf16 v[88:91], v[178:181], v[204:207], v[88:91]
	v_mfma_f32_16x16x32_bf16 v[76:79], v[170:173], v[212:215], v[76:79]
	v_mfma_f32_16x16x32_bf16 v[72:75], v[178:181], v[212:215], v[72:75]
	v_mfma_f32_16x16x32_bf16 v[124:127], v[174:177], v[190:193], v[124:127]
	v_mfma_f32_16x16x32_bf16 v[120:123], v[182:185], v[190:193], v[120:123]
	v_mfma_f32_16x16x32_bf16 v[108:111], v[174:177], v[200:203], v[108:111]
	v_mfma_f32_16x16x32_bf16 v[104:107], v[182:185], v[200:203], v[104:107]
	v_mfma_f32_16x16x32_bf16 v[92:95], v[174:177], v[208:211], v[92:95]
	v_mfma_f32_16x16x32_bf16 v[88:91], v[182:185], v[208:211], v[88:91]
	v_mfma_f32_16x16x32_bf16 v[76:79], v[174:177], v[216:219], v[76:79]
	v_mfma_f32_16x16x32_bf16 v[72:75], v[182:185], v[216:219], v[72:75]
	s_setprio 0
	s_barrier
	s_add_i32 s72, s54, s41
	v_lshl_add_u64 v[144:145], s[30:31], 0, v[132:133]
	s_mov_b32 m0, s72
	ds_read_b128 v[186:189], v151 offset:16384
	ds_read_b128 v[190:193], v151 offset:17408
	ds_read_b128 v[196:199], v151 offset:18432
	ds_read_b128 v[200:203], v151 offset:19456
	ds_read_b128 v[204:207], v151 offset:20480
	ds_read_b128 v[208:211], v151 offset:21504
	ds_read_b128 v[212:215], v151 offset:22528
	ds_read_b128 v[216:219], v151 offset:23552
	global_load_lds_dwordx4 v[144:145], off
	s_add_i32 m0, s72, 0x2000
	s_add_u32 s72, s30, 0x40000
	v_lshl_add_u64 v[220:221], s[30:31], 0, v[128:129]
	s_addc_u32 s73, s31, 0
	s_add_i32 s77, s55, s41
	global_load_lds_dwordx4 v[220:221], off
	s_mov_b32 m0, s77
	v_lshl_add_u64 v[224:225], s[34:35], 0, v[130:131]
	global_load_lds_dwordx4 v132, s[72:73]
	s_add_i32 m0, s77, 0x2000
	s_nop 0
	global_load_lds_dwordx4 v128, s[72:73]
	v_lshl_add_u64 v[222:223], s[34:35], 0, v[134:135]
	s_waitcnt vmcnt(6)
	s_waitcnt lgkmcnt(0)
	s_barrier
	s_setprio 1
	s_waitcnt lgkmcnt(0)
	v_mfma_f32_16x16x32_bf16 v[52:55], v[154:157], v[186:189], v[52:55]
	v_mfma_f32_16x16x32_bf16 v[48:51], v[162:165], v[186:189], v[48:51]
	v_mfma_f32_16x16x32_bf16 v[36:39], v[154:157], v[196:199], v[36:39]
	v_mfma_f32_16x16x32_bf16 v[32:35], v[162:165], v[196:199], v[32:35]
	v_mfma_f32_16x16x32_bf16 v[20:23], v[154:157], v[204:207], v[20:23]
	v_mfma_f32_16x16x32_bf16 v[16:19], v[162:165], v[204:207], v[16:19]
	v_mfma_f32_16x16x32_bf16 v[4:7], v[154:157], v[212:215], v[4:7]
	v_mfma_f32_16x16x32_bf16 v[0:3], v[162:165], v[212:215], v[0:3]
	v_mfma_f32_16x16x32_bf16 v[52:55], v[158:161], v[190:193], v[52:55]
	v_mfma_f32_16x16x32_bf16 v[48:51], v[166:169], v[190:193], v[48:51]
	v_mfma_f32_16x16x32_bf16 v[36:39], v[158:161], v[200:203], v[36:39]
	v_mfma_f32_16x16x32_bf16 v[32:35], v[166:169], v[200:203], v[32:35]
	v_mfma_f32_16x16x32_bf16 v[20:23], v[158:161], v[208:211], v[20:23]
	v_mfma_f32_16x16x32_bf16 v[16:19], v[166:169], v[208:211], v[16:19]
	v_mfma_f32_16x16x32_bf16 v[4:7], v[158:161], v[216:219], v[4:7]
	v_mfma_f32_16x16x32_bf16 v[0:3], v[166:169], v[216:219], v[0:3]
	s_setprio 0
	s_setprio 1
	v_mfma_f32_16x16x32_bf16 v[60:63], v[170:173], v[186:189], v[60:63]
	v_mfma_f32_16x16x32_bf16 v[56:59], v[178:181], v[186:189], v[56:59]
	v_mfma_f32_16x16x32_bf16 v[44:47], v[170:173], v[196:199], v[44:47]
	v_mfma_f32_16x16x32_bf16 v[40:43], v[178:181], v[196:199], v[40:43]
	v_mfma_f32_16x16x32_bf16 v[28:31], v[170:173], v[204:207], v[28:31]
	v_mfma_f32_16x16x32_bf16 v[24:27], v[178:181], v[204:207], v[24:27]
	v_mfma_f32_16x16x32_bf16 v[12:15], v[170:173], v[212:215], v[12:15]
	v_mfma_f32_16x16x32_bf16 v[8:11], v[178:181], v[212:215], v[8:11]
	v_mfma_f32_16x16x32_bf16 v[60:63], v[174:177], v[190:193], v[60:63]
	v_mfma_f32_16x16x32_bf16 v[56:59], v[182:185], v[190:193], v[56:59]
	v_mfma_f32_16x16x32_bf16 v[44:47], v[174:177], v[200:203], v[44:47]
	v_mfma_f32_16x16x32_bf16 v[40:43], v[182:185], v[200:203], v[40:43]
	v_mfma_f32_16x16x32_bf16 v[28:31], v[174:177], v[208:211], v[28:31]
	v_mfma_f32_16x16x32_bf16 v[24:27], v[182:185], v[208:211], v[24:27]
	v_mfma_f32_16x16x32_bf16 v[12:15], v[174:177], v[216:219], v[12:15]
	v_mfma_f32_16x16x32_bf16 v[8:11], v[182:185], v[216:219], v[8:11]
	s_setprio 0
	s_barrier
	s_add_i32 s72, 0, 0x18000
	v_add_u32_e32 v153, s72, v147
	s_add_i32 s73, 0, 0x1c000
	ds_read_b128 v[154:157], v153
	ds_read_b128 v[158:161], v153 offset:1024
	ds_read_b128 v[162:165], v153 offset:2048
	ds_read_b128 v[166:169], v153 offset:3072
	v_add_u32_e32 v153, s73, v147
	ds_read_b128 v[170:173], v153
	ds_read_b128 v[174:177], v153 offset:1024
	ds_read_b128 v[178:181], v153 offset:2048
	ds_read_b128 v[182:185], v153 offset:3072
	s_add_u32 s34, s34, 0x40000
	s_addc_u32 s35, s35, 0
	ds_read_b128 v[186:189], v151 offset:32768
	ds_read_b128 v[190:193], v151 offset:33792
	ds_read_b128 v[196:199], v151 offset:34816
	ds_read_b128 v[200:203], v151 offset:35840
	ds_read_b128 v[204:207], v151 offset:36864
	ds_read_b128 v[208:211], v151 offset:37888
	ds_read_b128 v[212:215], v151 offset:38912
	ds_read_b128 v[216:219], v151 offset:39936
	s_mov_b32 m0, s27
	s_nop 0
	global_load_lds_dwordx4 v[222:223], off
	s_mov_b32 m0, s43
	s_nop 0
	global_load_lds_dwordx4 v[224:225], off
	s_mov_b32 m0, s44
	s_nop 0
	global_load_lds_dwordx4 v134, s[34:35]
	s_mov_b32 m0, s45
	s_nop 0
	global_load_lds_dwordx4 v130, s[34:35]
	s_waitcnt vmcnt(8)
	s_waitcnt lgkmcnt(0)
	s_barrier
	s_setprio 1
	s_waitcnt lgkmcnt(0)
	v_mfma_f32_16x16x32_bf16 v[116:119], v[154:157], v[186:189], v[116:119]
	v_mfma_f32_16x16x32_bf16 v[112:115], v[162:165], v[186:189], v[112:115]
	v_mfma_f32_16x16x32_bf16 v[100:103], v[154:157], v[196:199], v[100:103]
	v_mfma_f32_16x16x32_bf16 v[96:99], v[162:165], v[196:199], v[96:99]
	v_mfma_f32_16x16x32_bf16 v[84:87], v[154:157], v[204:207], v[84:87]
	v_mfma_f32_16x16x32_bf16 v[80:83], v[162:165], v[204:207], v[80:83]
	v_mfma_f32_16x16x32_bf16 v[68:71], v[154:157], v[212:215], v[68:71]
	v_mfma_f32_16x16x32_bf16 v[64:67], v[162:165], v[212:215], v[64:67]
	v_mfma_f32_16x16x32_bf16 v[116:119], v[158:161], v[190:193], v[116:119]
	v_mfma_f32_16x16x32_bf16 v[112:115], v[166:169], v[190:193], v[112:115]
	v_mfma_f32_16x16x32_bf16 v[100:103], v[158:161], v[200:203], v[100:103]
	v_mfma_f32_16x16x32_bf16 v[96:99], v[166:169], v[200:203], v[96:99]
	v_mfma_f32_16x16x32_bf16 v[84:87], v[158:161], v[208:211], v[84:87]
	v_mfma_f32_16x16x32_bf16 v[80:83], v[166:169], v[208:211], v[80:83]
	v_mfma_f32_16x16x32_bf16 v[68:71], v[158:161], v[216:219], v[68:71]
	v_mfma_f32_16x16x32_bf16 v[64:67], v[166:169], v[216:219], v[64:67]
	s_setprio 0
	s_setprio 1
	v_mfma_f32_16x16x32_bf16 v[124:127], v[170:173], v[186:189], v[124:127]
	v_mfma_f32_16x16x32_bf16 v[120:123], v[178:181], v[186:189], v[120:123]
	v_mfma_f32_16x16x32_bf16 v[108:111], v[170:173], v[196:199], v[108:111]
	v_mfma_f32_16x16x32_bf16 v[104:107], v[178:181], v[196:199], v[104:107]
	v_mfma_f32_16x16x32_bf16 v[92:95], v[170:173], v[204:207], v[92:95]
	v_mfma_f32_16x16x32_bf16 v[88:91], v[178:181], v[204:207], v[88:91]
	v_mfma_f32_16x16x32_bf16 v[76:79], v[170:173], v[212:215], v[76:79]
	v_mfma_f32_16x16x32_bf16 v[72:75], v[178:181], v[212:215], v[72:75]
	v_mfma_f32_16x16x32_bf16 v[124:127], v[174:177], v[190:193], v[124:127]
	v_mfma_f32_16x16x32_bf16 v[120:123], v[182:185], v[190:193], v[120:123]
	v_mfma_f32_16x16x32_bf16 v[108:111], v[174:177], v[200:203], v[108:111]
	v_mfma_f32_16x16x32_bf16 v[104:107], v[182:185], v[200:203], v[104:107]
	v_mfma_f32_16x16x32_bf16 v[92:95], v[174:177], v[208:211], v[92:95]
	v_mfma_f32_16x16x32_bf16 v[88:91], v[182:185], v[208:211], v[88:91]
	v_mfma_f32_16x16x32_bf16 v[76:79], v[174:177], v[216:219], v[76:79]
	v_mfma_f32_16x16x32_bf16 v[72:75], v[182:185], v[216:219], v[72:75]
	s_setprio 0
	s_barrier
	s_add_i32 s34, s72, s41
	v_lshl_add_u64 v[144:145], v[144:145], 0, s[12:13]
	s_mov_b32 m0, s34
	ds_read_b128 v[186:189], v151 offset:49152
	ds_read_b128 v[190:193], v151 offset:50176
	ds_read_b128 v[196:199], v151 offset:51200
	ds_read_b128 v[200:203], v151 offset:52224
	ds_read_b128 v[204:207], v151 offset:53248
	ds_read_b128 v[208:211], v151 offset:54272
	ds_read_b128 v[212:215], v151 offset:55296
	ds_read_b128 v[216:219], v151 offset:56320
	global_load_lds_dwordx4 v[144:145], off
	s_add_i32 m0, s34, 0x2000
	s_add_u32 s30, s30, 0x40080
	v_lshl_add_u64 v[144:145], v[220:221], 0, s[12:13]
	s_addc_u32 s31, s31, 0
	s_add_i32 s34, s73, s41
	global_load_lds_dwordx4 v[144:145], off
	s_mov_b32 m0, s34
	s_nop 0
	global_load_lds_dwordx4 v132, s[30:31]
	s_add_i32 m0, s34, 0x2000
	s_nop 0
	global_load_lds_dwordx4 v128, s[30:31]
	s_waitcnt vmcnt(6)
	s_waitcnt lgkmcnt(0)
	s_barrier
	s_setprio 1
	s_waitcnt lgkmcnt(0)
	v_mfma_f32_16x16x32_bf16 v[52:55], v[154:157], v[186:189], v[52:55]
	v_mfma_f32_16x16x32_bf16 v[48:51], v[162:165], v[186:189], v[48:51]
	v_mfma_f32_16x16x32_bf16 v[36:39], v[154:157], v[196:199], v[36:39]
	v_mfma_f32_16x16x32_bf16 v[32:35], v[162:165], v[196:199], v[32:35]
	v_mfma_f32_16x16x32_bf16 v[20:23], v[154:157], v[204:207], v[20:23]
	v_mfma_f32_16x16x32_bf16 v[16:19], v[162:165], v[204:207], v[16:19]
	v_mfma_f32_16x16x32_bf16 v[4:7], v[154:157], v[212:215], v[4:7]
	v_mfma_f32_16x16x32_bf16 v[0:3], v[162:165], v[212:215], v[0:3]
	v_mfma_f32_16x16x32_bf16 v[52:55], v[158:161], v[190:193], v[52:55]
	v_mfma_f32_16x16x32_bf16 v[48:51], v[166:169], v[190:193], v[48:51]
	v_mfma_f32_16x16x32_bf16 v[36:39], v[158:161], v[200:203], v[36:39]
	v_mfma_f32_16x16x32_bf16 v[32:35], v[166:169], v[200:203], v[32:35]
	v_mfma_f32_16x16x32_bf16 v[20:23], v[158:161], v[208:211], v[20:23]
	v_mfma_f32_16x16x32_bf16 v[16:19], v[166:169], v[208:211], v[16:19]
	v_mfma_f32_16x16x32_bf16 v[4:7], v[158:161], v[216:219], v[4:7]
	v_mfma_f32_16x16x32_bf16 v[0:3], v[166:169], v[216:219], v[0:3]
	s_setprio 0
	s_setprio 1
	v_mfma_f32_16x16x32_bf16 v[60:63], v[170:173], v[186:189], v[60:63]
	v_mfma_f32_16x16x32_bf16 v[56:59], v[178:181], v[186:189], v[56:59]
	v_mfma_f32_16x16x32_bf16 v[44:47], v[170:173], v[196:199], v[44:47]
	v_mfma_f32_16x16x32_bf16 v[40:43], v[178:181], v[196:199], v[40:43]
	v_mfma_f32_16x16x32_bf16 v[28:31], v[170:173], v[204:207], v[28:31]
	v_mfma_f32_16x16x32_bf16 v[24:27], v[178:181], v[204:207], v[24:27]
	v_mfma_f32_16x16x32_bf16 v[12:15], v[170:173], v[212:215], v[12:15]
	v_mfma_f32_16x16x32_bf16 v[8:11], v[178:181], v[212:215], v[8:11]
	v_mfma_f32_16x16x32_bf16 v[60:63], v[174:177], v[190:193], v[60:63]
	v_mfma_f32_16x16x32_bf16 v[56:59], v[182:185], v[190:193], v[56:59]
	v_mfma_f32_16x16x32_bf16 v[44:47], v[174:177], v[200:203], v[44:47]
	v_mfma_f32_16x16x32_bf16 v[40:43], v[182:185], v[200:203], v[40:43]
	v_mfma_f32_16x16x32_bf16 v[28:31], v[174:177], v[208:211], v[28:31]
	v_mfma_f32_16x16x32_bf16 v[24:27], v[182:185], v[208:211], v[24:27]
	v_mfma_f32_16x16x32_bf16 v[12:15], v[174:177], v[216:219], v[12:15]
	v_mfma_f32_16x16x32_bf16 v[8:11], v[182:185], v[216:219], v[8:11]
	s_setprio 0
	s_barrier
	v_lshl_add_u64 v[222:223], v[222:223], 0, s[12:13]
	s_mov_b32 m0, s51
	s_nop 0
	global_load_lds_dwordx4 v[222:223], off
	v_lshl_add_u64 v[224:225], v[224:225], 0, s[12:13]
	s_mov_b32 m0, s52
	s_nop 0
	global_load_lds_dwordx4 v[224:225], off
	s_add_i32 s71, s71, 2
	s_add_u32 s28, s28, 0x100
	s_addc_u32 s29, s29, 0
	s_add_u32 s63, s63, 0x100
	s_addc_u32 s70, s70, 0
	s_cmp_gt_u32 s71, 13
	s_cbranch_scc0 .LBB0_410
	s_and_b64 vcc, exec, s[16:17]
	s_cbranch_vccz .LBB0_413
	s_barrier

.LBB0_532:
	ds_read_b128 v[146:149], v155
	ds_read_b128 v[160:163], v155 offset:1024
	ds_read_b128 v[164:167], v155 offset:2048
	ds_read_b128 v[168:171], v155 offset:3072
	ds_read_b128 v[172:175], v156
	ds_read_b128 v[176:179], v156 offset:1024
	ds_read_b128 v[180:183], v156 offset:2048
	ds_read_b128 v[184:187], v156 offset:3072
	s_add_u32 s30, s28, 0x100
	s_addc_u32 s31, s29, 0
	s_cmp_eq_u32 s77, 40
	s_cselect_b32 s37, s1, s31
	s_cselect_b32 s36, s0, s30
	s_cselect_b32 s35, s27, s73
	s_cselect_b32 s34, s26, s72
	v_lshl_add_u64 v[150:151], s[28:29], 0, v[138:139]
	s_add_i32 m0, s44, 0xc000
	ds_read_b128 v[188:191], v157
	ds_read_b128 v[196:199], v157 offset:1024
	ds_read_b128 v[200:203], v157 offset:2048
	ds_read_b128 v[204:207], v157 offset:3072
	ds_read_b128 v[208:211], v157 offset:4096
	ds_read_b128 v[212:215], v157 offset:5120
	ds_read_b128 v[216:219], v157 offset:6144
	ds_read_b128 v[220:223], v157 offset:7168
	global_load_lds_dwordx4 v[150:151], off
	v_lshl_add_u64 v[150:151], s[28:29], 0, v[140:141]
	s_add_i32 m0, s44, 0xe000
	s_nop 0
	global_load_lds_dwordx4 v[150:151], off
	s_waitcnt vmcnt(8)
	s_waitcnt lgkmcnt(0)
	s_barrier
	s_setprio 1
	s_waitcnt lgkmcnt(0)
	v_mfma_f32_16x16x32_bf16 v[124:127], v[146:149], v[188:191], v[124:127]
	v_mfma_f32_16x16x32_bf16 v[120:123], v[164:167], v[188:191], v[120:123]
	v_mfma_f32_16x16x32_bf16 v[108:111], v[146:149], v[200:203], v[108:111]
	v_mfma_f32_16x16x32_bf16 v[104:107], v[164:167], v[200:203], v[104:107]
	v_mfma_f32_16x16x32_bf16 v[92:95], v[146:149], v[208:211], v[92:95]
	v_mfma_f32_16x16x32_bf16 v[88:91], v[164:167], v[208:211], v[88:91]
	v_mfma_f32_16x16x32_bf16 v[76:79], v[146:149], v[216:219], v[76:79]
	v_mfma_f32_16x16x32_bf16 v[72:75], v[164:167], v[216:219], v[72:75]
	v_mfma_f32_16x16x32_bf16 v[124:127], v[160:163], v[196:199], v[124:127]
	v_mfma_f32_16x16x32_bf16 v[120:123], v[168:171], v[196:199], v[120:123]
	v_mfma_f32_16x16x32_bf16 v[108:111], v[160:163], v[204:207], v[108:111]
	v_mfma_f32_16x16x32_bf16 v[104:107], v[168:171], v[204:207], v[104:107]
	v_mfma_f32_16x16x32_bf16 v[92:95], v[160:163], v[212:215], v[92:95]
	v_mfma_f32_16x16x32_bf16 v[88:91], v[168:171], v[212:215], v[88:91]
	v_mfma_f32_16x16x32_bf16 v[76:79], v[160:163], v[220:223], v[76:79]
	v_mfma_f32_16x16x32_bf16 v[72:75], v[168:171], v[220:223], v[72:75]
	s_setprio 0
	s_setprio 1
	v_mfma_f32_16x16x32_bf16 v[116:119], v[172:175], v[188:191], v[116:119]
	v_mfma_f32_16x16x32_bf16 v[112:115], v[180:183], v[188:191], v[112:115]
	v_mfma_f32_16x16x32_bf16 v[100:103], v[172:175], v[200:203], v[100:103]
	v_mfma_f32_16x16x32_bf16 v[96:99], v[180:183], v[200:203], v[96:99]
	v_mfma_f32_16x16x32_bf16 v[84:87], v[172:175], v[208:211], v[84:87]
	v_mfma_f32_16x16x32_bf16 v[80:83], v[180:183], v[208:211], v[80:83]
	v_mfma_f32_16x16x32_bf16 v[68:71], v[172:175], v[216:219], v[68:71]
	v_mfma_f32_16x16x32_bf16 v[64:67], v[180:183], v[216:219], v[64:67]
	v_mfma_f32_16x16x32_bf16 v[116:119], v[176:179], v[196:199], v[116:119]
	v_mfma_f32_16x16x32_bf16 v[112:115], v[184:187], v[196:199], v[112:115]
	v_mfma_f32_16x16x32_bf16 v[100:103], v[176:179], v[204:207], v[100:103]
	v_mfma_f32_16x16x32_bf16 v[96:99], v[184:187], v[204:207], v[96:99]
	v_mfma_f32_16x16x32_bf16 v[84:87], v[176:179], v[212:215], v[84:87]
	v_mfma_f32_16x16x32_bf16 v[80:83], v[184:187], v[212:215], v[80:83]
	v_mfma_f32_16x16x32_bf16 v[68:71], v[176:179], v[220:223], v[68:71]
	v_mfma_f32_16x16x32_bf16 v[64:67], v[184:187], v[220:223], v[64:67]
	s_setprio 0
	s_barrier
	s_add_i32 s28, s60, s43
	v_lshl_add_u64 v[150:151], s[34:35], 0, v[132:133]
	s_mov_b32 m0, s28
	ds_read_b128 v[188:191], v157 offset:16384
	ds_read_b128 v[196:199], v157 offset:17408
	ds_read_b128 v[200:203], v157 offset:18432
	ds_read_b128 v[204:207], v157 offset:19456
	ds_read_b128 v[208:211], v157 offset:20480
	ds_read_b128 v[212:215], v157 offset:21504
	ds_read_b128 v[216:219], v157 offset:22528
	ds_read_b128 v[220:223], v157 offset:23552
	global_load_lds_dwordx4 v[150:151], off
	s_add_i32 m0, s28, 0x2000
	s_add_u32 s28, s34, 0xb0000
	v_lshl_add_u64 v[192:193], s[34:35], 0, v[136:137]
	s_addc_u32 s29, s35, 0
	s_add_i32 s78, s61, s43
	global_load_lds_dwordx4 v[192:193], off
	s_mov_b32 m0, s78
	v_lshl_add_u64 v[226:227], s[36:37], 0, v[134:135]
	global_load_lds_dwordx4 v132, s[28:29]
	s_add_i32 m0, s78, 0x2000
	s_nop 0
	global_load_lds_dwordx4 v136, s[28:29]
	v_lshl_add_u64 v[224:225], s[36:37], 0, v[130:131]
	s_waitcnt vmcnt(6)
	s_waitcnt lgkmcnt(0)
	s_barrier
	s_setprio 1
	s_waitcnt lgkmcnt(0)
	v_mfma_f32_16x16x32_bf16 v[60:63], v[146:149], v[188:191], v[60:63]
	v_mfma_f32_16x16x32_bf16 v[56:59], v[164:167], v[188:191], v[56:59]
	v_mfma_f32_16x16x32_bf16 v[44:47], v[146:149], v[200:203], v[44:47]
	v_mfma_f32_16x16x32_bf16 v[40:43], v[164:167], v[200:203], v[40:43]
	v_mfma_f32_16x16x32_bf16 v[28:31], v[146:149], v[208:211], v[28:31]
	v_mfma_f32_16x16x32_bf16 v[24:27], v[164:167], v[208:211], v[24:27]
	v_mfma_f32_16x16x32_bf16 v[12:15], v[146:149], v[216:219], v[12:15]
	v_mfma_f32_16x16x32_bf16 v[8:11], v[164:167], v[216:219], v[8:11]
	v_mfma_f32_16x16x32_bf16 v[60:63], v[160:163], v[196:199], v[60:63]
	v_mfma_f32_16x16x32_bf16 v[56:59], v[168:171], v[196:199], v[56:59]
	v_mfma_f32_16x16x32_bf16 v[44:47], v[160:163], v[204:207], v[44:47]
	v_mfma_f32_16x16x32_bf16 v[40:43], v[168:171], v[204:207], v[40:43]
	v_mfma_f32_16x16x32_bf16 v[28:31], v[160:163], v[212:215], v[28:31]
	v_mfma_f32_16x16x32_bf16 v[24:27], v[168:171], v[212:215], v[24:27]
	v_mfma_f32_16x16x32_bf16 v[12:15], v[160:163], v[220:223], v[12:15]
	v_mfma_f32_16x16x32_bf16 v[8:11], v[168:171], v[220:223], v[8:11]
	s_setprio 0
	s_setprio 1
	v_mfma_f32_16x16x32_bf16 v[52:55], v[172:175], v[188:191], v[52:55]
	v_mfma_f32_16x16x32_bf16 v[48:51], v[180:183], v[188:191], v[48:51]
	v_mfma_f32_16x16x32_bf16 v[36:39], v[172:175], v[200:203], v[36:39]
	v_mfma_f32_16x16x32_bf16 v[32:35], v[180:183], v[200:203], v[32:35]
	v_mfma_f32_16x16x32_bf16 v[20:23], v[172:175], v[208:211], v[20:23]
	v_mfma_f32_16x16x32_bf16 v[16:19], v[180:183], v[208:211], v[16:19]
	v_mfma_f32_16x16x32_bf16 v[4:7], v[172:175], v[216:219], v[4:7]
	v_mfma_f32_16x16x32_bf16 v[0:3], v[180:183], v[216:219], v[0:3]
	v_mfma_f32_16x16x32_bf16 v[52:55], v[176:179], v[196:199], v[52:55]
	v_mfma_f32_16x16x32_bf16 v[48:51], v[184:187], v[196:199], v[48:51]
	v_mfma_f32_16x16x32_bf16 v[36:39], v[176:179], v[204:207], v[36:39]
	v_mfma_f32_16x16x32_bf16 v[32:35], v[184:187], v[204:207], v[32:35]
	v_mfma_f32_16x16x32_bf16 v[20:23], v[176:179], v[212:215], v[20:23]
	v_mfma_f32_16x16x32_bf16 v[16:19], v[184:187], v[212:215], v[16:19]
	v_mfma_f32_16x16x32_bf16 v[4:7], v[176:179], v[220:223], v[4:7]
	v_mfma_f32_16x16x32_bf16 v[0:3], v[184:187], v[220:223], v[0:3]
	s_setprio 0
	s_barrier
	s_add_i32 s78, 0, 0x18000
	v_add_u32_e32 v159, s78, v153
	s_add_i32 s79, 0, 0x1c000
	ds_read_b128 v[146:149], v159
	ds_read_b128 v[160:163], v159 offset:1024
	ds_read_b128 v[164:167], v159 offset:2048
	ds_read_b128 v[168:171], v159 offset:3072
	v_add_u32_e32 v159, s79, v153
	ds_read_b128 v[172:175], v159
	ds_read_b128 v[176:179], v159 offset:1024
	ds_read_b128 v[180:183], v159 offset:2048
	ds_read_b128 v[184:187], v159 offset:3072
	s_add_u32 s28, s36, 0xb0000
	s_addc_u32 s29, s37, 0
	ds_read_b128 v[188:191], v157 offset:32768
	ds_read_b128 v[196:199], v157 offset:33792
	ds_read_b128 v[200:203], v157 offset:34816
	ds_read_b128 v[204:207], v157 offset:35840
	ds_read_b128 v[208:211], v157 offset:36864
	ds_read_b128 v[212:215], v157 offset:37888
	ds_read_b128 v[216:219], v157 offset:38912
	ds_read_b128 v[220:223], v157 offset:39936
	s_mov_b32 m0, s44
	s_nop 0
	global_load_lds_dwordx4 v[224:225], off
	s_mov_b32 m0, s45
	s_nop 0
	global_load_lds_dwordx4 v[226:227], off
	s_mov_b32 m0, s50
	s_nop 0
	global_load_lds_dwordx4 v130, s[28:29]
	s_mov_b32 m0, s51
	s_nop 0
	global_load_lds_dwordx4 v134, s[28:29]
	s_waitcnt vmcnt(8)
	s_waitcnt lgkmcnt(0)
	s_barrier
	s_setprio 1
	s_waitcnt lgkmcnt(0)
	v_mfma_f32_16x16x32_bf16 v[124:127], v[146:149], v[188:191], v[124:127]
	v_mfma_f32_16x16x32_bf16 v[120:123], v[164:167], v[188:191], v[120:123]
	v_mfma_f32_16x16x32_bf16 v[108:111], v[146:149], v[200:203], v[108:111]
	v_mfma_f32_16x16x32_bf16 v[104:107], v[164:167], v[200:203], v[104:107]
	v_mfma_f32_16x16x32_bf16 v[92:95], v[146:149], v[208:211], v[92:95]
	v_mfma_f32_16x16x32_bf16 v[88:91], v[164:167], v[208:211], v[88:91]
	v_mfma_f32_16x16x32_bf16 v[76:79], v[146:149], v[216:219], v[76:79]
	v_mfma_f32_16x16x32_bf16 v[72:75], v[164:167], v[216:219], v[72:75]
	v_mfma_f32_16x16x32_bf16 v[124:127], v[160:163], v[196:199], v[124:127]
	v_mfma_f32_16x16x32_bf16 v[120:123], v[168:171], v[196:199], v[120:123]
	v_mfma_f32_16x16x32_bf16 v[108:111], v[160:163], v[204:207], v[108:111]
	v_mfma_f32_16x16x32_bf16 v[104:107], v[168:171], v[204:207], v[104:107]
	v_mfma_f32_16x16x32_bf16 v[92:95], v[160:163], v[212:215], v[92:95]
	v_mfma_f32_16x16x32_bf16 v[88:91], v[168:171], v[212:215], v[88:91]
	v_mfma_f32_16x16x32_bf16 v[76:79], v[160:163], v[220:223], v[76:79]
	v_mfma_f32_16x16x32_bf16 v[72:75], v[168:171], v[220:223], v[72:75]
	s_setprio 0
	s_setprio 1
	v_mfma_f32_16x16x32_bf16 v[116:119], v[172:175], v[188:191], v[116:119]
	v_mfma_f32_16x16x32_bf16 v[112:115], v[180:183], v[188:191], v[112:115]
	v_mfma_f32_16x16x32_bf16 v[100:103], v[172:175], v[200:203], v[100:103]
	v_mfma_f32_16x16x32_bf16 v[96:99], v[180:183], v[200:203], v[96:99]
	v_mfma_f32_16x16x32_bf16 v[84:87], v[172:175], v[208:211], v[84:87]
	v_mfma_f32_16x16x32_bf16 v[80:83], v[180:183], v[208:211], v[80:83]
	v_mfma_f32_16x16x32_bf16 v[68:71], v[172:175], v[216:219], v[68:71]
	v_mfma_f32_16x16x32_bf16 v[64:67], v[180:183], v[216:219], v[64:67]
	v_mfma_f32_16x16x32_bf16 v[116:119], v[176:179], v[196:199], v[116:119]
	v_mfma_f32_16x16x32_bf16 v[112:115], v[184:187], v[196:199], v[112:115]
	v_mfma_f32_16x16x32_bf16 v[100:103], v[176:179], v[204:207], v[100:103]
	v_mfma_f32_16x16x32_bf16 v[96:99], v[184:187], v[204:207], v[96:99]
	v_mfma_f32_16x16x32_bf16 v[84:87], v[176:179], v[212:215], v[84:87]
	v_mfma_f32_16x16x32_bf16 v[80:83], v[184:187], v[212:215], v[80:83]
	v_mfma_f32_16x16x32_bf16 v[68:71], v[176:179], v[220:223], v[68:71]
	v_mfma_f32_16x16x32_bf16 v[64:67], v[184:187], v[220:223], v[64:67]
	s_setprio 0
	s_barrier
	s_add_i32 s28, s78, s43
	v_lshl_add_u64 v[150:151], v[150:151], 0, s[22:23]
	s_mov_b32 m0, s28
	ds_read_b128 v[188:191], v157 offset:49152
	ds_read_b128 v[196:199], v157 offset:50176
	ds_read_b128 v[200:203], v157 offset:51200
	ds_read_b128 v[204:207], v157 offset:52224
	ds_read_b128 v[208:211], v157 offset:53248
	ds_read_b128 v[212:215], v157 offset:54272
	ds_read_b128 v[216:219], v157 offset:55296
	ds_read_b128 v[220:223], v157 offset:56320
	global_load_lds_dwordx4 v[150:151], off
	s_add_i32 m0, s28, 0x2000
	s_add_u32 s28, s34, 0xb0080
	v_lshl_add_u64 v[150:151], v[192:193], 0, s[22:23]
	s_addc_u32 s29, s35, 0
	s_add_i32 s34, s79, s43
	global_load_lds_dwordx4 v[150:151], off
	s_mov_b32 m0, s34
	s_nop 0
	global_load_lds_dwordx4 v132, s[28:29]
	s_add_i32 m0, s34, 0x2000
	s_nop 0
	global_load_lds_dwordx4 v136, s[28:29]
	s_waitcnt vmcnt(6)
	s_waitcnt lgkmcnt(0)
	s_barrier
	s_setprio 1
	s_waitcnt lgkmcnt(0)
	v_mfma_f32_16x16x32_bf16 v[60:63], v[146:149], v[188:191], v[60:63]
	v_mfma_f32_16x16x32_bf16 v[56:59], v[164:167], v[188:191], v[56:59]
	v_mfma_f32_16x16x32_bf16 v[44:47], v[146:149], v[200:203], v[44:47]
	v_mfma_f32_16x16x32_bf16 v[40:43], v[164:167], v[200:203], v[40:43]
	v_mfma_f32_16x16x32_bf16 v[28:31], v[146:149], v[208:211], v[28:31]
	v_mfma_f32_16x16x32_bf16 v[24:27], v[164:167], v[208:211], v[24:27]
	v_mfma_f32_16x16x32_bf16 v[12:15], v[146:149], v[216:219], v[12:15]
	v_mfma_f32_16x16x32_bf16 v[8:11], v[164:167], v[216:219], v[8:11]
	v_mfma_f32_16x16x32_bf16 v[60:63], v[160:163], v[196:199], v[60:63]
	v_mfma_f32_16x16x32_bf16 v[56:59], v[168:171], v[196:199], v[56:59]
	v_mfma_f32_16x16x32_bf16 v[44:47], v[160:163], v[204:207], v[44:47]
	v_mfma_f32_16x16x32_bf16 v[40:43], v[168:171], v[204:207], v[40:43]
	v_mfma_f32_16x16x32_bf16 v[28:31], v[160:163], v[212:215], v[28:31]
	v_mfma_f32_16x16x32_bf16 v[24:27], v[168:171], v[212:215], v[24:27]
	v_mfma_f32_16x16x32_bf16 v[12:15], v[160:163], v[220:223], v[12:15]
	v_mfma_f32_16x16x32_bf16 v[8:11], v[168:171], v[220:223], v[8:11]
	s_setprio 0
	s_setprio 1
	v_mfma_f32_16x16x32_bf16 v[52:55], v[172:175], v[188:191], v[52:55]
	v_mfma_f32_16x16x32_bf16 v[48:51], v[180:183], v[188:191], v[48:51]
	v_mfma_f32_16x16x32_bf16 v[36:39], v[172:175], v[200:203], v[36:39]
	v_mfma_f32_16x16x32_bf16 v[32:35], v[180:183], v[200:203], v[32:35]
	v_mfma_f32_16x16x32_bf16 v[20:23], v[172:175], v[208:211], v[20:23]
	v_mfma_f32_16x16x32_bf16 v[16:19], v[180:183], v[208:211], v[16:19]
	v_mfma_f32_16x16x32_bf16 v[4:7], v[172:175], v[216:219], v[4:7]
	v_mfma_f32_16x16x32_bf16 v[0:3], v[180:183], v[216:219], v[0:3]
	v_mfma_f32_16x16x32_bf16 v[52:55], v[176:179], v[196:199], v[52:55]
	v_mfma_f32_16x16x32_bf16 v[48:51], v[184:187], v[196:199], v[48:51]
	v_mfma_f32_16x16x32_bf16 v[36:39], v[176:179], v[204:207], v[36:39]
	v_mfma_f32_16x16x32_bf16 v[32:35], v[184:187], v[204:207], v[32:35]
	v_mfma_f32_16x16x32_bf16 v[20:23], v[176:179], v[212:215], v[20:23]
	v_mfma_f32_16x16x32_bf16 v[16:19], v[184:187], v[212:215], v[16:19]
	v_mfma_f32_16x16x32_bf16 v[4:7], v[176:179], v[220:223], v[4:7]
	v_mfma_f32_16x16x32_bf16 v[0:3], v[184:187], v[220:223], v[0:3]
	s_setprio 0
	s_barrier
	v_lshl_add_u64 v[224:225], v[224:225], 0, s[22:23]
	s_mov_b32 m0, s55
	s_nop 0
	global_load_lds_dwordx4 v[224:225], off
	v_lshl_add_u64 v[226:227], v[226:227], 0, s[22:23]
	s_mov_b32 m0, s58
	s_nop 0
	global_load_lds_dwordx4 v[226:227], off
	s_add_i32 s77, s77, 2
	s_add_u32 s72, s72, 0x100
	s_addc_u32 s73, s73, 0
	s_cmp_gt_u32 s77, 41
	s_mov_b64 s[28:29], s[30:31]
	s_cbranch_scc0 .LBB0_532
	s_and_b64 vcc, exec, s[24:25]
	s_cbranch_vccz .LBB0_535
	s_barrier

.LBB0_626:
	ds_read_b128 v[152:155], v157
	ds_read_b128 v[162:165], v157 offset:1024
	ds_read_b128 v[166:169], v157 offset:2048
	ds_read_b128 v[170:173], v157 offset:3072
	ds_read_b128 v[174:177], v158
	ds_read_b128 v[178:181], v158 offset:1024
	ds_read_b128 v[182:185], v158 offset:2048
	ds_read_b128 v[186:189], v158 offset:3072
	s_add_u32 s40, s38, 0xfffc0080
	s_addc_u32 s41, s39, -1
	s_cmp_eq_u32 s86, 12
	s_cselect_b32 s43, s1, s41
	s_cselect_b32 s42, s11, s40
	s_cselect_b32 s41, s12, s85
	s_cselect_b32 s40, s29, s31
	s_add_i32 m0, s58, 0xc000
	ds_read_b128 v[190:193], v159
	ds_read_b128 v[196:199], v159 offset:1024
	ds_read_b128 v[200:203], v159 offset:2048
	ds_read_b128 v[204:207], v159 offset:3072
	ds_read_b128 v[208:211], v159 offset:4096
	ds_read_b128 v[212:215], v159 offset:5120
	ds_read_b128 v[216:219], v159 offset:6144
	ds_read_b128 v[220:223], v159 offset:7168
	global_load_lds_dwordx4 v144, s[38:39]
	s_add_i32 m0, s58, 0xe000
	s_nop 0
	global_load_lds_dwordx4 v146, s[38:39]
	s_waitcnt vmcnt(8)
	s_waitcnt lgkmcnt(0)
	s_barrier
	s_setprio 1
	s_waitcnt lgkmcnt(0)
	v_mfma_f32_16x16x32_bf16 v[124:127], v[152:155], v[190:193], v[124:127]
	v_mfma_f32_16x16x32_bf16 v[120:123], v[166:169], v[190:193], v[120:123]
	v_mfma_f32_16x16x32_bf16 v[108:111], v[152:155], v[200:203], v[108:111]
	v_mfma_f32_16x16x32_bf16 v[104:107], v[166:169], v[200:203], v[104:107]
	v_mfma_f32_16x16x32_bf16 v[92:95], v[152:155], v[208:211], v[92:95]
	v_mfma_f32_16x16x32_bf16 v[88:91], v[166:169], v[208:211], v[88:91]
	v_mfma_f32_16x16x32_bf16 v[76:79], v[152:155], v[216:219], v[76:79]
	v_mfma_f32_16x16x32_bf16 v[72:75], v[166:169], v[216:219], v[72:75]
	v_mfma_f32_16x16x32_bf16 v[124:127], v[162:165], v[196:199], v[124:127]
	v_mfma_f32_16x16x32_bf16 v[120:123], v[170:173], v[196:199], v[120:123]
	v_mfma_f32_16x16x32_bf16 v[108:111], v[162:165], v[204:207], v[108:111]
	v_mfma_f32_16x16x32_bf16 v[104:107], v[170:173], v[204:207], v[104:107]
	v_mfma_f32_16x16x32_bf16 v[92:95], v[162:165], v[212:215], v[92:95]
	v_mfma_f32_16x16x32_bf16 v[88:91], v[170:173], v[212:215], v[88:91]
	v_mfma_f32_16x16x32_bf16 v[76:79], v[162:165], v[220:223], v[76:79]
	v_mfma_f32_16x16x32_bf16 v[72:75], v[170:173], v[220:223], v[72:75]
	s_setprio 0
	s_setprio 1
	v_mfma_f32_16x16x32_bf16 v[116:119], v[174:177], v[190:193], v[116:119]
	v_mfma_f32_16x16x32_bf16 v[112:115], v[182:185], v[190:193], v[112:115]
	v_mfma_f32_16x16x32_bf16 v[100:103], v[174:177], v[200:203], v[100:103]
	v_mfma_f32_16x16x32_bf16 v[96:99], v[182:185], v[200:203], v[96:99]
	v_mfma_f32_16x16x32_bf16 v[84:87], v[174:177], v[208:211], v[84:87]
	v_mfma_f32_16x16x32_bf16 v[80:83], v[182:185], v[208:211], v[80:83]
	v_mfma_f32_16x16x32_bf16 v[68:71], v[174:177], v[216:219], v[68:71]
	v_mfma_f32_16x16x32_bf16 v[64:67], v[182:185], v[216:219], v[64:67]
	v_mfma_f32_16x16x32_bf16 v[116:119], v[178:181], v[196:199], v[116:119]
	v_mfma_f32_16x16x32_bf16 v[112:115], v[186:189], v[196:199], v[112:115]
	v_mfma_f32_16x16x32_bf16 v[100:103], v[178:181], v[204:207], v[100:103]
	v_mfma_f32_16x16x32_bf16 v[96:99], v[186:189], v[204:207], v[96:99]
	v_mfma_f32_16x16x32_bf16 v[84:87], v[178:181], v[212:215], v[84:87]
	v_mfma_f32_16x16x32_bf16 v[80:83], v[186:189], v[212:215], v[80:83]
	v_mfma_f32_16x16x32_bf16 v[68:71], v[178:181], v[220:223], v[68:71]
	v_mfma_f32_16x16x32_bf16 v[64:67], v[186:189], v[220:223], v[64:67]
	s_setprio 0
	s_barrier
	s_add_i32 s87, s73, s55
	v_lshl_add_u64 v[224:225], s[40:41], 0, v[130:131]
	s_mov_b32 m0, s87
	ds_read_b128 v[190:193], v159 offset:16384
	ds_read_b128 v[196:199], v159 offset:17408
	ds_read_b128 v[200:203], v159 offset:18432
	ds_read_b128 v[204:207], v159 offset:19456
	ds_read_b128 v[208:211], v159 offset:20480
	ds_read_b128 v[212:215], v159 offset:21504
	ds_read_b128 v[216:219], v159 offset:22528
	ds_read_b128 v[220:223], v159 offset:23552
	global_load_lds_dwordx4 v[224:225], off
	s_add_i32 m0, s87, 0x2000
	s_add_u32 s88, s40, 0x40000
	v_lshl_add_u64 v[226:227], s[40:41], 0, v[134:135]
	s_addc_u32 s89, s41, 0
	s_add_i32 s87, s77, s55
	global_load_lds_dwordx4 v[226:227], off
	s_mov_b32 m0, s87
	v_lshl_add_u64 v[230:231], s[42:43], 0, v[132:133]
	global_load_lds_dwordx4 v130, s[88:89]
	s_add_i32 m0, s87, 0x2000
	s_nop 0
	global_load_lds_dwordx4 v134, s[88:89]
	v_lshl_add_u64 v[228:229], s[42:43], 0, v[128:129]
	s_waitcnt vmcnt(6)
	s_waitcnt lgkmcnt(0)
	s_barrier
	s_setprio 1
	s_waitcnt lgkmcnt(0)
	v_mfma_f32_16x16x32_bf16 v[60:63], v[152:155], v[190:193], v[60:63]
	v_mfma_f32_16x16x32_bf16 v[56:59], v[166:169], v[190:193], v[56:59]
	v_mfma_f32_16x16x32_bf16 v[44:47], v[152:155], v[200:203], v[44:47]
	v_mfma_f32_16x16x32_bf16 v[40:43], v[166:169], v[200:203], v[40:43]
	v_mfma_f32_16x16x32_bf16 v[28:31], v[152:155], v[208:211], v[28:31]
	v_mfma_f32_16x16x32_bf16 v[24:27], v[166:169], v[208:211], v[24:27]
	v_mfma_f32_16x16x32_bf16 v[12:15], v[152:155], v[216:219], v[12:15]
	v_mfma_f32_16x16x32_bf16 v[8:11], v[166:169], v[216:219], v[8:11]
	v_mfma_f32_16x16x32_bf16 v[60:63], v[162:165], v[196:199], v[60:63]
	v_mfma_f32_16x16x32_bf16 v[56:59], v[170:173], v[196:199], v[56:59]
	v_mfma_f32_16x16x32_bf16 v[44:47], v[162:165], v[204:207], v[44:47]
	v_mfma_f32_16x16x32_bf16 v[40:43], v[170:173], v[204:207], v[40:43]
	v_mfma_f32_16x16x32_bf16 v[28:31], v[162:165], v[212:215], v[28:31]
	v_mfma_f32_16x16x32_bf16 v[24:27], v[170:173], v[212:215], v[24:27]
	v_mfma_f32_16x16x32_bf16 v[12:15], v[162:165], v[220:223], v[12:15]
	v_mfma_f32_16x16x32_bf16 v[8:11], v[170:173], v[220:223], v[8:11]
	s_setprio 0
	s_setprio 1
	v_mfma_f32_16x16x32_bf16 v[52:55], v[174:177], v[190:193], v[52:55]
	v_mfma_f32_16x16x32_bf16 v[48:51], v[182:185], v[190:193], v[48:51]
	v_mfma_f32_16x16x32_bf16 v[36:39], v[174:177], v[200:203], v[36:39]
	v_mfma_f32_16x16x32_bf16 v[32:35], v[182:185], v[200:203], v[32:35]
	v_mfma_f32_16x16x32_bf16 v[20:23], v[174:177], v[208:211], v[20:23]
	v_mfma_f32_16x16x32_bf16 v[16:19], v[182:185], v[208:211], v[16:19]
	v_mfma_f32_16x16x32_bf16 v[4:7], v[174:177], v[216:219], v[4:7]
	v_mfma_f32_16x16x32_bf16 v[0:3], v[182:185], v[216:219], v[0:3]
	v_mfma_f32_16x16x32_bf16 v[52:55], v[178:181], v[196:199], v[52:55]
	v_mfma_f32_16x16x32_bf16 v[48:51], v[186:189], v[196:199], v[48:51]
	v_mfma_f32_16x16x32_bf16 v[36:39], v[178:181], v[204:207], v[36:39]
	v_mfma_f32_16x16x32_bf16 v[32:35], v[186:189], v[204:207], v[32:35]
	v_mfma_f32_16x16x32_bf16 v[20:23], v[178:181], v[212:215], v[20:23]
	v_mfma_f32_16x16x32_bf16 v[16:19], v[186:189], v[212:215], v[16:19]
	v_mfma_f32_16x16x32_bf16 v[4:7], v[178:181], v[220:223], v[4:7]
	v_mfma_f32_16x16x32_bf16 v[0:3], v[186:189], v[220:223], v[0:3]
	s_setprio 0
	s_barrier
	s_add_i32 s87, 0, 0x18000
	v_add_u32_e32 v136, s87, v141
	s_add_i32 s88, 0, 0x1c000
	ds_read_b128 v[152:155], v136
	ds_read_b128 v[162:165], v136 offset:1024
	ds_read_b128 v[166:169], v136 offset:2048
	ds_read_b128 v[170:173], v136 offset:3072
	v_add_u32_e32 v136, s88, v141
	ds_read_b128 v[174:177], v136
	ds_read_b128 v[178:181], v136 offset:1024
	ds_read_b128 v[182:185], v136 offset:2048
	ds_read_b128 v[186:189], v136 offset:3072
	s_add_u32 s42, s42, 0x40000
	s_addc_u32 s43, s43, 0
	ds_read_b128 v[190:193], v159 offset:32768
	ds_read_b128 v[196:199], v159 offset:33792
	ds_read_b128 v[200:203], v159 offset:34816
	ds_read_b128 v[204:207], v159 offset:35840
	ds_read_b128 v[208:211], v159 offset:36864
	ds_read_b128 v[212:215], v159 offset:37888
	ds_read_b128 v[216:219], v159 offset:38912
	ds_read_b128 v[220:223], v159 offset:39936
	s_mov_b32 m0, s58
	s_nop 0
	global_load_lds_dwordx4 v[228:229], off
	s_mov_b32 m0, s59
	s_nop 0
	global_load_lds_dwordx4 v[230:231], off
	s_mov_b32 m0, s60
	s_nop 0
	global_load_lds_dwordx4 v128, s[42:43]
	s_mov_b32 m0, s61
	s_nop 0
	global_load_lds_dwordx4 v132, s[42:43]
	s_waitcnt vmcnt(8)
	s_waitcnt lgkmcnt(0)
	s_barrier
	s_setprio 1
	s_waitcnt lgkmcnt(0)
	v_mfma_f32_16x16x32_bf16 v[124:127], v[152:155], v[190:193], v[124:127]
	v_mfma_f32_16x16x32_bf16 v[120:123], v[166:169], v[190:193], v[120:123]
	v_mfma_f32_16x16x32_bf16 v[108:111], v[152:155], v[200:203], v[108:111]
	v_mfma_f32_16x16x32_bf16 v[104:107], v[166:169], v[200:203], v[104:107]
	v_mfma_f32_16x16x32_bf16 v[92:95], v[152:155], v[208:211], v[92:95]
	v_mfma_f32_16x16x32_bf16 v[88:91], v[166:169], v[208:211], v[88:91]
	v_mfma_f32_16x16x32_bf16 v[76:79], v[152:155], v[216:219], v[76:79]
	v_mfma_f32_16x16x32_bf16 v[72:75], v[166:169], v[216:219], v[72:75]
	v_mfma_f32_16x16x32_bf16 v[124:127], v[162:165], v[196:199], v[124:127]
	v_mfma_f32_16x16x32_bf16 v[120:123], v[170:173], v[196:199], v[120:123]
	v_mfma_f32_16x16x32_bf16 v[108:111], v[162:165], v[204:207], v[108:111]
	v_mfma_f32_16x16x32_bf16 v[104:107], v[170:173], v[204:207], v[104:107]
	v_mfma_f32_16x16x32_bf16 v[92:95], v[162:165], v[212:215], v[92:95]
	v_mfma_f32_16x16x32_bf16 v[88:91], v[170:173], v[212:215], v[88:91]
	v_mfma_f32_16x16x32_bf16 v[76:79], v[162:165], v[220:223], v[76:79]
	v_mfma_f32_16x16x32_bf16 v[72:75], v[170:173], v[220:223], v[72:75]
	s_setprio 0
	s_setprio 1
	v_mfma_f32_16x16x32_bf16 v[116:119], v[174:177], v[190:193], v[116:119]
	v_mfma_f32_16x16x32_bf16 v[112:115], v[182:185], v[190:193], v[112:115]
	v_mfma_f32_16x16x32_bf16 v[100:103], v[174:177], v[200:203], v[100:103]
	v_mfma_f32_16x16x32_bf16 v[96:99], v[182:185], v[200:203], v[96:99]
	v_mfma_f32_16x16x32_bf16 v[84:87], v[174:177], v[208:211], v[84:87]
	v_mfma_f32_16x16x32_bf16 v[80:83], v[182:185], v[208:211], v[80:83]
	v_mfma_f32_16x16x32_bf16 v[68:71], v[174:177], v[216:219], v[68:71]
	v_mfma_f32_16x16x32_bf16 v[64:67], v[182:185], v[216:219], v[64:67]
	v_mfma_f32_16x16x32_bf16 v[116:119], v[178:181], v[196:199], v[116:119]
	v_mfma_f32_16x16x32_bf16 v[112:115], v[186:189], v[196:199], v[112:115]
	v_mfma_f32_16x16x32_bf16 v[100:103], v[178:181], v[204:207], v[100:103]
	v_mfma_f32_16x16x32_bf16 v[96:99], v[186:189], v[204:207], v[96:99]
	v_mfma_f32_16x16x32_bf16 v[84:87], v[178:181], v[212:215], v[84:87]
	v_mfma_f32_16x16x32_bf16 v[80:83], v[186:189], v[212:215], v[80:83]
	v_mfma_f32_16x16x32_bf16 v[68:71], v[178:181], v[220:223], v[68:71]
	v_mfma_f32_16x16x32_bf16 v[64:67], v[186:189], v[220:223], v[64:67]
	s_setprio 0
	s_barrier
	s_add_i32 s42, s87, s55
	v_lshl_add_u64 v[224:225], v[224:225], 0, s[24:25]
	s_mov_b32 m0, s42
	ds_read_b128 v[190:193], v159 offset:49152
	ds_read_b128 v[196:199], v159 offset:50176
	ds_read_b128 v[200:203], v159 offset:51200
	ds_read_b128 v[204:207], v159 offset:52224
	ds_read_b128 v[208:211], v159 offset:53248
	ds_read_b128 v[212:215], v159 offset:54272
	ds_read_b128 v[216:219], v159 offset:55296
	ds_read_b128 v[220:223], v159 offset:56320
	global_load_lds_dwordx4 v[224:225], off
	s_add_i32 m0, s42, 0x2000
	s_add_u32 s40, s40, 0x40080
	v_lshl_add_u64 v[224:225], v[226:227], 0, s[24:25]
	s_addc_u32 s41, s41, 0
	s_add_i32 s42, s88, s55
	global_load_lds_dwordx4 v[224:225], off
	s_mov_b32 m0, s42
	s_nop 0
	global_load_lds_dwordx4 v130, s[40:41]
	s_add_i32 m0, s42, 0x2000
	s_nop 0
	global_load_lds_dwordx4 v134, s[40:41]
	s_waitcnt vmcnt(6)
	s_waitcnt lgkmcnt(0)
	s_barrier
	s_setprio 1
	s_waitcnt lgkmcnt(0)
	v_mfma_f32_16x16x32_bf16 v[60:63], v[152:155], v[190:193], v[60:63]
	v_mfma_f32_16x16x32_bf16 v[56:59], v[166:169], v[190:193], v[56:59]
	v_mfma_f32_16x16x32_bf16 v[44:47], v[152:155], v[200:203], v[44:47]
	v_mfma_f32_16x16x32_bf16 v[40:43], v[166:169], v[200:203], v[40:43]
	v_mfma_f32_16x16x32_bf16 v[28:31], v[152:155], v[208:211], v[28:31]
	v_mfma_f32_16x16x32_bf16 v[24:27], v[166:169], v[208:211], v[24:27]
	v_mfma_f32_16x16x32_bf16 v[12:15], v[152:155], v[216:219], v[12:15]
	v_mfma_f32_16x16x32_bf16 v[8:11], v[166:169], v[216:219], v[8:11]
	v_mfma_f32_16x16x32_bf16 v[60:63], v[162:165], v[196:199], v[60:63]
	v_mfma_f32_16x16x32_bf16 v[56:59], v[170:173], v[196:199], v[56:59]
	v_mfma_f32_16x16x32_bf16 v[44:47], v[162:165], v[204:207], v[44:47]
	v_mfma_f32_16x16x32_bf16 v[40:43], v[170:173], v[204:207], v[40:43]
	v_mfma_f32_16x16x32_bf16 v[28:31], v[162:165], v[212:215], v[28:31]
	v_mfma_f32_16x16x32_bf16 v[24:27], v[170:173], v[212:215], v[24:27]
	v_mfma_f32_16x16x32_bf16 v[12:15], v[162:165], v[220:223], v[12:15]
	v_mfma_f32_16x16x32_bf16 v[8:11], v[170:173], v[220:223], v[8:11]
	s_setprio 0
	s_setprio 1
	v_mfma_f32_16x16x32_bf16 v[52:55], v[174:177], v[190:193], v[52:55]
	v_mfma_f32_16x16x32_bf16 v[48:51], v[182:185], v[190:193], v[48:51]
	v_mfma_f32_16x16x32_bf16 v[36:39], v[174:177], v[200:203], v[36:39]
	v_mfma_f32_16x16x32_bf16 v[32:35], v[182:185], v[200:203], v[32:35]
	v_mfma_f32_16x16x32_bf16 v[20:23], v[174:177], v[208:211], v[20:23]
	v_mfma_f32_16x16x32_bf16 v[16:19], v[182:185], v[208:211], v[16:19]
	v_mfma_f32_16x16x32_bf16 v[4:7], v[174:177], v[216:219], v[4:7]
	v_mfma_f32_16x16x32_bf16 v[0:3], v[182:185], v[216:219], v[0:3]
	v_mfma_f32_16x16x32_bf16 v[52:55], v[178:181], v[196:199], v[52:55]
	v_mfma_f32_16x16x32_bf16 v[48:51], v[186:189], v[196:199], v[48:51]
	v_mfma_f32_16x16x32_bf16 v[36:39], v[178:181], v[204:207], v[36:39]
	v_mfma_f32_16x16x32_bf16 v[32:35], v[186:189], v[204:207], v[32:35]
	v_mfma_f32_16x16x32_bf16 v[20:23], v[178:181], v[212:215], v[20:23]
	v_mfma_f32_16x16x32_bf16 v[16:19], v[186:189], v[212:215], v[16:19]
	v_mfma_f32_16x16x32_bf16 v[4:7], v[178:181], v[220:223], v[4:7]
	v_mfma_f32_16x16x32_bf16 v[0:3], v[186:189], v[220:223], v[0:3]
	s_setprio 0
	s_barrier
	v_lshl_add_u64 v[228:229], v[228:229], 0, s[24:25]
	s_mov_b32 m0, s70
	s_nop 0
	global_load_lds_dwordx4 v[228:229], off
	v_lshl_add_u64 v[230:231], v[230:231], 0, s[24:25]
	s_mov_b32 m0, s71
	s_nop 0
	global_load_lds_dwordx4 v[230:231], off
	s_add_i32 s86, s86, 2
	s_add_u32 s38, s38, 0x100
	s_addc_u32 s39, s39, 0
	s_add_u32 s31, s31, 0x100
	s_addc_u32 s85, s85, 0
	s_cmp_gt_u32 s86, 13
	s_cbranch_scc0 .LBB0_626
	s_and_b64 vcc, exec, s[26:27]
	s_cbranch_vccz .LBB0_629
	s_barrier

.LBB0_760:
	ds_read_b128 v[148:151], v144
	ds_read_b128 v[152:155], v144 offset:1024
	ds_read_b128 v[156:159], v144 offset:2048
	ds_read_b128 v[160:163], v144 offset:3072
	ds_read_b128 v[164:167], v145
	ds_read_b128 v[168:171], v145 offset:1024
	ds_read_b128 v[172:175], v145 offset:2048
	ds_read_b128 v[176:179], v145 offset:3072
	s_add_u32 s36, s34, 0x100
	s_addc_u32 s37, s35, 0
	s_cmp_eq_u32 s83, 4
	s_cselect_b32 s41, s29, s37
	s_cselect_b32 s40, s28, s36
	s_cselect_b32 s39, s31, s25
	s_cselect_b32 s38, s30, s13
	v_lshl_add_u64 v[192:193], s[34:35], 0, v[138:139]
	s_add_i32 m0, s58, 0xc000
	ds_read_b128 v[180:183], v146
	ds_read_b128 v[184:187], v146 offset:1024
	ds_read_b128 v[188:191], v146 offset:2048
	ds_read_b128 v[196:199], v146 offset:3072
	ds_read_b128 v[200:203], v146 offset:4096
	ds_read_b128 v[204:207], v146 offset:5120
	ds_read_b128 v[208:211], v146 offset:6144
	ds_read_b128 v[212:215], v146 offset:7168
	global_load_lds_dwordx4 v[192:193], off
	v_lshl_add_u64 v[192:193], s[34:35], 0, v[140:141]
	s_add_i32 m0, s58, 0xe000
	s_nop 0
	global_load_lds_dwordx4 v[192:193], off
	s_waitcnt vmcnt(8)
	s_waitcnt lgkmcnt(0)
	s_barrier
	s_setprio 1
	s_waitcnt lgkmcnt(0)
	v_mfma_f32_16x16x32_bf16 v[124:127], v[148:151], v[180:183], v[124:127]
	v_mfma_f32_16x16x32_bf16 v[120:123], v[156:159], v[180:183], v[120:123]
	v_mfma_f32_16x16x32_bf16 v[116:119], v[148:151], v[188:191], v[116:119]
	v_mfma_f32_16x16x32_bf16 v[112:115], v[156:159], v[188:191], v[112:115]
	v_mfma_f32_16x16x32_bf16 v[104:107], v[148:151], v[200:203], v[104:107]
	v_mfma_f32_16x16x32_bf16 v[96:99], v[156:159], v[200:203], v[96:99]
	v_mfma_f32_16x16x32_bf16 v[88:91], v[148:151], v[208:211], v[88:91]
	v_mfma_f32_16x16x32_bf16 v[80:83], v[156:159], v[208:211], v[80:83]
	v_mfma_f32_16x16x32_bf16 v[124:127], v[152:155], v[184:187], v[124:127]
	v_mfma_f32_16x16x32_bf16 v[120:123], v[160:163], v[184:187], v[120:123]
	v_mfma_f32_16x16x32_bf16 v[116:119], v[152:155], v[196:199], v[116:119]
	v_mfma_f32_16x16x32_bf16 v[112:115], v[160:163], v[196:199], v[112:115]
	v_mfma_f32_16x16x32_bf16 v[104:107], v[152:155], v[204:207], v[104:107]
	v_mfma_f32_16x16x32_bf16 v[96:99], v[160:163], v[204:207], v[96:99]
	v_mfma_f32_16x16x32_bf16 v[88:91], v[152:155], v[212:215], v[88:91]
	v_mfma_f32_16x16x32_bf16 v[80:83], v[160:163], v[212:215], v[80:83]
	s_setprio 0
	s_setprio 1
	v_mfma_f32_16x16x32_bf16 v[108:111], v[164:167], v[180:183], v[108:111]
	v_mfma_f32_16x16x32_bf16 v[100:103], v[172:175], v[180:183], v[100:103]
	v_mfma_f32_16x16x32_bf16 v[92:95], v[164:167], v[188:191], v[92:95]
	v_mfma_f32_16x16x32_bf16 v[84:87], v[172:175], v[188:191], v[84:87]
	v_mfma_f32_16x16x32_bf16 v[76:79], v[164:167], v[200:203], v[76:79]
	v_mfma_f32_16x16x32_bf16 v[72:75], v[172:175], v[200:203], v[72:75]
	v_mfma_f32_16x16x32_bf16 v[68:71], v[164:167], v[208:211], v[68:71]
	v_mfma_f32_16x16x32_bf16 v[64:67], v[172:175], v[208:211], v[64:67]
	v_mfma_f32_16x16x32_bf16 v[108:111], v[168:171], v[184:187], v[108:111]
	v_mfma_f32_16x16x32_bf16 v[100:103], v[176:179], v[184:187], v[100:103]
	v_mfma_f32_16x16x32_bf16 v[92:95], v[168:171], v[196:199], v[92:95]
	v_mfma_f32_16x16x32_bf16 v[84:87], v[176:179], v[196:199], v[84:87]
	v_mfma_f32_16x16x32_bf16 v[76:79], v[168:171], v[204:207], v[76:79]
	v_mfma_f32_16x16x32_bf16 v[72:75], v[176:179], v[204:207], v[72:75]
	v_mfma_f32_16x16x32_bf16 v[68:71], v[168:171], v[212:215], v[68:71]
	v_mfma_f32_16x16x32_bf16 v[64:67], v[176:179], v[212:215], v[64:67]
	s_setprio 0
	s_barrier
	s_add_i32 s34, s77, s51
	v_lshl_add_u64 v[192:193], s[38:39], 0, v[132:133]
	s_mov_b32 m0, s34
	ds_read_b128 v[180:183], v146 offset:16384
	ds_read_b128 v[184:187], v146 offset:17408
	ds_read_b128 v[188:191], v146 offset:18432
	ds_read_b128 v[196:199], v146 offset:19456
	ds_read_b128 v[200:203], v146 offset:20480
	ds_read_b128 v[204:207], v146 offset:21504
	ds_read_b128 v[208:211], v146 offset:22528
	ds_read_b128 v[212:215], v146 offset:23552
	global_load_lds_dwordx4 v[192:193], off
	s_add_i32 m0, s34, 0x2000
	s_add_u32 s34, s38, 0x20000
	v_lshl_add_u64 v[216:217], s[38:39], 0, v[128:129]
	s_addc_u32 s35, s39, 0
	s_add_i32 s84, s78, s51
	global_load_lds_dwordx4 v[216:217], off
	s_mov_b32 m0, s84
	v_lshl_add_u64 v[220:221], s[40:41], 0, v[130:131]
	global_load_lds_dwordx4 v132, s[34:35]
	s_add_i32 m0, s84, 0x2000
	s_nop 0
	global_load_lds_dwordx4 v128, s[34:35]
	v_lshl_add_u64 v[218:219], s[40:41], 0, v[134:135]
	s_waitcnt vmcnt(6)
	s_waitcnt lgkmcnt(0)
	s_barrier
	s_setprio 1
	s_waitcnt lgkmcnt(0)
	v_mfma_f32_16x16x32_bf16 v[60:63], v[148:151], v[180:183], v[60:63]
	v_mfma_f32_16x16x32_bf16 v[56:59], v[156:159], v[180:183], v[56:59]
	v_mfma_f32_16x16x32_bf16 v[52:55], v[148:151], v[188:191], v[52:55]
	v_mfma_f32_16x16x32_bf16 v[48:51], v[156:159], v[188:191], v[48:51]
	v_mfma_f32_16x16x32_bf16 v[40:43], v[148:151], v[200:203], v[40:43]
	v_mfma_f32_16x16x32_bf16 v[32:35], v[156:159], v[200:203], v[32:35]
	v_mfma_f32_16x16x32_bf16 v[24:27], v[148:151], v[208:211], v[24:27]
	v_mfma_f32_16x16x32_bf16 v[16:19], v[156:159], v[208:211], v[16:19]
	v_mfma_f32_16x16x32_bf16 v[60:63], v[152:155], v[184:187], v[60:63]
	v_mfma_f32_16x16x32_bf16 v[56:59], v[160:163], v[184:187], v[56:59]
	v_mfma_f32_16x16x32_bf16 v[52:55], v[152:155], v[196:199], v[52:55]
	v_mfma_f32_16x16x32_bf16 v[48:51], v[160:163], v[196:199], v[48:51]
	v_mfma_f32_16x16x32_bf16 v[40:43], v[152:155], v[204:207], v[40:43]
	v_mfma_f32_16x16x32_bf16 v[32:35], v[160:163], v[204:207], v[32:35]
	v_mfma_f32_16x16x32_bf16 v[24:27], v[152:155], v[212:215], v[24:27]
	v_mfma_f32_16x16x32_bf16 v[16:19], v[160:163], v[212:215], v[16:19]
	s_setprio 0
	s_setprio 1
	v_mfma_f32_16x16x32_bf16 v[44:47], v[164:167], v[180:183], v[44:47]
	v_mfma_f32_16x16x32_bf16 v[36:39], v[172:175], v[180:183], v[36:39]
	v_mfma_f32_16x16x32_bf16 v[28:31], v[164:167], v[188:191], v[28:31]
	v_mfma_f32_16x16x32_bf16 v[20:23], v[172:175], v[188:191], v[20:23]
	v_mfma_f32_16x16x32_bf16 v[12:15], v[164:167], v[200:203], v[12:15]
	v_mfma_f32_16x16x32_bf16 v[8:11], v[172:175], v[200:203], v[8:11]
	v_mfma_f32_16x16x32_bf16 v[4:7], v[164:167], v[208:211], v[4:7]
	v_mfma_f32_16x16x32_bf16 v[0:3], v[172:175], v[208:211], v[0:3]
	v_mfma_f32_16x16x32_bf16 v[44:47], v[168:171], v[184:187], v[44:47]
	v_mfma_f32_16x16x32_bf16 v[36:39], v[176:179], v[184:187], v[36:39]
	v_mfma_f32_16x16x32_bf16 v[28:31], v[168:171], v[196:199], v[28:31]
	v_mfma_f32_16x16x32_bf16 v[20:23], v[176:179], v[196:199], v[20:23]
	v_mfma_f32_16x16x32_bf16 v[12:15], v[168:171], v[204:207], v[12:15]
	v_mfma_f32_16x16x32_bf16 v[8:11], v[176:179], v[204:207], v[8:11]
	v_mfma_f32_16x16x32_bf16 v[4:7], v[168:171], v[212:215], v[4:7]
	v_mfma_f32_16x16x32_bf16 v[0:3], v[176:179], v[212:215], v[0:3]
	s_setprio 0
	s_barrier
	s_add_i32 s84, 0, 0x18000
	v_add_u32_e32 v147, s84, v143
	s_add_i32 s85, 0, 0x1c000
	ds_read_b128 v[148:151], v147
	ds_read_b128 v[152:155], v147 offset:1024
	ds_read_b128 v[156:159], v147 offset:2048
	ds_read_b128 v[160:163], v147 offset:3072
	v_add_u32_e32 v147, s85, v143
	ds_read_b128 v[164:167], v147
	ds_read_b128 v[168:171], v147 offset:1024
	ds_read_b128 v[172:175], v147 offset:2048
	ds_read_b128 v[176:179], v147 offset:3072
	s_add_u32 s34, s40, 0x30000
	s_addc_u32 s35, s41, 0
	ds_read_b128 v[180:183], v146 offset:32768
	ds_read_b128 v[184:187], v146 offset:33792
	ds_read_b128 v[188:191], v146 offset:34816
	ds_read_b128 v[196:199], v146 offset:35840
	ds_read_b128 v[200:203], v146 offset:36864
	ds_read_b128 v[204:207], v146 offset:37888
	ds_read_b128 v[208:211], v146 offset:38912
	ds_read_b128 v[212:215], v146 offset:39936
	s_mov_b32 m0, s58
	s_nop 0
	global_load_lds_dwordx4 v[218:219], off
	s_mov_b32 m0, s59
	s_nop 0
	global_load_lds_dwordx4 v[220:221], off
	s_mov_b32 m0, s60
	s_nop 0
	global_load_lds_dwordx4 v134, s[34:35]
	s_mov_b32 m0, s61
	s_nop 0
	global_load_lds_dwordx4 v130, s[34:35]
	s_waitcnt vmcnt(8)
	s_waitcnt lgkmcnt(0)
	s_barrier
	s_setprio 1
	s_waitcnt lgkmcnt(0)
	v_mfma_f32_16x16x32_bf16 v[124:127], v[148:151], v[180:183], v[124:127]
	v_mfma_f32_16x16x32_bf16 v[120:123], v[156:159], v[180:183], v[120:123]
	v_mfma_f32_16x16x32_bf16 v[116:119], v[148:151], v[188:191], v[116:119]
	v_mfma_f32_16x16x32_bf16 v[112:115], v[156:159], v[188:191], v[112:115]
	v_mfma_f32_16x16x32_bf16 v[104:107], v[148:151], v[200:203], v[104:107]
	v_mfma_f32_16x16x32_bf16 v[96:99], v[156:159], v[200:203], v[96:99]
	v_mfma_f32_16x16x32_bf16 v[88:91], v[148:151], v[208:211], v[88:91]
	v_mfma_f32_16x16x32_bf16 v[80:83], v[156:159], v[208:211], v[80:83]
	v_mfma_f32_16x16x32_bf16 v[124:127], v[152:155], v[184:187], v[124:127]
	v_mfma_f32_16x16x32_bf16 v[120:123], v[160:163], v[184:187], v[120:123]
	v_mfma_f32_16x16x32_bf16 v[116:119], v[152:155], v[196:199], v[116:119]
	v_mfma_f32_16x16x32_bf16 v[112:115], v[160:163], v[196:199], v[112:115]
	v_mfma_f32_16x16x32_bf16 v[104:107], v[152:155], v[204:207], v[104:107]
	v_mfma_f32_16x16x32_bf16 v[96:99], v[160:163], v[204:207], v[96:99]
	v_mfma_f32_16x16x32_bf16 v[88:91], v[152:155], v[212:215], v[88:91]
	v_mfma_f32_16x16x32_bf16 v[80:83], v[160:163], v[212:215], v[80:83]
	s_setprio 0
	s_setprio 1
	v_mfma_f32_16x16x32_bf16 v[108:111], v[164:167], v[180:183], v[108:111]
	v_mfma_f32_16x16x32_bf16 v[100:103], v[172:175], v[180:183], v[100:103]
	v_mfma_f32_16x16x32_bf16 v[92:95], v[164:167], v[188:191], v[92:95]
	v_mfma_f32_16x16x32_bf16 v[84:87], v[172:175], v[188:191], v[84:87]
	v_mfma_f32_16x16x32_bf16 v[76:79], v[164:167], v[200:203], v[76:79]
	v_mfma_f32_16x16x32_bf16 v[72:75], v[172:175], v[200:203], v[72:75]
	v_mfma_f32_16x16x32_bf16 v[68:71], v[164:167], v[208:211], v[68:71]
	v_mfma_f32_16x16x32_bf16 v[64:67], v[172:175], v[208:211], v[64:67]
	v_mfma_f32_16x16x32_bf16 v[108:111], v[168:171], v[184:187], v[108:111]
	v_mfma_f32_16x16x32_bf16 v[100:103], v[176:179], v[184:187], v[100:103]
	v_mfma_f32_16x16x32_bf16 v[92:95], v[168:171], v[196:199], v[92:95]
	v_mfma_f32_16x16x32_bf16 v[84:87], v[176:179], v[196:199], v[84:87]
	v_mfma_f32_16x16x32_bf16 v[76:79], v[168:171], v[204:207], v[76:79]
	v_mfma_f32_16x16x32_bf16 v[72:75], v[176:179], v[204:207], v[72:75]
	v_mfma_f32_16x16x32_bf16 v[68:71], v[168:171], v[212:215], v[68:71]
	v_mfma_f32_16x16x32_bf16 v[64:67], v[176:179], v[212:215], v[64:67]
	s_setprio 0
	s_barrier
	s_add_i32 s34, s84, s51
	v_lshl_add_u64 v[192:193], v[192:193], 0, s[10:11]
	s_mov_b32 m0, s34
	ds_read_b128 v[180:183], v146 offset:49152
	ds_read_b128 v[184:187], v146 offset:50176
	ds_read_b128 v[188:191], v146 offset:51200
	ds_read_b128 v[196:199], v146 offset:52224
	ds_read_b128 v[200:203], v146 offset:53248
	ds_read_b128 v[204:207], v146 offset:54272
	ds_read_b128 v[208:211], v146 offset:55296
	ds_read_b128 v[212:215], v146 offset:56320
	global_load_lds_dwordx4 v[192:193], off
	s_add_i32 m0, s34, 0x2000
	s_add_u32 s34, s38, 0x20080
	v_lshl_add_u64 v[192:193], v[216:217], 0, s[10:11]
	s_addc_u32 s35, s39, 0
	s_add_i32 s38, s85, s51
	global_load_lds_dwordx4 v[192:193], off
	s_mov_b32 m0, s38
	s_nop 0
	global_load_lds_dwordx4 v132, s[34:35]
	s_add_i32 m0, s38, 0x2000
	s_nop 0
	global_load_lds_dwordx4 v128, s[34:35]
	s_waitcnt vmcnt(6)
	s_waitcnt lgkmcnt(0)
	s_barrier
	s_setprio 1
	s_waitcnt lgkmcnt(0)
	v_mfma_f32_16x16x32_bf16 v[60:63], v[148:151], v[180:183], v[60:63]
	v_mfma_f32_16x16x32_bf16 v[56:59], v[156:159], v[180:183], v[56:59]
	v_mfma_f32_16x16x32_bf16 v[52:55], v[148:151], v[188:191], v[52:55]
	v_mfma_f32_16x16x32_bf16 v[48:51], v[156:159], v[188:191], v[48:51]
	v_mfma_f32_16x16x32_bf16 v[40:43], v[148:151], v[200:203], v[40:43]
	v_mfma_f32_16x16x32_bf16 v[32:35], v[156:159], v[200:203], v[32:35]
	v_mfma_f32_16x16x32_bf16 v[24:27], v[148:151], v[208:211], v[24:27]
	v_mfma_f32_16x16x32_bf16 v[16:19], v[156:159], v[208:211], v[16:19]
	v_mfma_f32_16x16x32_bf16 v[60:63], v[152:155], v[184:187], v[60:63]
	v_mfma_f32_16x16x32_bf16 v[56:59], v[160:163], v[184:187], v[56:59]
	v_mfma_f32_16x16x32_bf16 v[52:55], v[152:155], v[196:199], v[52:55]
	v_mfma_f32_16x16x32_bf16 v[48:51], v[160:163], v[196:199], v[48:51]
	v_mfma_f32_16x16x32_bf16 v[40:43], v[152:155], v[204:207], v[40:43]
	v_mfma_f32_16x16x32_bf16 v[32:35], v[160:163], v[204:207], v[32:35]
	v_mfma_f32_16x16x32_bf16 v[24:27], v[152:155], v[212:215], v[24:27]
	v_mfma_f32_16x16x32_bf16 v[16:19], v[160:163], v[212:215], v[16:19]
	s_setprio 0
	s_setprio 1
	v_mfma_f32_16x16x32_bf16 v[44:47], v[164:167], v[180:183], v[44:47]
	v_mfma_f32_16x16x32_bf16 v[36:39], v[172:175], v[180:183], v[36:39]
	v_mfma_f32_16x16x32_bf16 v[28:31], v[164:167], v[188:191], v[28:31]
	v_mfma_f32_16x16x32_bf16 v[20:23], v[172:175], v[188:191], v[20:23]
	v_mfma_f32_16x16x32_bf16 v[12:15], v[164:167], v[200:203], v[12:15]
	v_mfma_f32_16x16x32_bf16 v[8:11], v[172:175], v[200:203], v[8:11]
	v_mfma_f32_16x16x32_bf16 v[4:7], v[164:167], v[208:211], v[4:7]
	v_mfma_f32_16x16x32_bf16 v[0:3], v[172:175], v[208:211], v[0:3]
	v_mfma_f32_16x16x32_bf16 v[44:47], v[168:171], v[184:187], v[44:47]
	v_mfma_f32_16x16x32_bf16 v[36:39], v[176:179], v[184:187], v[36:39]
	v_mfma_f32_16x16x32_bf16 v[28:31], v[168:171], v[196:199], v[28:31]
	v_mfma_f32_16x16x32_bf16 v[20:23], v[176:179], v[196:199], v[20:23]
	v_mfma_f32_16x16x32_bf16 v[12:15], v[168:171], v[204:207], v[12:15]
	v_mfma_f32_16x16x32_bf16 v[8:11], v[176:179], v[204:207], v[8:11]
	v_mfma_f32_16x16x32_bf16 v[4:7], v[168:171], v[212:215], v[4:7]
	v_mfma_f32_16x16x32_bf16 v[0:3], v[176:179], v[212:215], v[0:3]
	s_setprio 0
	s_barrier
	v_lshl_add_u64 v[218:219], v[218:219], 0, s[10:11]
	s_mov_b32 m0, s71
	s_nop 0
	global_load_lds_dwordx4 v[218:219], off
	v_lshl_add_u64 v[220:221], v[220:221], 0, s[10:11]
	s_mov_b32 m0, s72
	s_nop 0
	global_load_lds_dwordx4 v[220:221], off
	s_add_i32 s83, s83, 2
	s_add_u32 s13, s13, 0x100
	s_addc_u32 s25, s25, 0
	s_cmp_gt_u32 s83, 5
	s_mov_b64 s[34:35], s[36:37]
	s_cbranch_scc0 .LBB0_760
	s_and_b64 vcc, exec, s[16:17]
	s_cbranch_vccz .LBB0_763
	s_barrier

.LBB0_786:
	ds_read_b128 v[144:147], v153
	ds_read_b128 v[158:161], v153 offset:1024
	ds_read_b128 v[162:165], v153 offset:2048
	ds_read_b128 v[166:169], v153 offset:3072
	ds_read_b128 v[170:173], v154
	ds_read_b128 v[174:177], v154 offset:1024
	ds_read_b128 v[178:181], v154 offset:2048
	ds_read_b128 v[182:185], v154 offset:3072
	s_add_u32 s34, s30, 0xfffc0080
	s_addc_u32 s35, s31, -1
	s_cmp_eq_u32 s82, 12
	s_cselect_b32 s37, s25, s35
	s_cselect_b32 s36, s78, s34
	s_cselect_b32 s35, s23, s81
	s_cselect_b32 s34, s79, s80
	s_add_i32 m0, s50, 0xc000
	ds_read_b128 v[186:189], v155
	ds_read_b128 v[190:193], v155 offset:1024
	ds_read_b128 v[196:199], v155 offset:2048
	ds_read_b128 v[200:203], v155 offset:3072
	ds_read_b128 v[204:207], v155 offset:4096
	ds_read_b128 v[208:211], v155 offset:5120
	ds_read_b128 v[212:215], v155 offset:6144
	ds_read_b128 v[216:219], v155 offset:7168
	global_load_lds_dwordx4 v136, s[30:31]
	s_add_i32 m0, s50, 0xe000
	s_nop 0
	global_load_lds_dwordx4 v138, s[30:31]
	s_waitcnt vmcnt(8)
	s_waitcnt lgkmcnt(0)
	s_barrier
	s_setprio 1
	s_waitcnt lgkmcnt(0)
	v_mfma_f32_16x16x32_bf16 v[124:127], v[144:147], v[186:189], v[124:127]
	v_mfma_f32_16x16x32_bf16 v[120:123], v[162:165], v[186:189], v[120:123]
	v_mfma_f32_16x16x32_bf16 v[108:111], v[144:147], v[196:199], v[108:111]
	v_mfma_f32_16x16x32_bf16 v[104:107], v[162:165], v[196:199], v[104:107]
	v_mfma_f32_16x16x32_bf16 v[92:95], v[144:147], v[204:207], v[92:95]
	v_mfma_f32_16x16x32_bf16 v[88:91], v[162:165], v[204:207], v[88:91]
	v_mfma_f32_16x16x32_bf16 v[76:79], v[144:147], v[212:215], v[76:79]
	v_mfma_f32_16x16x32_bf16 v[72:75], v[162:165], v[212:215], v[72:75]
	v_mfma_f32_16x16x32_bf16 v[124:127], v[158:161], v[190:193], v[124:127]
	v_mfma_f32_16x16x32_bf16 v[120:123], v[166:169], v[190:193], v[120:123]
	v_mfma_f32_16x16x32_bf16 v[108:111], v[158:161], v[200:203], v[108:111]
	v_mfma_f32_16x16x32_bf16 v[104:107], v[166:169], v[200:203], v[104:107]
	v_mfma_f32_16x16x32_bf16 v[92:95], v[158:161], v[208:211], v[92:95]
	v_mfma_f32_16x16x32_bf16 v[88:91], v[166:169], v[208:211], v[88:91]
	v_mfma_f32_16x16x32_bf16 v[76:79], v[158:161], v[216:219], v[76:79]
	v_mfma_f32_16x16x32_bf16 v[72:75], v[166:169], v[216:219], v[72:75]
	s_setprio 0
	s_setprio 1
	v_mfma_f32_16x16x32_bf16 v[116:119], v[170:173], v[186:189], v[116:119]
	v_mfma_f32_16x16x32_bf16 v[112:115], v[178:181], v[186:189], v[112:115]
	v_mfma_f32_16x16x32_bf16 v[100:103], v[170:173], v[196:199], v[100:103]
	v_mfma_f32_16x16x32_bf16 v[96:99], v[178:181], v[196:199], v[96:99]
	v_mfma_f32_16x16x32_bf16 v[84:87], v[170:173], v[204:207], v[84:87]
	v_mfma_f32_16x16x32_bf16 v[80:83], v[178:181], v[204:207], v[80:83]
	v_mfma_f32_16x16x32_bf16 v[68:71], v[170:173], v[212:215], v[68:71]
	v_mfma_f32_16x16x32_bf16 v[64:67], v[178:181], v[212:215], v[64:67]
	v_mfma_f32_16x16x32_bf16 v[116:119], v[174:177], v[190:193], v[116:119]
	v_mfma_f32_16x16x32_bf16 v[112:115], v[182:185], v[190:193], v[112:115]
	v_mfma_f32_16x16x32_bf16 v[100:103], v[174:177], v[200:203], v[100:103]
	v_mfma_f32_16x16x32_bf16 v[96:99], v[182:185], v[200:203], v[96:99]
	v_mfma_f32_16x16x32_bf16 v[84:87], v[174:177], v[208:211], v[84:87]
	v_mfma_f32_16x16x32_bf16 v[80:83], v[182:185], v[208:211], v[80:83]
	v_mfma_f32_16x16x32_bf16 v[68:71], v[174:177], v[216:219], v[68:71]
	v_mfma_f32_16x16x32_bf16 v[64:67], v[182:185], v[216:219], v[64:67]
	s_setprio 0
	s_barrier
	s_add_i32 s83, s70, s45
	v_lshl_add_u64 v[148:149], s[34:35], 0, v[130:131]
	s_mov_b32 m0, s83
	ds_read_b128 v[186:189], v155 offset:16384
	ds_read_b128 v[190:193], v155 offset:17408
	ds_read_b128 v[196:199], v155 offset:18432
	ds_read_b128 v[200:203], v155 offset:19456
	ds_read_b128 v[204:207], v155 offset:20480
	ds_read_b128 v[208:211], v155 offset:21504
	ds_read_b128 v[212:215], v155 offset:22528
	ds_read_b128 v[216:219], v155 offset:23552
	global_load_lds_dwordx4 v[148:149], off
	s_add_i32 m0, s83, 0x2000
	s_add_u32 s84, s34, 0x40000
	v_lshl_add_u64 v[220:221], s[34:35], 0, v[134:135]
	s_addc_u32 s85, s35, 0
	s_add_i32 s83, s71, s45
	global_load_lds_dwordx4 v[220:221], off
	s_mov_b32 m0, s83
	v_lshl_add_u64 v[224:225], s[36:37], 0, v[132:133]
	global_load_lds_dwordx4 v130, s[84:85]
	s_add_i32 m0, s83, 0x2000
	s_nop 0
	global_load_lds_dwordx4 v134, s[84:85]
	v_lshl_add_u64 v[222:223], s[36:37], 0, v[128:129]
	s_waitcnt vmcnt(6)
	s_waitcnt lgkmcnt(0)
	s_barrier
	s_setprio 1
	s_waitcnt lgkmcnt(0)
	v_mfma_f32_16x16x32_bf16 v[60:63], v[144:147], v[186:189], v[60:63]
	v_mfma_f32_16x16x32_bf16 v[56:59], v[162:165], v[186:189], v[56:59]
	v_mfma_f32_16x16x32_bf16 v[44:47], v[144:147], v[196:199], v[44:47]
	v_mfma_f32_16x16x32_bf16 v[40:43], v[162:165], v[196:199], v[40:43]
	v_mfma_f32_16x16x32_bf16 v[28:31], v[144:147], v[204:207], v[28:31]
	v_mfma_f32_16x16x32_bf16 v[24:27], v[162:165], v[204:207], v[24:27]
	v_mfma_f32_16x16x32_bf16 v[12:15], v[144:147], v[212:215], v[12:15]
	v_mfma_f32_16x16x32_bf16 v[8:11], v[162:165], v[212:215], v[8:11]
	v_mfma_f32_16x16x32_bf16 v[60:63], v[158:161], v[190:193], v[60:63]
	v_mfma_f32_16x16x32_bf16 v[56:59], v[166:169], v[190:193], v[56:59]
	v_mfma_f32_16x16x32_bf16 v[44:47], v[158:161], v[200:203], v[44:47]
	v_mfma_f32_16x16x32_bf16 v[40:43], v[166:169], v[200:203], v[40:43]
	v_mfma_f32_16x16x32_bf16 v[28:31], v[158:161], v[208:211], v[28:31]
	v_mfma_f32_16x16x32_bf16 v[24:27], v[166:169], v[208:211], v[24:27]
	v_mfma_f32_16x16x32_bf16 v[12:15], v[158:161], v[216:219], v[12:15]
	v_mfma_f32_16x16x32_bf16 v[8:11], v[166:169], v[216:219], v[8:11]
	s_setprio 0
	s_setprio 1
	v_mfma_f32_16x16x32_bf16 v[52:55], v[170:173], v[186:189], v[52:55]
	v_mfma_f32_16x16x32_bf16 v[48:51], v[178:181], v[186:189], v[48:51]
	v_mfma_f32_16x16x32_bf16 v[36:39], v[170:173], v[196:199], v[36:39]
	v_mfma_f32_16x16x32_bf16 v[32:35], v[178:181], v[196:199], v[32:35]
	v_mfma_f32_16x16x32_bf16 v[20:23], v[170:173], v[204:207], v[20:23]
	v_mfma_f32_16x16x32_bf16 v[16:19], v[178:181], v[204:207], v[16:19]
	v_mfma_f32_16x16x32_bf16 v[4:7], v[170:173], v[212:215], v[4:7]
	v_mfma_f32_16x16x32_bf16 v[0:3], v[178:181], v[212:215], v[0:3]
	v_mfma_f32_16x16x32_bf16 v[52:55], v[174:177], v[190:193], v[52:55]
	v_mfma_f32_16x16x32_bf16 v[48:51], v[182:185], v[190:193], v[48:51]
	v_mfma_f32_16x16x32_bf16 v[36:39], v[174:177], v[200:203], v[36:39]
	v_mfma_f32_16x16x32_bf16 v[32:35], v[182:185], v[200:203], v[32:35]
	v_mfma_f32_16x16x32_bf16 v[20:23], v[174:177], v[208:211], v[20:23]
	v_mfma_f32_16x16x32_bf16 v[16:19], v[182:185], v[208:211], v[16:19]
	v_mfma_f32_16x16x32_bf16 v[4:7], v[174:177], v[216:219], v[4:7]
	v_mfma_f32_16x16x32_bf16 v[0:3], v[182:185], v[216:219], v[0:3]
	s_setprio 0
	s_barrier
	s_add_i32 s83, 0, 0x18000
	v_add_u32_e32 v157, s83, v151
	s_add_i32 s84, 0, 0x1c000
	ds_read_b128 v[144:147], v157
	ds_read_b128 v[158:161], v157 offset:1024
	ds_read_b128 v[162:165], v157 offset:2048
	ds_read_b128 v[166:169], v157 offset:3072
	v_add_u32_e32 v157, s84, v151
	ds_read_b128 v[170:173], v157
	ds_read_b128 v[174:177], v157 offset:1024
	ds_read_b128 v[178:181], v157 offset:2048
	ds_read_b128 v[182:185], v157 offset:3072
	s_add_u32 s36, s36, 0x40000
	s_addc_u32 s37, s37, 0
	ds_read_b128 v[186:189], v155 offset:32768
	ds_read_b128 v[190:193], v155 offset:33792
	ds_read_b128 v[196:199], v155 offset:34816
	ds_read_b128 v[200:203], v155 offset:35840
	ds_read_b128 v[204:207], v155 offset:36864
	ds_read_b128 v[208:211], v155 offset:37888
	ds_read_b128 v[212:215], v155 offset:38912
	ds_read_b128 v[216:219], v155 offset:39936
	s_mov_b32 m0, s50
	s_nop 0
	global_load_lds_dwordx4 v[222:223], off
	s_mov_b32 m0, s51
	s_nop 0
	global_load_lds_dwordx4 v[224:225], off
	s_mov_b32 m0, s58
	s_nop 0
	global_load_lds_dwordx4 v128, s[36:37]
	s_mov_b32 m0, s59
	s_nop 0
	global_load_lds_dwordx4 v132, s[36:37]
	s_waitcnt vmcnt(8)
	s_waitcnt lgkmcnt(0)
	s_barrier
	s_setprio 1
	s_waitcnt lgkmcnt(0)
	v_mfma_f32_16x16x32_bf16 v[124:127], v[144:147], v[186:189], v[124:127]
	v_mfma_f32_16x16x32_bf16 v[120:123], v[162:165], v[186:189], v[120:123]
	v_mfma_f32_16x16x32_bf16 v[108:111], v[144:147], v[196:199], v[108:111]
	v_mfma_f32_16x16x32_bf16 v[104:107], v[162:165], v[196:199], v[104:107]
	v_mfma_f32_16x16x32_bf16 v[92:95], v[144:147], v[204:207], v[92:95]
	v_mfma_f32_16x16x32_bf16 v[88:91], v[162:165], v[204:207], v[88:91]
	v_mfma_f32_16x16x32_bf16 v[76:79], v[144:147], v[212:215], v[76:79]
	v_mfma_f32_16x16x32_bf16 v[72:75], v[162:165], v[212:215], v[72:75]
	v_mfma_f32_16x16x32_bf16 v[124:127], v[158:161], v[190:193], v[124:127]
	v_mfma_f32_16x16x32_bf16 v[120:123], v[166:169], v[190:193], v[120:123]
	v_mfma_f32_16x16x32_bf16 v[108:111], v[158:161], v[200:203], v[108:111]
	v_mfma_f32_16x16x32_bf16 v[104:107], v[166:169], v[200:203], v[104:107]
	v_mfma_f32_16x16x32_bf16 v[92:95], v[158:161], v[208:211], v[92:95]
	v_mfma_f32_16x16x32_bf16 v[88:91], v[166:169], v[208:211], v[88:91]
	v_mfma_f32_16x16x32_bf16 v[76:79], v[158:161], v[216:219], v[76:79]
	v_mfma_f32_16x16x32_bf16 v[72:75], v[166:169], v[216:219], v[72:75]
	s_setprio 0
	s_setprio 1
	v_mfma_f32_16x16x32_bf16 v[116:119], v[170:173], v[186:189], v[116:119]
	v_mfma_f32_16x16x32_bf16 v[112:115], v[178:181], v[186:189], v[112:115]
	v_mfma_f32_16x16x32_bf16 v[100:103], v[170:173], v[196:199], v[100:103]
	v_mfma_f32_16x16x32_bf16 v[96:99], v[178:181], v[196:199], v[96:99]
	v_mfma_f32_16x16x32_bf16 v[84:87], v[170:173], v[204:207], v[84:87]
	v_mfma_f32_16x16x32_bf16 v[80:83], v[178:181], v[204:207], v[80:83]
	v_mfma_f32_16x16x32_bf16 v[68:71], v[170:173], v[212:215], v[68:71]
	v_mfma_f32_16x16x32_bf16 v[64:67], v[178:181], v[212:215], v[64:67]
	v_mfma_f32_16x16x32_bf16 v[116:119], v[174:177], v[190:193], v[116:119]
	v_mfma_f32_16x16x32_bf16 v[112:115], v[182:185], v[190:193], v[112:115]
	v_mfma_f32_16x16x32_bf16 v[100:103], v[174:177], v[200:203], v[100:103]
	v_mfma_f32_16x16x32_bf16 v[96:99], v[182:185], v[200:203], v[96:99]
	v_mfma_f32_16x16x32_bf16 v[84:87], v[174:177], v[208:211], v[84:87]
	v_mfma_f32_16x16x32_bf16 v[80:83], v[182:185], v[208:211], v[80:83]
	v_mfma_f32_16x16x32_bf16 v[68:71], v[174:177], v[216:219], v[68:71]
	v_mfma_f32_16x16x32_bf16 v[64:67], v[182:185], v[216:219], v[64:67]
	s_setprio 0
	s_barrier
	s_add_i32 s36, s83, s45
	v_lshl_add_u64 v[148:149], v[148:149], 0, s[18:19]
	s_mov_b32 m0, s36
	ds_read_b128 v[186:189], v155 offset:49152
	ds_read_b128 v[190:193], v155 offset:50176
	ds_read_b128 v[196:199], v155 offset:51200
	ds_read_b128 v[200:203], v155 offset:52224
	ds_read_b128 v[204:207], v155 offset:53248
	ds_read_b128 v[208:211], v155 offset:54272
	ds_read_b128 v[212:215], v155 offset:55296
	ds_read_b128 v[216:219], v155 offset:56320
	global_load_lds_dwordx4 v[148:149], off
	s_add_i32 m0, s36, 0x2000
	s_add_u32 s34, s34, 0x40080
	v_lshl_add_u64 v[148:149], v[220:221], 0, s[18:19]
	s_addc_u32 s35, s35, 0
	s_add_i32 s36, s84, s45
	global_load_lds_dwordx4 v[148:149], off
	s_mov_b32 m0, s36
	s_nop 0
	global_load_lds_dwordx4 v130, s[34:35]
	s_add_i32 m0, s36, 0x2000
	s_nop 0
	global_load_lds_dwordx4 v134, s[34:35]
	s_waitcnt vmcnt(6)
	s_waitcnt lgkmcnt(0)
	s_barrier
	s_setprio 1
	s_waitcnt lgkmcnt(0)
	v_mfma_f32_16x16x32_bf16 v[60:63], v[144:147], v[186:189], v[60:63]
	v_mfma_f32_16x16x32_bf16 v[56:59], v[162:165], v[186:189], v[56:59]
	v_mfma_f32_16x16x32_bf16 v[44:47], v[144:147], v[196:199], v[44:47]
	v_mfma_f32_16x16x32_bf16 v[40:43], v[162:165], v[196:199], v[40:43]
	v_mfma_f32_16x16x32_bf16 v[28:31], v[144:147], v[204:207], v[28:31]
	v_mfma_f32_16x16x32_bf16 v[24:27], v[162:165], v[204:207], v[24:27]
	v_mfma_f32_16x16x32_bf16 v[12:15], v[144:147], v[212:215], v[12:15]
	v_mfma_f32_16x16x32_bf16 v[8:11], v[162:165], v[212:215], v[8:11]
	v_mfma_f32_16x16x32_bf16 v[60:63], v[158:161], v[190:193], v[60:63]
	v_mfma_f32_16x16x32_bf16 v[56:59], v[166:169], v[190:193], v[56:59]
	v_mfma_f32_16x16x32_bf16 v[44:47], v[158:161], v[200:203], v[44:47]
	v_mfma_f32_16x16x32_bf16 v[40:43], v[166:169], v[200:203], v[40:43]
	v_mfma_f32_16x16x32_bf16 v[28:31], v[158:161], v[208:211], v[28:31]
	v_mfma_f32_16x16x32_bf16 v[24:27], v[166:169], v[208:211], v[24:27]
	v_mfma_f32_16x16x32_bf16 v[12:15], v[158:161], v[216:219], v[12:15]
	v_mfma_f32_16x16x32_bf16 v[8:11], v[166:169], v[216:219], v[8:11]
	s_setprio 0
	s_setprio 1
	v_mfma_f32_16x16x32_bf16 v[52:55], v[170:173], v[186:189], v[52:55]
	v_mfma_f32_16x16x32_bf16 v[48:51], v[178:181], v[186:189], v[48:51]
	v_mfma_f32_16x16x32_bf16 v[36:39], v[170:173], v[196:199], v[36:39]
	v_mfma_f32_16x16x32_bf16 v[32:35], v[178:181], v[196:199], v[32:35]
	v_mfma_f32_16x16x32_bf16 v[20:23], v[170:173], v[204:207], v[20:23]
	v_mfma_f32_16x16x32_bf16 v[16:19], v[178:181], v[204:207], v[16:19]
	v_mfma_f32_16x16x32_bf16 v[4:7], v[170:173], v[212:215], v[4:7]
	v_mfma_f32_16x16x32_bf16 v[0:3], v[178:181], v[212:215], v[0:3]
	v_mfma_f32_16x16x32_bf16 v[52:55], v[174:177], v[190:193], v[52:55]
	v_mfma_f32_16x16x32_bf16 v[48:51], v[182:185], v[190:193], v[48:51]
	v_mfma_f32_16x16x32_bf16 v[36:39], v[174:177], v[200:203], v[36:39]
	v_mfma_f32_16x16x32_bf16 v[32:35], v[182:185], v[200:203], v[32:35]
	v_mfma_f32_16x16x32_bf16 v[20:23], v[174:177], v[208:211], v[20:23]
	v_mfma_f32_16x16x32_bf16 v[16:19], v[182:185], v[208:211], v[16:19]
	v_mfma_f32_16x16x32_bf16 v[4:7], v[174:177], v[216:219], v[4:7]
	v_mfma_f32_16x16x32_bf16 v[0:3], v[182:185], v[216:219], v[0:3]
	s_setprio 0
	s_barrier
	v_lshl_add_u64 v[222:223], v[222:223], 0, s[18:19]
	s_mov_b32 m0, s61
	s_nop 0
	global_load_lds_dwordx4 v[222:223], off
	v_lshl_add_u64 v[224:225], v[224:225], 0, s[18:19]
	s_mov_b32 m0, s62
	s_nop 0
	global_load_lds_dwordx4 v[224:225], off
	s_add_i32 s82, s82, 2
	s_add_u32 s30, s30, 0x100
	s_addc_u32 s31, s31, 0
	s_add_u32 s80, s80, 0x100
	s_addc_u32 s81, s81, 0
	s_cmp_gt_u32 s82, 13
	s_cbranch_scc0 .LBB0_786
	s_and_b64 vcc, exec, s[20:21]
	s_cbranch_vccz .LBB0_789
	s_barrier

.LBB0_923:
	ds_read_b128 v[152:155], v148
	ds_read_b128 v[156:159], v148 offset:1024
	ds_read_b128 v[160:163], v148 offset:2048
	ds_read_b128 v[164:167], v148 offset:3072
	ds_read_b128 v[168:171], v149
	ds_read_b128 v[172:175], v149 offset:1024
	ds_read_b128 v[176:179], v149 offset:2048
	ds_read_b128 v[180:183], v149 offset:3072
	s_add_u32 s26, s24, 0x100
	s_addc_u32 s27, s25, 0
	s_cmp_eq_u32 s79, 8
	s_cselect_b32 s31, s21, s27
	s_cselect_b32 s30, s20, s26
	s_cselect_b32 s29, s23, s78
	s_cselect_b32 s28, s22, s73
	s_mov_b32 m0, s60
	v_lshl_add_u64 v[192:193], s[24:25], 0, v[138:139]
	ds_read_b128 v[184:187], v150
	ds_read_b128 v[188:191], v150 offset:1024
	ds_read_b128 v[196:199], v150 offset:2048
	ds_read_b128 v[200:203], v150 offset:3072
	ds_read_b128 v[204:207], v150 offset:4096
	ds_read_b128 v[208:211], v150 offset:5120
	ds_read_b128 v[212:215], v150 offset:6144
	ds_read_b128 v[216:219], v150 offset:7168
	global_load_lds_dwordx4 v[192:193], off
	v_lshl_add_u64 v[192:193], s[24:25], 0, v[140:141]
	s_add_i32 m0, s40, 0xe000
	s_nop 0
	global_load_lds_dwordx4 v[192:193], off
	s_waitcnt vmcnt(8)
	s_waitcnt lgkmcnt(0)
	s_barrier
	s_setprio 1
	s_waitcnt lgkmcnt(0)
	v_mfma_f32_16x16x32_bf16 v[124:127], v[152:155], v[184:187], v[124:127]
	v_mfma_f32_16x16x32_bf16 v[120:123], v[160:163], v[184:187], v[120:123]
	v_mfma_f32_16x16x32_bf16 v[108:111], v[152:155], v[196:199], v[108:111]
	v_mfma_f32_16x16x32_bf16 v[104:107], v[160:163], v[196:199], v[104:107]
	v_mfma_f32_16x16x32_bf16 v[92:95], v[152:155], v[204:207], v[92:95]
	v_mfma_f32_16x16x32_bf16 v[88:91], v[160:163], v[204:207], v[88:91]
	v_mfma_f32_16x16x32_bf16 v[76:79], v[152:155], v[212:215], v[76:79]
	v_mfma_f32_16x16x32_bf16 v[72:75], v[160:163], v[212:215], v[72:75]
	v_mfma_f32_16x16x32_bf16 v[124:127], v[156:159], v[188:191], v[124:127]
	v_mfma_f32_16x16x32_bf16 v[120:123], v[164:167], v[188:191], v[120:123]
	v_mfma_f32_16x16x32_bf16 v[108:111], v[156:159], v[200:203], v[108:111]
	v_mfma_f32_16x16x32_bf16 v[104:107], v[164:167], v[200:203], v[104:107]
	v_mfma_f32_16x16x32_bf16 v[92:95], v[156:159], v[208:211], v[92:95]
	v_mfma_f32_16x16x32_bf16 v[88:91], v[164:167], v[208:211], v[88:91]
	v_mfma_f32_16x16x32_bf16 v[76:79], v[156:159], v[216:219], v[76:79]
	v_mfma_f32_16x16x32_bf16 v[72:75], v[164:167], v[216:219], v[72:75]
	s_setprio 0
	s_setprio 1
	v_mfma_f32_16x16x32_bf16 v[116:119], v[168:171], v[184:187], v[116:119]
	v_mfma_f32_16x16x32_bf16 v[112:115], v[176:179], v[184:187], v[112:115]
	v_mfma_f32_16x16x32_bf16 v[100:103], v[168:171], v[196:199], v[100:103]
	v_mfma_f32_16x16x32_bf16 v[96:99], v[176:179], v[196:199], v[96:99]
	v_mfma_f32_16x16x32_bf16 v[84:87], v[168:171], v[204:207], v[84:87]
	v_mfma_f32_16x16x32_bf16 v[80:83], v[176:179], v[204:207], v[80:83]
	v_mfma_f32_16x16x32_bf16 v[68:71], v[168:171], v[212:215], v[68:71]
	v_mfma_f32_16x16x32_bf16 v[64:67], v[176:179], v[212:215], v[64:67]
	v_mfma_f32_16x16x32_bf16 v[116:119], v[172:175], v[188:191], v[116:119]
	v_mfma_f32_16x16x32_bf16 v[112:115], v[180:183], v[188:191], v[112:115]
	v_mfma_f32_16x16x32_bf16 v[100:103], v[172:175], v[200:203], v[100:103]
	v_mfma_f32_16x16x32_bf16 v[96:99], v[180:183], v[200:203], v[96:99]
	v_mfma_f32_16x16x32_bf16 v[84:87], v[172:175], v[208:211], v[84:87]
	v_mfma_f32_16x16x32_bf16 v[80:83], v[180:183], v[208:211], v[80:83]
	v_mfma_f32_16x16x32_bf16 v[68:71], v[172:175], v[216:219], v[68:71]
	v_mfma_f32_16x16x32_bf16 v[64:67], v[180:183], v[216:219], v[64:67]
	s_setprio 0
	s_barrier
	s_add_i32 s24, s58, s39
	v_lshl_add_u64 v[192:193], s[28:29], 0, v[132:133]
	s_mov_b32 m0, s24
	ds_read_b128 v[184:187], v150 offset:16384
	ds_read_b128 v[188:191], v150 offset:17408
	ds_read_b128 v[196:199], v150 offset:18432
	ds_read_b128 v[200:203], v150 offset:19456
	ds_read_b128 v[204:207], v150 offset:20480
	ds_read_b128 v[208:211], v150 offset:21504
	ds_read_b128 v[212:215], v150 offset:22528
	ds_read_b128 v[216:219], v150 offset:23552
	global_load_lds_dwordx4 v[192:193], off
	s_add_i32 m0, s24, 0x2000
	s_add_u32 s24, s28, 0x30000
	v_lshl_add_u64 v[220:221], s[28:29], 0, v[128:129]
	s_addc_u32 s25, s29, 0
	s_add_i32 s80, s59, s39
	global_load_lds_dwordx4 v[220:221], off
	s_mov_b32 m0, s80
	v_lshl_add_u64 v[224:225], s[30:31], 0, v[130:131]
	global_load_lds_dwordx4 v132, s[24:25]
	s_add_i32 m0, s80, 0x2000
	s_nop 0
	global_load_lds_dwordx4 v128, s[24:25]
	v_lshl_add_u64 v[222:223], s[30:31], 0, v[134:135]
	s_waitcnt vmcnt(6)
	s_waitcnt lgkmcnt(0)
	s_barrier
	s_setprio 1
	s_waitcnt lgkmcnt(0)
	v_mfma_f32_16x16x32_bf16 v[60:63], v[152:155], v[184:187], v[60:63]
	v_mfma_f32_16x16x32_bf16 v[56:59], v[160:163], v[184:187], v[56:59]
	v_mfma_f32_16x16x32_bf16 v[44:47], v[152:155], v[196:199], v[44:47]
	v_mfma_f32_16x16x32_bf16 v[40:43], v[160:163], v[196:199], v[40:43]
	v_mfma_f32_16x16x32_bf16 v[28:31], v[152:155], v[204:207], v[28:31]
	v_mfma_f32_16x16x32_bf16 v[24:27], v[160:163], v[204:207], v[24:27]
	v_mfma_f32_16x16x32_bf16 v[12:15], v[152:155], v[212:215], v[12:15]
	v_mfma_f32_16x16x32_bf16 v[8:11], v[160:163], v[212:215], v[8:11]
	v_mfma_f32_16x16x32_bf16 v[60:63], v[156:159], v[188:191], v[60:63]
	v_mfma_f32_16x16x32_bf16 v[56:59], v[164:167], v[188:191], v[56:59]
	v_mfma_f32_16x16x32_bf16 v[44:47], v[156:159], v[200:203], v[44:47]
	v_mfma_f32_16x16x32_bf16 v[40:43], v[164:167], v[200:203], v[40:43]
	v_mfma_f32_16x16x32_bf16 v[28:31], v[156:159], v[208:211], v[28:31]
	v_mfma_f32_16x16x32_bf16 v[24:27], v[164:167], v[208:211], v[24:27]
	v_mfma_f32_16x16x32_bf16 v[12:15], v[156:159], v[216:219], v[12:15]
	v_mfma_f32_16x16x32_bf16 v[8:11], v[164:167], v[216:219], v[8:11]
	s_setprio 0
	s_setprio 1
	v_mfma_f32_16x16x32_bf16 v[52:55], v[168:171], v[184:187], v[52:55]
	v_mfma_f32_16x16x32_bf16 v[48:51], v[176:179], v[184:187], v[48:51]
	v_mfma_f32_16x16x32_bf16 v[36:39], v[168:171], v[196:199], v[36:39]
	v_mfma_f32_16x16x32_bf16 v[32:35], v[176:179], v[196:199], v[32:35]
	v_mfma_f32_16x16x32_bf16 v[20:23], v[168:171], v[204:207], v[20:23]
	v_mfma_f32_16x16x32_bf16 v[16:19], v[176:179], v[204:207], v[16:19]
	v_mfma_f32_16x16x32_bf16 v[4:7], v[168:171], v[212:215], v[4:7]
	v_mfma_f32_16x16x32_bf16 v[0:3], v[176:179], v[212:215], v[0:3]
	v_mfma_f32_16x16x32_bf16 v[52:55], v[172:175], v[188:191], v[52:55]
	v_mfma_f32_16x16x32_bf16 v[48:51], v[180:183], v[188:191], v[48:51]
	v_mfma_f32_16x16x32_bf16 v[36:39], v[172:175], v[200:203], v[36:39]
	v_mfma_f32_16x16x32_bf16 v[32:35], v[180:183], v[200:203], v[32:35]
	v_mfma_f32_16x16x32_bf16 v[20:23], v[172:175], v[208:211], v[20:23]
	v_mfma_f32_16x16x32_bf16 v[16:19], v[180:183], v[208:211], v[16:19]
	v_mfma_f32_16x16x32_bf16 v[4:7], v[172:175], v[216:219], v[4:7]
	v_mfma_f32_16x16x32_bf16 v[0:3], v[180:183], v[216:219], v[0:3]
	s_setprio 0
	s_barrier
	s_add_i32 s80, 0, 0x18000
	v_add_u32_e32 v151, s80, v142
	s_add_i32 s81, 0, 0x1c000
	ds_read_b128 v[152:155], v151
	ds_read_b128 v[156:159], v151 offset:1024
	ds_read_b128 v[160:163], v151 offset:2048
	ds_read_b128 v[164:167], v151 offset:3072
	v_add_u32_e32 v151, s81, v142
	ds_read_b128 v[168:171], v151
	ds_read_b128 v[172:175], v151 offset:1024
	ds_read_b128 v[176:179], v151 offset:2048
	ds_read_b128 v[180:183], v151 offset:3072
	s_add_u32 s24, s30, 0x30000
	s_addc_u32 s25, s31, 0
	ds_read_b128 v[184:187], v150 offset:32768
	ds_read_b128 v[188:191], v150 offset:33792
	ds_read_b128 v[196:199], v150 offset:34816
	ds_read_b128 v[200:203], v150 offset:35840
	ds_read_b128 v[204:207], v150 offset:36864
	ds_read_b128 v[208:211], v150 offset:37888
	ds_read_b128 v[212:215], v150 offset:38912
	ds_read_b128 v[216:219], v150 offset:39936
	s_mov_b32 m0, s40
	s_nop 0
	global_load_lds_dwordx4 v[222:223], off
	s_mov_b32 m0, s41
	s_nop 0
	global_load_lds_dwordx4 v[224:225], off
	s_mov_b32 m0, s42
	s_nop 0
	global_load_lds_dwordx4 v134, s[24:25]
	s_mov_b32 m0, s43
	s_nop 0
	global_load_lds_dwordx4 v130, s[24:25]
	s_waitcnt vmcnt(8)
	s_waitcnt lgkmcnt(0)
	s_barrier
	s_setprio 1
	s_waitcnt lgkmcnt(0)
	v_mfma_f32_16x16x32_bf16 v[124:127], v[152:155], v[184:187], v[124:127]
	v_mfma_f32_16x16x32_bf16 v[120:123], v[160:163], v[184:187], v[120:123]
	v_mfma_f32_16x16x32_bf16 v[108:111], v[152:155], v[196:199], v[108:111]
	v_mfma_f32_16x16x32_bf16 v[104:107], v[160:163], v[196:199], v[104:107]
	v_mfma_f32_16x16x32_bf16 v[92:95], v[152:155], v[204:207], v[92:95]
	v_mfma_f32_16x16x32_bf16 v[88:91], v[160:163], v[204:207], v[88:91]
	v_mfma_f32_16x16x32_bf16 v[76:79], v[152:155], v[212:215], v[76:79]
	v_mfma_f32_16x16x32_bf16 v[72:75], v[160:163], v[212:215], v[72:75]
	v_mfma_f32_16x16x32_bf16 v[124:127], v[156:159], v[188:191], v[124:127]
	v_mfma_f32_16x16x32_bf16 v[120:123], v[164:167], v[188:191], v[120:123]
	v_mfma_f32_16x16x32_bf16 v[108:111], v[156:159], v[200:203], v[108:111]
	v_mfma_f32_16x16x32_bf16 v[104:107], v[164:167], v[200:203], v[104:107]
	v_mfma_f32_16x16x32_bf16 v[92:95], v[156:159], v[208:211], v[92:95]
	v_mfma_f32_16x16x32_bf16 v[88:91], v[164:167], v[208:211], v[88:91]
	v_mfma_f32_16x16x32_bf16 v[76:79], v[156:159], v[216:219], v[76:79]
	v_mfma_f32_16x16x32_bf16 v[72:75], v[164:167], v[216:219], v[72:75]
	s_setprio 0
	s_setprio 1
	v_mfma_f32_16x16x32_bf16 v[116:119], v[168:171], v[184:187], v[116:119]
	v_mfma_f32_16x16x32_bf16 v[112:115], v[176:179], v[184:187], v[112:115]
	v_mfma_f32_16x16x32_bf16 v[100:103], v[168:171], v[196:199], v[100:103]
	v_mfma_f32_16x16x32_bf16 v[96:99], v[176:179], v[196:199], v[96:99]
	v_mfma_f32_16x16x32_bf16 v[84:87], v[168:171], v[204:207], v[84:87]
	v_mfma_f32_16x16x32_bf16 v[80:83], v[176:179], v[204:207], v[80:83]
	v_mfma_f32_16x16x32_bf16 v[68:71], v[168:171], v[212:215], v[68:71]
	v_mfma_f32_16x16x32_bf16 v[64:67], v[176:179], v[212:215], v[64:67]
	v_mfma_f32_16x16x32_bf16 v[116:119], v[172:175], v[188:191], v[116:119]
	v_mfma_f32_16x16x32_bf16 v[112:115], v[180:183], v[188:191], v[112:115]
	v_mfma_f32_16x16x32_bf16 v[100:103], v[172:175], v[200:203], v[100:103]
	v_mfma_f32_16x16x32_bf16 v[96:99], v[180:183], v[200:203], v[96:99]
	v_mfma_f32_16x16x32_bf16 v[84:87], v[172:175], v[208:211], v[84:87]
	v_mfma_f32_16x16x32_bf16 v[80:83], v[180:183], v[208:211], v[80:83]
	v_mfma_f32_16x16x32_bf16 v[68:71], v[172:175], v[216:219], v[68:71]
	v_mfma_f32_16x16x32_bf16 v[64:67], v[180:183], v[216:219], v[64:67]
	s_setprio 0
	s_barrier
	s_add_i32 s24, s80, s39
	v_lshl_add_u64 v[192:193], v[192:193], 0, s[16:17]
	s_mov_b32 m0, s24
	ds_read_b128 v[184:187], v150 offset:49152
	ds_read_b128 v[188:191], v150 offset:50176
	ds_read_b128 v[196:199], v150 offset:51200
	ds_read_b128 v[200:203], v150 offset:52224
	ds_read_b128 v[204:207], v150 offset:53248
	ds_read_b128 v[208:211], v150 offset:54272
	ds_read_b128 v[212:215], v150 offset:55296
	ds_read_b128 v[216:219], v150 offset:56320
	global_load_lds_dwordx4 v[192:193], off
	s_add_i32 m0, s24, 0x2000
	s_add_u32 s24, s28, 0x30080
	v_lshl_add_u64 v[192:193], v[220:221], 0, s[16:17]
	s_addc_u32 s25, s29, 0
	s_add_i32 s28, s81, s39
	global_load_lds_dwordx4 v[192:193], off
	s_mov_b32 m0, s28
	s_nop 0
	global_load_lds_dwordx4 v132, s[24:25]
	s_add_i32 m0, s28, 0x2000
	s_nop 0
	global_load_lds_dwordx4 v128, s[24:25]
	s_waitcnt vmcnt(6)
	s_waitcnt lgkmcnt(0)
	s_barrier
	s_setprio 1
	s_waitcnt lgkmcnt(0)
	v_mfma_f32_16x16x32_bf16 v[60:63], v[152:155], v[184:187], v[60:63]
	v_mfma_f32_16x16x32_bf16 v[56:59], v[160:163], v[184:187], v[56:59]
	v_mfma_f32_16x16x32_bf16 v[44:47], v[152:155], v[196:199], v[44:47]
	v_mfma_f32_16x16x32_bf16 v[40:43], v[160:163], v[196:199], v[40:43]
	v_mfma_f32_16x16x32_bf16 v[28:31], v[152:155], v[204:207], v[28:31]
	v_mfma_f32_16x16x32_bf16 v[24:27], v[160:163], v[204:207], v[24:27]
	v_mfma_f32_16x16x32_bf16 v[12:15], v[152:155], v[212:215], v[12:15]
	v_mfma_f32_16x16x32_bf16 v[8:11], v[160:163], v[212:215], v[8:11]
	v_mfma_f32_16x16x32_bf16 v[60:63], v[156:159], v[188:191], v[60:63]
	v_mfma_f32_16x16x32_bf16 v[56:59], v[164:167], v[188:191], v[56:59]
	v_mfma_f32_16x16x32_bf16 v[44:47], v[156:159], v[200:203], v[44:47]
	v_mfma_f32_16x16x32_bf16 v[40:43], v[164:167], v[200:203], v[40:43]
	v_mfma_f32_16x16x32_bf16 v[28:31], v[156:159], v[208:211], v[28:31]
	v_mfma_f32_16x16x32_bf16 v[24:27], v[164:167], v[208:211], v[24:27]
	v_mfma_f32_16x16x32_bf16 v[12:15], v[156:159], v[216:219], v[12:15]
	v_mfma_f32_16x16x32_bf16 v[8:11], v[164:167], v[216:219], v[8:11]
	s_setprio 0
	s_setprio 1
	v_mfma_f32_16x16x32_bf16 v[52:55], v[168:171], v[184:187], v[52:55]
	v_mfma_f32_16x16x32_bf16 v[48:51], v[176:179], v[184:187], v[48:51]
	v_mfma_f32_16x16x32_bf16 v[36:39], v[168:171], v[196:199], v[36:39]
	v_mfma_f32_16x16x32_bf16 v[32:35], v[176:179], v[196:199], v[32:35]
	v_mfma_f32_16x16x32_bf16 v[20:23], v[168:171], v[204:207], v[20:23]
	v_mfma_f32_16x16x32_bf16 v[16:19], v[176:179], v[204:207], v[16:19]
	v_mfma_f32_16x16x32_bf16 v[4:7], v[168:171], v[212:215], v[4:7]
	v_mfma_f32_16x16x32_bf16 v[0:3], v[176:179], v[212:215], v[0:3]
	v_mfma_f32_16x16x32_bf16 v[52:55], v[172:175], v[188:191], v[52:55]
	v_mfma_f32_16x16x32_bf16 v[48:51], v[180:183], v[188:191], v[48:51]
	v_mfma_f32_16x16x32_bf16 v[36:39], v[172:175], v[200:203], v[36:39]
	v_mfma_f32_16x16x32_bf16 v[32:35], v[180:183], v[200:203], v[32:35]
	v_mfma_f32_16x16x32_bf16 v[20:23], v[172:175], v[208:211], v[20:23]
	v_mfma_f32_16x16x32_bf16 v[16:19], v[180:183], v[208:211], v[16:19]
	v_mfma_f32_16x16x32_bf16 v[4:7], v[172:175], v[216:219], v[4:7]
	v_mfma_f32_16x16x32_bf16 v[0:3], v[180:183], v[216:219], v[0:3]
	s_setprio 0
	s_barrier
	v_lshl_add_u64 v[222:223], v[222:223], 0, s[16:17]
	s_mov_b32 m0, s45
	s_nop 0
	global_load_lds_dwordx4 v[222:223], off
	v_lshl_add_u64 v[224:225], v[224:225], 0, s[16:17]
	s_mov_b32 m0, s50
	s_nop 0
	global_load_lds_dwordx4 v[224:225], off
	s_add_i32 s79, s79, 2
	s_add_u32 s73, s73, 0x100
	s_addc_u32 s78, s78, 0
	s_cmp_gt_u32 s79, 9
	s_mov_b64 s[24:25], s[26:27]
	s_cbranch_scc0 .LBB0_923
	s_and_b64 vcc, exec, s[18:19]
	s_cbranch_vccz .LBB0_926
	s_barrier

.LBB0_947:
	ds_read_b128 v[144:147], v153
	ds_read_b128 v[158:161], v153 offset:1024
	ds_read_b128 v[162:165], v153 offset:2048
	ds_read_b128 v[166:169], v153 offset:3072
	ds_read_b128 v[170:173], v154
	ds_read_b128 v[174:177], v154 offset:1024
	ds_read_b128 v[178:181], v154 offset:2048
	ds_read_b128 v[182:185], v154 offset:3072
	s_add_u32 s36, s34, 0xfffc0080
	s_addc_u32 s37, s35, -1
	s_cmp_eq_u32 s85, 12
	s_cselect_b32 s39, s27, s37
	s_cselect_b32 s38, s81, s36
	s_cselect_b32 s37, s25, s84
	s_cselect_b32 s36, s82, s83
	s_add_i32 m0, s59, 0xc000
	ds_read_b128 v[186:189], v155
	ds_read_b128 v[190:193], v155 offset:1024
	ds_read_b128 v[196:199], v155 offset:2048
	ds_read_b128 v[200:203], v155 offset:3072
	ds_read_b128 v[204:207], v155 offset:4096
	ds_read_b128 v[208:211], v155 offset:5120
	ds_read_b128 v[212:215], v155 offset:6144
	ds_read_b128 v[216:219], v155 offset:7168
	global_load_lds_dwordx4 v136, s[34:35]
	s_add_i32 m0, s59, 0xe000
	s_nop 0
	global_load_lds_dwordx4 v138, s[34:35]
	s_waitcnt vmcnt(8)
	s_waitcnt lgkmcnt(0)
	s_barrier
	s_setprio 1
	s_waitcnt lgkmcnt(0)
	v_mfma_f32_16x16x32_bf16 v[124:127], v[144:147], v[186:189], v[124:127]
	v_mfma_f32_16x16x32_bf16 v[120:123], v[162:165], v[186:189], v[120:123]
	v_mfma_f32_16x16x32_bf16 v[108:111], v[144:147], v[196:199], v[108:111]
	v_mfma_f32_16x16x32_bf16 v[104:107], v[162:165], v[196:199], v[104:107]
	v_mfma_f32_16x16x32_bf16 v[92:95], v[144:147], v[204:207], v[92:95]
	v_mfma_f32_16x16x32_bf16 v[88:91], v[162:165], v[204:207], v[88:91]
	v_mfma_f32_16x16x32_bf16 v[76:79], v[144:147], v[212:215], v[76:79]
	v_mfma_f32_16x16x32_bf16 v[72:75], v[162:165], v[212:215], v[72:75]
	v_mfma_f32_16x16x32_bf16 v[124:127], v[158:161], v[190:193], v[124:127]
	v_mfma_f32_16x16x32_bf16 v[120:123], v[166:169], v[190:193], v[120:123]
	v_mfma_f32_16x16x32_bf16 v[108:111], v[158:161], v[200:203], v[108:111]
	v_mfma_f32_16x16x32_bf16 v[104:107], v[166:169], v[200:203], v[104:107]
	v_mfma_f32_16x16x32_bf16 v[92:95], v[158:161], v[208:211], v[92:95]
	v_mfma_f32_16x16x32_bf16 v[88:91], v[166:169], v[208:211], v[88:91]
	v_mfma_f32_16x16x32_bf16 v[76:79], v[158:161], v[216:219], v[76:79]
	v_mfma_f32_16x16x32_bf16 v[72:75], v[166:169], v[216:219], v[72:75]
	s_setprio 0
	s_setprio 1
	v_mfma_f32_16x16x32_bf16 v[116:119], v[170:173], v[186:189], v[116:119]
	v_mfma_f32_16x16x32_bf16 v[112:115], v[178:181], v[186:189], v[112:115]
	v_mfma_f32_16x16x32_bf16 v[100:103], v[170:173], v[196:199], v[100:103]
	v_mfma_f32_16x16x32_bf16 v[96:99], v[178:181], v[196:199], v[96:99]
	v_mfma_f32_16x16x32_bf16 v[84:87], v[170:173], v[204:207], v[84:87]
	v_mfma_f32_16x16x32_bf16 v[80:83], v[178:181], v[204:207], v[80:83]
	v_mfma_f32_16x16x32_bf16 v[68:71], v[170:173], v[212:215], v[68:71]
	v_mfma_f32_16x16x32_bf16 v[64:67], v[178:181], v[212:215], v[64:67]
	v_mfma_f32_16x16x32_bf16 v[116:119], v[174:177], v[190:193], v[116:119]
	v_mfma_f32_16x16x32_bf16 v[112:115], v[182:185], v[190:193], v[112:115]
	v_mfma_f32_16x16x32_bf16 v[100:103], v[174:177], v[200:203], v[100:103]
	v_mfma_f32_16x16x32_bf16 v[96:99], v[182:185], v[200:203], v[96:99]
	v_mfma_f32_16x16x32_bf16 v[84:87], v[174:177], v[208:211], v[84:87]
	v_mfma_f32_16x16x32_bf16 v[80:83], v[182:185], v[208:211], v[80:83]
	v_mfma_f32_16x16x32_bf16 v[68:71], v[174:177], v[216:219], v[68:71]
	v_mfma_f32_16x16x32_bf16 v[64:67], v[182:185], v[216:219], v[64:67]
	s_setprio 0
	s_barrier
	s_add_i32 s86, s73, s58
	v_lshl_add_u64 v[148:149], s[36:37], 0, v[130:131]
	s_mov_b32 m0, s86
	ds_read_b128 v[186:189], v155 offset:16384
	ds_read_b128 v[190:193], v155 offset:17408
	ds_read_b128 v[196:199], v155 offset:18432
	ds_read_b128 v[200:203], v155 offset:19456
	ds_read_b128 v[204:207], v155 offset:20480
	ds_read_b128 v[208:211], v155 offset:21504
	ds_read_b128 v[212:215], v155 offset:22528
	ds_read_b128 v[216:219], v155 offset:23552
	global_load_lds_dwordx4 v[148:149], off
	s_add_i32 m0, s86, 0x2000
	s_add_u32 s86, s36, 0x40000
	v_lshl_add_u64 v[220:221], s[36:37], 0, v[134:135]
	s_addc_u32 s87, s37, 0
	s_add_i32 s88, s78, s58
	global_load_lds_dwordx4 v[220:221], off
	s_mov_b32 m0, s88
	v_lshl_add_u64 v[224:225], s[38:39], 0, v[132:133]
	global_load_lds_dwordx4 v130, s[86:87]
	s_add_i32 m0, s88, 0x2000
	s_nop 0
	global_load_lds_dwordx4 v134, s[86:87]
	v_lshl_add_u64 v[222:223], s[38:39], 0, v[128:129]
	s_waitcnt vmcnt(6)
	s_waitcnt lgkmcnt(0)
	s_barrier
	s_setprio 1
	s_waitcnt lgkmcnt(0)
	v_mfma_f32_16x16x32_bf16 v[60:63], v[144:147], v[186:189], v[60:63]
	v_mfma_f32_16x16x32_bf16 v[56:59], v[162:165], v[186:189], v[56:59]
	v_mfma_f32_16x16x32_bf16 v[44:47], v[144:147], v[196:199], v[44:47]
	v_mfma_f32_16x16x32_bf16 v[40:43], v[162:165], v[196:199], v[40:43]
	v_mfma_f32_16x16x32_bf16 v[28:31], v[144:147], v[204:207], v[28:31]
	v_mfma_f32_16x16x32_bf16 v[24:27], v[162:165], v[204:207], v[24:27]
	v_mfma_f32_16x16x32_bf16 v[12:15], v[144:147], v[212:215], v[12:15]
	v_mfma_f32_16x16x32_bf16 v[8:11], v[162:165], v[212:215], v[8:11]
	v_mfma_f32_16x16x32_bf16 v[60:63], v[158:161], v[190:193], v[60:63]
	v_mfma_f32_16x16x32_bf16 v[56:59], v[166:169], v[190:193], v[56:59]
	v_mfma_f32_16x16x32_bf16 v[44:47], v[158:161], v[200:203], v[44:47]
	v_mfma_f32_16x16x32_bf16 v[40:43], v[166:169], v[200:203], v[40:43]
	v_mfma_f32_16x16x32_bf16 v[28:31], v[158:161], v[208:211], v[28:31]
	v_mfma_f32_16x16x32_bf16 v[24:27], v[166:169], v[208:211], v[24:27]
	v_mfma_f32_16x16x32_bf16 v[12:15], v[158:161], v[216:219], v[12:15]
	v_mfma_f32_16x16x32_bf16 v[8:11], v[166:169], v[216:219], v[8:11]
	s_setprio 0
	s_setprio 1
	v_mfma_f32_16x16x32_bf16 v[52:55], v[170:173], v[186:189], v[52:55]
	v_mfma_f32_16x16x32_bf16 v[48:51], v[178:181], v[186:189], v[48:51]
	v_mfma_f32_16x16x32_bf16 v[36:39], v[170:173], v[196:199], v[36:39]
	v_mfma_f32_16x16x32_bf16 v[32:35], v[178:181], v[196:199], v[32:35]
	v_mfma_f32_16x16x32_bf16 v[20:23], v[170:173], v[204:207], v[20:23]
	v_mfma_f32_16x16x32_bf16 v[16:19], v[178:181], v[204:207], v[16:19]
	v_mfma_f32_16x16x32_bf16 v[4:7], v[170:173], v[212:215], v[4:7]
	v_mfma_f32_16x16x32_bf16 v[0:3], v[178:181], v[212:215], v[0:3]
	v_mfma_f32_16x16x32_bf16 v[52:55], v[174:177], v[190:193], v[52:55]
	v_mfma_f32_16x16x32_bf16 v[48:51], v[182:185], v[190:193], v[48:51]
	v_mfma_f32_16x16x32_bf16 v[36:39], v[174:177], v[200:203], v[36:39]
	v_mfma_f32_16x16x32_bf16 v[32:35], v[182:185], v[200:203], v[32:35]
	v_mfma_f32_16x16x32_bf16 v[20:23], v[174:177], v[208:211], v[20:23]
	v_mfma_f32_16x16x32_bf16 v[16:19], v[182:185], v[208:211], v[16:19]
	v_mfma_f32_16x16x32_bf16 v[4:7], v[174:177], v[216:219], v[4:7]
	v_mfma_f32_16x16x32_bf16 v[0:3], v[182:185], v[216:219], v[0:3]
	s_setprio 0
	s_barrier
	s_add_i32 s86, 0, 0x18000
	v_add_u32_e32 v157, s86, v151
	s_add_i32 s87, 0, 0x1c000
	ds_read_b128 v[144:147], v157
	ds_read_b128 v[158:161], v157 offset:1024
	ds_read_b128 v[162:165], v157 offset:2048
	ds_read_b128 v[166:169], v157 offset:3072
	v_add_u32_e32 v157, s87, v151
	ds_read_b128 v[170:173], v157
	ds_read_b128 v[174:177], v157 offset:1024
	ds_read_b128 v[178:181], v157 offset:2048
	ds_read_b128 v[182:185], v157 offset:3072
	s_add_u32 s38, s38, 0x40000
	s_addc_u32 s39, s39, 0
	ds_read_b128 v[186:189], v155 offset:32768
	ds_read_b128 v[190:193], v155 offset:33792
	ds_read_b128 v[196:199], v155 offset:34816
	ds_read_b128 v[200:203], v155 offset:35840
	ds_read_b128 v[204:207], v155 offset:36864
	ds_read_b128 v[208:211], v155 offset:37888
	ds_read_b128 v[212:215], v155 offset:38912
	ds_read_b128 v[216:219], v155 offset:39936
	s_mov_b32 m0, s59
	s_nop 0
	global_load_lds_dwordx4 v[222:223], off
	s_mov_b32 m0, s60
	s_nop 0
	global_load_lds_dwordx4 v[224:225], off
	s_mov_b32 m0, s61
	s_nop 0
	global_load_lds_dwordx4 v128, s[38:39]
	s_mov_b32 m0, s62
	s_nop 0
	global_load_lds_dwordx4 v132, s[38:39]
	s_waitcnt vmcnt(8)
	s_waitcnt lgkmcnt(0)
	s_barrier
	s_setprio 1
	s_waitcnt lgkmcnt(0)
	v_mfma_f32_16x16x32_bf16 v[124:127], v[144:147], v[186:189], v[124:127]
	v_mfma_f32_16x16x32_bf16 v[120:123], v[162:165], v[186:189], v[120:123]
	v_mfma_f32_16x16x32_bf16 v[108:111], v[144:147], v[196:199], v[108:111]
	v_mfma_f32_16x16x32_bf16 v[104:107], v[162:165], v[196:199], v[104:107]
	v_mfma_f32_16x16x32_bf16 v[92:95], v[144:147], v[204:207], v[92:95]
	v_mfma_f32_16x16x32_bf16 v[88:91], v[162:165], v[204:207], v[88:91]
	v_mfma_f32_16x16x32_bf16 v[76:79], v[144:147], v[212:215], v[76:79]
	v_mfma_f32_16x16x32_bf16 v[72:75], v[162:165], v[212:215], v[72:75]
	v_mfma_f32_16x16x32_bf16 v[124:127], v[158:161], v[190:193], v[124:127]
	v_mfma_f32_16x16x32_bf16 v[120:123], v[166:169], v[190:193], v[120:123]
	v_mfma_f32_16x16x32_bf16 v[108:111], v[158:161], v[200:203], v[108:111]
	v_mfma_f32_16x16x32_bf16 v[104:107], v[166:169], v[200:203], v[104:107]
	v_mfma_f32_16x16x32_bf16 v[92:95], v[158:161], v[208:211], v[92:95]
	v_mfma_f32_16x16x32_bf16 v[88:91], v[166:169], v[208:211], v[88:91]
	v_mfma_f32_16x16x32_bf16 v[76:79], v[158:161], v[216:219], v[76:79]
	v_mfma_f32_16x16x32_bf16 v[72:75], v[166:169], v[216:219], v[72:75]
	s_setprio 0
	s_setprio 1
	v_mfma_f32_16x16x32_bf16 v[116:119], v[170:173], v[186:189], v[116:119]
	v_mfma_f32_16x16x32_bf16 v[112:115], v[178:181], v[186:189], v[112:115]
	v_mfma_f32_16x16x32_bf16 v[100:103], v[170:173], v[196:199], v[100:103]
	v_mfma_f32_16x16x32_bf16 v[96:99], v[178:181], v[196:199], v[96:99]
	v_mfma_f32_16x16x32_bf16 v[84:87], v[170:173], v[204:207], v[84:87]
	v_mfma_f32_16x16x32_bf16 v[80:83], v[178:181], v[204:207], v[80:83]
	v_mfma_f32_16x16x32_bf16 v[68:71], v[170:173], v[212:215], v[68:71]
	v_mfma_f32_16x16x32_bf16 v[64:67], v[178:181], v[212:215], v[64:67]
	v_mfma_f32_16x16x32_bf16 v[116:119], v[174:177], v[190:193], v[116:119]
	v_mfma_f32_16x16x32_bf16 v[112:115], v[182:185], v[190:193], v[112:115]
	v_mfma_f32_16x16x32_bf16 v[100:103], v[174:177], v[200:203], v[100:103]
	v_mfma_f32_16x16x32_bf16 v[96:99], v[182:185], v[200:203], v[96:99]
	v_mfma_f32_16x16x32_bf16 v[84:87], v[174:177], v[208:211], v[84:87]
	v_mfma_f32_16x16x32_bf16 v[80:83], v[182:185], v[208:211], v[80:83]
	v_mfma_f32_16x16x32_bf16 v[68:71], v[174:177], v[216:219], v[68:71]
	v_mfma_f32_16x16x32_bf16 v[64:67], v[182:185], v[216:219], v[64:67]
	s_setprio 0
	s_barrier
	s_add_i32 s38, s86, s58
	v_lshl_add_u64 v[148:149], v[148:149], 0, s[20:21]
	s_mov_b32 m0, s38
	ds_read_b128 v[186:189], v155 offset:49152
	ds_read_b128 v[190:193], v155 offset:50176
	ds_read_b128 v[196:199], v155 offset:51200
	ds_read_b128 v[200:203], v155 offset:52224
	ds_read_b128 v[204:207], v155 offset:53248
	ds_read_b128 v[208:211], v155 offset:54272
	ds_read_b128 v[212:215], v155 offset:55296
	ds_read_b128 v[216:219], v155 offset:56320
	global_load_lds_dwordx4 v[148:149], off
	s_add_i32 m0, s38, 0x2000
	s_add_u32 s36, s36, 0x40080
	v_lshl_add_u64 v[148:149], v[220:221], 0, s[20:21]
	s_addc_u32 s37, s37, 0
	s_add_i32 s38, s87, s58
	global_load_lds_dwordx4 v[148:149], off
	s_mov_b32 m0, s38
	s_nop 0
	global_load_lds_dwordx4 v130, s[36:37]
	s_add_i32 m0, s38, 0x2000
	s_nop 0
	global_load_lds_dwordx4 v134, s[36:37]
	s_waitcnt vmcnt(6)
	s_waitcnt lgkmcnt(0)
	s_barrier
	s_setprio 1
	s_waitcnt lgkmcnt(0)
	v_mfma_f32_16x16x32_bf16 v[60:63], v[144:147], v[186:189], v[60:63]
	v_mfma_f32_16x16x32_bf16 v[56:59], v[162:165], v[186:189], v[56:59]
	v_mfma_f32_16x16x32_bf16 v[44:47], v[144:147], v[196:199], v[44:47]
	v_mfma_f32_16x16x32_bf16 v[40:43], v[162:165], v[196:199], v[40:43]
	v_mfma_f32_16x16x32_bf16 v[28:31], v[144:147], v[204:207], v[28:31]
	v_mfma_f32_16x16x32_bf16 v[24:27], v[162:165], v[204:207], v[24:27]
	v_mfma_f32_16x16x32_bf16 v[12:15], v[144:147], v[212:215], v[12:15]
	v_mfma_f32_16x16x32_bf16 v[8:11], v[162:165], v[212:215], v[8:11]
	v_mfma_f32_16x16x32_bf16 v[60:63], v[158:161], v[190:193], v[60:63]
	v_mfma_f32_16x16x32_bf16 v[56:59], v[166:169], v[190:193], v[56:59]
	v_mfma_f32_16x16x32_bf16 v[44:47], v[158:161], v[200:203], v[44:47]
	v_mfma_f32_16x16x32_bf16 v[40:43], v[166:169], v[200:203], v[40:43]
	v_mfma_f32_16x16x32_bf16 v[28:31], v[158:161], v[208:211], v[28:31]
	v_mfma_f32_16x16x32_bf16 v[24:27], v[166:169], v[208:211], v[24:27]
	v_mfma_f32_16x16x32_bf16 v[12:15], v[158:161], v[216:219], v[12:15]
	v_mfma_f32_16x16x32_bf16 v[8:11], v[166:169], v[216:219], v[8:11]
	s_setprio 0
	s_setprio 1
	v_mfma_f32_16x16x32_bf16 v[52:55], v[170:173], v[186:189], v[52:55]
	v_mfma_f32_16x16x32_bf16 v[48:51], v[178:181], v[186:189], v[48:51]
	v_mfma_f32_16x16x32_bf16 v[36:39], v[170:173], v[196:199], v[36:39]
	v_mfma_f32_16x16x32_bf16 v[32:35], v[178:181], v[196:199], v[32:35]
	v_mfma_f32_16x16x32_bf16 v[20:23], v[170:173], v[204:207], v[20:23]
	v_mfma_f32_16x16x32_bf16 v[16:19], v[178:181], v[204:207], v[16:19]
	v_mfma_f32_16x16x32_bf16 v[4:7], v[170:173], v[212:215], v[4:7]
	v_mfma_f32_16x16x32_bf16 v[0:3], v[178:181], v[212:215], v[0:3]
	v_mfma_f32_16x16x32_bf16 v[52:55], v[174:177], v[190:193], v[52:55]
	v_mfma_f32_16x16x32_bf16 v[48:51], v[182:185], v[190:193], v[48:51]
	v_mfma_f32_16x16x32_bf16 v[36:39], v[174:177], v[200:203], v[36:39]
	v_mfma_f32_16x16x32_bf16 v[32:35], v[182:185], v[200:203], v[32:35]
	v_mfma_f32_16x16x32_bf16 v[20:23], v[174:177], v[208:211], v[20:23]
	v_mfma_f32_16x16x32_bf16 v[16:19], v[182:185], v[208:211], v[16:19]
	v_mfma_f32_16x16x32_bf16 v[4:7], v[174:177], v[216:219], v[4:7]
	v_mfma_f32_16x16x32_bf16 v[0:3], v[182:185], v[216:219], v[0:3]
	s_setprio 0
	s_barrier
	v_lshl_add_u64 v[222:223], v[222:223], 0, s[20:21]
	s_mov_b32 m0, s70
	s_nop 0
	global_load_lds_dwordx4 v[222:223], off
	v_lshl_add_u64 v[224:225], v[224:225], 0, s[20:21]
	s_mov_b32 m0, s71
	s_nop 0
	global_load_lds_dwordx4 v[224:225], off
	s_add_i32 s85, s85, 2
	s_add_u32 s34, s34, 0x100
	s_addc_u32 s35, s35, 0
	s_add_u32 s83, s83, 0x100
	s_addc_u32 s84, s84, 0
	s_cmp_gt_u32 s85, 13
	s_cbranch_scc0 .LBB0_947
	s_and_b64 vcc, exec, s[22:23]
	s_cbranch_vccz .LBB0_950
	s_barrier

.LBB0_1023:
	ds_read_b128 v[144:147], v153
	ds_read_b128 v[156:159], v153 offset:1024
	ds_read_b128 v[160:163], v153 offset:2048
	ds_read_b128 v[164:167], v153 offset:3072
	ds_read_b128 v[168:171], v154
	ds_read_b128 v[172:175], v154 offset:1024
	ds_read_b128 v[176:179], v154 offset:2048
	ds_read_b128 v[180:183], v154 offset:3072
	s_add_u32 s44, s42, 0xfffe0080
	s_addc_u32 s45, s43, -1
	s_cmp_eq_u32 s87, 4
	s_cselect_b32 s59, s35, s45
	s_cselect_b32 s58, s83, s44
	s_cselect_b32 s45, s31, s86
	s_cselect_b32 s44, s84, s85
	s_add_i32 m0, s41, 0xc000
	ds_read_b128 v[184:187], v155
	ds_read_b128 v[188:191], v155 offset:1024
	ds_read_b128 v[196:199], v155 offset:2048
	ds_read_b128 v[200:203], v155 offset:3072
	ds_read_b128 v[204:207], v155 offset:4096
	ds_read_b128 v[208:211], v155 offset:5120
	ds_read_b128 v[212:215], v155 offset:6144
	ds_read_b128 v[216:219], v155 offset:7168
	global_load_lds_dwordx4 v136, s[42:43]
	s_add_i32 m0, s41, 0xe000
	s_nop 0
	global_load_lds_dwordx4 v138, s[42:43]
	s_waitcnt vmcnt(8)
	s_waitcnt lgkmcnt(0)
	s_barrier
	s_setprio 1
	s_waitcnt lgkmcnt(0)
	v_mfma_f32_16x16x32_bf16 v[124:127], v[144:147], v[184:187], v[124:127]
	v_mfma_f32_16x16x32_bf16 v[120:123], v[160:163], v[184:187], v[120:123]
	v_mfma_f32_16x16x32_bf16 v[108:111], v[144:147], v[196:199], v[108:111]
	v_mfma_f32_16x16x32_bf16 v[104:107], v[160:163], v[196:199], v[104:107]
	v_mfma_f32_16x16x32_bf16 v[92:95], v[144:147], v[204:207], v[92:95]
	v_mfma_f32_16x16x32_bf16 v[88:91], v[160:163], v[204:207], v[88:91]
	v_mfma_f32_16x16x32_bf16 v[76:79], v[144:147], v[212:215], v[76:79]
	v_mfma_f32_16x16x32_bf16 v[72:75], v[160:163], v[212:215], v[72:75]
	v_mfma_f32_16x16x32_bf16 v[124:127], v[156:159], v[188:191], v[124:127]
	v_mfma_f32_16x16x32_bf16 v[120:123], v[164:167], v[188:191], v[120:123]
	v_mfma_f32_16x16x32_bf16 v[108:111], v[156:159], v[200:203], v[108:111]
	v_mfma_f32_16x16x32_bf16 v[104:107], v[164:167], v[200:203], v[104:107]
	v_mfma_f32_16x16x32_bf16 v[92:95], v[156:159], v[208:211], v[92:95]
	v_mfma_f32_16x16x32_bf16 v[88:91], v[164:167], v[208:211], v[88:91]
	v_mfma_f32_16x16x32_bf16 v[76:79], v[156:159], v[216:219], v[76:79]
	v_mfma_f32_16x16x32_bf16 v[72:75], v[164:167], v[216:219], v[72:75]
	s_setprio 0
	s_setprio 1
	v_mfma_f32_16x16x32_bf16 v[116:119], v[168:171], v[184:187], v[116:119]
	v_mfma_f32_16x16x32_bf16 v[112:115], v[176:179], v[184:187], v[112:115]
	v_mfma_f32_16x16x32_bf16 v[100:103], v[168:171], v[196:199], v[100:103]
	v_mfma_f32_16x16x32_bf16 v[96:99], v[176:179], v[196:199], v[96:99]
	v_mfma_f32_16x16x32_bf16 v[84:87], v[168:171], v[204:207], v[84:87]
	v_mfma_f32_16x16x32_bf16 v[80:83], v[176:179], v[204:207], v[80:83]
	v_mfma_f32_16x16x32_bf16 v[68:71], v[168:171], v[212:215], v[68:71]
	v_mfma_f32_16x16x32_bf16 v[64:67], v[176:179], v[212:215], v[64:67]
	v_mfma_f32_16x16x32_bf16 v[116:119], v[172:175], v[188:191], v[116:119]
	v_mfma_f32_16x16x32_bf16 v[112:115], v[180:183], v[188:191], v[112:115]
	v_mfma_f32_16x16x32_bf16 v[100:103], v[172:175], v[200:203], v[100:103]
	v_mfma_f32_16x16x32_bf16 v[96:99], v[180:183], v[200:203], v[96:99]
	v_mfma_f32_16x16x32_bf16 v[84:87], v[172:175], v[208:211], v[84:87]
	v_mfma_f32_16x16x32_bf16 v[80:83], v[180:183], v[208:211], v[80:83]
	v_mfma_f32_16x16x32_bf16 v[68:71], v[172:175], v[216:219], v[68:71]
	v_mfma_f32_16x16x32_bf16 v[64:67], v[180:183], v[216:219], v[64:67]
	s_setprio 0
	s_barrier
	s_add_i32 s88, s80, s62
	v_lshl_add_u64 v[148:149], s[44:45], 0, v[130:131]
	s_mov_b32 m0, s88
	ds_read_b128 v[184:187], v155 offset:16384
	ds_read_b128 v[188:191], v155 offset:17408
	ds_read_b128 v[196:199], v155 offset:18432
	ds_read_b128 v[200:203], v155 offset:19456
	ds_read_b128 v[204:207], v155 offset:20480
	ds_read_b128 v[208:211], v155 offset:21504
	ds_read_b128 v[212:215], v155 offset:22528
	ds_read_b128 v[216:219], v155 offset:23552
	global_load_lds_dwordx4 v[148:149], off
	s_add_i32 m0, s88, 0x2000
	s_add_u32 s88, s44, 0x20000
	v_lshl_add_u64 v[192:193], s[44:45], 0, v[134:135]
	s_addc_u32 s89, s45, 0
	s_add_i32 s90, s81, s62
	global_load_lds_dwordx4 v[192:193], off
	s_mov_b32 m0, s90
	v_lshl_add_u64 v[222:223], s[58:59], 0, v[132:133]
	global_load_lds_dwordx4 v130, s[88:89]
	s_add_i32 m0, s90, 0x2000
	s_nop 0
	global_load_lds_dwordx4 v134, s[88:89]
	v_lshl_add_u64 v[220:221], s[58:59], 0, v[128:129]
	s_waitcnt vmcnt(6)
	s_waitcnt lgkmcnt(0)
	s_barrier
	s_setprio 1
	s_waitcnt lgkmcnt(0)
	v_mfma_f32_16x16x32_bf16 v[60:63], v[144:147], v[184:187], v[60:63]
	v_mfma_f32_16x16x32_bf16 v[56:59], v[160:163], v[184:187], v[56:59]
	v_mfma_f32_16x16x32_bf16 v[44:47], v[144:147], v[196:199], v[44:47]
	v_mfma_f32_16x16x32_bf16 v[40:43], v[160:163], v[196:199], v[40:43]
	v_mfma_f32_16x16x32_bf16 v[28:31], v[144:147], v[204:207], v[28:31]
	v_mfma_f32_16x16x32_bf16 v[24:27], v[160:163], v[204:207], v[24:27]
	v_mfma_f32_16x16x32_bf16 v[12:15], v[144:147], v[212:215], v[12:15]
	v_mfma_f32_16x16x32_bf16 v[8:11], v[160:163], v[212:215], v[8:11]
	v_mfma_f32_16x16x32_bf16 v[60:63], v[156:159], v[188:191], v[60:63]
	v_mfma_f32_16x16x32_bf16 v[56:59], v[164:167], v[188:191], v[56:59]
	v_mfma_f32_16x16x32_bf16 v[44:47], v[156:159], v[200:203], v[44:47]
	v_mfma_f32_16x16x32_bf16 v[40:43], v[164:167], v[200:203], v[40:43]
	v_mfma_f32_16x16x32_bf16 v[28:31], v[156:159], v[208:211], v[28:31]
	v_mfma_f32_16x16x32_bf16 v[24:27], v[164:167], v[208:211], v[24:27]
	v_mfma_f32_16x16x32_bf16 v[12:15], v[156:159], v[216:219], v[12:15]
	v_mfma_f32_16x16x32_bf16 v[8:11], v[164:167], v[216:219], v[8:11]
	s_setprio 0
	s_setprio 1
	v_mfma_f32_16x16x32_bf16 v[52:55], v[168:171], v[184:187], v[52:55]
	v_mfma_f32_16x16x32_bf16 v[48:51], v[176:179], v[184:187], v[48:51]
	v_mfma_f32_16x16x32_bf16 v[36:39], v[168:171], v[196:199], v[36:39]
	v_mfma_f32_16x16x32_bf16 v[32:35], v[176:179], v[196:199], v[32:35]
	v_mfma_f32_16x16x32_bf16 v[20:23], v[168:171], v[204:207], v[20:23]
	v_mfma_f32_16x16x32_bf16 v[16:19], v[176:179], v[204:207], v[16:19]
	v_mfma_f32_16x16x32_bf16 v[4:7], v[168:171], v[212:215], v[4:7]
	v_mfma_f32_16x16x32_bf16 v[0:3], v[176:179], v[212:215], v[0:3]
	v_mfma_f32_16x16x32_bf16 v[52:55], v[172:175], v[188:191], v[52:55]
	v_mfma_f32_16x16x32_bf16 v[48:51], v[180:183], v[188:191], v[48:51]
	v_mfma_f32_16x16x32_bf16 v[36:39], v[172:175], v[200:203], v[36:39]
	v_mfma_f32_16x16x32_bf16 v[32:35], v[180:183], v[200:203], v[32:35]
	v_mfma_f32_16x16x32_bf16 v[20:23], v[172:175], v[208:211], v[20:23]
	v_mfma_f32_16x16x32_bf16 v[16:19], v[180:183], v[208:211], v[16:19]
	v_mfma_f32_16x16x32_bf16 v[4:7], v[172:175], v[216:219], v[4:7]
	v_mfma_f32_16x16x32_bf16 v[0:3], v[180:183], v[216:219], v[0:3]
	s_setprio 0
	s_barrier
	s_add_i32 s88, 0, 0x18000
	s_add_i32 s89, 0, 0x1c000
	v_add_u32_e32 v164, s88, v151
	v_add_u32_e32 v180, s89, v151
	ds_read_b128 v[144:147], v164
	ds_read_b128 v[156:159], v164 offset:1024
	ds_read_b128 v[160:163], v164 offset:2048
	ds_read_b128 v[164:167], v164 offset:3072
	ds_read_b128 v[168:171], v180
	ds_read_b128 v[172:175], v180 offset:1024
	ds_read_b128 v[176:179], v180 offset:2048
	ds_read_b128 v[180:183], v180 offset:3072
	s_add_u32 s58, s58, 0x20000
	s_addc_u32 s59, s59, 0
	ds_read_b128 v[184:187], v155 offset:32768
	ds_read_b128 v[188:191], v155 offset:33792
	ds_read_b128 v[196:199], v155 offset:34816
	ds_read_b128 v[200:203], v155 offset:35840
	ds_read_b128 v[204:207], v155 offset:36864
	ds_read_b128 v[208:211], v155 offset:37888
	ds_read_b128 v[212:215], v155 offset:38912
	ds_read_b128 v[216:219], v155 offset:39936
	s_mov_b32 m0, s41
	s_nop 0
	global_load_lds_dwordx4 v[220:221], off
	s_mov_b32 m0, s63
	s_nop 0
	global_load_lds_dwordx4 v[222:223], off
	s_mov_b32 m0, s70
	s_nop 0
	global_load_lds_dwordx4 v128, s[58:59]
	s_mov_b32 m0, s71
	s_nop 0
	global_load_lds_dwordx4 v132, s[58:59]
	s_waitcnt vmcnt(8)
	s_waitcnt lgkmcnt(0)
	s_barrier
	s_setprio 1
	s_waitcnt lgkmcnt(0)
	v_mfma_f32_16x16x32_bf16 v[124:127], v[144:147], v[184:187], v[124:127]
	v_mfma_f32_16x16x32_bf16 v[120:123], v[160:163], v[184:187], v[120:123]
	v_mfma_f32_16x16x32_bf16 v[108:111], v[144:147], v[196:199], v[108:111]
	v_mfma_f32_16x16x32_bf16 v[104:107], v[160:163], v[196:199], v[104:107]
	v_mfma_f32_16x16x32_bf16 v[92:95], v[144:147], v[204:207], v[92:95]
	v_mfma_f32_16x16x32_bf16 v[88:91], v[160:163], v[204:207], v[88:91]
	v_mfma_f32_16x16x32_bf16 v[76:79], v[144:147], v[212:215], v[76:79]
	v_mfma_f32_16x16x32_bf16 v[72:75], v[160:163], v[212:215], v[72:75]
	v_mfma_f32_16x16x32_bf16 v[124:127], v[156:159], v[188:191], v[124:127]
	v_mfma_f32_16x16x32_bf16 v[120:123], v[164:167], v[188:191], v[120:123]
	v_mfma_f32_16x16x32_bf16 v[108:111], v[156:159], v[200:203], v[108:111]
	v_mfma_f32_16x16x32_bf16 v[104:107], v[164:167], v[200:203], v[104:107]
	v_mfma_f32_16x16x32_bf16 v[92:95], v[156:159], v[208:211], v[92:95]
	v_mfma_f32_16x16x32_bf16 v[88:91], v[164:167], v[208:211], v[88:91]
	v_mfma_f32_16x16x32_bf16 v[76:79], v[156:159], v[216:219], v[76:79]
	v_mfma_f32_16x16x32_bf16 v[72:75], v[164:167], v[216:219], v[72:75]
	s_setprio 0
	s_setprio 1
	v_mfma_f32_16x16x32_bf16 v[116:119], v[168:171], v[184:187], v[116:119]
	v_mfma_f32_16x16x32_bf16 v[112:115], v[176:179], v[184:187], v[112:115]
	v_mfma_f32_16x16x32_bf16 v[100:103], v[168:171], v[196:199], v[100:103]
	v_mfma_f32_16x16x32_bf16 v[96:99], v[176:179], v[196:199], v[96:99]
	v_mfma_f32_16x16x32_bf16 v[84:87], v[168:171], v[204:207], v[84:87]
	v_mfma_f32_16x16x32_bf16 v[80:83], v[176:179], v[204:207], v[80:83]
	v_mfma_f32_16x16x32_bf16 v[68:71], v[168:171], v[212:215], v[68:71]
	v_mfma_f32_16x16x32_bf16 v[64:67], v[176:179], v[212:215], v[64:67]
	v_mfma_f32_16x16x32_bf16 v[116:119], v[172:175], v[188:191], v[116:119]
	v_mfma_f32_16x16x32_bf16 v[112:115], v[180:183], v[188:191], v[112:115]
	v_mfma_f32_16x16x32_bf16 v[100:103], v[172:175], v[200:203], v[100:103]
	v_mfma_f32_16x16x32_bf16 v[96:99], v[180:183], v[200:203], v[96:99]
	v_mfma_f32_16x16x32_bf16 v[84:87], v[172:175], v[208:211], v[84:87]
	v_mfma_f32_16x16x32_bf16 v[80:83], v[180:183], v[208:211], v[80:83]
	v_mfma_f32_16x16x32_bf16 v[68:71], v[172:175], v[216:219], v[68:71]
	v_mfma_f32_16x16x32_bf16 v[64:67], v[180:183], v[216:219], v[64:67]
	s_setprio 0
	s_barrier
	s_add_i32 s58, s88, s62
	v_lshl_add_u64 v[148:149], v[148:149], 0, s[20:21]
	s_mov_b32 m0, s58
	ds_read_b128 v[184:187], v155 offset:49152
	ds_read_b128 v[188:191], v155 offset:50176
	ds_read_b128 v[196:199], v155 offset:51200
	ds_read_b128 v[200:203], v155 offset:52224
	ds_read_b128 v[204:207], v155 offset:53248
	ds_read_b128 v[208:211], v155 offset:54272
	ds_read_b128 v[212:215], v155 offset:55296
	ds_read_b128 v[216:219], v155 offset:56320
	global_load_lds_dwordx4 v[148:149], off
	s_add_i32 m0, s58, 0x2000
	s_add_u32 s44, s44, 0x20080
	v_lshl_add_u64 v[148:149], v[192:193], 0, s[20:21]
	s_addc_u32 s45, s45, 0
	s_add_i32 s58, s89, s62
	global_load_lds_dwordx4 v[148:149], off
	s_mov_b32 m0, s58
	s_nop 0
	global_load_lds_dwordx4 v130, s[44:45]
	s_add_i32 m0, s58, 0x2000
	s_nop 0
	global_load_lds_dwordx4 v134, s[44:45]
	s_waitcnt vmcnt(6)
	s_waitcnt lgkmcnt(0)
	s_barrier
	s_setprio 1
	s_waitcnt lgkmcnt(0)
	v_mfma_f32_16x16x32_bf16 v[60:63], v[144:147], v[184:187], v[60:63]
	v_mfma_f32_16x16x32_bf16 v[56:59], v[160:163], v[184:187], v[56:59]
	v_mfma_f32_16x16x32_bf16 v[44:47], v[144:147], v[196:199], v[44:47]
	v_mfma_f32_16x16x32_bf16 v[40:43], v[160:163], v[196:199], v[40:43]
	v_mfma_f32_16x16x32_bf16 v[28:31], v[144:147], v[204:207], v[28:31]
	v_mfma_f32_16x16x32_bf16 v[24:27], v[160:163], v[204:207], v[24:27]
	v_mfma_f32_16x16x32_bf16 v[12:15], v[144:147], v[212:215], v[12:15]
	v_mfma_f32_16x16x32_bf16 v[8:11], v[160:163], v[212:215], v[8:11]
	v_mfma_f32_16x16x32_bf16 v[60:63], v[156:159], v[188:191], v[60:63]
	v_mfma_f32_16x16x32_bf16 v[56:59], v[164:167], v[188:191], v[56:59]
	v_mfma_f32_16x16x32_bf16 v[44:47], v[156:159], v[200:203], v[44:47]
	v_mfma_f32_16x16x32_bf16 v[40:43], v[164:167], v[200:203], v[40:43]
	v_mfma_f32_16x16x32_bf16 v[28:31], v[156:159], v[208:211], v[28:31]
	v_mfma_f32_16x16x32_bf16 v[24:27], v[164:167], v[208:211], v[24:27]
	v_mfma_f32_16x16x32_bf16 v[12:15], v[156:159], v[216:219], v[12:15]
	v_mfma_f32_16x16x32_bf16 v[8:11], v[164:167], v[216:219], v[8:11]
	s_setprio 0
	s_setprio 1
	v_mfma_f32_16x16x32_bf16 v[52:55], v[168:171], v[184:187], v[52:55]
	v_mfma_f32_16x16x32_bf16 v[48:51], v[176:179], v[184:187], v[48:51]
	v_mfma_f32_16x16x32_bf16 v[36:39], v[168:171], v[196:199], v[36:39]
	v_mfma_f32_16x16x32_bf16 v[32:35], v[176:179], v[196:199], v[32:35]
	v_mfma_f32_16x16x32_bf16 v[20:23], v[168:171], v[204:207], v[20:23]
	v_mfma_f32_16x16x32_bf16 v[16:19], v[176:179], v[204:207], v[16:19]
	v_mfma_f32_16x16x32_bf16 v[4:7], v[168:171], v[212:215], v[4:7]
	v_mfma_f32_16x16x32_bf16 v[0:3], v[176:179], v[212:215], v[0:3]
	v_mfma_f32_16x16x32_bf16 v[52:55], v[172:175], v[188:191], v[52:55]
	v_mfma_f32_16x16x32_bf16 v[48:51], v[180:183], v[188:191], v[48:51]
	v_mfma_f32_16x16x32_bf16 v[36:39], v[172:175], v[200:203], v[36:39]
	v_mfma_f32_16x16x32_bf16 v[32:35], v[180:183], v[200:203], v[32:35]
	v_mfma_f32_16x16x32_bf16 v[20:23], v[172:175], v[208:211], v[20:23]
	v_mfma_f32_16x16x32_bf16 v[16:19], v[180:183], v[208:211], v[16:19]
	v_mfma_f32_16x16x32_bf16 v[4:7], v[172:175], v[216:219], v[4:7]
	v_mfma_f32_16x16x32_bf16 v[0:3], v[180:183], v[216:219], v[0:3]
	s_setprio 0
	s_barrier
	v_lshl_add_u64 v[220:221], v[220:221], 0, s[20:21]
	s_mov_b32 m0, s73
	s_nop 0
	global_load_lds_dwordx4 v[220:221], off
	v_lshl_add_u64 v[222:223], v[222:223], 0, s[20:21]
	s_mov_b32 m0, s78
	s_nop 0
	global_load_lds_dwordx4 v[222:223], off
	s_add_i32 s87, s87, 2
	s_add_u32 s42, s42, 0x100
	s_addc_u32 s43, s43, 0
	s_add_u32 s85, s85, 0x100
	s_addc_u32 s86, s86, 0
	s_cmp_gt_u32 s87, 5
	s_cbranch_scc0 .LBB0_1023
	s_and_b64 vcc, exec, s[22:23]
	s_cbranch_vccz .LBB0_1026
	s_barrier

.LBB0_1421:
	ds_read_b128 v[146:149], v155
	ds_read_b128 v[160:163], v155 offset:1024
	ds_read_b128 v[164:167], v155 offset:2048
	ds_read_b128 v[168:171], v155 offset:3072
	ds_read_b128 v[172:175], v156
	ds_read_b128 v[176:179], v156 offset:1024
	ds_read_b128 v[180:183], v156 offset:2048
	ds_read_b128 v[184:187], v156 offset:3072
	s_add_u32 s40, s0, 0xfffc0080
	s_addc_u32 s41, s1, -1
	s_cmp_eq_u32 s83, 12
	s_cselect_b32 s43, s25, s41
	s_cselect_b32 s42, s27, s40
	s_cselect_b32 s41, s31, s82
	s_cselect_b32 s40, s30, s29
	s_add_i32 m0, s39, 0xc000
	ds_read_b128 v[188:191], v157
	ds_read_b128 v[196:199], v157 offset:1024
	ds_read_b128 v[200:203], v157 offset:2048
	ds_read_b128 v[204:207], v157 offset:3072
	ds_read_b128 v[208:211], v157 offset:4096
	ds_read_b128 v[212:215], v157 offset:5120
	ds_read_b128 v[216:219], v157 offset:6144
	ds_read_b128 v[220:223], v157 offset:7168
	global_load_lds_dwordx4 v138, s[0:1]
	s_add_i32 m0, s39, 0xe000
	s_nop 0
	global_load_lds_dwordx4 v140, s[0:1]
	s_waitcnt vmcnt(8)
	s_waitcnt lgkmcnt(0)
	s_barrier
	s_setprio 1
	s_waitcnt lgkmcnt(0)
	v_mfma_f32_16x16x32_bf16 v[124:127], v[146:149], v[188:191], v[124:127]
	v_mfma_f32_16x16x32_bf16 v[120:123], v[164:167], v[188:191], v[120:123]
	v_mfma_f32_16x16x32_bf16 v[108:111], v[146:149], v[200:203], v[108:111]
	v_mfma_f32_16x16x32_bf16 v[104:107], v[164:167], v[200:203], v[104:107]
	v_mfma_f32_16x16x32_bf16 v[92:95], v[146:149], v[208:211], v[92:95]
	v_mfma_f32_16x16x32_bf16 v[88:91], v[164:167], v[208:211], v[88:91]
	v_mfma_f32_16x16x32_bf16 v[76:79], v[146:149], v[216:219], v[76:79]
	v_mfma_f32_16x16x32_bf16 v[72:75], v[164:167], v[216:219], v[72:75]
	v_mfma_f32_16x16x32_bf16 v[124:127], v[160:163], v[196:199], v[124:127]
	v_mfma_f32_16x16x32_bf16 v[120:123], v[168:171], v[196:199], v[120:123]
	v_mfma_f32_16x16x32_bf16 v[108:111], v[160:163], v[204:207], v[108:111]
	v_mfma_f32_16x16x32_bf16 v[104:107], v[168:171], v[204:207], v[104:107]
	v_mfma_f32_16x16x32_bf16 v[92:95], v[160:163], v[212:215], v[92:95]
	v_mfma_f32_16x16x32_bf16 v[88:91], v[168:171], v[212:215], v[88:91]
	v_mfma_f32_16x16x32_bf16 v[76:79], v[160:163], v[220:223], v[76:79]
	v_mfma_f32_16x16x32_bf16 v[72:75], v[168:171], v[220:223], v[72:75]
	s_setprio 0
	s_setprio 1
	v_mfma_f32_16x16x32_bf16 v[116:119], v[172:175], v[188:191], v[116:119]
	v_mfma_f32_16x16x32_bf16 v[112:115], v[180:183], v[188:191], v[112:115]
	v_mfma_f32_16x16x32_bf16 v[100:103], v[172:175], v[200:203], v[100:103]
	v_mfma_f32_16x16x32_bf16 v[96:99], v[180:183], v[200:203], v[96:99]
	v_mfma_f32_16x16x32_bf16 v[84:87], v[172:175], v[208:211], v[84:87]
	v_mfma_f32_16x16x32_bf16 v[80:83], v[180:183], v[208:211], v[80:83]
	v_mfma_f32_16x16x32_bf16 v[68:71], v[172:175], v[216:219], v[68:71]
	v_mfma_f32_16x16x32_bf16 v[64:67], v[180:183], v[216:219], v[64:67]
	v_mfma_f32_16x16x32_bf16 v[116:119], v[176:179], v[196:199], v[116:119]
	v_mfma_f32_16x16x32_bf16 v[112:115], v[184:187], v[196:199], v[112:115]
	v_mfma_f32_16x16x32_bf16 v[100:103], v[176:179], v[204:207], v[100:103]
	v_mfma_f32_16x16x32_bf16 v[96:99], v[184:187], v[204:207], v[96:99]
	v_mfma_f32_16x16x32_bf16 v[84:87], v[176:179], v[212:215], v[84:87]
	v_mfma_f32_16x16x32_bf16 v[80:83], v[184:187], v[212:215], v[80:83]
	v_mfma_f32_16x16x32_bf16 v[68:71], v[176:179], v[220:223], v[68:71]
	v_mfma_f32_16x16x32_bf16 v[64:67], v[184:187], v[220:223], v[64:67]
	s_setprio 0
	s_barrier
	s_add_i32 s84, s78, s60
	v_lshl_add_u64 v[150:151], s[40:41], 0, v[132:133]
	s_mov_b32 m0, s84
	ds_read_b128 v[188:191], v157 offset:16384
	ds_read_b128 v[196:199], v157 offset:17408
	ds_read_b128 v[200:203], v157 offset:18432
	ds_read_b128 v[204:207], v157 offset:19456
	ds_read_b128 v[208:211], v157 offset:20480
	ds_read_b128 v[212:215], v157 offset:21504
	ds_read_b128 v[216:219], v157 offset:22528
	ds_read_b128 v[220:223], v157 offset:23552
	global_load_lds_dwordx4 v[150:151], off
	s_add_i32 m0, s84, 0x2000
	s_add_u32 s84, s40, 0x40000
	v_lshl_add_u64 v[192:193], s[40:41], 0, v[136:137]
	s_addc_u32 s85, s41, 0
	s_add_i32 s86, s79, s60
	global_load_lds_dwordx4 v[192:193], off
	s_mov_b32 m0, s86
	v_lshl_add_u64 v[226:227], s[42:43], 0, v[134:135]
	global_load_lds_dwordx4 v132, s[84:85]
	s_add_i32 m0, s86, 0x2000
	s_nop 0
	global_load_lds_dwordx4 v136, s[84:85]
	v_lshl_add_u64 v[224:225], s[42:43], 0, v[130:131]
	s_waitcnt vmcnt(6)
	s_waitcnt lgkmcnt(0)
	s_barrier
	s_setprio 1
	s_waitcnt lgkmcnt(0)
	v_mfma_f32_16x16x32_bf16 v[60:63], v[146:149], v[188:191], v[60:63]
	v_mfma_f32_16x16x32_bf16 v[56:59], v[164:167], v[188:191], v[56:59]
	v_mfma_f32_16x16x32_bf16 v[44:47], v[146:149], v[200:203], v[44:47]
	v_mfma_f32_16x16x32_bf16 v[40:43], v[164:167], v[200:203], v[40:43]
	v_mfma_f32_16x16x32_bf16 v[28:31], v[146:149], v[208:211], v[28:31]
	v_mfma_f32_16x16x32_bf16 v[24:27], v[164:167], v[208:211], v[24:27]
	v_mfma_f32_16x16x32_bf16 v[12:15], v[146:149], v[216:219], v[12:15]
	v_mfma_f32_16x16x32_bf16 v[8:11], v[164:167], v[216:219], v[8:11]
	v_mfma_f32_16x16x32_bf16 v[60:63], v[160:163], v[196:199], v[60:63]
	v_mfma_f32_16x16x32_bf16 v[56:59], v[168:171], v[196:199], v[56:59]
	v_mfma_f32_16x16x32_bf16 v[44:47], v[160:163], v[204:207], v[44:47]
	v_mfma_f32_16x16x32_bf16 v[40:43], v[168:171], v[204:207], v[40:43]
	v_mfma_f32_16x16x32_bf16 v[28:31], v[160:163], v[212:215], v[28:31]
	v_mfma_f32_16x16x32_bf16 v[24:27], v[168:171], v[212:215], v[24:27]
	v_mfma_f32_16x16x32_bf16 v[12:15], v[160:163], v[220:223], v[12:15]
	v_mfma_f32_16x16x32_bf16 v[8:11], v[168:171], v[220:223], v[8:11]
	s_setprio 0
	s_setprio 1
	v_mfma_f32_16x16x32_bf16 v[52:55], v[172:175], v[188:191], v[52:55]
	v_mfma_f32_16x16x32_bf16 v[48:51], v[180:183], v[188:191], v[48:51]
	v_mfma_f32_16x16x32_bf16 v[36:39], v[172:175], v[200:203], v[36:39]
	v_mfma_f32_16x16x32_bf16 v[32:35], v[180:183], v[200:203], v[32:35]
	v_mfma_f32_16x16x32_bf16 v[20:23], v[172:175], v[208:211], v[20:23]
	v_mfma_f32_16x16x32_bf16 v[16:19], v[180:183], v[208:211], v[16:19]
	v_mfma_f32_16x16x32_bf16 v[4:7], v[172:175], v[216:219], v[4:7]
	v_mfma_f32_16x16x32_bf16 v[0:3], v[180:183], v[216:219], v[0:3]
	v_mfma_f32_16x16x32_bf16 v[52:55], v[176:179], v[196:199], v[52:55]
	v_mfma_f32_16x16x32_bf16 v[48:51], v[184:187], v[196:199], v[48:51]
	v_mfma_f32_16x16x32_bf16 v[36:39], v[176:179], v[204:207], v[36:39]
	v_mfma_f32_16x16x32_bf16 v[32:35], v[184:187], v[204:207], v[32:35]
	v_mfma_f32_16x16x32_bf16 v[20:23], v[176:179], v[212:215], v[20:23]
	v_mfma_f32_16x16x32_bf16 v[16:19], v[184:187], v[212:215], v[16:19]
	v_mfma_f32_16x16x32_bf16 v[4:7], v[176:179], v[220:223], v[4:7]
	v_mfma_f32_16x16x32_bf16 v[0:3], v[184:187], v[220:223], v[0:3]
	s_setprio 0
	s_barrier
	s_add_i32 s84, 0, 0x18000
	v_add_u32_e32 v159, s84, v153
	s_add_i32 s85, 0, 0x1c000
	ds_read_b128 v[146:149], v159
	ds_read_b128 v[160:163], v159 offset:1024
	ds_read_b128 v[164:167], v159 offset:2048
	ds_read_b128 v[168:171], v159 offset:3072
	v_add_u32_e32 v159, s85, v153
	ds_read_b128 v[172:175], v159
	ds_read_b128 v[176:179], v159 offset:1024
	ds_read_b128 v[180:183], v159 offset:2048
	ds_read_b128 v[184:187], v159 offset:3072
	s_add_u32 s42, s42, 0x40000
	s_addc_u32 s43, s43, 0
	ds_read_b128 v[188:191], v157 offset:32768
	ds_read_b128 v[196:199], v157 offset:33792
	ds_read_b128 v[200:203], v157 offset:34816
	ds_read_b128 v[204:207], v157 offset:35840
	ds_read_b128 v[208:211], v157 offset:36864
	ds_read_b128 v[212:215], v157 offset:37888
	ds_read_b128 v[216:219], v157 offset:38912
	ds_read_b128 v[220:223], v157 offset:39936
	s_mov_b32 m0, s39
	s_nop 0
	global_load_lds_dwordx4 v[224:225], off
	s_mov_b32 m0, s61
	s_nop 0
	global_load_lds_dwordx4 v[226:227], off
	s_mov_b32 m0, s62
	s_nop 0
	global_load_lds_dwordx4 v130, s[42:43]
	s_mov_b32 m0, s63
	s_nop 0
	global_load_lds_dwordx4 v134, s[42:43]
	s_waitcnt vmcnt(8)
	s_waitcnt lgkmcnt(0)
	s_barrier
	s_setprio 1
	s_waitcnt lgkmcnt(0)
	v_mfma_f32_16x16x32_bf16 v[124:127], v[146:149], v[188:191], v[124:127]
	v_mfma_f32_16x16x32_bf16 v[120:123], v[164:167], v[188:191], v[120:123]
	v_mfma_f32_16x16x32_bf16 v[108:111], v[146:149], v[200:203], v[108:111]
	v_mfma_f32_16x16x32_bf16 v[104:107], v[164:167], v[200:203], v[104:107]
	v_mfma_f32_16x16x32_bf16 v[92:95], v[146:149], v[208:211], v[92:95]
	v_mfma_f32_16x16x32_bf16 v[88:91], v[164:167], v[208:211], v[88:91]
	v_mfma_f32_16x16x32_bf16 v[76:79], v[146:149], v[216:219], v[76:79]
	v_mfma_f32_16x16x32_bf16 v[72:75], v[164:167], v[216:219], v[72:75]
	v_mfma_f32_16x16x32_bf16 v[124:127], v[160:163], v[196:199], v[124:127]
	v_mfma_f32_16x16x32_bf16 v[120:123], v[168:171], v[196:199], v[120:123]
	v_mfma_f32_16x16x32_bf16 v[108:111], v[160:163], v[204:207], v[108:111]
	v_mfma_f32_16x16x32_bf16 v[104:107], v[168:171], v[204:207], v[104:107]
	v_mfma_f32_16x16x32_bf16 v[92:95], v[160:163], v[212:215], v[92:95]
	v_mfma_f32_16x16x32_bf16 v[88:91], v[168:171], v[212:215], v[88:91]
	v_mfma_f32_16x16x32_bf16 v[76:79], v[160:163], v[220:223], v[76:79]
	v_mfma_f32_16x16x32_bf16 v[72:75], v[168:171], v[220:223], v[72:75]
	s_setprio 0
	s_setprio 1
	v_mfma_f32_16x16x32_bf16 v[116:119], v[172:175], v[188:191], v[116:119]
	v_mfma_f32_16x16x32_bf16 v[112:115], v[180:183], v[188:191], v[112:115]
	v_mfma_f32_16x16x32_bf16 v[100:103], v[172:175], v[200:203], v[100:103]
	v_mfma_f32_16x16x32_bf16 v[96:99], v[180:183], v[200:203], v[96:99]
	v_mfma_f32_16x16x32_bf16 v[84:87], v[172:175], v[208:211], v[84:87]
	v_mfma_f32_16x16x32_bf16 v[80:83], v[180:183], v[208:211], v[80:83]
	v_mfma_f32_16x16x32_bf16 v[68:71], v[172:175], v[216:219], v[68:71]
	v_mfma_f32_16x16x32_bf16 v[64:67], v[180:183], v[216:219], v[64:67]
	v_mfma_f32_16x16x32_bf16 v[116:119], v[176:179], v[196:199], v[116:119]
	v_mfma_f32_16x16x32_bf16 v[112:115], v[184:187], v[196:199], v[112:115]
	v_mfma_f32_16x16x32_bf16 v[100:103], v[176:179], v[204:207], v[100:103]
	v_mfma_f32_16x16x32_bf16 v[96:99], v[184:187], v[204:207], v[96:99]
	v_mfma_f32_16x16x32_bf16 v[84:87], v[176:179], v[212:215], v[84:87]
	v_mfma_f32_16x16x32_bf16 v[80:83], v[184:187], v[212:215], v[80:83]
	v_mfma_f32_16x16x32_bf16 v[68:71], v[176:179], v[220:223], v[68:71]
	v_mfma_f32_16x16x32_bf16 v[64:67], v[184:187], v[220:223], v[64:67]
	s_setprio 0
	s_barrier
	s_add_i32 s42, s84, s60
	v_lshl_add_u64 v[150:151], v[150:151], 0, s[20:21]
	s_mov_b32 m0, s42
	ds_read_b128 v[188:191], v157 offset:49152
	ds_read_b128 v[196:199], v157 offset:50176
	ds_read_b128 v[200:203], v157 offset:51200
	ds_read_b128 v[204:207], v157 offset:52224
	ds_read_b128 v[208:211], v157 offset:53248
	ds_read_b128 v[212:215], v157 offset:54272
	ds_read_b128 v[216:219], v157 offset:55296
	ds_read_b128 v[220:223], v157 offset:56320
	global_load_lds_dwordx4 v[150:151], off
	s_add_i32 m0, s42, 0x2000
	s_add_u32 s40, s40, 0x40080
	v_lshl_add_u64 v[150:151], v[192:193], 0, s[20:21]
	s_addc_u32 s41, s41, 0
	s_add_i32 s42, s85, s60
	global_load_lds_dwordx4 v[150:151], off
	s_mov_b32 m0, s42
	s_nop 0
	global_load_lds_dwordx4 v132, s[40:41]
	s_add_i32 m0, s42, 0x2000
	s_nop 0
	global_load_lds_dwordx4 v136, s[40:41]
	s_waitcnt vmcnt(6)
	s_waitcnt lgkmcnt(0)
	s_barrier
	s_setprio 1
	s_waitcnt lgkmcnt(0)
	v_mfma_f32_16x16x32_bf16 v[60:63], v[146:149], v[188:191], v[60:63]
	v_mfma_f32_16x16x32_bf16 v[56:59], v[164:167], v[188:191], v[56:59]
	v_mfma_f32_16x16x32_bf16 v[44:47], v[146:149], v[200:203], v[44:47]
	v_mfma_f32_16x16x32_bf16 v[40:43], v[164:167], v[200:203], v[40:43]
	v_mfma_f32_16x16x32_bf16 v[28:31], v[146:149], v[208:211], v[28:31]
	v_mfma_f32_16x16x32_bf16 v[24:27], v[164:167], v[208:211], v[24:27]
	v_mfma_f32_16x16x32_bf16 v[12:15], v[146:149], v[216:219], v[12:15]
	v_mfma_f32_16x16x32_bf16 v[8:11], v[164:167], v[216:219], v[8:11]
	v_mfma_f32_16x16x32_bf16 v[60:63], v[160:163], v[196:199], v[60:63]
	v_mfma_f32_16x16x32_bf16 v[56:59], v[168:171], v[196:199], v[56:59]
	v_mfma_f32_16x16x32_bf16 v[44:47], v[160:163], v[204:207], v[44:47]
	v_mfma_f32_16x16x32_bf16 v[40:43], v[168:171], v[204:207], v[40:43]
	v_mfma_f32_16x16x32_bf16 v[28:31], v[160:163], v[212:215], v[28:31]
	v_mfma_f32_16x16x32_bf16 v[24:27], v[168:171], v[212:215], v[24:27]
	v_mfma_f32_16x16x32_bf16 v[12:15], v[160:163], v[220:223], v[12:15]
	v_mfma_f32_16x16x32_bf16 v[8:11], v[168:171], v[220:223], v[8:11]
	s_setprio 0
	s_setprio 1
	v_mfma_f32_16x16x32_bf16 v[52:55], v[172:175], v[188:191], v[52:55]
	v_mfma_f32_16x16x32_bf16 v[48:51], v[180:183], v[188:191], v[48:51]
	v_mfma_f32_16x16x32_bf16 v[36:39], v[172:175], v[200:203], v[36:39]
	v_mfma_f32_16x16x32_bf16 v[32:35], v[180:183], v[200:203], v[32:35]
	v_mfma_f32_16x16x32_bf16 v[20:23], v[172:175], v[208:211], v[20:23]
	v_mfma_f32_16x16x32_bf16 v[16:19], v[180:183], v[208:211], v[16:19]
	v_mfma_f32_16x16x32_bf16 v[4:7], v[172:175], v[216:219], v[4:7]
	v_mfma_f32_16x16x32_bf16 v[0:3], v[180:183], v[216:219], v[0:3]
	v_mfma_f32_16x16x32_bf16 v[52:55], v[176:179], v[196:199], v[52:55]
	v_mfma_f32_16x16x32_bf16 v[48:51], v[184:187], v[196:199], v[48:51]
	v_mfma_f32_16x16x32_bf16 v[36:39], v[176:179], v[204:207], v[36:39]
	v_mfma_f32_16x16x32_bf16 v[32:35], v[184:187], v[204:207], v[32:35]
	v_mfma_f32_16x16x32_bf16 v[20:23], v[176:179], v[212:215], v[20:23]
	v_mfma_f32_16x16x32_bf16 v[16:19], v[184:187], v[212:215], v[16:19]
	v_mfma_f32_16x16x32_bf16 v[4:7], v[176:179], v[220:223], v[4:7]
	v_mfma_f32_16x16x32_bf16 v[0:3], v[184:187], v[220:223], v[0:3]
	s_setprio 0
	s_barrier
	v_lshl_add_u64 v[224:225], v[224:225], 0, s[20:21]
	s_mov_b32 m0, s70
	s_nop 0
	global_load_lds_dwordx4 v[224:225], off
	v_lshl_add_u64 v[226:227], v[226:227], 0, s[20:21]
	s_mov_b32 m0, s71
	s_nop 0
	global_load_lds_dwordx4 v[226:227], off
	s_add_i32 s83, s83, 2
	s_add_u32 s0, s0, 0x100
	s_addc_u32 s1, s1, 0
	s_add_u32 s29, s29, 0x100
	s_addc_u32 s82, s82, 0
	s_cmp_gt_u32 s83, 13
	s_cbranch_scc0 .LBB0_1421
	s_and_b64 vcc, exec, s[22:23]
	s_cbranch_vccz .LBB0_1424
	s_barrier

.LBB0_1451:
	ds_read_b128 v[144:147], v159
	ds_read_b128 v[148:151], v159 offset:1024
	ds_read_b128 v[152:155], v159 offset:2048
	ds_read_b128 v[162:165], v159 offset:3072
	ds_read_b128 v[166:169], v160
	ds_read_b128 v[170:173], v160 offset:1024
	ds_read_b128 v[174:177], v160 offset:2048
	ds_read_b128 v[178:181], v160 offset:3072
	s_add_u32 s41, s58, 0xfffe0080
	s_addc_u32 s43, s59, -1
	s_cmp_eq_u32 s39, 4
	s_cselect_b32 s71, s1, s43
	s_cselect_b32 s70, s0, s41
	s_cselect_b32 s63, s45, s17
	s_cselect_b32 s62, s44, s15
	s_add_i32 m0, s83, 0xc000
	ds_read_b128 v[182:185], v161
	ds_read_b128 v[186:189], v161 offset:1024
	ds_read_b128 v[190:193], v161 offset:2048
	ds_read_b128 v[196:199], v161 offset:3072
	ds_read_b128 v[200:203], v161 offset:4096
	ds_read_b128 v[204:207], v161 offset:5120
	ds_read_b128 v[208:211], v161 offset:6144
	ds_read_b128 v[212:215], v161 offset:7168
	global_load_lds_dwordx4 v136, s[58:59]
	s_add_i32 m0, s83, 0xe000
	s_nop 0
	global_load_lds_dwordx4 v138, s[58:59]
	s_waitcnt vmcnt(8)
	s_waitcnt lgkmcnt(0)
	s_barrier
	s_setprio 1
	s_waitcnt lgkmcnt(0)
	v_mfma_f32_16x16x32_bf16 v[124:127], v[144:147], v[182:185], v[124:127]
	v_mfma_f32_16x16x32_bf16 v[120:123], v[152:155], v[182:185], v[120:123]
	v_mfma_f32_16x16x32_bf16 v[108:111], v[144:147], v[190:193], v[108:111]
	v_mfma_f32_16x16x32_bf16 v[104:107], v[152:155], v[190:193], v[104:107]
	v_mfma_f32_16x16x32_bf16 v[92:95], v[144:147], v[200:203], v[92:95]
	v_mfma_f32_16x16x32_bf16 v[88:91], v[152:155], v[200:203], v[88:91]
	v_mfma_f32_16x16x32_bf16 v[76:79], v[144:147], v[208:211], v[76:79]
	v_mfma_f32_16x16x32_bf16 v[72:75], v[152:155], v[208:211], v[72:75]
	v_mfma_f32_16x16x32_bf16 v[124:127], v[148:151], v[186:189], v[124:127]
	v_mfma_f32_16x16x32_bf16 v[120:123], v[162:165], v[186:189], v[120:123]
	v_mfma_f32_16x16x32_bf16 v[108:111], v[148:151], v[196:199], v[108:111]
	v_mfma_f32_16x16x32_bf16 v[104:107], v[162:165], v[196:199], v[104:107]
	v_mfma_f32_16x16x32_bf16 v[92:95], v[148:151], v[204:207], v[92:95]
	v_mfma_f32_16x16x32_bf16 v[88:91], v[162:165], v[204:207], v[88:91]
	v_mfma_f32_16x16x32_bf16 v[76:79], v[148:151], v[212:215], v[76:79]
	v_mfma_f32_16x16x32_bf16 v[72:75], v[162:165], v[212:215], v[72:75]
	s_setprio 0
	s_setprio 1
	v_mfma_f32_16x16x32_bf16 v[116:119], v[166:169], v[182:185], v[116:119]
	v_mfma_f32_16x16x32_bf16 v[112:115], v[174:177], v[182:185], v[112:115]
	v_mfma_f32_16x16x32_bf16 v[100:103], v[166:169], v[190:193], v[100:103]
	v_mfma_f32_16x16x32_bf16 v[96:99], v[174:177], v[190:193], v[96:99]
	v_mfma_f32_16x16x32_bf16 v[84:87], v[166:169], v[200:203], v[84:87]
	v_mfma_f32_16x16x32_bf16 v[80:83], v[174:177], v[200:203], v[80:83]
	v_mfma_f32_16x16x32_bf16 v[68:71], v[166:169], v[208:211], v[68:71]
	v_mfma_f32_16x16x32_bf16 v[64:67], v[174:177], v[208:211], v[64:67]
	v_mfma_f32_16x16x32_bf16 v[116:119], v[170:173], v[186:189], v[116:119]
	v_mfma_f32_16x16x32_bf16 v[112:115], v[178:181], v[186:189], v[112:115]
	v_mfma_f32_16x16x32_bf16 v[100:103], v[170:173], v[196:199], v[100:103]
	v_mfma_f32_16x16x32_bf16 v[96:99], v[178:181], v[196:199], v[96:99]
	v_mfma_f32_16x16x32_bf16 v[84:87], v[170:173], v[204:207], v[84:87]
	v_mfma_f32_16x16x32_bf16 v[80:83], v[178:181], v[204:207], v[80:83]
	v_mfma_f32_16x16x32_bf16 v[68:71], v[170:173], v[212:215], v[68:71]
	v_mfma_f32_16x16x32_bf16 v[64:67], v[178:181], v[212:215], v[64:67]
	s_setprio 0
	s_barrier
	s_add_i32 s41, s90, s80
	v_lshl_add_u64 v[216:217], s[62:63], 0, v[130:131]
	s_mov_b32 m0, s41
	ds_read_b128 v[182:185], v161 offset:16384
	ds_read_b128 v[186:189], v161 offset:17408
	ds_read_b128 v[190:193], v161 offset:18432
	ds_read_b128 v[196:199], v161 offset:19456
	ds_read_b128 v[200:203], v161 offset:20480
	ds_read_b128 v[204:207], v161 offset:21504
	ds_read_b128 v[208:211], v161 offset:22528
	ds_read_b128 v[212:215], v161 offset:23552
	global_load_lds_dwordx4 v[216:217], off
	s_add_i32 m0, s41, 0x2000
	s_add_u32 s94, s62, 0x20000
	v_lshl_add_u64 v[218:219], s[62:63], 0, v[134:135]
	s_addc_u32 s95, s63, 0
	s_add_i32 s41, s91, s80
	global_load_lds_dwordx4 v[218:219], off
	s_mov_b32 m0, s41
	v_lshl_add_u64 v[222:223], s[70:71], 0, v[132:133]
	global_load_lds_dwordx4 v130, s[94:95]
	s_add_i32 m0, s41, 0x2000
	s_nop 0
	global_load_lds_dwordx4 v134, s[94:95]
	v_lshl_add_u64 v[220:221], s[70:71], 0, v[128:129]
	s_waitcnt vmcnt(6)
	s_waitcnt lgkmcnt(0)
	s_barrier
	s_setprio 1
	s_waitcnt lgkmcnt(0)
	v_mfma_f32_16x16x32_bf16 v[60:63], v[144:147], v[182:185], v[60:63]
	v_mfma_f32_16x16x32_bf16 v[56:59], v[152:155], v[182:185], v[56:59]
	v_mfma_f32_16x16x32_bf16 v[44:47], v[144:147], v[190:193], v[44:47]
	v_mfma_f32_16x16x32_bf16 v[40:43], v[152:155], v[190:193], v[40:43]
	v_mfma_f32_16x16x32_bf16 v[28:31], v[144:147], v[200:203], v[28:31]
	v_mfma_f32_16x16x32_bf16 v[24:27], v[152:155], v[200:203], v[24:27]
	v_mfma_f32_16x16x32_bf16 v[12:15], v[144:147], v[208:211], v[12:15]
	v_mfma_f32_16x16x32_bf16 v[8:11], v[152:155], v[208:211], v[8:11]
	v_mfma_f32_16x16x32_bf16 v[60:63], v[148:151], v[186:189], v[60:63]
	v_mfma_f32_16x16x32_bf16 v[56:59], v[162:165], v[186:189], v[56:59]
	v_mfma_f32_16x16x32_bf16 v[44:47], v[148:151], v[196:199], v[44:47]
	v_mfma_f32_16x16x32_bf16 v[40:43], v[162:165], v[196:199], v[40:43]
	v_mfma_f32_16x16x32_bf16 v[28:31], v[148:151], v[204:207], v[28:31]
	v_mfma_f32_16x16x32_bf16 v[24:27], v[162:165], v[204:207], v[24:27]
	v_mfma_f32_16x16x32_bf16 v[12:15], v[148:151], v[212:215], v[12:15]
	v_mfma_f32_16x16x32_bf16 v[8:11], v[162:165], v[212:215], v[8:11]
	s_setprio 0
	s_setprio 1
	v_mfma_f32_16x16x32_bf16 v[52:55], v[166:169], v[182:185], v[52:55]
	v_mfma_f32_16x16x32_bf16 v[48:51], v[174:177], v[182:185], v[48:51]
	v_mfma_f32_16x16x32_bf16 v[36:39], v[166:169], v[190:193], v[36:39]
	v_mfma_f32_16x16x32_bf16 v[32:35], v[174:177], v[190:193], v[32:35]
	v_mfma_f32_16x16x32_bf16 v[20:23], v[166:169], v[200:203], v[20:23]
	v_mfma_f32_16x16x32_bf16 v[16:19], v[174:177], v[200:203], v[16:19]
	v_mfma_f32_16x16x32_bf16 v[4:7], v[166:169], v[208:211], v[4:7]
	v_mfma_f32_16x16x32_bf16 v[0:3], v[174:177], v[208:211], v[0:3]
	v_mfma_f32_16x16x32_bf16 v[52:55], v[170:173], v[186:189], v[52:55]
	v_mfma_f32_16x16x32_bf16 v[48:51], v[178:181], v[186:189], v[48:51]
	v_mfma_f32_16x16x32_bf16 v[36:39], v[170:173], v[196:199], v[36:39]
	v_mfma_f32_16x16x32_bf16 v[32:35], v[178:181], v[196:199], v[32:35]
	v_mfma_f32_16x16x32_bf16 v[20:23], v[170:173], v[204:207], v[20:23]
	v_mfma_f32_16x16x32_bf16 v[16:19], v[178:181], v[204:207], v[16:19]
	v_mfma_f32_16x16x32_bf16 v[4:7], v[170:173], v[212:215], v[4:7]
	v_mfma_f32_16x16x32_bf16 v[0:3], v[178:181], v[212:215], v[0:3]
	s_setprio 0
	s_barrier
	s_add_i32 s41, 0, 0x18000
	s_add_i32 s43, 0, 0x1c000
	v_add_u32_e32 v162, s41, v157
	v_add_u32_e32 v178, s43, v157
	ds_read_b128 v[144:147], v162
	ds_read_b128 v[148:151], v162 offset:1024
	ds_read_b128 v[152:155], v162 offset:2048
	ds_read_b128 v[162:165], v162 offset:3072
	ds_read_b128 v[166:169], v178
	ds_read_b128 v[170:173], v178 offset:1024
	ds_read_b128 v[174:177], v178 offset:2048
	ds_read_b128 v[178:181], v178 offset:3072
	s_add_u32 s70, s70, 0x20000
	s_addc_u32 s71, s71, 0
	ds_read_b128 v[182:185], v161 offset:32768
	ds_read_b128 v[186:189], v161 offset:33792
	ds_read_b128 v[190:193], v161 offset:34816
	ds_read_b128 v[196:199], v161 offset:35840
	ds_read_b128 v[200:203], v161 offset:36864
	ds_read_b128 v[204:207], v161 offset:37888
	ds_read_b128 v[208:211], v161 offset:38912
	ds_read_b128 v[212:215], v161 offset:39936
	s_mov_b32 m0, s83
	s_nop 0
	global_load_lds_dwordx4 v[220:221], off
	s_mov_b32 m0, s84
	s_nop 0
	global_load_lds_dwordx4 v[222:223], off
	s_mov_b32 m0, s85
	s_nop 0
	global_load_lds_dwordx4 v128, s[70:71]
	s_mov_b32 m0, s86
	s_nop 0
	global_load_lds_dwordx4 v132, s[70:71]
	s_waitcnt vmcnt(8)
	s_waitcnt lgkmcnt(0)
	s_barrier
	s_setprio 1
	s_waitcnt lgkmcnt(0)
	v_mfma_f32_16x16x32_bf16 v[124:127], v[144:147], v[182:185], v[124:127]
	v_mfma_f32_16x16x32_bf16 v[120:123], v[152:155], v[182:185], v[120:123]
	v_mfma_f32_16x16x32_bf16 v[108:111], v[144:147], v[190:193], v[108:111]
	v_mfma_f32_16x16x32_bf16 v[104:107], v[152:155], v[190:193], v[104:107]
	v_mfma_f32_16x16x32_bf16 v[92:95], v[144:147], v[200:203], v[92:95]
	v_mfma_f32_16x16x32_bf16 v[88:91], v[152:155], v[200:203], v[88:91]
	v_mfma_f32_16x16x32_bf16 v[76:79], v[144:147], v[208:211], v[76:79]
	v_mfma_f32_16x16x32_bf16 v[72:75], v[152:155], v[208:211], v[72:75]
	v_mfma_f32_16x16x32_bf16 v[124:127], v[148:151], v[186:189], v[124:127]
	v_mfma_f32_16x16x32_bf16 v[120:123], v[162:165], v[186:189], v[120:123]
	v_mfma_f32_16x16x32_bf16 v[108:111], v[148:151], v[196:199], v[108:111]
	v_mfma_f32_16x16x32_bf16 v[104:107], v[162:165], v[196:199], v[104:107]
	v_mfma_f32_16x16x32_bf16 v[92:95], v[148:151], v[204:207], v[92:95]
	v_mfma_f32_16x16x32_bf16 v[88:91], v[162:165], v[204:207], v[88:91]
	v_mfma_f32_16x16x32_bf16 v[76:79], v[148:151], v[212:215], v[76:79]
	v_mfma_f32_16x16x32_bf16 v[72:75], v[162:165], v[212:215], v[72:75]
	s_setprio 0
	s_setprio 1
	v_mfma_f32_16x16x32_bf16 v[116:119], v[166:169], v[182:185], v[116:119]
	v_mfma_f32_16x16x32_bf16 v[112:115], v[174:177], v[182:185], v[112:115]
	v_mfma_f32_16x16x32_bf16 v[100:103], v[166:169], v[190:193], v[100:103]
	v_mfma_f32_16x16x32_bf16 v[96:99], v[174:177], v[190:193], v[96:99]
	v_mfma_f32_16x16x32_bf16 v[84:87], v[166:169], v[200:203], v[84:87]
	v_mfma_f32_16x16x32_bf16 v[80:83], v[174:177], v[200:203], v[80:83]
	v_mfma_f32_16x16x32_bf16 v[68:71], v[166:169], v[208:211], v[68:71]
	v_mfma_f32_16x16x32_bf16 v[64:67], v[174:177], v[208:211], v[64:67]
	v_mfma_f32_16x16x32_bf16 v[116:119], v[170:173], v[186:189], v[116:119]
	v_mfma_f32_16x16x32_bf16 v[112:115], v[178:181], v[186:189], v[112:115]
	v_mfma_f32_16x16x32_bf16 v[100:103], v[170:173], v[196:199], v[100:103]
	v_mfma_f32_16x16x32_bf16 v[96:99], v[178:181], v[196:199], v[96:99]
	v_mfma_f32_16x16x32_bf16 v[84:87], v[170:173], v[204:207], v[84:87]
	v_mfma_f32_16x16x32_bf16 v[80:83], v[178:181], v[204:207], v[80:83]
	v_mfma_f32_16x16x32_bf16 v[68:71], v[170:173], v[212:215], v[68:71]
	v_mfma_f32_16x16x32_bf16 v[64:67], v[178:181], v[212:215], v[64:67]
	s_setprio 0
	s_barrier
	s_add_i32 s41, s41, s80
	v_lshl_add_u64 v[216:217], v[216:217], 0, s[26:27]
	s_mov_b32 m0, s41
	ds_read_b128 v[182:185], v161 offset:49152
	ds_read_b128 v[186:189], v161 offset:50176
	ds_read_b128 v[190:193], v161 offset:51200
	ds_read_b128 v[196:199], v161 offset:52224
	ds_read_b128 v[200:203], v161 offset:53248
	ds_read_b128 v[204:207], v161 offset:54272
	ds_read_b128 v[208:211], v161 offset:55296
	ds_read_b128 v[212:215], v161 offset:56320
	global_load_lds_dwordx4 v[216:217], off
	s_add_i32 m0, s41, 0x2000
	s_add_u32 s62, s62, 0x20080
	v_lshl_add_u64 v[216:217], v[218:219], 0, s[26:27]
	s_addc_u32 s63, s63, 0
	s_add_i32 s41, s43, s80
	global_load_lds_dwordx4 v[216:217], off
	s_mov_b32 m0, s41
	s_nop 0
	global_load_lds_dwordx4 v130, s[62:63]
	s_add_i32 m0, s41, 0x2000
	s_nop 0
	global_load_lds_dwordx4 v134, s[62:63]
	s_waitcnt vmcnt(6)
	s_waitcnt lgkmcnt(0)
	s_barrier
	s_setprio 1
	s_waitcnt lgkmcnt(0)
	v_mfma_f32_16x16x32_bf16 v[60:63], v[144:147], v[182:185], v[60:63]
	v_mfma_f32_16x16x32_bf16 v[56:59], v[152:155], v[182:185], v[56:59]
	v_mfma_f32_16x16x32_bf16 v[44:47], v[144:147], v[190:193], v[44:47]
	v_mfma_f32_16x16x32_bf16 v[40:43], v[152:155], v[190:193], v[40:43]
	v_mfma_f32_16x16x32_bf16 v[28:31], v[144:147], v[200:203], v[28:31]
	v_mfma_f32_16x16x32_bf16 v[24:27], v[152:155], v[200:203], v[24:27]
	v_mfma_f32_16x16x32_bf16 v[12:15], v[144:147], v[208:211], v[12:15]
	v_mfma_f32_16x16x32_bf16 v[8:11], v[152:155], v[208:211], v[8:11]
	v_mfma_f32_16x16x32_bf16 v[60:63], v[148:151], v[186:189], v[60:63]
	v_mfma_f32_16x16x32_bf16 v[56:59], v[162:165], v[186:189], v[56:59]
	v_mfma_f32_16x16x32_bf16 v[44:47], v[148:151], v[196:199], v[44:47]
	v_mfma_f32_16x16x32_bf16 v[40:43], v[162:165], v[196:199], v[40:43]
	v_mfma_f32_16x16x32_bf16 v[28:31], v[148:151], v[204:207], v[28:31]
	v_mfma_f32_16x16x32_bf16 v[24:27], v[162:165], v[204:207], v[24:27]
	v_mfma_f32_16x16x32_bf16 v[12:15], v[148:151], v[212:215], v[12:15]
	v_mfma_f32_16x16x32_bf16 v[8:11], v[162:165], v[212:215], v[8:11]
	s_setprio 0
	s_setprio 1
	v_mfma_f32_16x16x32_bf16 v[52:55], v[166:169], v[182:185], v[52:55]
	v_mfma_f32_16x16x32_bf16 v[48:51], v[174:177], v[182:185], v[48:51]
	v_mfma_f32_16x16x32_bf16 v[36:39], v[166:169], v[190:193], v[36:39]
	v_mfma_f32_16x16x32_bf16 v[32:35], v[174:177], v[190:193], v[32:35]
	v_mfma_f32_16x16x32_bf16 v[20:23], v[166:169], v[200:203], v[20:23]
	v_mfma_f32_16x16x32_bf16 v[16:19], v[174:177], v[200:203], v[16:19]
	v_mfma_f32_16x16x32_bf16 v[4:7], v[166:169], v[208:211], v[4:7]
	v_mfma_f32_16x16x32_bf16 v[0:3], v[174:177], v[208:211], v[0:3]
	v_mfma_f32_16x16x32_bf16 v[52:55], v[170:173], v[186:189], v[52:55]
	v_mfma_f32_16x16x32_bf16 v[48:51], v[178:181], v[186:189], v[48:51]
	v_mfma_f32_16x16x32_bf16 v[36:39], v[170:173], v[196:199], v[36:39]
	v_mfma_f32_16x16x32_bf16 v[32:35], v[178:181], v[196:199], v[32:35]
	v_mfma_f32_16x16x32_bf16 v[20:23], v[170:173], v[204:207], v[20:23]
	v_mfma_f32_16x16x32_bf16 v[16:19], v[178:181], v[204:207], v[16:19]
	v_mfma_f32_16x16x32_bf16 v[4:7], v[170:173], v[212:215], v[4:7]
	v_mfma_f32_16x16x32_bf16 v[0:3], v[178:181], v[212:215], v[0:3]
	s_setprio 0
	s_barrier
	v_lshl_add_u64 v[220:221], v[220:221], 0, s[26:27]
	s_mov_b32 m0, s87
	s_nop 0
	global_load_lds_dwordx4 v[220:221], off
	v_lshl_add_u64 v[222:223], v[222:223], 0, s[26:27]
	s_mov_b32 m0, s88
	s_nop 0
	global_load_lds_dwordx4 v[222:223], off
	s_add_i32 s39, s39, 2
	s_add_u32 s58, s58, 0x100
	s_addc_u32 s59, s59, 0
	s_add_u32 s15, s15, 0x100
	s_addc_u32 s17, s17, 0
	s_cmp_gt_u32 s39, 5
	s_cbranch_scc0 .LBB0_1451
	s_and_b64 vcc, exec, s[28:29]
	s_cbranch_vccz .LBB0_1454
	s_barrier

.LBB0_1625:
	ds_read_b128 v[144:147], v151
	ds_read_b128 v[156:159], v151 offset:1024
	ds_read_b128 v[160:163], v151 offset:2048
	ds_read_b128 v[164:167], v151 offset:3072
	ds_read_b128 v[168:171], v152
	ds_read_b128 v[172:175], v152 offset:1024
	ds_read_b128 v[176:179], v152 offset:2048
	ds_read_b128 v[180:183], v152 offset:3072
	s_add_u32 s42, s40, 0xfffc0080
	s_addc_u32 s43, s41, -1
	s_cmp_eq_u32 s87, 12
	s_cselect_b32 s45, s31, s43
	s_cselect_b32 s44, s39, s42
	s_cselect_b32 s43, s29, s86
	s_cselect_b32 s42, s84, s85
	s_add_i32 m0, s63, 0xc000
	ds_read_b128 v[184:187], v153
	ds_read_b128 v[188:191], v153 offset:1024
	ds_read_b128 v[196:199], v153 offset:2048
	ds_read_b128 v[200:203], v153 offset:3072
	ds_read_b128 v[204:207], v153 offset:4096
	ds_read_b128 v[208:211], v153 offset:5120
	ds_read_b128 v[212:215], v153 offset:6144
	ds_read_b128 v[216:219], v153 offset:7168
	global_load_lds_dwordx4 v136, s[40:41]
	s_add_i32 m0, s63, 0xe000
	s_nop 0
	global_load_lds_dwordx4 v138, s[40:41]
	s_waitcnt vmcnt(8)
	s_waitcnt lgkmcnt(0)
	s_barrier
	s_setprio 1
	s_waitcnt lgkmcnt(0)
	v_mfma_f32_16x16x32_bf16 v[124:127], v[144:147], v[184:187], v[124:127]
	v_mfma_f32_16x16x32_bf16 v[120:123], v[160:163], v[184:187], v[120:123]
	v_mfma_f32_16x16x32_bf16 v[108:111], v[144:147], v[196:199], v[108:111]
	v_mfma_f32_16x16x32_bf16 v[104:107], v[160:163], v[196:199], v[104:107]
	v_mfma_f32_16x16x32_bf16 v[92:95], v[144:147], v[204:207], v[92:95]
	v_mfma_f32_16x16x32_bf16 v[88:91], v[160:163], v[204:207], v[88:91]
	v_mfma_f32_16x16x32_bf16 v[76:79], v[144:147], v[212:215], v[76:79]
	v_mfma_f32_16x16x32_bf16 v[72:75], v[160:163], v[212:215], v[72:75]
	v_mfma_f32_16x16x32_bf16 v[124:127], v[156:159], v[188:191], v[124:127]
	v_mfma_f32_16x16x32_bf16 v[120:123], v[164:167], v[188:191], v[120:123]
	v_mfma_f32_16x16x32_bf16 v[108:111], v[156:159], v[200:203], v[108:111]
	v_mfma_f32_16x16x32_bf16 v[104:107], v[164:167], v[200:203], v[104:107]
	v_mfma_f32_16x16x32_bf16 v[92:95], v[156:159], v[208:211], v[92:95]
	v_mfma_f32_16x16x32_bf16 v[88:91], v[164:167], v[208:211], v[88:91]
	v_mfma_f32_16x16x32_bf16 v[76:79], v[156:159], v[216:219], v[76:79]
	v_mfma_f32_16x16x32_bf16 v[72:75], v[164:167], v[216:219], v[72:75]
	s_setprio 0
	s_setprio 1
	v_mfma_f32_16x16x32_bf16 v[116:119], v[168:171], v[184:187], v[116:119]
	v_mfma_f32_16x16x32_bf16 v[112:115], v[176:179], v[184:187], v[112:115]
	v_mfma_f32_16x16x32_bf16 v[100:103], v[168:171], v[196:199], v[100:103]
	v_mfma_f32_16x16x32_bf16 v[96:99], v[176:179], v[196:199], v[96:99]
	v_mfma_f32_16x16x32_bf16 v[84:87], v[168:171], v[204:207], v[84:87]
	v_mfma_f32_16x16x32_bf16 v[80:83], v[176:179], v[204:207], v[80:83]
	v_mfma_f32_16x16x32_bf16 v[68:71], v[168:171], v[212:215], v[68:71]
	v_mfma_f32_16x16x32_bf16 v[64:67], v[176:179], v[212:215], v[64:67]
	v_mfma_f32_16x16x32_bf16 v[116:119], v[172:175], v[188:191], v[116:119]
	v_mfma_f32_16x16x32_bf16 v[112:115], v[180:183], v[188:191], v[112:115]
	v_mfma_f32_16x16x32_bf16 v[100:103], v[172:175], v[200:203], v[100:103]
	v_mfma_f32_16x16x32_bf16 v[96:99], v[180:183], v[200:203], v[96:99]
	v_mfma_f32_16x16x32_bf16 v[84:87], v[172:175], v[208:211], v[84:87]
	v_mfma_f32_16x16x32_bf16 v[80:83], v[180:183], v[208:211], v[80:83]
	v_mfma_f32_16x16x32_bf16 v[68:71], v[172:175], v[216:219], v[68:71]
	v_mfma_f32_16x16x32_bf16 v[64:67], v[180:183], v[216:219], v[64:67]
	s_setprio 0
	s_barrier
	s_add_i32 s88, s81, s62
	v_lshl_add_u64 v[192:193], s[42:43], 0, v[130:131]
	s_mov_b32 m0, s88
	ds_read_b128 v[184:187], v153 offset:16384
	ds_read_b128 v[188:191], v153 offset:17408
	ds_read_b128 v[196:199], v153 offset:18432
	ds_read_b128 v[200:203], v153 offset:19456
	ds_read_b128 v[204:207], v153 offset:20480
	ds_read_b128 v[208:211], v153 offset:21504
	ds_read_b128 v[212:215], v153 offset:22528
	ds_read_b128 v[216:219], v153 offset:23552
	global_load_lds_dwordx4 v[192:193], off
	s_add_i32 m0, s88, 0x2000
	s_add_u32 s88, s42, 0x40000
	v_lshl_add_u64 v[220:221], s[42:43], 0, v[134:135]
	s_addc_u32 s89, s43, 0
	s_add_i32 s90, s82, s62
	global_load_lds_dwordx4 v[220:221], off
	s_mov_b32 m0, s90
	v_lshl_add_u64 v[224:225], s[44:45], 0, v[132:133]
	global_load_lds_dwordx4 v130, s[88:89]
	s_add_i32 m0, s90, 0x2000
	s_nop 0
	global_load_lds_dwordx4 v134, s[88:89]
	v_lshl_add_u64 v[222:223], s[44:45], 0, v[128:129]
	s_waitcnt vmcnt(6)
	s_waitcnt lgkmcnt(0)
	s_barrier
	s_setprio 1
	s_waitcnt lgkmcnt(0)
	v_mfma_f32_16x16x32_bf16 v[60:63], v[144:147], v[184:187], v[60:63]
	v_mfma_f32_16x16x32_bf16 v[56:59], v[160:163], v[184:187], v[56:59]
	v_mfma_f32_16x16x32_bf16 v[44:47], v[144:147], v[196:199], v[44:47]
	v_mfma_f32_16x16x32_bf16 v[40:43], v[160:163], v[196:199], v[40:43]
	v_mfma_f32_16x16x32_bf16 v[28:31], v[144:147], v[204:207], v[28:31]
	v_mfma_f32_16x16x32_bf16 v[24:27], v[160:163], v[204:207], v[24:27]
	v_mfma_f32_16x16x32_bf16 v[12:15], v[144:147], v[212:215], v[12:15]
	v_mfma_f32_16x16x32_bf16 v[8:11], v[160:163], v[212:215], v[8:11]
	v_mfma_f32_16x16x32_bf16 v[60:63], v[156:159], v[188:191], v[60:63]
	v_mfma_f32_16x16x32_bf16 v[56:59], v[164:167], v[188:191], v[56:59]
	v_mfma_f32_16x16x32_bf16 v[44:47], v[156:159], v[200:203], v[44:47]
	v_mfma_f32_16x16x32_bf16 v[40:43], v[164:167], v[200:203], v[40:43]
	v_mfma_f32_16x16x32_bf16 v[28:31], v[156:159], v[208:211], v[28:31]
	v_mfma_f32_16x16x32_bf16 v[24:27], v[164:167], v[208:211], v[24:27]
	v_mfma_f32_16x16x32_bf16 v[12:15], v[156:159], v[216:219], v[12:15]
	v_mfma_f32_16x16x32_bf16 v[8:11], v[164:167], v[216:219], v[8:11]
	s_setprio 0
	s_setprio 1
	v_mfma_f32_16x16x32_bf16 v[52:55], v[168:171], v[184:187], v[52:55]
	v_mfma_f32_16x16x32_bf16 v[48:51], v[176:179], v[184:187], v[48:51]
	v_mfma_f32_16x16x32_bf16 v[36:39], v[168:171], v[196:199], v[36:39]
	v_mfma_f32_16x16x32_bf16 v[32:35], v[176:179], v[196:199], v[32:35]
	v_mfma_f32_16x16x32_bf16 v[20:23], v[168:171], v[204:207], v[20:23]
	v_mfma_f32_16x16x32_bf16 v[16:19], v[176:179], v[204:207], v[16:19]
	v_mfma_f32_16x16x32_bf16 v[4:7], v[168:171], v[212:215], v[4:7]
	v_mfma_f32_16x16x32_bf16 v[0:3], v[176:179], v[212:215], v[0:3]
	v_mfma_f32_16x16x32_bf16 v[52:55], v[172:175], v[188:191], v[52:55]
	v_mfma_f32_16x16x32_bf16 v[48:51], v[180:183], v[188:191], v[48:51]
	v_mfma_f32_16x16x32_bf16 v[36:39], v[172:175], v[200:203], v[36:39]
	v_mfma_f32_16x16x32_bf16 v[32:35], v[180:183], v[200:203], v[32:35]
	v_mfma_f32_16x16x32_bf16 v[20:23], v[172:175], v[208:211], v[20:23]
	v_mfma_f32_16x16x32_bf16 v[16:19], v[180:183], v[208:211], v[16:19]
	v_mfma_f32_16x16x32_bf16 v[4:7], v[172:175], v[216:219], v[4:7]
	v_mfma_f32_16x16x32_bf16 v[0:3], v[180:183], v[216:219], v[0:3]
	s_setprio 0
	s_barrier
	s_add_i32 s88, 0, 0x18000
	v_add_u32_e32 v155, s88, v149
	s_add_i32 s89, 0, 0x1c000
	ds_read_b128 v[144:147], v155
	ds_read_b128 v[156:159], v155 offset:1024
	ds_read_b128 v[160:163], v155 offset:2048
	ds_read_b128 v[164:167], v155 offset:3072
	v_add_u32_e32 v155, s89, v149
	ds_read_b128 v[168:171], v155
	ds_read_b128 v[172:175], v155 offset:1024
	ds_read_b128 v[176:179], v155 offset:2048
	ds_read_b128 v[180:183], v155 offset:3072
	s_add_u32 s44, s44, 0x40000
	s_addc_u32 s45, s45, 0
	ds_read_b128 v[184:187], v153 offset:32768
	ds_read_b128 v[188:191], v153 offset:33792
	ds_read_b128 v[196:199], v153 offset:34816
	ds_read_b128 v[200:203], v153 offset:35840
	ds_read_b128 v[204:207], v153 offset:36864
	ds_read_b128 v[208:211], v153 offset:37888
	ds_read_b128 v[212:215], v153 offset:38912
	ds_read_b128 v[216:219], v153 offset:39936
	s_mov_b32 m0, s63
	s_nop 0
	global_load_lds_dwordx4 v[222:223], off
	s_mov_b32 m0, s70
	s_nop 0
	global_load_lds_dwordx4 v[224:225], off
	s_mov_b32 m0, s71
	s_nop 0
	global_load_lds_dwordx4 v128, s[44:45]
	s_mov_b32 m0, s72
	s_nop 0
	global_load_lds_dwordx4 v132, s[44:45]
	s_waitcnt vmcnt(8)
	s_waitcnt lgkmcnt(0)
	s_barrier
	s_setprio 1
	s_waitcnt lgkmcnt(0)
	v_mfma_f32_16x16x32_bf16 v[124:127], v[144:147], v[184:187], v[124:127]
	v_mfma_f32_16x16x32_bf16 v[120:123], v[160:163], v[184:187], v[120:123]
	v_mfma_f32_16x16x32_bf16 v[108:111], v[144:147], v[196:199], v[108:111]
	v_mfma_f32_16x16x32_bf16 v[104:107], v[160:163], v[196:199], v[104:107]
	v_mfma_f32_16x16x32_bf16 v[92:95], v[144:147], v[204:207], v[92:95]
	v_mfma_f32_16x16x32_bf16 v[88:91], v[160:163], v[204:207], v[88:91]
	v_mfma_f32_16x16x32_bf16 v[76:79], v[144:147], v[212:215], v[76:79]
	v_mfma_f32_16x16x32_bf16 v[72:75], v[160:163], v[212:215], v[72:75]
	v_mfma_f32_16x16x32_bf16 v[124:127], v[156:159], v[188:191], v[124:127]
	v_mfma_f32_16x16x32_bf16 v[120:123], v[164:167], v[188:191], v[120:123]
	v_mfma_f32_16x16x32_bf16 v[108:111], v[156:159], v[200:203], v[108:111]
	v_mfma_f32_16x16x32_bf16 v[104:107], v[164:167], v[200:203], v[104:107]
	v_mfma_f32_16x16x32_bf16 v[92:95], v[156:159], v[208:211], v[92:95]
	v_mfma_f32_16x16x32_bf16 v[88:91], v[164:167], v[208:211], v[88:91]
	v_mfma_f32_16x16x32_bf16 v[76:79], v[156:159], v[216:219], v[76:79]
	v_mfma_f32_16x16x32_bf16 v[72:75], v[164:167], v[216:219], v[72:75]
	s_setprio 0
	s_setprio 1
	v_mfma_f32_16x16x32_bf16 v[116:119], v[168:171], v[184:187], v[116:119]
	v_mfma_f32_16x16x32_bf16 v[112:115], v[176:179], v[184:187], v[112:115]
	v_mfma_f32_16x16x32_bf16 v[100:103], v[168:171], v[196:199], v[100:103]
	v_mfma_f32_16x16x32_bf16 v[96:99], v[176:179], v[196:199], v[96:99]
	v_mfma_f32_16x16x32_bf16 v[84:87], v[168:171], v[204:207], v[84:87]
	v_mfma_f32_16x16x32_bf16 v[80:83], v[176:179], v[204:207], v[80:83]
	v_mfma_f32_16x16x32_bf16 v[68:71], v[168:171], v[212:215], v[68:71]
	v_mfma_f32_16x16x32_bf16 v[64:67], v[176:179], v[212:215], v[64:67]
	v_mfma_f32_16x16x32_bf16 v[116:119], v[172:175], v[188:191], v[116:119]
	v_mfma_f32_16x16x32_bf16 v[112:115], v[180:183], v[188:191], v[112:115]
	v_mfma_f32_16x16x32_bf16 v[100:103], v[172:175], v[200:203], v[100:103]
	v_mfma_f32_16x16x32_bf16 v[96:99], v[180:183], v[200:203], v[96:99]
	v_mfma_f32_16x16x32_bf16 v[84:87], v[172:175], v[208:211], v[84:87]
	v_mfma_f32_16x16x32_bf16 v[80:83], v[180:183], v[208:211], v[80:83]
	v_mfma_f32_16x16x32_bf16 v[68:71], v[172:175], v[216:219], v[68:71]
	v_mfma_f32_16x16x32_bf16 v[64:67], v[180:183], v[216:219], v[64:67]
	s_setprio 0
	s_barrier
	s_add_i32 s44, s88, s62
	v_lshl_add_u64 v[192:193], v[192:193], 0, s[24:25]
	s_mov_b32 m0, s44
	ds_read_b128 v[184:187], v153 offset:49152
	ds_read_b128 v[188:191], v153 offset:50176
	ds_read_b128 v[196:199], v153 offset:51200
	ds_read_b128 v[200:203], v153 offset:52224
	ds_read_b128 v[204:207], v153 offset:53248
	ds_read_b128 v[208:211], v153 offset:54272
	ds_read_b128 v[212:215], v153 offset:55296
	ds_read_b128 v[216:219], v153 offset:56320
	global_load_lds_dwordx4 v[192:193], off
	s_add_i32 m0, s44, 0x2000
	s_add_u32 s42, s42, 0x40080
	v_lshl_add_u64 v[192:193], v[220:221], 0, s[24:25]
	s_addc_u32 s43, s43, 0
	s_add_i32 s44, s89, s62
	global_load_lds_dwordx4 v[192:193], off
	s_mov_b32 m0, s44
	s_nop 0
	global_load_lds_dwordx4 v130, s[42:43]
	s_add_i32 m0, s44, 0x2000
	s_nop 0
	global_load_lds_dwordx4 v134, s[42:43]
	s_waitcnt vmcnt(6)
	s_waitcnt lgkmcnt(0)
	s_barrier
	s_setprio 1
	s_waitcnt lgkmcnt(0)
	v_mfma_f32_16x16x32_bf16 v[60:63], v[144:147], v[184:187], v[60:63]
	v_mfma_f32_16x16x32_bf16 v[56:59], v[160:163], v[184:187], v[56:59]
	v_mfma_f32_16x16x32_bf16 v[44:47], v[144:147], v[196:199], v[44:47]
	v_mfma_f32_16x16x32_bf16 v[40:43], v[160:163], v[196:199], v[40:43]
	v_mfma_f32_16x16x32_bf16 v[28:31], v[144:147], v[204:207], v[28:31]
	v_mfma_f32_16x16x32_bf16 v[24:27], v[160:163], v[204:207], v[24:27]
	v_mfma_f32_16x16x32_bf16 v[12:15], v[144:147], v[212:215], v[12:15]
	v_mfma_f32_16x16x32_bf16 v[8:11], v[160:163], v[212:215], v[8:11]
	v_mfma_f32_16x16x32_bf16 v[60:63], v[156:159], v[188:191], v[60:63]
	v_mfma_f32_16x16x32_bf16 v[56:59], v[164:167], v[188:191], v[56:59]
	v_mfma_f32_16x16x32_bf16 v[44:47], v[156:159], v[200:203], v[44:47]
	v_mfma_f32_16x16x32_bf16 v[40:43], v[164:167], v[200:203], v[40:43]
	v_mfma_f32_16x16x32_bf16 v[28:31], v[156:159], v[208:211], v[28:31]
	v_mfma_f32_16x16x32_bf16 v[24:27], v[164:167], v[208:211], v[24:27]
	v_mfma_f32_16x16x32_bf16 v[12:15], v[156:159], v[216:219], v[12:15]
	v_mfma_f32_16x16x32_bf16 v[8:11], v[164:167], v[216:219], v[8:11]
	s_setprio 0
	s_setprio 1
	v_mfma_f32_16x16x32_bf16 v[52:55], v[168:171], v[184:187], v[52:55]
	v_mfma_f32_16x16x32_bf16 v[48:51], v[176:179], v[184:187], v[48:51]
	v_mfma_f32_16x16x32_bf16 v[36:39], v[168:171], v[196:199], v[36:39]
	v_mfma_f32_16x16x32_bf16 v[32:35], v[176:179], v[196:199], v[32:35]
	v_mfma_f32_16x16x32_bf16 v[20:23], v[168:171], v[204:207], v[20:23]
	v_mfma_f32_16x16x32_bf16 v[16:19], v[176:179], v[204:207], v[16:19]
	v_mfma_f32_16x16x32_bf16 v[4:7], v[168:171], v[212:215], v[4:7]
	v_mfma_f32_16x16x32_bf16 v[0:3], v[176:179], v[212:215], v[0:3]
	v_mfma_f32_16x16x32_bf16 v[52:55], v[172:175], v[188:191], v[52:55]
	v_mfma_f32_16x16x32_bf16 v[48:51], v[180:183], v[188:191], v[48:51]
	v_mfma_f32_16x16x32_bf16 v[36:39], v[172:175], v[200:203], v[36:39]
	v_mfma_f32_16x16x32_bf16 v[32:35], v[180:183], v[200:203], v[32:35]
	v_mfma_f32_16x16x32_bf16 v[20:23], v[172:175], v[208:211], v[20:23]
	v_mfma_f32_16x16x32_bf16 v[16:19], v[180:183], v[208:211], v[16:19]
	v_mfma_f32_16x16x32_bf16 v[4:7], v[172:175], v[216:219], v[4:7]
	v_mfma_f32_16x16x32_bf16 v[0:3], v[180:183], v[216:219], v[0:3]
	s_setprio 0
	s_barrier
	v_lshl_add_u64 v[222:223], v[222:223], 0, s[24:25]
	s_mov_b32 m0, s78
	s_nop 0
	global_load_lds_dwordx4 v[222:223], off
	v_lshl_add_u64 v[224:225], v[224:225], 0, s[24:25]
	s_mov_b32 m0, s79
	s_nop 0
	global_load_lds_dwordx4 v[224:225], off
	s_add_i32 s87, s87, 2
	s_add_u32 s40, s40, 0x100
	s_addc_u32 s41, s41, 0
	s_add_u32 s85, s85, 0x100
	s_addc_u32 s86, s86, 0
	s_cmp_gt_u32 s87, 13
	s_cbranch_scc0 .LBB0_1625
	s_and_b64 vcc, exec, s[26:27]
	s_cbranch_vccz .LBB0_1628
	s_barrier

.LBB0_1709:
	ds_read_b128 v[154:157], v149
	ds_read_b128 v[158:161], v149 offset:1024
	ds_read_b128 v[162:165], v149 offset:2048
	ds_read_b128 v[166:169], v149 offset:3072
	ds_read_b128 v[170:173], v150
	ds_read_b128 v[174:177], v150 offset:1024
	ds_read_b128 v[178:181], v150 offset:2048
	ds_read_b128 v[182:185], v150 offset:3072
	s_add_u32 s38, s36, 0xfffc0080
	s_addc_u32 s39, s37, -1
	s_cmp_eq_u32 s84, 12
	s_cselect_b32 s41, s27, s39
	s_cselect_b32 s40, s80, s38
	s_cselect_b32 s39, s25, s83
	s_cselect_b32 s38, s81, s82
	s_add_i32 m0, s35, 0xc000
	ds_read_b128 v[186:189], v151
	ds_read_b128 v[190:193], v151 offset:1024
	ds_read_b128 v[196:199], v151 offset:2048
	ds_read_b128 v[200:203], v151 offset:3072
	ds_read_b128 v[204:207], v151 offset:4096
	ds_read_b128 v[208:211], v151 offset:5120
	ds_read_b128 v[212:215], v151 offset:6144
	ds_read_b128 v[216:219], v151 offset:7168
	global_load_lds_dwordx4 v136, s[36:37]
	s_add_i32 m0, s35, 0xe000
	s_nop 0
	global_load_lds_dwordx4 v138, s[36:37]
	s_waitcnt vmcnt(8)
	s_waitcnt lgkmcnt(0)
	s_barrier
	s_setprio 1
	s_waitcnt lgkmcnt(0)
	v_mfma_f32_16x16x32_bf16 v[116:119], v[154:157], v[186:189], v[116:119]
	v_mfma_f32_16x16x32_bf16 v[112:115], v[162:165], v[186:189], v[112:115]
	v_mfma_f32_16x16x32_bf16 v[100:103], v[154:157], v[196:199], v[100:103]
	v_mfma_f32_16x16x32_bf16 v[96:99], v[162:165], v[196:199], v[96:99]
	v_mfma_f32_16x16x32_bf16 v[84:87], v[154:157], v[204:207], v[84:87]
	v_mfma_f32_16x16x32_bf16 v[80:83], v[162:165], v[204:207], v[80:83]
	v_mfma_f32_16x16x32_bf16 v[68:71], v[154:157], v[212:215], v[68:71]
	v_mfma_f32_16x16x32_bf16 v[64:67], v[162:165], v[212:215], v[64:67]
	v_mfma_f32_16x16x32_bf16 v[116:119], v[158:161], v[190:193], v[116:119]
	v_mfma_f32_16x16x32_bf16 v[112:115], v[166:169], v[190:193], v[112:115]
	v_mfma_f32_16x16x32_bf16 v[100:103], v[158:161], v[200:203], v[100:103]
	v_mfma_f32_16x16x32_bf16 v[96:99], v[166:169], v[200:203], v[96:99]
	v_mfma_f32_16x16x32_bf16 v[84:87], v[158:161], v[208:211], v[84:87]
	v_mfma_f32_16x16x32_bf16 v[80:83], v[166:169], v[208:211], v[80:83]
	v_mfma_f32_16x16x32_bf16 v[68:71], v[158:161], v[216:219], v[68:71]
	v_mfma_f32_16x16x32_bf16 v[64:67], v[166:169], v[216:219], v[64:67]
	s_setprio 0
	s_setprio 1
	v_mfma_f32_16x16x32_bf16 v[124:127], v[170:173], v[186:189], v[124:127]
	v_mfma_f32_16x16x32_bf16 v[120:123], v[178:181], v[186:189], v[120:123]
	v_mfma_f32_16x16x32_bf16 v[108:111], v[170:173], v[196:199], v[108:111]
	v_mfma_f32_16x16x32_bf16 v[104:107], v[178:181], v[196:199], v[104:107]
	v_mfma_f32_16x16x32_bf16 v[92:95], v[170:173], v[204:207], v[92:95]
	v_mfma_f32_16x16x32_bf16 v[88:91], v[178:181], v[204:207], v[88:91]
	v_mfma_f32_16x16x32_bf16 v[76:79], v[170:173], v[212:215], v[76:79]
	v_mfma_f32_16x16x32_bf16 v[72:75], v[178:181], v[212:215], v[72:75]
	v_mfma_f32_16x16x32_bf16 v[124:127], v[174:177], v[190:193], v[124:127]
	v_mfma_f32_16x16x32_bf16 v[120:123], v[182:185], v[190:193], v[120:123]
	v_mfma_f32_16x16x32_bf16 v[108:111], v[174:177], v[200:203], v[108:111]
	v_mfma_f32_16x16x32_bf16 v[104:107], v[182:185], v[200:203], v[104:107]
	v_mfma_f32_16x16x32_bf16 v[92:95], v[174:177], v[208:211], v[92:95]
	v_mfma_f32_16x16x32_bf16 v[88:91], v[182:185], v[208:211], v[88:91]
	v_mfma_f32_16x16x32_bf16 v[76:79], v[174:177], v[216:219], v[76:79]
	v_mfma_f32_16x16x32_bf16 v[72:75], v[182:185], v[216:219], v[72:75]
	s_setprio 0
	s_barrier
	s_add_i32 s85, s71, s56
	v_lshl_add_u64 v[144:145], s[38:39], 0, v[132:133]
	s_mov_b32 m0, s85
	ds_read_b128 v[186:189], v151 offset:16384
	ds_read_b128 v[190:193], v151 offset:17408
	ds_read_b128 v[196:199], v151 offset:18432
	ds_read_b128 v[200:203], v151 offset:19456
	ds_read_b128 v[204:207], v151 offset:20480
	ds_read_b128 v[208:211], v151 offset:21504
	ds_read_b128 v[212:215], v151 offset:22528
	ds_read_b128 v[216:219], v151 offset:23552
	global_load_lds_dwordx4 v[144:145], off
	s_add_i32 m0, s85, 0x2000
	s_add_u32 s86, s38, 0x40000
	v_lshl_add_u64 v[220:221], s[38:39], 0, v[128:129]
	s_addc_u32 s87, s39, 0
	s_add_i32 s85, s72, s56
	global_load_lds_dwordx4 v[220:221], off
	s_mov_b32 m0, s85
	v_lshl_add_u64 v[224:225], s[40:41], 0, v[130:131]
	global_load_lds_dwordx4 v132, s[86:87]
	s_add_i32 m0, s85, 0x2000
	s_nop 0
	global_load_lds_dwordx4 v128, s[86:87]
	v_lshl_add_u64 v[222:223], s[40:41], 0, v[134:135]
	s_waitcnt vmcnt(6)
	s_waitcnt lgkmcnt(0)
	s_barrier
	s_setprio 1
	s_waitcnt lgkmcnt(0)
	v_mfma_f32_16x16x32_bf16 v[52:55], v[154:157], v[186:189], v[52:55]
	v_mfma_f32_16x16x32_bf16 v[48:51], v[162:165], v[186:189], v[48:51]
	v_mfma_f32_16x16x32_bf16 v[36:39], v[154:157], v[196:199], v[36:39]
	v_mfma_f32_16x16x32_bf16 v[32:35], v[162:165], v[196:199], v[32:35]
	v_mfma_f32_16x16x32_bf16 v[20:23], v[154:157], v[204:207], v[20:23]
	v_mfma_f32_16x16x32_bf16 v[16:19], v[162:165], v[204:207], v[16:19]
	v_mfma_f32_16x16x32_bf16 v[4:7], v[154:157], v[212:215], v[4:7]
	v_mfma_f32_16x16x32_bf16 v[0:3], v[162:165], v[212:215], v[0:3]
	v_mfma_f32_16x16x32_bf16 v[52:55], v[158:161], v[190:193], v[52:55]
	v_mfma_f32_16x16x32_bf16 v[48:51], v[166:169], v[190:193], v[48:51]
	v_mfma_f32_16x16x32_bf16 v[36:39], v[158:161], v[200:203], v[36:39]
	v_mfma_f32_16x16x32_bf16 v[32:35], v[166:169], v[200:203], v[32:35]
	v_mfma_f32_16x16x32_bf16 v[20:23], v[158:161], v[208:211], v[20:23]
	v_mfma_f32_16x16x32_bf16 v[16:19], v[166:169], v[208:211], v[16:19]
	v_mfma_f32_16x16x32_bf16 v[4:7], v[158:161], v[216:219], v[4:7]
	v_mfma_f32_16x16x32_bf16 v[0:3], v[166:169], v[216:219], v[0:3]
	s_setprio 0
	s_setprio 1
	v_mfma_f32_16x16x32_bf16 v[60:63], v[170:173], v[186:189], v[60:63]
	v_mfma_f32_16x16x32_bf16 v[56:59], v[178:181], v[186:189], v[56:59]
	v_mfma_f32_16x16x32_bf16 v[44:47], v[170:173], v[196:199], v[44:47]
	v_mfma_f32_16x16x32_bf16 v[40:43], v[178:181], v[196:199], v[40:43]
	v_mfma_f32_16x16x32_bf16 v[28:31], v[170:173], v[204:207], v[28:31]
	v_mfma_f32_16x16x32_bf16 v[24:27], v[178:181], v[204:207], v[24:27]
	v_mfma_f32_16x16x32_bf16 v[12:15], v[170:173], v[212:215], v[12:15]
	v_mfma_f32_16x16x32_bf16 v[8:11], v[178:181], v[212:215], v[8:11]
	v_mfma_f32_16x16x32_bf16 v[60:63], v[174:177], v[190:193], v[60:63]
	v_mfma_f32_16x16x32_bf16 v[56:59], v[182:185], v[190:193], v[56:59]
	v_mfma_f32_16x16x32_bf16 v[44:47], v[174:177], v[200:203], v[44:47]
	v_mfma_f32_16x16x32_bf16 v[40:43], v[182:185], v[200:203], v[40:43]
	v_mfma_f32_16x16x32_bf16 v[28:31], v[174:177], v[208:211], v[28:31]
	v_mfma_f32_16x16x32_bf16 v[24:27], v[182:185], v[208:211], v[24:27]
	v_mfma_f32_16x16x32_bf16 v[12:15], v[174:177], v[216:219], v[12:15]
	v_mfma_f32_16x16x32_bf16 v[8:11], v[182:185], v[216:219], v[8:11]
	s_setprio 0
	s_barrier
	s_add_i32 s85, 0, 0x18000
	v_add_u32_e32 v153, s85, v147
	s_add_i32 s86, 0, 0x1c000
	ds_read_b128 v[154:157], v153
	ds_read_b128 v[158:161], v153 offset:1024
	ds_read_b128 v[162:165], v153 offset:2048
	ds_read_b128 v[166:169], v153 offset:3072
	v_add_u32_e32 v153, s86, v147
	ds_read_b128 v[170:173], v153
	ds_read_b128 v[174:177], v153 offset:1024
	ds_read_b128 v[178:181], v153 offset:2048
	ds_read_b128 v[182:185], v153 offset:3072
	s_add_u32 s40, s40, 0x40000
	s_addc_u32 s41, s41, 0
	ds_read_b128 v[186:189], v151 offset:32768
	ds_read_b128 v[190:193], v151 offset:33792
	ds_read_b128 v[196:199], v151 offset:34816
	ds_read_b128 v[200:203], v151 offset:35840
	ds_read_b128 v[204:207], v151 offset:36864
	ds_read_b128 v[208:211], v151 offset:37888
	ds_read_b128 v[212:215], v151 offset:38912
	ds_read_b128 v[216:219], v151 offset:39936
	s_mov_b32 m0, s35
	s_nop 0
	global_load_lds_dwordx4 v[222:223], off
	s_mov_b32 m0, s58
	s_nop 0
	global_load_lds_dwordx4 v[224:225], off
	s_mov_b32 m0, s59
	s_nop 0
	global_load_lds_dwordx4 v134, s[40:41]
	s_mov_b32 m0, s60
	s_nop 0
	global_load_lds_dwordx4 v130, s[40:41]
	s_waitcnt vmcnt(8)
	s_waitcnt lgkmcnt(0)
	s_barrier
	s_setprio 1
	s_waitcnt lgkmcnt(0)
	v_mfma_f32_16x16x32_bf16 v[116:119], v[154:157], v[186:189], v[116:119]
	v_mfma_f32_16x16x32_bf16 v[112:115], v[162:165], v[186:189], v[112:115]
	v_mfma_f32_16x16x32_bf16 v[100:103], v[154:157], v[196:199], v[100:103]
	v_mfma_f32_16x16x32_bf16 v[96:99], v[162:165], v[196:199], v[96:99]
	v_mfma_f32_16x16x32_bf16 v[84:87], v[154:157], v[204:207], v[84:87]
	v_mfma_f32_16x16x32_bf16 v[80:83], v[162:165], v[204:207], v[80:83]
	v_mfma_f32_16x16x32_bf16 v[68:71], v[154:157], v[212:215], v[68:71]
	v_mfma_f32_16x16x32_bf16 v[64:67], v[162:165], v[212:215], v[64:67]
	v_mfma_f32_16x16x32_bf16 v[116:119], v[158:161], v[190:193], v[116:119]
	v_mfma_f32_16x16x32_bf16 v[112:115], v[166:169], v[190:193], v[112:115]
	v_mfma_f32_16x16x32_bf16 v[100:103], v[158:161], v[200:203], v[100:103]
	v_mfma_f32_16x16x32_bf16 v[96:99], v[166:169], v[200:203], v[96:99]
	v_mfma_f32_16x16x32_bf16 v[84:87], v[158:161], v[208:211], v[84:87]
	v_mfma_f32_16x16x32_bf16 v[80:83], v[166:169], v[208:211], v[80:83]
	v_mfma_f32_16x16x32_bf16 v[68:71], v[158:161], v[216:219], v[68:71]
	v_mfma_f32_16x16x32_bf16 v[64:67], v[166:169], v[216:219], v[64:67]
	s_setprio 0
	s_setprio 1
	v_mfma_f32_16x16x32_bf16 v[124:127], v[170:173], v[186:189], v[124:127]
	v_mfma_f32_16x16x32_bf16 v[120:123], v[178:181], v[186:189], v[120:123]
	v_mfma_f32_16x16x32_bf16 v[108:111], v[170:173], v[196:199], v[108:111]
	v_mfma_f32_16x16x32_bf16 v[104:107], v[178:181], v[196:199], v[104:107]
	v_mfma_f32_16x16x32_bf16 v[92:95], v[170:173], v[204:207], v[92:95]
	v_mfma_f32_16x16x32_bf16 v[88:91], v[178:181], v[204:207], v[88:91]
	v_mfma_f32_16x16x32_bf16 v[76:79], v[170:173], v[212:215], v[76:79]
	v_mfma_f32_16x16x32_bf16 v[72:75], v[178:181], v[212:215], v[72:75]
	v_mfma_f32_16x16x32_bf16 v[124:127], v[174:177], v[190:193], v[124:127]
	v_mfma_f32_16x16x32_bf16 v[120:123], v[182:185], v[190:193], v[120:123]
	v_mfma_f32_16x16x32_bf16 v[108:111], v[174:177], v[200:203], v[108:111]
	v_mfma_f32_16x16x32_bf16 v[104:107], v[182:185], v[200:203], v[104:107]
	v_mfma_f32_16x16x32_bf16 v[92:95], v[174:177], v[208:211], v[92:95]
	v_mfma_f32_16x16x32_bf16 v[88:91], v[182:185], v[208:211], v[88:91]
	v_mfma_f32_16x16x32_bf16 v[76:79], v[174:177], v[216:219], v[76:79]
	v_mfma_f32_16x16x32_bf16 v[72:75], v[182:185], v[216:219], v[72:75]
	s_setprio 0
	s_barrier
	s_add_i32 s40, s85, s56
	v_lshl_add_u64 v[144:145], v[144:145], 0, s[20:21]
	s_mov_b32 m0, s40
	ds_read_b128 v[186:189], v151 offset:49152
	ds_read_b128 v[190:193], v151 offset:50176
	ds_read_b128 v[196:199], v151 offset:51200
	ds_read_b128 v[200:203], v151 offset:52224
	ds_read_b128 v[204:207], v151 offset:53248
	ds_read_b128 v[208:211], v151 offset:54272
	ds_read_b128 v[212:215], v151 offset:55296
	ds_read_b128 v[216:219], v151 offset:56320
	global_load_lds_dwordx4 v[144:145], off
	s_add_i32 m0, s40, 0x2000
	s_add_u32 s38, s38, 0x40080
	v_lshl_add_u64 v[144:145], v[220:221], 0, s[20:21]
	s_addc_u32 s39, s39, 0
	s_add_i32 s40, s86, s56
	global_load_lds_dwordx4 v[144:145], off
	s_mov_b32 m0, s40
	s_nop 0
	global_load_lds_dwordx4 v132, s[38:39]
	s_add_i32 m0, s40, 0x2000
	s_nop 0
	global_load_lds_dwordx4 v128, s[38:39]
	s_waitcnt vmcnt(6)
	s_waitcnt lgkmcnt(0)
	s_barrier
	s_setprio 1
	s_waitcnt lgkmcnt(0)
	v_mfma_f32_16x16x32_bf16 v[52:55], v[154:157], v[186:189], v[52:55]
	v_mfma_f32_16x16x32_bf16 v[48:51], v[162:165], v[186:189], v[48:51]
	v_mfma_f32_16x16x32_bf16 v[36:39], v[154:157], v[196:199], v[36:39]
	v_mfma_f32_16x16x32_bf16 v[32:35], v[162:165], v[196:199], v[32:35]
	v_mfma_f32_16x16x32_bf16 v[20:23], v[154:157], v[204:207], v[20:23]
	v_mfma_f32_16x16x32_bf16 v[16:19], v[162:165], v[204:207], v[16:19]
	v_mfma_f32_16x16x32_bf16 v[4:7], v[154:157], v[212:215], v[4:7]
	v_mfma_f32_16x16x32_bf16 v[0:3], v[162:165], v[212:215], v[0:3]
	v_mfma_f32_16x16x32_bf16 v[52:55], v[158:161], v[190:193], v[52:55]
	v_mfma_f32_16x16x32_bf16 v[48:51], v[166:169], v[190:193], v[48:51]
	v_mfma_f32_16x16x32_bf16 v[36:39], v[158:161], v[200:203], v[36:39]
	v_mfma_f32_16x16x32_bf16 v[32:35], v[166:169], v[200:203], v[32:35]
	v_mfma_f32_16x16x32_bf16 v[20:23], v[158:161], v[208:211], v[20:23]
	v_mfma_f32_16x16x32_bf16 v[16:19], v[166:169], v[208:211], v[16:19]
	v_mfma_f32_16x16x32_bf16 v[4:7], v[158:161], v[216:219], v[4:7]
	v_mfma_f32_16x16x32_bf16 v[0:3], v[166:169], v[216:219], v[0:3]
	s_setprio 0
	s_setprio 1
	v_mfma_f32_16x16x32_bf16 v[60:63], v[170:173], v[186:189], v[60:63]
	v_mfma_f32_16x16x32_bf16 v[56:59], v[178:181], v[186:189], v[56:59]
	v_mfma_f32_16x16x32_bf16 v[44:47], v[170:173], v[196:199], v[44:47]
	v_mfma_f32_16x16x32_bf16 v[40:43], v[178:181], v[196:199], v[40:43]
	v_mfma_f32_16x16x32_bf16 v[28:31], v[170:173], v[204:207], v[28:31]
	v_mfma_f32_16x16x32_bf16 v[24:27], v[178:181], v[204:207], v[24:27]
	v_mfma_f32_16x16x32_bf16 v[12:15], v[170:173], v[212:215], v[12:15]
	v_mfma_f32_16x16x32_bf16 v[8:11], v[178:181], v[212:215], v[8:11]
	v_mfma_f32_16x16x32_bf16 v[60:63], v[174:177], v[190:193], v[60:63]
	v_mfma_f32_16x16x32_bf16 v[56:59], v[182:185], v[190:193], v[56:59]
	v_mfma_f32_16x16x32_bf16 v[44:47], v[174:177], v[200:203], v[44:47]
	v_mfma_f32_16x16x32_bf16 v[40:43], v[182:185], v[200:203], v[40:43]
	v_mfma_f32_16x16x32_bf16 v[28:31], v[174:177], v[208:211], v[28:31]
	v_mfma_f32_16x16x32_bf16 v[24:27], v[182:185], v[208:211], v[24:27]
	v_mfma_f32_16x16x32_bf16 v[12:15], v[174:177], v[216:219], v[12:15]
	v_mfma_f32_16x16x32_bf16 v[8:11], v[182:185], v[216:219], v[8:11]
	s_setprio 0
	s_barrier
	v_lshl_add_u64 v[222:223], v[222:223], 0, s[20:21]
	s_mov_b32 m0, s62
	s_nop 0
	global_load_lds_dwordx4 v[222:223], off
	v_lshl_add_u64 v[224:225], v[224:225], 0, s[20:21]
	s_mov_b32 m0, s63
	s_nop 0
	global_load_lds_dwordx4 v[224:225], off
	s_add_i32 s84, s84, 2
	s_add_u32 s36, s36, 0x100
	s_addc_u32 s37, s37, 0
	s_add_u32 s82, s82, 0x100
	s_addc_u32 s83, s83, 0
	s_cmp_gt_u32 s84, 13
	s_cbranch_scc0 .LBB0_1709
	s_and_b64 vcc, exec, s[22:23]
	s_cbranch_vccz .LBB0_1712
	s_barrier

.LBB0_1791:
	ds_read_b128 v[144:147], v151
	ds_read_b128 v[156:159], v151 offset:1024
	ds_read_b128 v[160:163], v151 offset:2048
	ds_read_b128 v[164:167], v151 offset:3072
	ds_read_b128 v[168:171], v152
	ds_read_b128 v[172:175], v152 offset:1024
	ds_read_b128 v[176:179], v152 offset:2048
	ds_read_b128 v[180:183], v152 offset:3072
	s_add_u32 s38, s36, 0x100
	s_addc_u32 s39, s37, 0
	s_cmp_eq_u32 s85, 40
	s_cselect_b32 s43, s1, s39
	s_cselect_b32 s42, s0, s38
	s_cselect_b32 s41, s35, s84
	s_cselect_b32 s40, s34, s83
	v_lshl_add_u64 v[192:193], s[36:37], 0, v[136:137]
	s_add_i32 m0, s59, 0xc000
	ds_read_b128 v[184:187], v153
	ds_read_b128 v[188:191], v153 offset:1024
	ds_read_b128 v[196:199], v153 offset:2048
	ds_read_b128 v[200:203], v153 offset:3072
	ds_read_b128 v[204:207], v153 offset:4096
	ds_read_b128 v[208:211], v153 offset:5120
	ds_read_b128 v[212:215], v153 offset:6144
	ds_read_b128 v[216:219], v153 offset:7168
	global_load_lds_dwordx4 v[192:193], off
	v_lshl_add_u64 v[192:193], s[36:37], 0, v[138:139]
	s_add_i32 m0, s59, 0xe000
	s_nop 0
	global_load_lds_dwordx4 v[192:193], off
	s_waitcnt vmcnt(8)
	s_waitcnt lgkmcnt(0)
	s_barrier
	s_setprio 1
	s_waitcnt lgkmcnt(0)
	v_mfma_f32_16x16x32_bf16 v[124:127], v[144:147], v[184:187], v[124:127]
	v_mfma_f32_16x16x32_bf16 v[120:123], v[160:163], v[184:187], v[120:123]
	v_mfma_f32_16x16x32_bf16 v[108:111], v[144:147], v[196:199], v[108:111]
	v_mfma_f32_16x16x32_bf16 v[104:107], v[160:163], v[196:199], v[104:107]
	v_mfma_f32_16x16x32_bf16 v[92:95], v[144:147], v[204:207], v[92:95]
	v_mfma_f32_16x16x32_bf16 v[88:91], v[160:163], v[204:207], v[88:91]
	v_mfma_f32_16x16x32_bf16 v[76:79], v[144:147], v[212:215], v[76:79]
	v_mfma_f32_16x16x32_bf16 v[72:75], v[160:163], v[212:215], v[72:75]
	v_mfma_f32_16x16x32_bf16 v[124:127], v[156:159], v[188:191], v[124:127]
	v_mfma_f32_16x16x32_bf16 v[120:123], v[164:167], v[188:191], v[120:123]
	v_mfma_f32_16x16x32_bf16 v[108:111], v[156:159], v[200:203], v[108:111]
	v_mfma_f32_16x16x32_bf16 v[104:107], v[164:167], v[200:203], v[104:107]
	v_mfma_f32_16x16x32_bf16 v[92:95], v[156:159], v[208:211], v[92:95]
	v_mfma_f32_16x16x32_bf16 v[88:91], v[164:167], v[208:211], v[88:91]
	v_mfma_f32_16x16x32_bf16 v[76:79], v[156:159], v[216:219], v[76:79]
	v_mfma_f32_16x16x32_bf16 v[72:75], v[164:167], v[216:219], v[72:75]
	s_setprio 0
	s_setprio 1
	v_mfma_f32_16x16x32_bf16 v[116:119], v[168:171], v[184:187], v[116:119]
	v_mfma_f32_16x16x32_bf16 v[112:115], v[176:179], v[184:187], v[112:115]
	v_mfma_f32_16x16x32_bf16 v[100:103], v[168:171], v[196:199], v[100:103]
	v_mfma_f32_16x16x32_bf16 v[96:99], v[176:179], v[196:199], v[96:99]
	v_mfma_f32_16x16x32_bf16 v[84:87], v[168:171], v[204:207], v[84:87]
	v_mfma_f32_16x16x32_bf16 v[80:83], v[176:179], v[204:207], v[80:83]
	v_mfma_f32_16x16x32_bf16 v[68:71], v[168:171], v[212:215], v[68:71]
	v_mfma_f32_16x16x32_bf16 v[64:67], v[176:179], v[212:215], v[64:67]
	v_mfma_f32_16x16x32_bf16 v[116:119], v[172:175], v[188:191], v[116:119]
	v_mfma_f32_16x16x32_bf16 v[112:115], v[180:183], v[188:191], v[112:115]
	v_mfma_f32_16x16x32_bf16 v[100:103], v[172:175], v[200:203], v[100:103]
	v_mfma_f32_16x16x32_bf16 v[96:99], v[180:183], v[200:203], v[96:99]
	v_mfma_f32_16x16x32_bf16 v[84:87], v[172:175], v[208:211], v[84:87]
	v_mfma_f32_16x16x32_bf16 v[80:83], v[180:183], v[208:211], v[80:83]
	v_mfma_f32_16x16x32_bf16 v[68:71], v[172:175], v[216:219], v[68:71]
	v_mfma_f32_16x16x32_bf16 v[64:67], v[180:183], v[216:219], v[64:67]
	s_setprio 0
	s_barrier
	s_add_i32 s36, s73, s58
	v_lshl_add_u64 v[192:193], s[40:41], 0, v[130:131]
	s_mov_b32 m0, s36
	ds_read_b128 v[184:187], v153 offset:16384
	ds_read_b128 v[188:191], v153 offset:17408
	ds_read_b128 v[196:199], v153 offset:18432
	ds_read_b128 v[200:203], v153 offset:19456
	ds_read_b128 v[204:207], v153 offset:20480
	ds_read_b128 v[208:211], v153 offset:21504
	ds_read_b128 v[212:215], v153 offset:22528
	ds_read_b128 v[216:219], v153 offset:23552
	global_load_lds_dwordx4 v[192:193], off
	s_add_i32 m0, s36, 0x2000
	s_add_u32 s36, s40, 0xb0000
	v_lshl_add_u64 v[220:221], s[40:41], 0, v[134:135]
	s_addc_u32 s37, s41, 0
	s_add_i32 s86, s78, s58
	global_load_lds_dwordx4 v[220:221], off
	s_mov_b32 m0, s86
	v_lshl_add_u64 v[224:225], s[42:43], 0, v[132:133]
	global_load_lds_dwordx4 v130, s[36:37]
	s_add_i32 m0, s86, 0x2000
	s_nop 0
	global_load_lds_dwordx4 v134, s[36:37]
	v_lshl_add_u64 v[222:223], s[42:43], 0, v[128:129]
	s_waitcnt vmcnt(6)
	s_waitcnt lgkmcnt(0)
	s_barrier
	s_setprio 1
	s_waitcnt lgkmcnt(0)
	v_mfma_f32_16x16x32_bf16 v[60:63], v[144:147], v[184:187], v[60:63]
	v_mfma_f32_16x16x32_bf16 v[56:59], v[160:163], v[184:187], v[56:59]
	v_mfma_f32_16x16x32_bf16 v[44:47], v[144:147], v[196:199], v[44:47]
	v_mfma_f32_16x16x32_bf16 v[40:43], v[160:163], v[196:199], v[40:43]
	v_mfma_f32_16x16x32_bf16 v[28:31], v[144:147], v[204:207], v[28:31]
	v_mfma_f32_16x16x32_bf16 v[24:27], v[160:163], v[204:207], v[24:27]
	v_mfma_f32_16x16x32_bf16 v[12:15], v[144:147], v[212:215], v[12:15]
	v_mfma_f32_16x16x32_bf16 v[8:11], v[160:163], v[212:215], v[8:11]
	v_mfma_f32_16x16x32_bf16 v[60:63], v[156:159], v[188:191], v[60:63]
	v_mfma_f32_16x16x32_bf16 v[56:59], v[164:167], v[188:191], v[56:59]
	v_mfma_f32_16x16x32_bf16 v[44:47], v[156:159], v[200:203], v[44:47]
	v_mfma_f32_16x16x32_bf16 v[40:43], v[164:167], v[200:203], v[40:43]
	v_mfma_f32_16x16x32_bf16 v[28:31], v[156:159], v[208:211], v[28:31]
	v_mfma_f32_16x16x32_bf16 v[24:27], v[164:167], v[208:211], v[24:27]
	v_mfma_f32_16x16x32_bf16 v[12:15], v[156:159], v[216:219], v[12:15]
	v_mfma_f32_16x16x32_bf16 v[8:11], v[164:167], v[216:219], v[8:11]
	s_setprio 0
	s_setprio 1
	v_mfma_f32_16x16x32_bf16 v[52:55], v[168:171], v[184:187], v[52:55]
	v_mfma_f32_16x16x32_bf16 v[48:51], v[176:179], v[184:187], v[48:51]
	v_mfma_f32_16x16x32_bf16 v[36:39], v[168:171], v[196:199], v[36:39]
	v_mfma_f32_16x16x32_bf16 v[32:35], v[176:179], v[196:199], v[32:35]
	v_mfma_f32_16x16x32_bf16 v[20:23], v[168:171], v[204:207], v[20:23]
	v_mfma_f32_16x16x32_bf16 v[16:19], v[176:179], v[204:207], v[16:19]
	v_mfma_f32_16x16x32_bf16 v[4:7], v[168:171], v[212:215], v[4:7]
	v_mfma_f32_16x16x32_bf16 v[0:3], v[176:179], v[212:215], v[0:3]
	v_mfma_f32_16x16x32_bf16 v[52:55], v[172:175], v[188:191], v[52:55]
	v_mfma_f32_16x16x32_bf16 v[48:51], v[180:183], v[188:191], v[48:51]
	v_mfma_f32_16x16x32_bf16 v[36:39], v[172:175], v[200:203], v[36:39]
	v_mfma_f32_16x16x32_bf16 v[32:35], v[180:183], v[200:203], v[32:35]
	v_mfma_f32_16x16x32_bf16 v[20:23], v[172:175], v[208:211], v[20:23]
	v_mfma_f32_16x16x32_bf16 v[16:19], v[180:183], v[208:211], v[16:19]
	v_mfma_f32_16x16x32_bf16 v[4:7], v[172:175], v[216:219], v[4:7]
	v_mfma_f32_16x16x32_bf16 v[0:3], v[180:183], v[216:219], v[0:3]
	s_setprio 0
	s_barrier
	s_add_i32 s86, 0, 0x18000
	v_add_u32_e32 v155, s86, v149
	s_add_i32 s87, 0, 0x1c000
	ds_read_b128 v[144:147], v155
	ds_read_b128 v[156:159], v155 offset:1024
	ds_read_b128 v[160:163], v155 offset:2048
	ds_read_b128 v[164:167], v155 offset:3072
	v_add_u32_e32 v155, s87, v149
	ds_read_b128 v[168:171], v155
	ds_read_b128 v[172:175], v155 offset:1024
	ds_read_b128 v[176:179], v155 offset:2048
	ds_read_b128 v[180:183], v155 offset:3072
	s_add_u32 s36, s42, 0xb0000
	s_addc_u32 s37, s43, 0
	ds_read_b128 v[184:187], v153 offset:32768
	ds_read_b128 v[188:191], v153 offset:33792
	ds_read_b128 v[196:199], v153 offset:34816
	ds_read_b128 v[200:203], v153 offset:35840
	ds_read_b128 v[204:207], v153 offset:36864
	ds_read_b128 v[208:211], v153 offset:37888
	ds_read_b128 v[212:215], v153 offset:38912
	ds_read_b128 v[216:219], v153 offset:39936
	s_mov_b32 m0, s59
	s_nop 0
	global_load_lds_dwordx4 v[222:223], off
	s_mov_b32 m0, s60
	s_nop 0
	global_load_lds_dwordx4 v[224:225], off
	s_mov_b32 m0, s61
	s_nop 0
	global_load_lds_dwordx4 v128, s[36:37]
	s_mov_b32 m0, s62
	s_nop 0
	global_load_lds_dwordx4 v132, s[36:37]
	s_waitcnt vmcnt(8)
	s_waitcnt lgkmcnt(0)
	s_barrier
	s_setprio 1
	s_waitcnt lgkmcnt(0)
	v_mfma_f32_16x16x32_bf16 v[124:127], v[144:147], v[184:187], v[124:127]
	v_mfma_f32_16x16x32_bf16 v[120:123], v[160:163], v[184:187], v[120:123]
	v_mfma_f32_16x16x32_bf16 v[108:111], v[144:147], v[196:199], v[108:111]
	v_mfma_f32_16x16x32_bf16 v[104:107], v[160:163], v[196:199], v[104:107]
	v_mfma_f32_16x16x32_bf16 v[92:95], v[144:147], v[204:207], v[92:95]
	v_mfma_f32_16x16x32_bf16 v[88:91], v[160:163], v[204:207], v[88:91]
	v_mfma_f32_16x16x32_bf16 v[76:79], v[144:147], v[212:215], v[76:79]
	v_mfma_f32_16x16x32_bf16 v[72:75], v[160:163], v[212:215], v[72:75]
	v_mfma_f32_16x16x32_bf16 v[124:127], v[156:159], v[188:191], v[124:127]
	v_mfma_f32_16x16x32_bf16 v[120:123], v[164:167], v[188:191], v[120:123]
	v_mfma_f32_16x16x32_bf16 v[108:111], v[156:159], v[200:203], v[108:111]
	v_mfma_f32_16x16x32_bf16 v[104:107], v[164:167], v[200:203], v[104:107]
	v_mfma_f32_16x16x32_bf16 v[92:95], v[156:159], v[208:211], v[92:95]
	v_mfma_f32_16x16x32_bf16 v[88:91], v[164:167], v[208:211], v[88:91]
	v_mfma_f32_16x16x32_bf16 v[76:79], v[156:159], v[216:219], v[76:79]
	v_mfma_f32_16x16x32_bf16 v[72:75], v[164:167], v[216:219], v[72:75]
	s_setprio 0
	s_setprio 1
	v_mfma_f32_16x16x32_bf16 v[116:119], v[168:171], v[184:187], v[116:119]
	v_mfma_f32_16x16x32_bf16 v[112:115], v[176:179], v[184:187], v[112:115]
	v_mfma_f32_16x16x32_bf16 v[100:103], v[168:171], v[196:199], v[100:103]
	v_mfma_f32_16x16x32_bf16 v[96:99], v[176:179], v[196:199], v[96:99]
	v_mfma_f32_16x16x32_bf16 v[84:87], v[168:171], v[204:207], v[84:87]
	v_mfma_f32_16x16x32_bf16 v[80:83], v[176:179], v[204:207], v[80:83]
	v_mfma_f32_16x16x32_bf16 v[68:71], v[168:171], v[212:215], v[68:71]
	v_mfma_f32_16x16x32_bf16 v[64:67], v[176:179], v[212:215], v[64:67]
	v_mfma_f32_16x16x32_bf16 v[116:119], v[172:175], v[188:191], v[116:119]
	v_mfma_f32_16x16x32_bf16 v[112:115], v[180:183], v[188:191], v[112:115]
	v_mfma_f32_16x16x32_bf16 v[100:103], v[172:175], v[200:203], v[100:103]
	v_mfma_f32_16x16x32_bf16 v[96:99], v[180:183], v[200:203], v[96:99]
	v_mfma_f32_16x16x32_bf16 v[84:87], v[172:175], v[208:211], v[84:87]
	v_mfma_f32_16x16x32_bf16 v[80:83], v[180:183], v[208:211], v[80:83]
	v_mfma_f32_16x16x32_bf16 v[68:71], v[172:175], v[216:219], v[68:71]
	v_mfma_f32_16x16x32_bf16 v[64:67], v[180:183], v[216:219], v[64:67]
	s_setprio 0
	s_barrier
	s_add_i32 s36, s86, s58
	v_lshl_add_u64 v[192:193], v[192:193], 0, s[28:29]
	s_mov_b32 m0, s36
	ds_read_b128 v[184:187], v153 offset:49152
	ds_read_b128 v[188:191], v153 offset:50176
	ds_read_b128 v[196:199], v153 offset:51200
	ds_read_b128 v[200:203], v153 offset:52224
	ds_read_b128 v[204:207], v153 offset:53248
	ds_read_b128 v[208:211], v153 offset:54272
	ds_read_b128 v[212:215], v153 offset:55296
	ds_read_b128 v[216:219], v153 offset:56320
	global_load_lds_dwordx4 v[192:193], off
	s_add_i32 m0, s36, 0x2000
	s_add_u32 s36, s40, 0xb0080
	v_lshl_add_u64 v[192:193], v[220:221], 0, s[28:29]
	s_addc_u32 s37, s41, 0
	s_add_i32 s40, s87, s58
	global_load_lds_dwordx4 v[192:193], off
	s_mov_b32 m0, s40
	s_nop 0
	global_load_lds_dwordx4 v130, s[36:37]
	s_add_i32 m0, s40, 0x2000
	s_nop 0
	global_load_lds_dwordx4 v134, s[36:37]
	s_waitcnt vmcnt(6)
	s_waitcnt lgkmcnt(0)
	s_barrier
	s_setprio 1
	s_waitcnt lgkmcnt(0)
	v_mfma_f32_16x16x32_bf16 v[60:63], v[144:147], v[184:187], v[60:63]
	v_mfma_f32_16x16x32_bf16 v[56:59], v[160:163], v[184:187], v[56:59]
	v_mfma_f32_16x16x32_bf16 v[44:47], v[144:147], v[196:199], v[44:47]
	v_mfma_f32_16x16x32_bf16 v[40:43], v[160:163], v[196:199], v[40:43]
	v_mfma_f32_16x16x32_bf16 v[28:31], v[144:147], v[204:207], v[28:31]
	v_mfma_f32_16x16x32_bf16 v[24:27], v[160:163], v[204:207], v[24:27]
	v_mfma_f32_16x16x32_bf16 v[12:15], v[144:147], v[212:215], v[12:15]
	v_mfma_f32_16x16x32_bf16 v[8:11], v[160:163], v[212:215], v[8:11]
	v_mfma_f32_16x16x32_bf16 v[60:63], v[156:159], v[188:191], v[60:63]
	v_mfma_f32_16x16x32_bf16 v[56:59], v[164:167], v[188:191], v[56:59]
	v_mfma_f32_16x16x32_bf16 v[44:47], v[156:159], v[200:203], v[44:47]
	v_mfma_f32_16x16x32_bf16 v[40:43], v[164:167], v[200:203], v[40:43]
	v_mfma_f32_16x16x32_bf16 v[28:31], v[156:159], v[208:211], v[28:31]
	v_mfma_f32_16x16x32_bf16 v[24:27], v[164:167], v[208:211], v[24:27]
	v_mfma_f32_16x16x32_bf16 v[12:15], v[156:159], v[216:219], v[12:15]
	v_mfma_f32_16x16x32_bf16 v[8:11], v[164:167], v[216:219], v[8:11]
	s_setprio 0
	s_setprio 1
	v_mfma_f32_16x16x32_bf16 v[52:55], v[168:171], v[184:187], v[52:55]
	v_mfma_f32_16x16x32_bf16 v[48:51], v[176:179], v[184:187], v[48:51]
	v_mfma_f32_16x16x32_bf16 v[36:39], v[168:171], v[196:199], v[36:39]
	v_mfma_f32_16x16x32_bf16 v[32:35], v[176:179], v[196:199], v[32:35]
	v_mfma_f32_16x16x32_bf16 v[20:23], v[168:171], v[204:207], v[20:23]
	v_mfma_f32_16x16x32_bf16 v[16:19], v[176:179], v[204:207], v[16:19]
	v_mfma_f32_16x16x32_bf16 v[4:7], v[168:171], v[212:215], v[4:7]
	v_mfma_f32_16x16x32_bf16 v[0:3], v[176:179], v[212:215], v[0:3]
	v_mfma_f32_16x16x32_bf16 v[52:55], v[172:175], v[188:191], v[52:55]
	v_mfma_f32_16x16x32_bf16 v[48:51], v[180:183], v[188:191], v[48:51]
	v_mfma_f32_16x16x32_bf16 v[36:39], v[172:175], v[200:203], v[36:39]
	v_mfma_f32_16x16x32_bf16 v[32:35], v[180:183], v[200:203], v[32:35]
	v_mfma_f32_16x16x32_bf16 v[20:23], v[172:175], v[208:211], v[20:23]
	v_mfma_f32_16x16x32_bf16 v[16:19], v[180:183], v[208:211], v[16:19]
	v_mfma_f32_16x16x32_bf16 v[4:7], v[172:175], v[216:219], v[4:7]
	v_mfma_f32_16x16x32_bf16 v[0:3], v[180:183], v[216:219], v[0:3]
	s_setprio 0
	s_barrier
	v_lshl_add_u64 v[222:223], v[222:223], 0, s[28:29]
	s_mov_b32 m0, s70
	s_nop 0
	global_load_lds_dwordx4 v[222:223], off
	v_lshl_add_u64 v[224:225], v[224:225], 0, s[28:29]
	s_mov_b32 m0, s71
	s_nop 0
	global_load_lds_dwordx4 v[224:225], off
	s_add_i32 s85, s85, 2
	s_add_u32 s83, s83, 0x100
	s_addc_u32 s84, s84, 0
	s_cmp_gt_u32 s85, 41
	s_mov_b64 s[36:37], s[38:39]
	s_cbranch_scc0 .LBB0_1791
	s_and_b64 vcc, exec, s[30:31]
	s_cbranch_vccz .LBB0_1794
	s_barrier

.LBB0_2142:
	ds_read_b128 v[144:147], v151
	ds_read_b128 v[156:159], v151 offset:1024
	ds_read_b128 v[160:163], v151 offset:2048
	ds_read_b128 v[164:167], v151 offset:3072
	ds_read_b128 v[168:171], v152
	ds_read_b128 v[172:175], v152 offset:1024
	ds_read_b128 v[176:179], v152 offset:2048
	ds_read_b128 v[180:183], v152 offset:3072
	s_add_u32 s38, s36, 0x100
	s_addc_u32 s39, s37, 0
	s_cmp_eq_u32 s83, 40
	s_cselect_b32 s43, s1, s39
	s_cselect_b32 s42, s0, s38
	s_cselect_b32 s41, s35, s82
	s_cselect_b32 s40, s34, s81
	v_lshl_add_u64 v[192:193], s[36:37], 0, v[136:137]
	s_add_i32 m0, s57, 0xc000
	ds_read_b128 v[184:187], v153
	ds_read_b128 v[188:191], v153 offset:1024
	ds_read_b128 v[196:199], v153 offset:2048
	ds_read_b128 v[200:203], v153 offset:3072
	ds_read_b128 v[204:207], v153 offset:4096
	ds_read_b128 v[208:211], v153 offset:5120
	ds_read_b128 v[212:215], v153 offset:6144
	ds_read_b128 v[216:219], v153 offset:7168
	global_load_lds_dwordx4 v[192:193], off
	v_lshl_add_u64 v[192:193], s[36:37], 0, v[138:139]
	s_add_i32 m0, s57, 0xe000
	s_nop 0
	global_load_lds_dwordx4 v[192:193], off
	s_waitcnt vmcnt(8)
	s_waitcnt lgkmcnt(0)
	s_barrier
	s_setprio 1
	s_waitcnt lgkmcnt(0)
	v_mfma_f32_16x16x32_bf16 v[124:127], v[144:147], v[184:187], v[124:127]
	v_mfma_f32_16x16x32_bf16 v[120:123], v[160:163], v[184:187], v[120:123]
	v_mfma_f32_16x16x32_bf16 v[108:111], v[144:147], v[196:199], v[108:111]
	v_mfma_f32_16x16x32_bf16 v[104:107], v[160:163], v[196:199], v[104:107]
	v_mfma_f32_16x16x32_bf16 v[92:95], v[144:147], v[204:207], v[92:95]
	v_mfma_f32_16x16x32_bf16 v[88:91], v[160:163], v[204:207], v[88:91]
	v_mfma_f32_16x16x32_bf16 v[76:79], v[144:147], v[212:215], v[76:79]
	v_mfma_f32_16x16x32_bf16 v[72:75], v[160:163], v[212:215], v[72:75]
	v_mfma_f32_16x16x32_bf16 v[124:127], v[156:159], v[188:191], v[124:127]
	v_mfma_f32_16x16x32_bf16 v[120:123], v[164:167], v[188:191], v[120:123]
	v_mfma_f32_16x16x32_bf16 v[108:111], v[156:159], v[200:203], v[108:111]
	v_mfma_f32_16x16x32_bf16 v[104:107], v[164:167], v[200:203], v[104:107]
	v_mfma_f32_16x16x32_bf16 v[92:95], v[156:159], v[208:211], v[92:95]
	v_mfma_f32_16x16x32_bf16 v[88:91], v[164:167], v[208:211], v[88:91]
	v_mfma_f32_16x16x32_bf16 v[76:79], v[156:159], v[216:219], v[76:79]
	v_mfma_f32_16x16x32_bf16 v[72:75], v[164:167], v[216:219], v[72:75]
	s_setprio 0
	s_setprio 1
	v_mfma_f32_16x16x32_bf16 v[116:119], v[168:171], v[184:187], v[116:119]
	v_mfma_f32_16x16x32_bf16 v[112:115], v[176:179], v[184:187], v[112:115]
	v_mfma_f32_16x16x32_bf16 v[100:103], v[168:171], v[196:199], v[100:103]
	v_mfma_f32_16x16x32_bf16 v[96:99], v[176:179], v[196:199], v[96:99]
	v_mfma_f32_16x16x32_bf16 v[84:87], v[168:171], v[204:207], v[84:87]
	v_mfma_f32_16x16x32_bf16 v[80:83], v[176:179], v[204:207], v[80:83]
	v_mfma_f32_16x16x32_bf16 v[68:71], v[168:171], v[212:215], v[68:71]
	v_mfma_f32_16x16x32_bf16 v[64:67], v[176:179], v[212:215], v[64:67]
	v_mfma_f32_16x16x32_bf16 v[116:119], v[172:175], v[188:191], v[116:119]
	v_mfma_f32_16x16x32_bf16 v[112:115], v[180:183], v[188:191], v[112:115]
	v_mfma_f32_16x16x32_bf16 v[100:103], v[172:175], v[200:203], v[100:103]
	v_mfma_f32_16x16x32_bf16 v[96:99], v[180:183], v[200:203], v[96:99]
	v_mfma_f32_16x16x32_bf16 v[84:87], v[172:175], v[208:211], v[84:87]
	v_mfma_f32_16x16x32_bf16 v[80:83], v[180:183], v[208:211], v[80:83]
	v_mfma_f32_16x16x32_bf16 v[68:71], v[172:175], v[216:219], v[68:71]
	v_mfma_f32_16x16x32_bf16 v[64:67], v[180:183], v[216:219], v[64:67]
	s_setprio 0
	s_barrier
	s_add_i32 s36, s71, s56
	v_lshl_add_u64 v[192:193], s[40:41], 0, v[130:131]
	s_mov_b32 m0, s36
	ds_read_b128 v[184:187], v153 offset:16384
	ds_read_b128 v[188:191], v153 offset:17408
	ds_read_b128 v[196:199], v153 offset:18432
	ds_read_b128 v[200:203], v153 offset:19456
	ds_read_b128 v[204:207], v153 offset:20480
	ds_read_b128 v[208:211], v153 offset:21504
	ds_read_b128 v[212:215], v153 offset:22528
	ds_read_b128 v[216:219], v153 offset:23552
	global_load_lds_dwordx4 v[192:193], off
	s_add_i32 m0, s36, 0x2000
	s_add_u32 s36, s40, 0xb0000
	v_lshl_add_u64 v[220:221], s[40:41], 0, v[134:135]
	s_addc_u32 s37, s41, 0
	s_add_i32 s84, s72, s56
	global_load_lds_dwordx4 v[220:221], off
	s_mov_b32 m0, s84
	v_lshl_add_u64 v[224:225], s[42:43], 0, v[132:133]
	global_load_lds_dwordx4 v130, s[36:37]
	s_add_i32 m0, s84, 0x2000
	s_nop 0
	global_load_lds_dwordx4 v134, s[36:37]
	v_lshl_add_u64 v[222:223], s[42:43], 0, v[128:129]
	s_waitcnt vmcnt(6)
	s_waitcnt lgkmcnt(0)
	s_barrier
	s_setprio 1
	s_waitcnt lgkmcnt(0)
	v_mfma_f32_16x16x32_bf16 v[60:63], v[144:147], v[184:187], v[60:63]
	v_mfma_f32_16x16x32_bf16 v[56:59], v[160:163], v[184:187], v[56:59]
	v_mfma_f32_16x16x32_bf16 v[44:47], v[144:147], v[196:199], v[44:47]
	v_mfma_f32_16x16x32_bf16 v[40:43], v[160:163], v[196:199], v[40:43]
	v_mfma_f32_16x16x32_bf16 v[28:31], v[144:147], v[204:207], v[28:31]
	v_mfma_f32_16x16x32_bf16 v[24:27], v[160:163], v[204:207], v[24:27]
	v_mfma_f32_16x16x32_bf16 v[12:15], v[144:147], v[212:215], v[12:15]
	v_mfma_f32_16x16x32_bf16 v[8:11], v[160:163], v[212:215], v[8:11]
	v_mfma_f32_16x16x32_bf16 v[60:63], v[156:159], v[188:191], v[60:63]
	v_mfma_f32_16x16x32_bf16 v[56:59], v[164:167], v[188:191], v[56:59]
	v_mfma_f32_16x16x32_bf16 v[44:47], v[156:159], v[200:203], v[44:47]
	v_mfma_f32_16x16x32_bf16 v[40:43], v[164:167], v[200:203], v[40:43]
	v_mfma_f32_16x16x32_bf16 v[28:31], v[156:159], v[208:211], v[28:31]
	v_mfma_f32_16x16x32_bf16 v[24:27], v[164:167], v[208:211], v[24:27]
	v_mfma_f32_16x16x32_bf16 v[12:15], v[156:159], v[216:219], v[12:15]
	v_mfma_f32_16x16x32_bf16 v[8:11], v[164:167], v[216:219], v[8:11]
	s_setprio 0
	s_setprio 1
	v_mfma_f32_16x16x32_bf16 v[52:55], v[168:171], v[184:187], v[52:55]
	v_mfma_f32_16x16x32_bf16 v[48:51], v[176:179], v[184:187], v[48:51]
	v_mfma_f32_16x16x32_bf16 v[36:39], v[168:171], v[196:199], v[36:39]
	v_mfma_f32_16x16x32_bf16 v[32:35], v[176:179], v[196:199], v[32:35]
	v_mfma_f32_16x16x32_bf16 v[20:23], v[168:171], v[204:207], v[20:23]
	v_mfma_f32_16x16x32_bf16 v[16:19], v[176:179], v[204:207], v[16:19]
	v_mfma_f32_16x16x32_bf16 v[4:7], v[168:171], v[212:215], v[4:7]
	v_mfma_f32_16x16x32_bf16 v[0:3], v[176:179], v[212:215], v[0:3]
	v_mfma_f32_16x16x32_bf16 v[52:55], v[172:175], v[188:191], v[52:55]
	v_mfma_f32_16x16x32_bf16 v[48:51], v[180:183], v[188:191], v[48:51]
	v_mfma_f32_16x16x32_bf16 v[36:39], v[172:175], v[200:203], v[36:39]
	v_mfma_f32_16x16x32_bf16 v[32:35], v[180:183], v[200:203], v[32:35]
	v_mfma_f32_16x16x32_bf16 v[20:23], v[172:175], v[208:211], v[20:23]
	v_mfma_f32_16x16x32_bf16 v[16:19], v[180:183], v[208:211], v[16:19]
	v_mfma_f32_16x16x32_bf16 v[4:7], v[172:175], v[216:219], v[4:7]
	v_mfma_f32_16x16x32_bf16 v[0:3], v[180:183], v[216:219], v[0:3]
	s_setprio 0
	s_barrier
	s_add_i32 s84, 0, 0x18000
	v_add_u32_e32 v155, s84, v149
	s_add_i32 s85, 0, 0x1c000
	ds_read_b128 v[144:147], v155
	ds_read_b128 v[156:159], v155 offset:1024
	ds_read_b128 v[160:163], v155 offset:2048
	ds_read_b128 v[164:167], v155 offset:3072
	v_add_u32_e32 v155, s85, v149
	ds_read_b128 v[168:171], v155
	ds_read_b128 v[172:175], v155 offset:1024
	ds_read_b128 v[176:179], v155 offset:2048
	ds_read_b128 v[180:183], v155 offset:3072
	s_add_u32 s36, s42, 0xb0000
	s_addc_u32 s37, s43, 0
	ds_read_b128 v[184:187], v153 offset:32768
	ds_read_b128 v[188:191], v153 offset:33792
	ds_read_b128 v[196:199], v153 offset:34816
	ds_read_b128 v[200:203], v153 offset:35840
	ds_read_b128 v[204:207], v153 offset:36864
	ds_read_b128 v[208:211], v153 offset:37888
	ds_read_b128 v[212:215], v153 offset:38912
	ds_read_b128 v[216:219], v153 offset:39936
	s_mov_b32 m0, s57
	s_nop 0
	global_load_lds_dwordx4 v[222:223], off
	s_mov_b32 m0, s58
	s_nop 0
	global_load_lds_dwordx4 v[224:225], off
	s_mov_b32 m0, s59
	s_nop 0
	global_load_lds_dwordx4 v128, s[36:37]
	s_mov_b32 m0, s60
	s_nop 0
	global_load_lds_dwordx4 v132, s[36:37]
	s_waitcnt vmcnt(8)
	s_waitcnt lgkmcnt(0)
	s_barrier
	s_setprio 1
	s_waitcnt lgkmcnt(0)
	v_mfma_f32_16x16x32_bf16 v[124:127], v[144:147], v[184:187], v[124:127]
	v_mfma_f32_16x16x32_bf16 v[120:123], v[160:163], v[184:187], v[120:123]
	v_mfma_f32_16x16x32_bf16 v[108:111], v[144:147], v[196:199], v[108:111]
	v_mfma_f32_16x16x32_bf16 v[104:107], v[160:163], v[196:199], v[104:107]
	v_mfma_f32_16x16x32_bf16 v[92:95], v[144:147], v[204:207], v[92:95]
	v_mfma_f32_16x16x32_bf16 v[88:91], v[160:163], v[204:207], v[88:91]
	v_mfma_f32_16x16x32_bf16 v[76:79], v[144:147], v[212:215], v[76:79]
	v_mfma_f32_16x16x32_bf16 v[72:75], v[160:163], v[212:215], v[72:75]
	v_mfma_f32_16x16x32_bf16 v[124:127], v[156:159], v[188:191], v[124:127]
	v_mfma_f32_16x16x32_bf16 v[120:123], v[164:167], v[188:191], v[120:123]
	v_mfma_f32_16x16x32_bf16 v[108:111], v[156:159], v[200:203], v[108:111]
	v_mfma_f32_16x16x32_bf16 v[104:107], v[164:167], v[200:203], v[104:107]
	v_mfma_f32_16x16x32_bf16 v[92:95], v[156:159], v[208:211], v[92:95]
	v_mfma_f32_16x16x32_bf16 v[88:91], v[164:167], v[208:211], v[88:91]
	v_mfma_f32_16x16x32_bf16 v[76:79], v[156:159], v[216:219], v[76:79]
	v_mfma_f32_16x16x32_bf16 v[72:75], v[164:167], v[216:219], v[72:75]
	s_setprio 0
	s_setprio 1
	v_mfma_f32_16x16x32_bf16 v[116:119], v[168:171], v[184:187], v[116:119]
	v_mfma_f32_16x16x32_bf16 v[112:115], v[176:179], v[184:187], v[112:115]
	v_mfma_f32_16x16x32_bf16 v[100:103], v[168:171], v[196:199], v[100:103]
	v_mfma_f32_16x16x32_bf16 v[96:99], v[176:179], v[196:199], v[96:99]
	v_mfma_f32_16x16x32_bf16 v[84:87], v[168:171], v[204:207], v[84:87]
	v_mfma_f32_16x16x32_bf16 v[80:83], v[176:179], v[204:207], v[80:83]
	v_mfma_f32_16x16x32_bf16 v[68:71], v[168:171], v[212:215], v[68:71]
	v_mfma_f32_16x16x32_bf16 v[64:67], v[176:179], v[212:215], v[64:67]
	v_mfma_f32_16x16x32_bf16 v[116:119], v[172:175], v[188:191], v[116:119]
	v_mfma_f32_16x16x32_bf16 v[112:115], v[180:183], v[188:191], v[112:115]
	v_mfma_f32_16x16x32_bf16 v[100:103], v[172:175], v[200:203], v[100:103]
	v_mfma_f32_16x16x32_bf16 v[96:99], v[180:183], v[200:203], v[96:99]
	v_mfma_f32_16x16x32_bf16 v[84:87], v[172:175], v[208:211], v[84:87]
	v_mfma_f32_16x16x32_bf16 v[80:83], v[180:183], v[208:211], v[80:83]
	v_mfma_f32_16x16x32_bf16 v[68:71], v[172:175], v[216:219], v[68:71]
	v_mfma_f32_16x16x32_bf16 v[64:67], v[180:183], v[216:219], v[64:67]
	s_setprio 0
	s_barrier
	s_add_i32 s36, s84, s56
	v_lshl_add_u64 v[192:193], v[192:193], 0, s[28:29]
	s_mov_b32 m0, s36
	ds_read_b128 v[184:187], v153 offset:49152
	ds_read_b128 v[188:191], v153 offset:50176
	ds_read_b128 v[196:199], v153 offset:51200
	ds_read_b128 v[200:203], v153 offset:52224
	ds_read_b128 v[204:207], v153 offset:53248
	ds_read_b128 v[208:211], v153 offset:54272
	ds_read_b128 v[212:215], v153 offset:55296
	ds_read_b128 v[216:219], v153 offset:56320
	global_load_lds_dwordx4 v[192:193], off
	s_add_i32 m0, s36, 0x2000
	s_add_u32 s36, s40, 0xb0080
	v_lshl_add_u64 v[192:193], v[220:221], 0, s[28:29]
	s_addc_u32 s37, s41, 0
	s_add_i32 s40, s85, s56
	global_load_lds_dwordx4 v[192:193], off
	s_mov_b32 m0, s40
	s_nop 0
	global_load_lds_dwordx4 v130, s[36:37]
	s_add_i32 m0, s40, 0x2000
	s_nop 0
	global_load_lds_dwordx4 v134, s[36:37]
	s_waitcnt vmcnt(6)
	s_waitcnt lgkmcnt(0)
	s_barrier
	s_setprio 1
	s_waitcnt lgkmcnt(0)
	v_mfma_f32_16x16x32_bf16 v[60:63], v[144:147], v[184:187], v[60:63]
	v_mfma_f32_16x16x32_bf16 v[56:59], v[160:163], v[184:187], v[56:59]
	v_mfma_f32_16x16x32_bf16 v[44:47], v[144:147], v[196:199], v[44:47]
	v_mfma_f32_16x16x32_bf16 v[40:43], v[160:163], v[196:199], v[40:43]
	v_mfma_f32_16x16x32_bf16 v[28:31], v[144:147], v[204:207], v[28:31]
	v_mfma_f32_16x16x32_bf16 v[24:27], v[160:163], v[204:207], v[24:27]
	v_mfma_f32_16x16x32_bf16 v[12:15], v[144:147], v[212:215], v[12:15]
	v_mfma_f32_16x16x32_bf16 v[8:11], v[160:163], v[212:215], v[8:11]
	v_mfma_f32_16x16x32_bf16 v[60:63], v[156:159], v[188:191], v[60:63]
	v_mfma_f32_16x16x32_bf16 v[56:59], v[164:167], v[188:191], v[56:59]
	v_mfma_f32_16x16x32_bf16 v[44:47], v[156:159], v[200:203], v[44:47]
	v_mfma_f32_16x16x32_bf16 v[40:43], v[164:167], v[200:203], v[40:43]
	v_mfma_f32_16x16x32_bf16 v[28:31], v[156:159], v[208:211], v[28:31]
	v_mfma_f32_16x16x32_bf16 v[24:27], v[164:167], v[208:211], v[24:27]
	v_mfma_f32_16x16x32_bf16 v[12:15], v[156:159], v[216:219], v[12:15]
	v_mfma_f32_16x16x32_bf16 v[8:11], v[164:167], v[216:219], v[8:11]
	s_setprio 0
	s_setprio 1
	v_mfma_f32_16x16x32_bf16 v[52:55], v[168:171], v[184:187], v[52:55]
	v_mfma_f32_16x16x32_bf16 v[48:51], v[176:179], v[184:187], v[48:51]
	v_mfma_f32_16x16x32_bf16 v[36:39], v[168:171], v[196:199], v[36:39]
	v_mfma_f32_16x16x32_bf16 v[32:35], v[176:179], v[196:199], v[32:35]
	v_mfma_f32_16x16x32_bf16 v[20:23], v[168:171], v[204:207], v[20:23]
	v_mfma_f32_16x16x32_bf16 v[16:19], v[176:179], v[204:207], v[16:19]
	v_mfma_f32_16x16x32_bf16 v[4:7], v[168:171], v[212:215], v[4:7]
	v_mfma_f32_16x16x32_bf16 v[0:3], v[176:179], v[212:215], v[0:3]
	v_mfma_f32_16x16x32_bf16 v[52:55], v[172:175], v[188:191], v[52:55]
	v_mfma_f32_16x16x32_bf16 v[48:51], v[180:183], v[188:191], v[48:51]
	v_mfma_f32_16x16x32_bf16 v[36:39], v[172:175], v[200:203], v[36:39]
	v_mfma_f32_16x16x32_bf16 v[32:35], v[180:183], v[200:203], v[32:35]
	v_mfma_f32_16x16x32_bf16 v[20:23], v[172:175], v[208:211], v[20:23]
	v_mfma_f32_16x16x32_bf16 v[16:19], v[180:183], v[208:211], v[16:19]
	v_mfma_f32_16x16x32_bf16 v[4:7], v[172:175], v[216:219], v[4:7]
	v_mfma_f32_16x16x32_bf16 v[0:3], v[180:183], v[216:219], v[0:3]
	s_setprio 0
	s_barrier
	v_lshl_add_u64 v[222:223], v[222:223], 0, s[28:29]
	s_mov_b32 m0, s62
	s_nop 0
	global_load_lds_dwordx4 v[222:223], off
	v_lshl_add_u64 v[224:225], v[224:225], 0, s[28:29]
	s_mov_b32 m0, s63
	s_nop 0
	global_load_lds_dwordx4 v[224:225], off
	s_add_i32 s83, s83, 2
	s_add_u32 s81, s81, 0x100
	s_addc_u32 s82, s82, 0
	s_cmp_gt_u32 s83, 41
	s_mov_b64 s[36:37], s[38:39]
	s_cbranch_scc0 .LBB0_2142
	s_and_b64 vcc, exec, s[30:31]
	s_cbranch_vccz .LBB0_2145
	s_barrier

.LBB0_2236:
	ds_read_b128 v[152:155], v157
	ds_read_b128 v[162:165], v157 offset:1024
	ds_read_b128 v[166:169], v157 offset:2048
	ds_read_b128 v[170:173], v157 offset:3072
	ds_read_b128 v[174:177], v158
	ds_read_b128 v[178:181], v158 offset:1024
	ds_read_b128 v[182:185], v158 offset:2048
	ds_read_b128 v[186:189], v158 offset:3072
	s_add_u32 s42, s40, 0xfffc0080
	s_addc_u32 s43, s41, -1
	s_cmp_eq_u32 s88, 12
	s_cselect_b32 s45, s1, s43
	s_cselect_b32 s44, s15, s42
	s_cselect_b32 s43, s16, s87
	s_cselect_b32 s42, s31, s35
	s_add_i32 m0, s59, 0xc000
	ds_read_b128 v[190:193], v159
	ds_read_b128 v[196:199], v159 offset:1024
	ds_read_b128 v[200:203], v159 offset:2048
	ds_read_b128 v[204:207], v159 offset:3072
	ds_read_b128 v[208:211], v159 offset:4096
	ds_read_b128 v[212:215], v159 offset:5120
	ds_read_b128 v[216:219], v159 offset:6144
	ds_read_b128 v[220:223], v159 offset:7168
	global_load_lds_dwordx4 v144, s[40:41]
	s_add_i32 m0, s59, 0xe000
	s_nop 0
	global_load_lds_dwordx4 v146, s[40:41]
	s_waitcnt vmcnt(8)
	s_waitcnt lgkmcnt(0)
	s_barrier
	s_setprio 1
	s_waitcnt lgkmcnt(0)
	v_mfma_f32_16x16x32_bf16 v[124:127], v[152:155], v[190:193], v[124:127]
	v_mfma_f32_16x16x32_bf16 v[120:123], v[166:169], v[190:193], v[120:123]
	v_mfma_f32_16x16x32_bf16 v[108:111], v[152:155], v[200:203], v[108:111]
	v_mfma_f32_16x16x32_bf16 v[104:107], v[166:169], v[200:203], v[104:107]
	v_mfma_f32_16x16x32_bf16 v[92:95], v[152:155], v[208:211], v[92:95]
	v_mfma_f32_16x16x32_bf16 v[88:91], v[166:169], v[208:211], v[88:91]
	v_mfma_f32_16x16x32_bf16 v[76:79], v[152:155], v[216:219], v[76:79]
	v_mfma_f32_16x16x32_bf16 v[72:75], v[166:169], v[216:219], v[72:75]
	v_mfma_f32_16x16x32_bf16 v[124:127], v[162:165], v[196:199], v[124:127]
	v_mfma_f32_16x16x32_bf16 v[120:123], v[170:173], v[196:199], v[120:123]
	v_mfma_f32_16x16x32_bf16 v[108:111], v[162:165], v[204:207], v[108:111]
	v_mfma_f32_16x16x32_bf16 v[104:107], v[170:173], v[204:207], v[104:107]
	v_mfma_f32_16x16x32_bf16 v[92:95], v[162:165], v[212:215], v[92:95]
	v_mfma_f32_16x16x32_bf16 v[88:91], v[170:173], v[212:215], v[88:91]
	v_mfma_f32_16x16x32_bf16 v[76:79], v[162:165], v[220:223], v[76:79]
	v_mfma_f32_16x16x32_bf16 v[72:75], v[170:173], v[220:223], v[72:75]
	s_setprio 0
	s_setprio 1
	v_mfma_f32_16x16x32_bf16 v[116:119], v[174:177], v[190:193], v[116:119]
	v_mfma_f32_16x16x32_bf16 v[112:115], v[182:185], v[190:193], v[112:115]
	v_mfma_f32_16x16x32_bf16 v[100:103], v[174:177], v[200:203], v[100:103]
	v_mfma_f32_16x16x32_bf16 v[96:99], v[182:185], v[200:203], v[96:99]
	v_mfma_f32_16x16x32_bf16 v[84:87], v[174:177], v[208:211], v[84:87]
	v_mfma_f32_16x16x32_bf16 v[80:83], v[182:185], v[208:211], v[80:83]
	v_mfma_f32_16x16x32_bf16 v[68:71], v[174:177], v[216:219], v[68:71]
	v_mfma_f32_16x16x32_bf16 v[64:67], v[182:185], v[216:219], v[64:67]
	v_mfma_f32_16x16x32_bf16 v[116:119], v[178:181], v[196:199], v[116:119]
	v_mfma_f32_16x16x32_bf16 v[112:115], v[186:189], v[196:199], v[112:115]
	v_mfma_f32_16x16x32_bf16 v[100:103], v[178:181], v[204:207], v[100:103]
	v_mfma_f32_16x16x32_bf16 v[96:99], v[186:189], v[204:207], v[96:99]
	v_mfma_f32_16x16x32_bf16 v[84:87], v[178:181], v[212:215], v[84:87]
	v_mfma_f32_16x16x32_bf16 v[80:83], v[186:189], v[212:215], v[80:83]
	v_mfma_f32_16x16x32_bf16 v[68:71], v[178:181], v[220:223], v[68:71]
	v_mfma_f32_16x16x32_bf16 v[64:67], v[186:189], v[220:223], v[64:67]
	s_setprio 0
	s_barrier
	s_add_i32 s89, s78, s58
	v_lshl_add_u64 v[224:225], s[42:43], 0, v[130:131]
	s_mov_b32 m0, s89
	ds_read_b128 v[190:193], v159 offset:16384
	ds_read_b128 v[196:199], v159 offset:17408
	ds_read_b128 v[200:203], v159 offset:18432
	ds_read_b128 v[204:207], v159 offset:19456
	ds_read_b128 v[208:211], v159 offset:20480
	ds_read_b128 v[212:215], v159 offset:21504
	ds_read_b128 v[216:219], v159 offset:22528
	ds_read_b128 v[220:223], v159 offset:23552
	global_load_lds_dwordx4 v[224:225], off
	s_add_i32 m0, s89, 0x2000
	s_add_u32 s90, s42, 0x40000
	v_lshl_add_u64 v[226:227], s[42:43], 0, v[134:135]
	s_addc_u32 s91, s43, 0
	s_add_i32 s89, s79, s58
	global_load_lds_dwordx4 v[226:227], off
	s_mov_b32 m0, s89
	v_lshl_add_u64 v[230:231], s[44:45], 0, v[132:133]
	global_load_lds_dwordx4 v130, s[90:91]
	s_add_i32 m0, s89, 0x2000
	s_nop 0
	global_load_lds_dwordx4 v134, s[90:91]
	v_lshl_add_u64 v[228:229], s[44:45], 0, v[128:129]
	s_waitcnt vmcnt(6)
	s_waitcnt lgkmcnt(0)
	s_barrier
	s_setprio 1
	s_waitcnt lgkmcnt(0)
	v_mfma_f32_16x16x32_bf16 v[60:63], v[152:155], v[190:193], v[60:63]
	v_mfma_f32_16x16x32_bf16 v[56:59], v[166:169], v[190:193], v[56:59]
	v_mfma_f32_16x16x32_bf16 v[44:47], v[152:155], v[200:203], v[44:47]
	v_mfma_f32_16x16x32_bf16 v[40:43], v[166:169], v[200:203], v[40:43]
	v_mfma_f32_16x16x32_bf16 v[28:31], v[152:155], v[208:211], v[28:31]
	v_mfma_f32_16x16x32_bf16 v[24:27], v[166:169], v[208:211], v[24:27]
	v_mfma_f32_16x16x32_bf16 v[12:15], v[152:155], v[216:219], v[12:15]
	v_mfma_f32_16x16x32_bf16 v[8:11], v[166:169], v[216:219], v[8:11]
	v_mfma_f32_16x16x32_bf16 v[60:63], v[162:165], v[196:199], v[60:63]
	v_mfma_f32_16x16x32_bf16 v[56:59], v[170:173], v[196:199], v[56:59]
	v_mfma_f32_16x16x32_bf16 v[44:47], v[162:165], v[204:207], v[44:47]
	v_mfma_f32_16x16x32_bf16 v[40:43], v[170:173], v[204:207], v[40:43]
	v_mfma_f32_16x16x32_bf16 v[28:31], v[162:165], v[212:215], v[28:31]
	v_mfma_f32_16x16x32_bf16 v[24:27], v[170:173], v[212:215], v[24:27]
	v_mfma_f32_16x16x32_bf16 v[12:15], v[162:165], v[220:223], v[12:15]
	v_mfma_f32_16x16x32_bf16 v[8:11], v[170:173], v[220:223], v[8:11]
	s_setprio 0
	s_setprio 1
	v_mfma_f32_16x16x32_bf16 v[52:55], v[174:177], v[190:193], v[52:55]
	v_mfma_f32_16x16x32_bf16 v[48:51], v[182:185], v[190:193], v[48:51]
	v_mfma_f32_16x16x32_bf16 v[36:39], v[174:177], v[200:203], v[36:39]
	v_mfma_f32_16x16x32_bf16 v[32:35], v[182:185], v[200:203], v[32:35]
	v_mfma_f32_16x16x32_bf16 v[20:23], v[174:177], v[208:211], v[20:23]
	v_mfma_f32_16x16x32_bf16 v[16:19], v[182:185], v[208:211], v[16:19]
	v_mfma_f32_16x16x32_bf16 v[4:7], v[174:177], v[216:219], v[4:7]
	v_mfma_f32_16x16x32_bf16 v[0:3], v[182:185], v[216:219], v[0:3]
	v_mfma_f32_16x16x32_bf16 v[52:55], v[178:181], v[196:199], v[52:55]
	v_mfma_f32_16x16x32_bf16 v[48:51], v[186:189], v[196:199], v[48:51]
	v_mfma_f32_16x16x32_bf16 v[36:39], v[178:181], v[204:207], v[36:39]
	v_mfma_f32_16x16x32_bf16 v[32:35], v[186:189], v[204:207], v[32:35]
	v_mfma_f32_16x16x32_bf16 v[20:23], v[178:181], v[212:215], v[20:23]
	v_mfma_f32_16x16x32_bf16 v[16:19], v[186:189], v[212:215], v[16:19]
	v_mfma_f32_16x16x32_bf16 v[4:7], v[178:181], v[220:223], v[4:7]
	v_mfma_f32_16x16x32_bf16 v[0:3], v[186:189], v[220:223], v[0:3]
	s_setprio 0
	s_barrier
	s_add_i32 s89, 0, 0x18000
	v_add_u32_e32 v136, s89, v141
	s_add_i32 s90, 0, 0x1c000
	ds_read_b128 v[152:155], v136
	ds_read_b128 v[162:165], v136 offset:1024
	ds_read_b128 v[166:169], v136 offset:2048
	ds_read_b128 v[170:173], v136 offset:3072
	v_add_u32_e32 v136, s90, v141
	ds_read_b128 v[174:177], v136
	ds_read_b128 v[178:181], v136 offset:1024
	ds_read_b128 v[182:185], v136 offset:2048
	ds_read_b128 v[186:189], v136 offset:3072
	s_add_u32 s44, s44, 0x40000
	s_addc_u32 s45, s45, 0
	ds_read_b128 v[190:193], v159 offset:32768
	ds_read_b128 v[196:199], v159 offset:33792
	ds_read_b128 v[200:203], v159 offset:34816
	ds_read_b128 v[204:207], v159 offset:35840
	ds_read_b128 v[208:211], v159 offset:36864
	ds_read_b128 v[212:215], v159 offset:37888
	ds_read_b128 v[216:219], v159 offset:38912
	ds_read_b128 v[220:223], v159 offset:39936
	s_mov_b32 m0, s59
	s_nop 0
	global_load_lds_dwordx4 v[228:229], off
	s_mov_b32 m0, s60
	s_nop 0
	global_load_lds_dwordx4 v[230:231], off
	s_mov_b32 m0, s61
	s_nop 0
	global_load_lds_dwordx4 v128, s[44:45]
	s_mov_b32 m0, s62
	s_nop 0
	global_load_lds_dwordx4 v132, s[44:45]
	s_waitcnt vmcnt(8)
	s_waitcnt lgkmcnt(0)
	s_barrier
	s_setprio 1
	s_waitcnt lgkmcnt(0)
	v_mfma_f32_16x16x32_bf16 v[124:127], v[152:155], v[190:193], v[124:127]
	v_mfma_f32_16x16x32_bf16 v[120:123], v[166:169], v[190:193], v[120:123]
	v_mfma_f32_16x16x32_bf16 v[108:111], v[152:155], v[200:203], v[108:111]
	v_mfma_f32_16x16x32_bf16 v[104:107], v[166:169], v[200:203], v[104:107]
	v_mfma_f32_16x16x32_bf16 v[92:95], v[152:155], v[208:211], v[92:95]
	v_mfma_f32_16x16x32_bf16 v[88:91], v[166:169], v[208:211], v[88:91]
	v_mfma_f32_16x16x32_bf16 v[76:79], v[152:155], v[216:219], v[76:79]
	v_mfma_f32_16x16x32_bf16 v[72:75], v[166:169], v[216:219], v[72:75]
	v_mfma_f32_16x16x32_bf16 v[124:127], v[162:165], v[196:199], v[124:127]
	v_mfma_f32_16x16x32_bf16 v[120:123], v[170:173], v[196:199], v[120:123]
	v_mfma_f32_16x16x32_bf16 v[108:111], v[162:165], v[204:207], v[108:111]
	v_mfma_f32_16x16x32_bf16 v[104:107], v[170:173], v[204:207], v[104:107]
	v_mfma_f32_16x16x32_bf16 v[92:95], v[162:165], v[212:215], v[92:95]
	v_mfma_f32_16x16x32_bf16 v[88:91], v[170:173], v[212:215], v[88:91]
	v_mfma_f32_16x16x32_bf16 v[76:79], v[162:165], v[220:223], v[76:79]
	v_mfma_f32_16x16x32_bf16 v[72:75], v[170:173], v[220:223], v[72:75]
	s_setprio 0
	s_setprio 1
	v_mfma_f32_16x16x32_bf16 v[116:119], v[174:177], v[190:193], v[116:119]
	v_mfma_f32_16x16x32_bf16 v[112:115], v[182:185], v[190:193], v[112:115]
	v_mfma_f32_16x16x32_bf16 v[100:103], v[174:177], v[200:203], v[100:103]
	v_mfma_f32_16x16x32_bf16 v[96:99], v[182:185], v[200:203], v[96:99]
	v_mfma_f32_16x16x32_bf16 v[84:87], v[174:177], v[208:211], v[84:87]
	v_mfma_f32_16x16x32_bf16 v[80:83], v[182:185], v[208:211], v[80:83]
	v_mfma_f32_16x16x32_bf16 v[68:71], v[174:177], v[216:219], v[68:71]
	v_mfma_f32_16x16x32_bf16 v[64:67], v[182:185], v[216:219], v[64:67]
	v_mfma_f32_16x16x32_bf16 v[116:119], v[178:181], v[196:199], v[116:119]
	v_mfma_f32_16x16x32_bf16 v[112:115], v[186:189], v[196:199], v[112:115]
	v_mfma_f32_16x16x32_bf16 v[100:103], v[178:181], v[204:207], v[100:103]
	v_mfma_f32_16x16x32_bf16 v[96:99], v[186:189], v[204:207], v[96:99]
	v_mfma_f32_16x16x32_bf16 v[84:87], v[178:181], v[212:215], v[84:87]
	v_mfma_f32_16x16x32_bf16 v[80:83], v[186:189], v[212:215], v[80:83]
	v_mfma_f32_16x16x32_bf16 v[68:71], v[178:181], v[220:223], v[68:71]
	v_mfma_f32_16x16x32_bf16 v[64:67], v[186:189], v[220:223], v[64:67]
	s_setprio 0
	s_barrier
	s_add_i32 s44, s89, s58
	v_lshl_add_u64 v[224:225], v[224:225], 0, s[26:27]
	s_mov_b32 m0, s44
	ds_read_b128 v[190:193], v159 offset:49152
	ds_read_b128 v[196:199], v159 offset:50176
	ds_read_b128 v[200:203], v159 offset:51200
	ds_read_b128 v[204:207], v159 offset:52224
	ds_read_b128 v[208:211], v159 offset:53248
	ds_read_b128 v[212:215], v159 offset:54272
	ds_read_b128 v[216:219], v159 offset:55296
	ds_read_b128 v[220:223], v159 offset:56320
	global_load_lds_dwordx4 v[224:225], off
	s_add_i32 m0, s44, 0x2000
	s_add_u32 s42, s42, 0x40080
	v_lshl_add_u64 v[224:225], v[226:227], 0, s[26:27]
	s_addc_u32 s43, s43, 0
	s_add_i32 s44, s90, s58
	global_load_lds_dwordx4 v[224:225], off
	s_mov_b32 m0, s44
	s_nop 0
	global_load_lds_dwordx4 v130, s[42:43]
	s_add_i32 m0, s44, 0x2000
	s_nop 0
	global_load_lds_dwordx4 v134, s[42:43]
	s_waitcnt vmcnt(6)
	s_waitcnt lgkmcnt(0)
	s_barrier
	s_setprio 1
	s_waitcnt lgkmcnt(0)
	v_mfma_f32_16x16x32_bf16 v[60:63], v[152:155], v[190:193], v[60:63]
	v_mfma_f32_16x16x32_bf16 v[56:59], v[166:169], v[190:193], v[56:59]
	v_mfma_f32_16x16x32_bf16 v[44:47], v[152:155], v[200:203], v[44:47]
	v_mfma_f32_16x16x32_bf16 v[40:43], v[166:169], v[200:203], v[40:43]
	v_mfma_f32_16x16x32_bf16 v[28:31], v[152:155], v[208:211], v[28:31]
	v_mfma_f32_16x16x32_bf16 v[24:27], v[166:169], v[208:211], v[24:27]
	v_mfma_f32_16x16x32_bf16 v[12:15], v[152:155], v[216:219], v[12:15]
	v_mfma_f32_16x16x32_bf16 v[8:11], v[166:169], v[216:219], v[8:11]
	v_mfma_f32_16x16x32_bf16 v[60:63], v[162:165], v[196:199], v[60:63]
	v_mfma_f32_16x16x32_bf16 v[56:59], v[170:173], v[196:199], v[56:59]
	v_mfma_f32_16x16x32_bf16 v[44:47], v[162:165], v[204:207], v[44:47]
	v_mfma_f32_16x16x32_bf16 v[40:43], v[170:173], v[204:207], v[40:43]
	v_mfma_f32_16x16x32_bf16 v[28:31], v[162:165], v[212:215], v[28:31]
	v_mfma_f32_16x16x32_bf16 v[24:27], v[170:173], v[212:215], v[24:27]
	v_mfma_f32_16x16x32_bf16 v[12:15], v[162:165], v[220:223], v[12:15]
	v_mfma_f32_16x16x32_bf16 v[8:11], v[170:173], v[220:223], v[8:11]
	s_setprio 0
	s_setprio 1
	v_mfma_f32_16x16x32_bf16 v[52:55], v[174:177], v[190:193], v[52:55]
	v_mfma_f32_16x16x32_bf16 v[48:51], v[182:185], v[190:193], v[48:51]
	v_mfma_f32_16x16x32_bf16 v[36:39], v[174:177], v[200:203], v[36:39]
	v_mfma_f32_16x16x32_bf16 v[32:35], v[182:185], v[200:203], v[32:35]
	v_mfma_f32_16x16x32_bf16 v[20:23], v[174:177], v[208:211], v[20:23]
	v_mfma_f32_16x16x32_bf16 v[16:19], v[182:185], v[208:211], v[16:19]
	v_mfma_f32_16x16x32_bf16 v[4:7], v[174:177], v[216:219], v[4:7]
	v_mfma_f32_16x16x32_bf16 v[0:3], v[182:185], v[216:219], v[0:3]
	v_mfma_f32_16x16x32_bf16 v[52:55], v[178:181], v[196:199], v[52:55]
	v_mfma_f32_16x16x32_bf16 v[48:51], v[186:189], v[196:199], v[48:51]
	v_mfma_f32_16x16x32_bf16 v[36:39], v[178:181], v[204:207], v[36:39]
	v_mfma_f32_16x16x32_bf16 v[32:35], v[186:189], v[204:207], v[32:35]
	v_mfma_f32_16x16x32_bf16 v[20:23], v[178:181], v[212:215], v[20:23]
	v_mfma_f32_16x16x32_bf16 v[16:19], v[186:189], v[212:215], v[16:19]
	v_mfma_f32_16x16x32_bf16 v[4:7], v[178:181], v[220:223], v[4:7]
	v_mfma_f32_16x16x32_bf16 v[0:3], v[186:189], v[220:223], v[0:3]
	s_setprio 0
	s_barrier
	v_lshl_add_u64 v[228:229], v[228:229], 0, s[26:27]
	s_mov_b32 m0, s71
	s_nop 0
	global_load_lds_dwordx4 v[228:229], off
	v_lshl_add_u64 v[230:231], v[230:231], 0, s[26:27]
	s_mov_b32 m0, s72
	s_nop 0
	global_load_lds_dwordx4 v[230:231], off
	s_add_i32 s88, s88, 2
	s_add_u32 s40, s40, 0x100
	s_addc_u32 s41, s41, 0
	s_add_u32 s35, s35, 0x100
	s_addc_u32 s87, s87, 0
	s_cmp_gt_u32 s88, 13
	s_cbranch_scc0 .LBB0_2236
	s_and_b64 vcc, exec, s[28:29]
	s_cbranch_vccz .LBB0_2239
	s_barrier

.LBB0_2370:
	ds_read_b128 v[148:151], v144
	ds_read_b128 v[152:155], v144 offset:1024
	ds_read_b128 v[156:159], v144 offset:2048
	ds_read_b128 v[160:163], v144 offset:3072
	ds_read_b128 v[164:167], v145
	ds_read_b128 v[168:171], v145 offset:1024
	ds_read_b128 v[172:175], v145 offset:2048
	ds_read_b128 v[176:179], v145 offset:3072
	s_add_u32 s38, s36, 0x100
	s_addc_u32 s39, s37, 0
	s_cmp_eq_u32 s81, 4
	s_cselect_b32 s43, s31, s39
	s_cselect_b32 s42, s30, s38
	s_cselect_b32 s41, s35, s27
	s_cselect_b32 s40, s34, s17
	v_lshl_add_u64 v[192:193], s[36:37], 0, v[138:139]
	s_add_i32 m0, s55, 0xc000
	ds_read_b128 v[180:183], v146
	ds_read_b128 v[184:187], v146 offset:1024
	ds_read_b128 v[188:191], v146 offset:2048
	ds_read_b128 v[196:199], v146 offset:3072
	ds_read_b128 v[200:203], v146 offset:4096
	ds_read_b128 v[204:207], v146 offset:5120
	ds_read_b128 v[208:211], v146 offset:6144
	ds_read_b128 v[212:215], v146 offset:7168
	global_load_lds_dwordx4 v[192:193], off
	v_lshl_add_u64 v[192:193], s[36:37], 0, v[140:141]
	s_add_i32 m0, s55, 0xe000
	s_nop 0
	global_load_lds_dwordx4 v[192:193], off
	s_waitcnt vmcnt(8)
	s_waitcnt lgkmcnt(0)
	s_barrier
	s_setprio 1
	s_waitcnt lgkmcnt(0)
	v_mfma_f32_16x16x32_bf16 v[124:127], v[148:151], v[180:183], v[124:127]
	v_mfma_f32_16x16x32_bf16 v[120:123], v[156:159], v[180:183], v[120:123]
	v_mfma_f32_16x16x32_bf16 v[116:119], v[148:151], v[188:191], v[116:119]
	v_mfma_f32_16x16x32_bf16 v[112:115], v[156:159], v[188:191], v[112:115]
	v_mfma_f32_16x16x32_bf16 v[104:107], v[148:151], v[200:203], v[104:107]
	v_mfma_f32_16x16x32_bf16 v[96:99], v[156:159], v[200:203], v[96:99]
	v_mfma_f32_16x16x32_bf16 v[88:91], v[148:151], v[208:211], v[88:91]
	v_mfma_f32_16x16x32_bf16 v[80:83], v[156:159], v[208:211], v[80:83]
	v_mfma_f32_16x16x32_bf16 v[124:127], v[152:155], v[184:187], v[124:127]
	v_mfma_f32_16x16x32_bf16 v[120:123], v[160:163], v[184:187], v[120:123]
	v_mfma_f32_16x16x32_bf16 v[116:119], v[152:155], v[196:199], v[116:119]
	v_mfma_f32_16x16x32_bf16 v[112:115], v[160:163], v[196:199], v[112:115]
	v_mfma_f32_16x16x32_bf16 v[104:107], v[152:155], v[204:207], v[104:107]
	v_mfma_f32_16x16x32_bf16 v[96:99], v[160:163], v[204:207], v[96:99]
	v_mfma_f32_16x16x32_bf16 v[88:91], v[152:155], v[212:215], v[88:91]
	v_mfma_f32_16x16x32_bf16 v[80:83], v[160:163], v[212:215], v[80:83]
	s_setprio 0
	s_setprio 1
	v_mfma_f32_16x16x32_bf16 v[108:111], v[164:167], v[180:183], v[108:111]
	v_mfma_f32_16x16x32_bf16 v[100:103], v[172:175], v[180:183], v[100:103]
	v_mfma_f32_16x16x32_bf16 v[92:95], v[164:167], v[188:191], v[92:95]
	v_mfma_f32_16x16x32_bf16 v[84:87], v[172:175], v[188:191], v[84:87]
	v_mfma_f32_16x16x32_bf16 v[76:79], v[164:167], v[200:203], v[76:79]
	v_mfma_f32_16x16x32_bf16 v[72:75], v[172:175], v[200:203], v[72:75]
	v_mfma_f32_16x16x32_bf16 v[68:71], v[164:167], v[208:211], v[68:71]
	v_mfma_f32_16x16x32_bf16 v[64:67], v[172:175], v[208:211], v[64:67]
	v_mfma_f32_16x16x32_bf16 v[108:111], v[168:171], v[184:187], v[108:111]
	v_mfma_f32_16x16x32_bf16 v[100:103], v[176:179], v[184:187], v[100:103]
	v_mfma_f32_16x16x32_bf16 v[92:95], v[168:171], v[196:199], v[92:95]
	v_mfma_f32_16x16x32_bf16 v[84:87], v[176:179], v[196:199], v[84:87]
	v_mfma_f32_16x16x32_bf16 v[76:79], v[168:171], v[204:207], v[76:79]
	v_mfma_f32_16x16x32_bf16 v[72:75], v[176:179], v[204:207], v[72:75]
	v_mfma_f32_16x16x32_bf16 v[68:71], v[168:171], v[212:215], v[68:71]
	v_mfma_f32_16x16x32_bf16 v[64:67], v[176:179], v[212:215], v[64:67]
	s_setprio 0
	s_barrier
	s_add_i32 s36, s71, s54
	v_lshl_add_u64 v[192:193], s[40:41], 0, v[132:133]
	s_mov_b32 m0, s36
	ds_read_b128 v[180:183], v146 offset:16384
	ds_read_b128 v[184:187], v146 offset:17408
	ds_read_b128 v[188:191], v146 offset:18432
	ds_read_b128 v[196:199], v146 offset:19456
	ds_read_b128 v[200:203], v146 offset:20480
	ds_read_b128 v[204:207], v146 offset:21504
	ds_read_b128 v[208:211], v146 offset:22528
	ds_read_b128 v[212:215], v146 offset:23552
	global_load_lds_dwordx4 v[192:193], off
	s_add_i32 m0, s36, 0x2000
	s_add_u32 s36, s40, 0x20000
	v_lshl_add_u64 v[216:217], s[40:41], 0, v[128:129]
	s_addc_u32 s37, s41, 0
	s_add_i32 s82, s72, s54
	global_load_lds_dwordx4 v[216:217], off
	s_mov_b32 m0, s82
	v_lshl_add_u64 v[220:221], s[42:43], 0, v[130:131]
	global_load_lds_dwordx4 v132, s[36:37]
	s_add_i32 m0, s82, 0x2000
	s_nop 0
	global_load_lds_dwordx4 v128, s[36:37]
	v_lshl_add_u64 v[218:219], s[42:43], 0, v[134:135]
	s_waitcnt vmcnt(6)
	s_waitcnt lgkmcnt(0)
	s_barrier
	s_setprio 1
	s_waitcnt lgkmcnt(0)
	v_mfma_f32_16x16x32_bf16 v[60:63], v[148:151], v[180:183], v[60:63]
	v_mfma_f32_16x16x32_bf16 v[56:59], v[156:159], v[180:183], v[56:59]
	v_mfma_f32_16x16x32_bf16 v[52:55], v[148:151], v[188:191], v[52:55]
	v_mfma_f32_16x16x32_bf16 v[48:51], v[156:159], v[188:191], v[48:51]
	v_mfma_f32_16x16x32_bf16 v[40:43], v[148:151], v[200:203], v[40:43]
	v_mfma_f32_16x16x32_bf16 v[32:35], v[156:159], v[200:203], v[32:35]
	v_mfma_f32_16x16x32_bf16 v[24:27], v[148:151], v[208:211], v[24:27]
	v_mfma_f32_16x16x32_bf16 v[16:19], v[156:159], v[208:211], v[16:19]
	v_mfma_f32_16x16x32_bf16 v[60:63], v[152:155], v[184:187], v[60:63]
	v_mfma_f32_16x16x32_bf16 v[56:59], v[160:163], v[184:187], v[56:59]
	v_mfma_f32_16x16x32_bf16 v[52:55], v[152:155], v[196:199], v[52:55]
	v_mfma_f32_16x16x32_bf16 v[48:51], v[160:163], v[196:199], v[48:51]
	v_mfma_f32_16x16x32_bf16 v[40:43], v[152:155], v[204:207], v[40:43]
	v_mfma_f32_16x16x32_bf16 v[32:35], v[160:163], v[204:207], v[32:35]
	v_mfma_f32_16x16x32_bf16 v[24:27], v[152:155], v[212:215], v[24:27]
	v_mfma_f32_16x16x32_bf16 v[16:19], v[160:163], v[212:215], v[16:19]
	s_setprio 0
	s_setprio 1
	v_mfma_f32_16x16x32_bf16 v[44:47], v[164:167], v[180:183], v[44:47]
	v_mfma_f32_16x16x32_bf16 v[36:39], v[172:175], v[180:183], v[36:39]
	v_mfma_f32_16x16x32_bf16 v[28:31], v[164:167], v[188:191], v[28:31]
	v_mfma_f32_16x16x32_bf16 v[20:23], v[172:175], v[188:191], v[20:23]
	v_mfma_f32_16x16x32_bf16 v[12:15], v[164:167], v[200:203], v[12:15]
	v_mfma_f32_16x16x32_bf16 v[8:11], v[172:175], v[200:203], v[8:11]
	v_mfma_f32_16x16x32_bf16 v[4:7], v[164:167], v[208:211], v[4:7]
	v_mfma_f32_16x16x32_bf16 v[0:3], v[172:175], v[208:211], v[0:3]
	v_mfma_f32_16x16x32_bf16 v[44:47], v[168:171], v[184:187], v[44:47]
	v_mfma_f32_16x16x32_bf16 v[36:39], v[176:179], v[184:187], v[36:39]
	v_mfma_f32_16x16x32_bf16 v[28:31], v[168:171], v[196:199], v[28:31]
	v_mfma_f32_16x16x32_bf16 v[20:23], v[176:179], v[196:199], v[20:23]
	v_mfma_f32_16x16x32_bf16 v[12:15], v[168:171], v[204:207], v[12:15]
	v_mfma_f32_16x16x32_bf16 v[8:11], v[176:179], v[204:207], v[8:11]
	v_mfma_f32_16x16x32_bf16 v[4:7], v[168:171], v[212:215], v[4:7]
	v_mfma_f32_16x16x32_bf16 v[0:3], v[176:179], v[212:215], v[0:3]
	s_setprio 0
	s_barrier
	s_add_i32 s82, 0, 0x18000
	v_add_u32_e32 v147, s82, v143
	s_add_i32 s83, 0, 0x1c000
	ds_read_b128 v[148:151], v147
	ds_read_b128 v[152:155], v147 offset:1024
	ds_read_b128 v[156:159], v147 offset:2048
	ds_read_b128 v[160:163], v147 offset:3072
	v_add_u32_e32 v147, s83, v143
	ds_read_b128 v[164:167], v147
	ds_read_b128 v[168:171], v147 offset:1024
	ds_read_b128 v[172:175], v147 offset:2048
	ds_read_b128 v[176:179], v147 offset:3072
	s_add_u32 s36, s42, 0x30000
	s_addc_u32 s37, s43, 0
	ds_read_b128 v[180:183], v146 offset:32768
	ds_read_b128 v[184:187], v146 offset:33792
	ds_read_b128 v[188:191], v146 offset:34816
	ds_read_b128 v[196:199], v146 offset:35840
	ds_read_b128 v[200:203], v146 offset:36864
	ds_read_b128 v[204:207], v146 offset:37888
	ds_read_b128 v[208:211], v146 offset:38912
	ds_read_b128 v[212:215], v146 offset:39936
	s_mov_b32 m0, s55
	s_nop 0
	global_load_lds_dwordx4 v[218:219], off
	s_mov_b32 m0, s56
	s_nop 0
	global_load_lds_dwordx4 v[220:221], off
	s_mov_b32 m0, s57
	s_nop 0
	global_load_lds_dwordx4 v134, s[36:37]
	s_mov_b32 m0, s58
	s_nop 0
	global_load_lds_dwordx4 v130, s[36:37]
	s_waitcnt vmcnt(8)
	s_waitcnt lgkmcnt(0)
	s_barrier
	s_setprio 1
	s_waitcnt lgkmcnt(0)
	v_mfma_f32_16x16x32_bf16 v[124:127], v[148:151], v[180:183], v[124:127]
	v_mfma_f32_16x16x32_bf16 v[120:123], v[156:159], v[180:183], v[120:123]
	v_mfma_f32_16x16x32_bf16 v[116:119], v[148:151], v[188:191], v[116:119]
	v_mfma_f32_16x16x32_bf16 v[112:115], v[156:159], v[188:191], v[112:115]
	v_mfma_f32_16x16x32_bf16 v[104:107], v[148:151], v[200:203], v[104:107]
	v_mfma_f32_16x16x32_bf16 v[96:99], v[156:159], v[200:203], v[96:99]
	v_mfma_f32_16x16x32_bf16 v[88:91], v[148:151], v[208:211], v[88:91]
	v_mfma_f32_16x16x32_bf16 v[80:83], v[156:159], v[208:211], v[80:83]
	v_mfma_f32_16x16x32_bf16 v[124:127], v[152:155], v[184:187], v[124:127]
	v_mfma_f32_16x16x32_bf16 v[120:123], v[160:163], v[184:187], v[120:123]
	v_mfma_f32_16x16x32_bf16 v[116:119], v[152:155], v[196:199], v[116:119]
	v_mfma_f32_16x16x32_bf16 v[112:115], v[160:163], v[196:199], v[112:115]
	v_mfma_f32_16x16x32_bf16 v[104:107], v[152:155], v[204:207], v[104:107]
	v_mfma_f32_16x16x32_bf16 v[96:99], v[160:163], v[204:207], v[96:99]
	v_mfma_f32_16x16x32_bf16 v[88:91], v[152:155], v[212:215], v[88:91]
	v_mfma_f32_16x16x32_bf16 v[80:83], v[160:163], v[212:215], v[80:83]
	s_setprio 0
	s_setprio 1
	v_mfma_f32_16x16x32_bf16 v[108:111], v[164:167], v[180:183], v[108:111]
	v_mfma_f32_16x16x32_bf16 v[100:103], v[172:175], v[180:183], v[100:103]
	v_mfma_f32_16x16x32_bf16 v[92:95], v[164:167], v[188:191], v[92:95]
	v_mfma_f32_16x16x32_bf16 v[84:87], v[172:175], v[188:191], v[84:87]
	v_mfma_f32_16x16x32_bf16 v[76:79], v[164:167], v[200:203], v[76:79]
	v_mfma_f32_16x16x32_bf16 v[72:75], v[172:175], v[200:203], v[72:75]
	v_mfma_f32_16x16x32_bf16 v[68:71], v[164:167], v[208:211], v[68:71]
	v_mfma_f32_16x16x32_bf16 v[64:67], v[172:175], v[208:211], v[64:67]
	v_mfma_f32_16x16x32_bf16 v[108:111], v[168:171], v[184:187], v[108:111]
	v_mfma_f32_16x16x32_bf16 v[100:103], v[176:179], v[184:187], v[100:103]
	v_mfma_f32_16x16x32_bf16 v[92:95], v[168:171], v[196:199], v[92:95]
	v_mfma_f32_16x16x32_bf16 v[84:87], v[176:179], v[196:199], v[84:87]
	v_mfma_f32_16x16x32_bf16 v[76:79], v[168:171], v[204:207], v[76:79]
	v_mfma_f32_16x16x32_bf16 v[72:75], v[176:179], v[204:207], v[72:75]
	v_mfma_f32_16x16x32_bf16 v[68:71], v[168:171], v[212:215], v[68:71]
	v_mfma_f32_16x16x32_bf16 v[64:67], v[176:179], v[212:215], v[64:67]
	s_setprio 0
	s_barrier
	s_add_i32 s36, s82, s54
	v_lshl_add_u64 v[192:193], v[192:193], 0, s[14:15]
	s_mov_b32 m0, s36
	ds_read_b128 v[180:183], v146 offset:49152
	ds_read_b128 v[184:187], v146 offset:50176
	ds_read_b128 v[188:191], v146 offset:51200
	ds_read_b128 v[196:199], v146 offset:52224
	ds_read_b128 v[200:203], v146 offset:53248
	ds_read_b128 v[204:207], v146 offset:54272
	ds_read_b128 v[208:211], v146 offset:55296
	ds_read_b128 v[212:215], v146 offset:56320
	global_load_lds_dwordx4 v[192:193], off
	s_add_i32 m0, s36, 0x2000
	s_add_u32 s36, s40, 0x20080
	v_lshl_add_u64 v[192:193], v[216:217], 0, s[14:15]
	s_addc_u32 s37, s41, 0
	s_add_i32 s40, s83, s54
	global_load_lds_dwordx4 v[192:193], off
	s_mov_b32 m0, s40
	s_nop 0
	global_load_lds_dwordx4 v132, s[36:37]
	s_add_i32 m0, s40, 0x2000
	s_nop 0
	global_load_lds_dwordx4 v128, s[36:37]
	s_waitcnt vmcnt(6)
	s_waitcnt lgkmcnt(0)
	s_barrier
	s_setprio 1
	s_waitcnt lgkmcnt(0)
	v_mfma_f32_16x16x32_bf16 v[60:63], v[148:151], v[180:183], v[60:63]
	v_mfma_f32_16x16x32_bf16 v[56:59], v[156:159], v[180:183], v[56:59]
	v_mfma_f32_16x16x32_bf16 v[52:55], v[148:151], v[188:191], v[52:55]
	v_mfma_f32_16x16x32_bf16 v[48:51], v[156:159], v[188:191], v[48:51]
	v_mfma_f32_16x16x32_bf16 v[40:43], v[148:151], v[200:203], v[40:43]
	v_mfma_f32_16x16x32_bf16 v[32:35], v[156:159], v[200:203], v[32:35]
	v_mfma_f32_16x16x32_bf16 v[24:27], v[148:151], v[208:211], v[24:27]
	v_mfma_f32_16x16x32_bf16 v[16:19], v[156:159], v[208:211], v[16:19]
	v_mfma_f32_16x16x32_bf16 v[60:63], v[152:155], v[184:187], v[60:63]
	v_mfma_f32_16x16x32_bf16 v[56:59], v[160:163], v[184:187], v[56:59]
	v_mfma_f32_16x16x32_bf16 v[52:55], v[152:155], v[196:199], v[52:55]
	v_mfma_f32_16x16x32_bf16 v[48:51], v[160:163], v[196:199], v[48:51]
	v_mfma_f32_16x16x32_bf16 v[40:43], v[152:155], v[204:207], v[40:43]
	v_mfma_f32_16x16x32_bf16 v[32:35], v[160:163], v[204:207], v[32:35]
	v_mfma_f32_16x16x32_bf16 v[24:27], v[152:155], v[212:215], v[24:27]
	v_mfma_f32_16x16x32_bf16 v[16:19], v[160:163], v[212:215], v[16:19]
	s_setprio 0
	s_setprio 1
	v_mfma_f32_16x16x32_bf16 v[44:47], v[164:167], v[180:183], v[44:47]
	v_mfma_f32_16x16x32_bf16 v[36:39], v[172:175], v[180:183], v[36:39]
	v_mfma_f32_16x16x32_bf16 v[28:31], v[164:167], v[188:191], v[28:31]
	v_mfma_f32_16x16x32_bf16 v[20:23], v[172:175], v[188:191], v[20:23]
	v_mfma_f32_16x16x32_bf16 v[12:15], v[164:167], v[200:203], v[12:15]
	v_mfma_f32_16x16x32_bf16 v[8:11], v[172:175], v[200:203], v[8:11]
	v_mfma_f32_16x16x32_bf16 v[4:7], v[164:167], v[208:211], v[4:7]
	v_mfma_f32_16x16x32_bf16 v[0:3], v[172:175], v[208:211], v[0:3]
	v_mfma_f32_16x16x32_bf16 v[44:47], v[168:171], v[184:187], v[44:47]
	v_mfma_f32_16x16x32_bf16 v[36:39], v[176:179], v[184:187], v[36:39]
	v_mfma_f32_16x16x32_bf16 v[28:31], v[168:171], v[196:199], v[28:31]
	v_mfma_f32_16x16x32_bf16 v[20:23], v[176:179], v[196:199], v[20:23]
	v_mfma_f32_16x16x32_bf16 v[12:15], v[168:171], v[204:207], v[12:15]
	v_mfma_f32_16x16x32_bf16 v[8:11], v[176:179], v[204:207], v[8:11]
	v_mfma_f32_16x16x32_bf16 v[4:7], v[168:171], v[212:215], v[4:7]
	v_mfma_f32_16x16x32_bf16 v[0:3], v[176:179], v[212:215], v[0:3]
	s_setprio 0
	s_barrier
	v_lshl_add_u64 v[218:219], v[218:219], 0, s[14:15]
	s_mov_b32 m0, s62
	s_nop 0
	global_load_lds_dwordx4 v[218:219], off
	v_lshl_add_u64 v[220:221], v[220:221], 0, s[14:15]
	s_mov_b32 m0, s63
	s_nop 0
	global_load_lds_dwordx4 v[220:221], off
	s_add_i32 s81, s81, 2
	s_add_u32 s17, s17, 0x100
	s_addc_u32 s27, s27, 0
	s_cmp_gt_u32 s81, 5
	s_mov_b64 s[36:37], s[38:39]
	s_cbranch_scc0 .LBB0_2370
	s_and_b64 vcc, exec, s[18:19]
	s_cbranch_vccz .LBB0_2373
	s_barrier

.LBB0_2396:
	ds_read_b128 v[144:147], v153
	ds_read_b128 v[158:161], v153 offset:1024
	ds_read_b128 v[162:165], v153 offset:2048
	ds_read_b128 v[166:169], v153 offset:3072
	ds_read_b128 v[170:173], v154
	ds_read_b128 v[174:177], v154 offset:1024
	ds_read_b128 v[178:181], v154 offset:2048
	ds_read_b128 v[182:185], v154 offset:3072
	s_add_u32 s36, s34, 0xfffc0080
	s_addc_u32 s37, s35, -1
	s_cmp_eq_u32 s78, 12
	s_cselect_b32 s39, s27, s37
	s_cselect_b32 s38, s71, s36
	s_cselect_b32 s37, s25, s77
	s_cselect_b32 s36, s72, s73
	s_add_i32 m0, s53, 0xc000
	ds_read_b128 v[186:189], v155
	ds_read_b128 v[190:193], v155 offset:1024
	ds_read_b128 v[196:199], v155 offset:2048
	ds_read_b128 v[200:203], v155 offset:3072
	ds_read_b128 v[204:207], v155 offset:4096
	ds_read_b128 v[208:211], v155 offset:5120
	ds_read_b128 v[212:215], v155 offset:6144
	ds_read_b128 v[216:219], v155 offset:7168
	global_load_lds_dwordx4 v136, s[34:35]
	s_add_i32 m0, s53, 0xe000
	s_nop 0
	global_load_lds_dwordx4 v138, s[34:35]
	s_waitcnt vmcnt(8)
	s_waitcnt lgkmcnt(0)
	s_barrier
	s_setprio 1
	s_waitcnt lgkmcnt(0)
	v_mfma_f32_16x16x32_bf16 v[124:127], v[144:147], v[186:189], v[124:127]
	v_mfma_f32_16x16x32_bf16 v[120:123], v[162:165], v[186:189], v[120:123]
	v_mfma_f32_16x16x32_bf16 v[108:111], v[144:147], v[196:199], v[108:111]
	v_mfma_f32_16x16x32_bf16 v[104:107], v[162:165], v[196:199], v[104:107]
	v_mfma_f32_16x16x32_bf16 v[92:95], v[144:147], v[204:207], v[92:95]
	v_mfma_f32_16x16x32_bf16 v[88:91], v[162:165], v[204:207], v[88:91]
	v_mfma_f32_16x16x32_bf16 v[76:79], v[144:147], v[212:215], v[76:79]
	v_mfma_f32_16x16x32_bf16 v[72:75], v[162:165], v[212:215], v[72:75]
	v_mfma_f32_16x16x32_bf16 v[124:127], v[158:161], v[190:193], v[124:127]
	v_mfma_f32_16x16x32_bf16 v[120:123], v[166:169], v[190:193], v[120:123]
	v_mfma_f32_16x16x32_bf16 v[108:111], v[158:161], v[200:203], v[108:111]
	v_mfma_f32_16x16x32_bf16 v[104:107], v[166:169], v[200:203], v[104:107]
	v_mfma_f32_16x16x32_bf16 v[92:95], v[158:161], v[208:211], v[92:95]
	v_mfma_f32_16x16x32_bf16 v[88:91], v[166:169], v[208:211], v[88:91]
	v_mfma_f32_16x16x32_bf16 v[76:79], v[158:161], v[216:219], v[76:79]
	v_mfma_f32_16x16x32_bf16 v[72:75], v[166:169], v[216:219], v[72:75]
	s_setprio 0
	s_setprio 1
	v_mfma_f32_16x16x32_bf16 v[116:119], v[170:173], v[186:189], v[116:119]
	v_mfma_f32_16x16x32_bf16 v[112:115], v[178:181], v[186:189], v[112:115]
	v_mfma_f32_16x16x32_bf16 v[100:103], v[170:173], v[196:199], v[100:103]
	v_mfma_f32_16x16x32_bf16 v[96:99], v[178:181], v[196:199], v[96:99]
	v_mfma_f32_16x16x32_bf16 v[84:87], v[170:173], v[204:207], v[84:87]
	v_mfma_f32_16x16x32_bf16 v[80:83], v[178:181], v[204:207], v[80:83]
	v_mfma_f32_16x16x32_bf16 v[68:71], v[170:173], v[212:215], v[68:71]
	v_mfma_f32_16x16x32_bf16 v[64:67], v[178:181], v[212:215], v[64:67]
	v_mfma_f32_16x16x32_bf16 v[116:119], v[174:177], v[190:193], v[116:119]
	v_mfma_f32_16x16x32_bf16 v[112:115], v[182:185], v[190:193], v[112:115]
	v_mfma_f32_16x16x32_bf16 v[100:103], v[174:177], v[200:203], v[100:103]
	v_mfma_f32_16x16x32_bf16 v[96:99], v[182:185], v[200:203], v[96:99]
	v_mfma_f32_16x16x32_bf16 v[84:87], v[174:177], v[208:211], v[84:87]
	v_mfma_f32_16x16x32_bf16 v[80:83], v[182:185], v[208:211], v[80:83]
	v_mfma_f32_16x16x32_bf16 v[68:71], v[174:177], v[216:219], v[68:71]
	v_mfma_f32_16x16x32_bf16 v[64:67], v[182:185], v[216:219], v[64:67]
	s_setprio 0
	s_barrier
	s_add_i32 s79, s61, s52
	v_lshl_add_u64 v[148:149], s[36:37], 0, v[130:131]
	s_mov_b32 m0, s79
	ds_read_b128 v[186:189], v155 offset:16384
	ds_read_b128 v[190:193], v155 offset:17408
	ds_read_b128 v[196:199], v155 offset:18432
	ds_read_b128 v[200:203], v155 offset:19456
	ds_read_b128 v[204:207], v155 offset:20480
	ds_read_b128 v[208:211], v155 offset:21504
	ds_read_b128 v[212:215], v155 offset:22528
	ds_read_b128 v[216:219], v155 offset:23552
	global_load_lds_dwordx4 v[148:149], off
	s_add_i32 m0, s79, 0x2000
	s_add_u32 s80, s36, 0x40000
	v_lshl_add_u64 v[220:221], s[36:37], 0, v[134:135]
	s_addc_u32 s81, s37, 0
	s_add_i32 s79, s62, s52
	global_load_lds_dwordx4 v[220:221], off
	s_mov_b32 m0, s79
	v_lshl_add_u64 v[224:225], s[38:39], 0, v[132:133]
	global_load_lds_dwordx4 v130, s[80:81]
	s_add_i32 m0, s79, 0x2000
	s_nop 0
	global_load_lds_dwordx4 v134, s[80:81]
	v_lshl_add_u64 v[222:223], s[38:39], 0, v[128:129]
	s_waitcnt vmcnt(6)
	s_waitcnt lgkmcnt(0)
	s_barrier
	s_setprio 1
	s_waitcnt lgkmcnt(0)
	v_mfma_f32_16x16x32_bf16 v[60:63], v[144:147], v[186:189], v[60:63]
	v_mfma_f32_16x16x32_bf16 v[56:59], v[162:165], v[186:189], v[56:59]
	v_mfma_f32_16x16x32_bf16 v[44:47], v[144:147], v[196:199], v[44:47]
	v_mfma_f32_16x16x32_bf16 v[40:43], v[162:165], v[196:199], v[40:43]
	v_mfma_f32_16x16x32_bf16 v[28:31], v[144:147], v[204:207], v[28:31]
	v_mfma_f32_16x16x32_bf16 v[24:27], v[162:165], v[204:207], v[24:27]
	v_mfma_f32_16x16x32_bf16 v[12:15], v[144:147], v[212:215], v[12:15]
	v_mfma_f32_16x16x32_bf16 v[8:11], v[162:165], v[212:215], v[8:11]
	v_mfma_f32_16x16x32_bf16 v[60:63], v[158:161], v[190:193], v[60:63]
	v_mfma_f32_16x16x32_bf16 v[56:59], v[166:169], v[190:193], v[56:59]
	v_mfma_f32_16x16x32_bf16 v[44:47], v[158:161], v[200:203], v[44:47]
	v_mfma_f32_16x16x32_bf16 v[40:43], v[166:169], v[200:203], v[40:43]
	v_mfma_f32_16x16x32_bf16 v[28:31], v[158:161], v[208:211], v[28:31]
	v_mfma_f32_16x16x32_bf16 v[24:27], v[166:169], v[208:211], v[24:27]
	v_mfma_f32_16x16x32_bf16 v[12:15], v[158:161], v[216:219], v[12:15]
	v_mfma_f32_16x16x32_bf16 v[8:11], v[166:169], v[216:219], v[8:11]
	s_setprio 0
	s_setprio 1
	v_mfma_f32_16x16x32_bf16 v[52:55], v[170:173], v[186:189], v[52:55]
	v_mfma_f32_16x16x32_bf16 v[48:51], v[178:181], v[186:189], v[48:51]
	v_mfma_f32_16x16x32_bf16 v[36:39], v[170:173], v[196:199], v[36:39]
	v_mfma_f32_16x16x32_bf16 v[32:35], v[178:181], v[196:199], v[32:35]
	v_mfma_f32_16x16x32_bf16 v[20:23], v[170:173], v[204:207], v[20:23]
	v_mfma_f32_16x16x32_bf16 v[16:19], v[178:181], v[204:207], v[16:19]
	v_mfma_f32_16x16x32_bf16 v[4:7], v[170:173], v[212:215], v[4:7]
	v_mfma_f32_16x16x32_bf16 v[0:3], v[178:181], v[212:215], v[0:3]
	v_mfma_f32_16x16x32_bf16 v[52:55], v[174:177], v[190:193], v[52:55]
	v_mfma_f32_16x16x32_bf16 v[48:51], v[182:185], v[190:193], v[48:51]
	v_mfma_f32_16x16x32_bf16 v[36:39], v[174:177], v[200:203], v[36:39]
	v_mfma_f32_16x16x32_bf16 v[32:35], v[182:185], v[200:203], v[32:35]
	v_mfma_f32_16x16x32_bf16 v[20:23], v[174:177], v[208:211], v[20:23]
	v_mfma_f32_16x16x32_bf16 v[16:19], v[182:185], v[208:211], v[16:19]
	v_mfma_f32_16x16x32_bf16 v[4:7], v[174:177], v[216:219], v[4:7]
	v_mfma_f32_16x16x32_bf16 v[0:3], v[182:185], v[216:219], v[0:3]
	s_setprio 0
	s_barrier
	s_add_i32 s79, 0, 0x18000
	v_add_u32_e32 v157, s79, v151
	s_add_i32 s80, 0, 0x1c000
	ds_read_b128 v[144:147], v157
	ds_read_b128 v[158:161], v157 offset:1024
	ds_read_b128 v[162:165], v157 offset:2048
	ds_read_b128 v[166:169], v157 offset:3072
	v_add_u32_e32 v157, s80, v151
	ds_read_b128 v[170:173], v157
	ds_read_b128 v[174:177], v157 offset:1024
	ds_read_b128 v[178:181], v157 offset:2048
	ds_read_b128 v[182:185], v157 offset:3072
	s_add_u32 s38, s38, 0x40000
	s_addc_u32 s39, s39, 0
	ds_read_b128 v[186:189], v155 offset:32768
	ds_read_b128 v[190:193], v155 offset:33792
	ds_read_b128 v[196:199], v155 offset:34816
	ds_read_b128 v[200:203], v155 offset:35840
	ds_read_b128 v[204:207], v155 offset:36864
	ds_read_b128 v[208:211], v155 offset:37888
	ds_read_b128 v[212:215], v155 offset:38912
	ds_read_b128 v[216:219], v155 offset:39936
	s_mov_b32 m0, s53
	s_nop 0
	global_load_lds_dwordx4 v[222:223], off
	s_mov_b32 m0, s54
	s_nop 0
	global_load_lds_dwordx4 v[224:225], off
	s_mov_b32 m0, s55
	s_nop 0
	global_load_lds_dwordx4 v128, s[38:39]
	s_mov_b32 m0, s56
	s_nop 0
	global_load_lds_dwordx4 v132, s[38:39]
	s_waitcnt vmcnt(8)
	s_waitcnt lgkmcnt(0)
	s_barrier
	s_setprio 1
	s_waitcnt lgkmcnt(0)
	v_mfma_f32_16x16x32_bf16 v[124:127], v[144:147], v[186:189], v[124:127]
	v_mfma_f32_16x16x32_bf16 v[120:123], v[162:165], v[186:189], v[120:123]
	v_mfma_f32_16x16x32_bf16 v[108:111], v[144:147], v[196:199], v[108:111]
	v_mfma_f32_16x16x32_bf16 v[104:107], v[162:165], v[196:199], v[104:107]
	v_mfma_f32_16x16x32_bf16 v[92:95], v[144:147], v[204:207], v[92:95]
	v_mfma_f32_16x16x32_bf16 v[88:91], v[162:165], v[204:207], v[88:91]
	v_mfma_f32_16x16x32_bf16 v[76:79], v[144:147], v[212:215], v[76:79]
	v_mfma_f32_16x16x32_bf16 v[72:75], v[162:165], v[212:215], v[72:75]
	v_mfma_f32_16x16x32_bf16 v[124:127], v[158:161], v[190:193], v[124:127]
	v_mfma_f32_16x16x32_bf16 v[120:123], v[166:169], v[190:193], v[120:123]
	v_mfma_f32_16x16x32_bf16 v[108:111], v[158:161], v[200:203], v[108:111]
	v_mfma_f32_16x16x32_bf16 v[104:107], v[166:169], v[200:203], v[104:107]
	v_mfma_f32_16x16x32_bf16 v[92:95], v[158:161], v[208:211], v[92:95]
	v_mfma_f32_16x16x32_bf16 v[88:91], v[166:169], v[208:211], v[88:91]
	v_mfma_f32_16x16x32_bf16 v[76:79], v[158:161], v[216:219], v[76:79]
	v_mfma_f32_16x16x32_bf16 v[72:75], v[166:169], v[216:219], v[72:75]
	s_setprio 0
	s_setprio 1
	v_mfma_f32_16x16x32_bf16 v[116:119], v[170:173], v[186:189], v[116:119]
	v_mfma_f32_16x16x32_bf16 v[112:115], v[178:181], v[186:189], v[112:115]
	v_mfma_f32_16x16x32_bf16 v[100:103], v[170:173], v[196:199], v[100:103]
	v_mfma_f32_16x16x32_bf16 v[96:99], v[178:181], v[196:199], v[96:99]
	v_mfma_f32_16x16x32_bf16 v[84:87], v[170:173], v[204:207], v[84:87]
	v_mfma_f32_16x16x32_bf16 v[80:83], v[178:181], v[204:207], v[80:83]
	v_mfma_f32_16x16x32_bf16 v[68:71], v[170:173], v[212:215], v[68:71]
	v_mfma_f32_16x16x32_bf16 v[64:67], v[178:181], v[212:215], v[64:67]
	v_mfma_f32_16x16x32_bf16 v[116:119], v[174:177], v[190:193], v[116:119]
	v_mfma_f32_16x16x32_bf16 v[112:115], v[182:185], v[190:193], v[112:115]
	v_mfma_f32_16x16x32_bf16 v[100:103], v[174:177], v[200:203], v[100:103]
	v_mfma_f32_16x16x32_bf16 v[96:99], v[182:185], v[200:203], v[96:99]
	v_mfma_f32_16x16x32_bf16 v[84:87], v[174:177], v[208:211], v[84:87]
	v_mfma_f32_16x16x32_bf16 v[80:83], v[182:185], v[208:211], v[80:83]
	v_mfma_f32_16x16x32_bf16 v[68:71], v[174:177], v[216:219], v[68:71]
	v_mfma_f32_16x16x32_bf16 v[64:67], v[182:185], v[216:219], v[64:67]
	s_setprio 0
	s_barrier
	s_add_i32 s38, s79, s52
	v_lshl_add_u64 v[148:149], v[148:149], 0, s[20:21]
	s_mov_b32 m0, s38
	ds_read_b128 v[186:189], v155 offset:49152
	ds_read_b128 v[190:193], v155 offset:50176
	ds_read_b128 v[196:199], v155 offset:51200
	ds_read_b128 v[200:203], v155 offset:52224
	ds_read_b128 v[204:207], v155 offset:53248
	ds_read_b128 v[208:211], v155 offset:54272
	ds_read_b128 v[212:215], v155 offset:55296
	ds_read_b128 v[216:219], v155 offset:56320
	global_load_lds_dwordx4 v[148:149], off
	s_add_i32 m0, s38, 0x2000
	s_add_u32 s36, s36, 0x40080
	v_lshl_add_u64 v[148:149], v[220:221], 0, s[20:21]
	s_addc_u32 s37, s37, 0
	s_add_i32 s38, s80, s52
	global_load_lds_dwordx4 v[148:149], off
	s_mov_b32 m0, s38
	s_nop 0
	global_load_lds_dwordx4 v130, s[36:37]
	s_add_i32 m0, s38, 0x2000
	s_nop 0
	global_load_lds_dwordx4 v134, s[36:37]
	s_waitcnt vmcnt(6)
	s_waitcnt lgkmcnt(0)
	s_barrier
	s_setprio 1
	s_waitcnt lgkmcnt(0)
	v_mfma_f32_16x16x32_bf16 v[60:63], v[144:147], v[186:189], v[60:63]
	v_mfma_f32_16x16x32_bf16 v[56:59], v[162:165], v[186:189], v[56:59]
	v_mfma_f32_16x16x32_bf16 v[44:47], v[144:147], v[196:199], v[44:47]
	v_mfma_f32_16x16x32_bf16 v[40:43], v[162:165], v[196:199], v[40:43]
	v_mfma_f32_16x16x32_bf16 v[28:31], v[144:147], v[204:207], v[28:31]
	v_mfma_f32_16x16x32_bf16 v[24:27], v[162:165], v[204:207], v[24:27]
	v_mfma_f32_16x16x32_bf16 v[12:15], v[144:147], v[212:215], v[12:15]
	v_mfma_f32_16x16x32_bf16 v[8:11], v[162:165], v[212:215], v[8:11]
	v_mfma_f32_16x16x32_bf16 v[60:63], v[158:161], v[190:193], v[60:63]
	v_mfma_f32_16x16x32_bf16 v[56:59], v[166:169], v[190:193], v[56:59]
	v_mfma_f32_16x16x32_bf16 v[44:47], v[158:161], v[200:203], v[44:47]
	v_mfma_f32_16x16x32_bf16 v[40:43], v[166:169], v[200:203], v[40:43]
	v_mfma_f32_16x16x32_bf16 v[28:31], v[158:161], v[208:211], v[28:31]
	v_mfma_f32_16x16x32_bf16 v[24:27], v[166:169], v[208:211], v[24:27]
	v_mfma_f32_16x16x32_bf16 v[12:15], v[158:161], v[216:219], v[12:15]
	v_mfma_f32_16x16x32_bf16 v[8:11], v[166:169], v[216:219], v[8:11]
	s_setprio 0
	s_setprio 1
	v_mfma_f32_16x16x32_bf16 v[52:55], v[170:173], v[186:189], v[52:55]
	v_mfma_f32_16x16x32_bf16 v[48:51], v[178:181], v[186:189], v[48:51]
	v_mfma_f32_16x16x32_bf16 v[36:39], v[170:173], v[196:199], v[36:39]
	v_mfma_f32_16x16x32_bf16 v[32:35], v[178:181], v[196:199], v[32:35]
	v_mfma_f32_16x16x32_bf16 v[20:23], v[170:173], v[204:207], v[20:23]
	v_mfma_f32_16x16x32_bf16 v[16:19], v[178:181], v[204:207], v[16:19]
	v_mfma_f32_16x16x32_bf16 v[4:7], v[170:173], v[212:215], v[4:7]
	v_mfma_f32_16x16x32_bf16 v[0:3], v[178:181], v[212:215], v[0:3]
	v_mfma_f32_16x16x32_bf16 v[52:55], v[174:177], v[190:193], v[52:55]
	v_mfma_f32_16x16x32_bf16 v[48:51], v[182:185], v[190:193], v[48:51]
	v_mfma_f32_16x16x32_bf16 v[36:39], v[174:177], v[200:203], v[36:39]
	v_mfma_f32_16x16x32_bf16 v[32:35], v[182:185], v[200:203], v[32:35]
	v_mfma_f32_16x16x32_bf16 v[20:23], v[174:177], v[208:211], v[20:23]
	v_mfma_f32_16x16x32_bf16 v[16:19], v[182:185], v[208:211], v[16:19]
	v_mfma_f32_16x16x32_bf16 v[4:7], v[174:177], v[216:219], v[4:7]
	v_mfma_f32_16x16x32_bf16 v[0:3], v[182:185], v[216:219], v[0:3]
	s_setprio 0
	s_barrier
	v_lshl_add_u64 v[222:223], v[222:223], 0, s[20:21]
	s_mov_b32 m0, s58
	s_nop 0
	global_load_lds_dwordx4 v[222:223], off
	v_lshl_add_u64 v[224:225], v[224:225], 0, s[20:21]
	s_mov_b32 m0, s59
	s_nop 0
	global_load_lds_dwordx4 v[224:225], off
	s_add_i32 s78, s78, 2
	s_add_u32 s34, s34, 0x100
	s_addc_u32 s35, s35, 0
	s_add_u32 s73, s73, 0x100
	s_addc_u32 s77, s77, 0
	s_cmp_gt_u32 s78, 13
	s_cbranch_scc0 .LBB0_2396
	s_and_b64 vcc, exec, s[22:23]
	s_cbranch_vccz .LBB0_2399
	s_barrier

.LBB0_2533:
	ds_read_b128 v[152:155], v148
	ds_read_b128 v[156:159], v148 offset:1024
	ds_read_b128 v[160:163], v148 offset:2048
	ds_read_b128 v[164:167], v148 offset:3072
	ds_read_b128 v[168:171], v149
	ds_read_b128 v[172:175], v149 offset:1024
	ds_read_b128 v[176:179], v149 offset:2048
	ds_read_b128 v[180:183], v149 offset:3072
	s_add_u32 s26, s24, 0x100
	s_addc_u32 s27, s25, 0
	s_cmp_eq_u32 s62, 8
	s_cselect_b32 s31, s21, s27
	s_cselect_b32 s30, s20, s26
	s_cselect_b32 s29, s23, s61
	s_cselect_b32 s28, s22, s60
	s_mov_b32 m0, s53
	v_lshl_add_u64 v[192:193], s[24:25], 0, v[138:139]
	ds_read_b128 v[184:187], v150
	ds_read_b128 v[188:191], v150 offset:1024
	ds_read_b128 v[196:199], v150 offset:2048
	ds_read_b128 v[200:203], v150 offset:3072
	ds_read_b128 v[204:207], v150 offset:4096
	ds_read_b128 v[208:211], v150 offset:5120
	ds_read_b128 v[212:215], v150 offset:6144
	ds_read_b128 v[216:219], v150 offset:7168
	global_load_lds_dwordx4 v[192:193], off
	v_lshl_add_u64 v[192:193], s[24:25], 0, v[140:141]
	s_add_i32 m0, s40, 0xe000
	s_nop 0
	global_load_lds_dwordx4 v[192:193], off
	s_waitcnt vmcnt(8)
	s_waitcnt lgkmcnt(0)
	s_barrier
	s_setprio 1
	s_waitcnt lgkmcnt(0)
	v_mfma_f32_16x16x32_bf16 v[124:127], v[152:155], v[184:187], v[124:127]
	v_mfma_f32_16x16x32_bf16 v[120:123], v[160:163], v[184:187], v[120:123]
	v_mfma_f32_16x16x32_bf16 v[108:111], v[152:155], v[196:199], v[108:111]
	v_mfma_f32_16x16x32_bf16 v[104:107], v[160:163], v[196:199], v[104:107]
	v_mfma_f32_16x16x32_bf16 v[92:95], v[152:155], v[204:207], v[92:95]
	v_mfma_f32_16x16x32_bf16 v[88:91], v[160:163], v[204:207], v[88:91]
	v_mfma_f32_16x16x32_bf16 v[76:79], v[152:155], v[212:215], v[76:79]
	v_mfma_f32_16x16x32_bf16 v[72:75], v[160:163], v[212:215], v[72:75]
	v_mfma_f32_16x16x32_bf16 v[124:127], v[156:159], v[188:191], v[124:127]
	v_mfma_f32_16x16x32_bf16 v[120:123], v[164:167], v[188:191], v[120:123]
	v_mfma_f32_16x16x32_bf16 v[108:111], v[156:159], v[200:203], v[108:111]
	v_mfma_f32_16x16x32_bf16 v[104:107], v[164:167], v[200:203], v[104:107]
	v_mfma_f32_16x16x32_bf16 v[92:95], v[156:159], v[208:211], v[92:95]
	v_mfma_f32_16x16x32_bf16 v[88:91], v[164:167], v[208:211], v[88:91]
	v_mfma_f32_16x16x32_bf16 v[76:79], v[156:159], v[216:219], v[76:79]
	v_mfma_f32_16x16x32_bf16 v[72:75], v[164:167], v[216:219], v[72:75]
	s_setprio 0
	s_setprio 1
	v_mfma_f32_16x16x32_bf16 v[116:119], v[168:171], v[184:187], v[116:119]
	v_mfma_f32_16x16x32_bf16 v[112:115], v[176:179], v[184:187], v[112:115]
	v_mfma_f32_16x16x32_bf16 v[100:103], v[168:171], v[196:199], v[100:103]
	v_mfma_f32_16x16x32_bf16 v[96:99], v[176:179], v[196:199], v[96:99]
	v_mfma_f32_16x16x32_bf16 v[84:87], v[168:171], v[204:207], v[84:87]
	v_mfma_f32_16x16x32_bf16 v[80:83], v[176:179], v[204:207], v[80:83]
	v_mfma_f32_16x16x32_bf16 v[68:71], v[168:171], v[212:215], v[68:71]
	v_mfma_f32_16x16x32_bf16 v[64:67], v[176:179], v[212:215], v[64:67]
	v_mfma_f32_16x16x32_bf16 v[116:119], v[172:175], v[188:191], v[116:119]
	v_mfma_f32_16x16x32_bf16 v[112:115], v[180:183], v[188:191], v[112:115]
	v_mfma_f32_16x16x32_bf16 v[100:103], v[172:175], v[200:203], v[100:103]
	v_mfma_f32_16x16x32_bf16 v[96:99], v[180:183], v[200:203], v[96:99]
	v_mfma_f32_16x16x32_bf16 v[84:87], v[172:175], v[208:211], v[84:87]
	v_mfma_f32_16x16x32_bf16 v[80:83], v[180:183], v[208:211], v[80:83]
	v_mfma_f32_16x16x32_bf16 v[68:71], v[172:175], v[216:219], v[68:71]
	v_mfma_f32_16x16x32_bf16 v[64:67], v[180:183], v[216:219], v[64:67]
	s_setprio 0
	s_barrier
	s_add_i32 s24, s51, s39
	v_lshl_add_u64 v[192:193], s[28:29], 0, v[132:133]
	s_mov_b32 m0, s24
	ds_read_b128 v[184:187], v150 offset:16384
	ds_read_b128 v[188:191], v150 offset:17408
	ds_read_b128 v[196:199], v150 offset:18432
	ds_read_b128 v[200:203], v150 offset:19456
	ds_read_b128 v[204:207], v150 offset:20480
	ds_read_b128 v[208:211], v150 offset:21504
	ds_read_b128 v[212:215], v150 offset:22528
	ds_read_b128 v[216:219], v150 offset:23552
	global_load_lds_dwordx4 v[192:193], off
	s_add_i32 m0, s24, 0x2000
	s_add_u32 s24, s28, 0x30000
	v_lshl_add_u64 v[220:221], s[28:29], 0, v[128:129]
	s_addc_u32 s25, s29, 0
	s_add_i32 s63, s52, s39
	global_load_lds_dwordx4 v[220:221], off
	s_mov_b32 m0, s63
	v_lshl_add_u64 v[224:225], s[30:31], 0, v[130:131]
	global_load_lds_dwordx4 v132, s[24:25]
	s_add_i32 m0, s63, 0x2000
	s_nop 0
	global_load_lds_dwordx4 v128, s[24:25]
	v_lshl_add_u64 v[222:223], s[30:31], 0, v[134:135]
	s_waitcnt vmcnt(6)
	s_waitcnt lgkmcnt(0)
	s_barrier
	s_setprio 1
	s_waitcnt lgkmcnt(0)
	v_mfma_f32_16x16x32_bf16 v[60:63], v[152:155], v[184:187], v[60:63]
	v_mfma_f32_16x16x32_bf16 v[56:59], v[160:163], v[184:187], v[56:59]
	v_mfma_f32_16x16x32_bf16 v[44:47], v[152:155], v[196:199], v[44:47]
	v_mfma_f32_16x16x32_bf16 v[40:43], v[160:163], v[196:199], v[40:43]
	v_mfma_f32_16x16x32_bf16 v[28:31], v[152:155], v[204:207], v[28:31]
	v_mfma_f32_16x16x32_bf16 v[24:27], v[160:163], v[204:207], v[24:27]
	v_mfma_f32_16x16x32_bf16 v[12:15], v[152:155], v[212:215], v[12:15]
	v_mfma_f32_16x16x32_bf16 v[8:11], v[160:163], v[212:215], v[8:11]
	v_mfma_f32_16x16x32_bf16 v[60:63], v[156:159], v[188:191], v[60:63]
	v_mfma_f32_16x16x32_bf16 v[56:59], v[164:167], v[188:191], v[56:59]
	v_mfma_f32_16x16x32_bf16 v[44:47], v[156:159], v[200:203], v[44:47]
	v_mfma_f32_16x16x32_bf16 v[40:43], v[164:167], v[200:203], v[40:43]
	v_mfma_f32_16x16x32_bf16 v[28:31], v[156:159], v[208:211], v[28:31]
	v_mfma_f32_16x16x32_bf16 v[24:27], v[164:167], v[208:211], v[24:27]
	v_mfma_f32_16x16x32_bf16 v[12:15], v[156:159], v[216:219], v[12:15]
	v_mfma_f32_16x16x32_bf16 v[8:11], v[164:167], v[216:219], v[8:11]
	s_setprio 0
	s_setprio 1
	v_mfma_f32_16x16x32_bf16 v[52:55], v[168:171], v[184:187], v[52:55]
	v_mfma_f32_16x16x32_bf16 v[48:51], v[176:179], v[184:187], v[48:51]
	v_mfma_f32_16x16x32_bf16 v[36:39], v[168:171], v[196:199], v[36:39]
	v_mfma_f32_16x16x32_bf16 v[32:35], v[176:179], v[196:199], v[32:35]
	v_mfma_f32_16x16x32_bf16 v[20:23], v[168:171], v[204:207], v[20:23]
	v_mfma_f32_16x16x32_bf16 v[16:19], v[176:179], v[204:207], v[16:19]
	v_mfma_f32_16x16x32_bf16 v[4:7], v[168:171], v[212:215], v[4:7]
	v_mfma_f32_16x16x32_bf16 v[0:3], v[176:179], v[212:215], v[0:3]
	v_mfma_f32_16x16x32_bf16 v[52:55], v[172:175], v[188:191], v[52:55]
	v_mfma_f32_16x16x32_bf16 v[48:51], v[180:183], v[188:191], v[48:51]
	v_mfma_f32_16x16x32_bf16 v[36:39], v[172:175], v[200:203], v[36:39]
	v_mfma_f32_16x16x32_bf16 v[32:35], v[180:183], v[200:203], v[32:35]
	v_mfma_f32_16x16x32_bf16 v[20:23], v[172:175], v[208:211], v[20:23]
	v_mfma_f32_16x16x32_bf16 v[16:19], v[180:183], v[208:211], v[16:19]
	v_mfma_f32_16x16x32_bf16 v[4:7], v[172:175], v[216:219], v[4:7]
	v_mfma_f32_16x16x32_bf16 v[0:3], v[180:183], v[216:219], v[0:3]
	s_setprio 0
	s_barrier
	s_add_i32 s63, 0, 0x18000
	v_add_u32_e32 v151, s63, v142
	s_add_i32 s70, 0, 0x1c000
	ds_read_b128 v[152:155], v151
	ds_read_b128 v[156:159], v151 offset:1024
	ds_read_b128 v[160:163], v151 offset:2048
	ds_read_b128 v[164:167], v151 offset:3072
	v_add_u32_e32 v151, s70, v142
	ds_read_b128 v[168:171], v151
	ds_read_b128 v[172:175], v151 offset:1024
	ds_read_b128 v[176:179], v151 offset:2048
	ds_read_b128 v[180:183], v151 offset:3072
	s_add_u32 s24, s30, 0x30000
	s_addc_u32 s25, s31, 0
	ds_read_b128 v[184:187], v150 offset:32768
	ds_read_b128 v[188:191], v150 offset:33792
	ds_read_b128 v[196:199], v150 offset:34816
	ds_read_b128 v[200:203], v150 offset:35840
	ds_read_b128 v[204:207], v150 offset:36864
	ds_read_b128 v[208:211], v150 offset:37888
	ds_read_b128 v[212:215], v150 offset:38912
	ds_read_b128 v[216:219], v150 offset:39936
	s_mov_b32 m0, s40
	s_nop 0
	global_load_lds_dwordx4 v[222:223], off
	s_mov_b32 m0, s41
	s_nop 0
	global_load_lds_dwordx4 v[224:225], off
	s_mov_b32 m0, s42
	s_nop 0
	global_load_lds_dwordx4 v134, s[24:25]
	s_mov_b32 m0, s43
	s_nop 0
	global_load_lds_dwordx4 v130, s[24:25]
	s_waitcnt vmcnt(8)
	s_waitcnt lgkmcnt(0)
	s_barrier
	s_setprio 1
	s_waitcnt lgkmcnt(0)
	v_mfma_f32_16x16x32_bf16 v[124:127], v[152:155], v[184:187], v[124:127]
	v_mfma_f32_16x16x32_bf16 v[120:123], v[160:163], v[184:187], v[120:123]
	v_mfma_f32_16x16x32_bf16 v[108:111], v[152:155], v[196:199], v[108:111]
	v_mfma_f32_16x16x32_bf16 v[104:107], v[160:163], v[196:199], v[104:107]
	v_mfma_f32_16x16x32_bf16 v[92:95], v[152:155], v[204:207], v[92:95]
	v_mfma_f32_16x16x32_bf16 v[88:91], v[160:163], v[204:207], v[88:91]
	v_mfma_f32_16x16x32_bf16 v[76:79], v[152:155], v[212:215], v[76:79]
	v_mfma_f32_16x16x32_bf16 v[72:75], v[160:163], v[212:215], v[72:75]
	v_mfma_f32_16x16x32_bf16 v[124:127], v[156:159], v[188:191], v[124:127]
	v_mfma_f32_16x16x32_bf16 v[120:123], v[164:167], v[188:191], v[120:123]
	v_mfma_f32_16x16x32_bf16 v[108:111], v[156:159], v[200:203], v[108:111]
	v_mfma_f32_16x16x32_bf16 v[104:107], v[164:167], v[200:203], v[104:107]
	v_mfma_f32_16x16x32_bf16 v[92:95], v[156:159], v[208:211], v[92:95]
	v_mfma_f32_16x16x32_bf16 v[88:91], v[164:167], v[208:211], v[88:91]
	v_mfma_f32_16x16x32_bf16 v[76:79], v[156:159], v[216:219], v[76:79]
	v_mfma_f32_16x16x32_bf16 v[72:75], v[164:167], v[216:219], v[72:75]
	s_setprio 0
	s_setprio 1
	v_mfma_f32_16x16x32_bf16 v[116:119], v[168:171], v[184:187], v[116:119]
	v_mfma_f32_16x16x32_bf16 v[112:115], v[176:179], v[184:187], v[112:115]
	v_mfma_f32_16x16x32_bf16 v[100:103], v[168:171], v[196:199], v[100:103]
	v_mfma_f32_16x16x32_bf16 v[96:99], v[176:179], v[196:199], v[96:99]
	v_mfma_f32_16x16x32_bf16 v[84:87], v[168:171], v[204:207], v[84:87]
	v_mfma_f32_16x16x32_bf16 v[80:83], v[176:179], v[204:207], v[80:83]
	v_mfma_f32_16x16x32_bf16 v[68:71], v[168:171], v[212:215], v[68:71]
	v_mfma_f32_16x16x32_bf16 v[64:67], v[176:179], v[212:215], v[64:67]
	v_mfma_f32_16x16x32_bf16 v[116:119], v[172:175], v[188:191], v[116:119]
	v_mfma_f32_16x16x32_bf16 v[112:115], v[180:183], v[188:191], v[112:115]
	v_mfma_f32_16x16x32_bf16 v[100:103], v[172:175], v[200:203], v[100:103]
	v_mfma_f32_16x16x32_bf16 v[96:99], v[180:183], v[200:203], v[96:99]
	v_mfma_f32_16x16x32_bf16 v[84:87], v[172:175], v[208:211], v[84:87]
	v_mfma_f32_16x16x32_bf16 v[80:83], v[180:183], v[208:211], v[80:83]
	v_mfma_f32_16x16x32_bf16 v[68:71], v[172:175], v[216:219], v[68:71]
	v_mfma_f32_16x16x32_bf16 v[64:67], v[180:183], v[216:219], v[64:67]
	s_setprio 0
	s_barrier
	s_add_i32 s24, s63, s39
	v_lshl_add_u64 v[192:193], v[192:193], 0, s[16:17]
	s_mov_b32 m0, s24
	ds_read_b128 v[184:187], v150 offset:49152
	ds_read_b128 v[188:191], v150 offset:50176
	ds_read_b128 v[196:199], v150 offset:51200
	ds_read_b128 v[200:203], v150 offset:52224
	ds_read_b128 v[204:207], v150 offset:53248
	ds_read_b128 v[208:211], v150 offset:54272
	ds_read_b128 v[212:215], v150 offset:55296
	ds_read_b128 v[216:219], v150 offset:56320
	global_load_lds_dwordx4 v[192:193], off
	s_add_i32 m0, s24, 0x2000
	s_add_u32 s24, s28, 0x30080
	v_lshl_add_u64 v[192:193], v[220:221], 0, s[16:17]
	s_addc_u32 s25, s29, 0
	s_add_i32 s28, s70, s39
	global_load_lds_dwordx4 v[192:193], off
	s_mov_b32 m0, s28
	s_nop 0
	global_load_lds_dwordx4 v132, s[24:25]
	s_add_i32 m0, s28, 0x2000
	s_nop 0
	global_load_lds_dwordx4 v128, s[24:25]
	s_waitcnt vmcnt(6)
	s_waitcnt lgkmcnt(0)
	s_barrier
	s_setprio 1
	s_waitcnt lgkmcnt(0)
	v_mfma_f32_16x16x32_bf16 v[60:63], v[152:155], v[184:187], v[60:63]
	v_mfma_f32_16x16x32_bf16 v[56:59], v[160:163], v[184:187], v[56:59]
	v_mfma_f32_16x16x32_bf16 v[44:47], v[152:155], v[196:199], v[44:47]
	v_mfma_f32_16x16x32_bf16 v[40:43], v[160:163], v[196:199], v[40:43]
	v_mfma_f32_16x16x32_bf16 v[28:31], v[152:155], v[204:207], v[28:31]
	v_mfma_f32_16x16x32_bf16 v[24:27], v[160:163], v[204:207], v[24:27]
	v_mfma_f32_16x16x32_bf16 v[12:15], v[152:155], v[212:215], v[12:15]
	v_mfma_f32_16x16x32_bf16 v[8:11], v[160:163], v[212:215], v[8:11]
	v_mfma_f32_16x16x32_bf16 v[60:63], v[156:159], v[188:191], v[60:63]
	v_mfma_f32_16x16x32_bf16 v[56:59], v[164:167], v[188:191], v[56:59]
	v_mfma_f32_16x16x32_bf16 v[44:47], v[156:159], v[200:203], v[44:47]
	v_mfma_f32_16x16x32_bf16 v[40:43], v[164:167], v[200:203], v[40:43]
	v_mfma_f32_16x16x32_bf16 v[28:31], v[156:159], v[208:211], v[28:31]
	v_mfma_f32_16x16x32_bf16 v[24:27], v[164:167], v[208:211], v[24:27]
	v_mfma_f32_16x16x32_bf16 v[12:15], v[156:159], v[216:219], v[12:15]
	v_mfma_f32_16x16x32_bf16 v[8:11], v[164:167], v[216:219], v[8:11]
	s_setprio 0
	s_setprio 1
	v_mfma_f32_16x16x32_bf16 v[52:55], v[168:171], v[184:187], v[52:55]
	v_mfma_f32_16x16x32_bf16 v[48:51], v[176:179], v[184:187], v[48:51]
	v_mfma_f32_16x16x32_bf16 v[36:39], v[168:171], v[196:199], v[36:39]
	v_mfma_f32_16x16x32_bf16 v[32:35], v[176:179], v[196:199], v[32:35]
	v_mfma_f32_16x16x32_bf16 v[20:23], v[168:171], v[204:207], v[20:23]
	v_mfma_f32_16x16x32_bf16 v[16:19], v[176:179], v[204:207], v[16:19]
	v_mfma_f32_16x16x32_bf16 v[4:7], v[168:171], v[212:215], v[4:7]
	v_mfma_f32_16x16x32_bf16 v[0:3], v[176:179], v[212:215], v[0:3]
	v_mfma_f32_16x16x32_bf16 v[52:55], v[172:175], v[188:191], v[52:55]
	v_mfma_f32_16x16x32_bf16 v[48:51], v[180:183], v[188:191], v[48:51]
	v_mfma_f32_16x16x32_bf16 v[36:39], v[172:175], v[200:203], v[36:39]
	v_mfma_f32_16x16x32_bf16 v[32:35], v[180:183], v[200:203], v[32:35]
	v_mfma_f32_16x16x32_bf16 v[20:23], v[172:175], v[208:211], v[20:23]
	v_mfma_f32_16x16x32_bf16 v[16:19], v[180:183], v[208:211], v[16:19]
	v_mfma_f32_16x16x32_bf16 v[4:7], v[172:175], v[216:219], v[4:7]
	v_mfma_f32_16x16x32_bf16 v[0:3], v[180:183], v[216:219], v[0:3]
	s_setprio 0
	s_barrier
	v_lshl_add_u64 v[222:223], v[222:223], 0, s[16:17]
	s_mov_b32 m0, s45
	s_nop 0
	global_load_lds_dwordx4 v[222:223], off
	v_lshl_add_u64 v[224:225], v[224:225], 0, s[16:17]
	s_mov_b32 m0, s48
	s_nop 0
	global_load_lds_dwordx4 v[224:225], off
	s_add_i32 s62, s62, 2
	s_add_u32 s60, s60, 0x100
	s_addc_u32 s61, s61, 0
	s_cmp_gt_u32 s62, 9
	s_mov_b64 s[24:25], s[26:27]
	s_cbranch_scc0 .LBB0_2533
	s_and_b64 vcc, exec, s[18:19]
	s_cbranch_vccz .LBB0_2536
	s_barrier

.LBB0_2557:
	ds_read_b128 v[144:147], v153
	ds_read_b128 v[158:161], v153 offset:1024
	ds_read_b128 v[162:165], v153 offset:2048
	ds_read_b128 v[166:169], v153 offset:3072
	ds_read_b128 v[170:173], v154
	ds_read_b128 v[174:177], v154 offset:1024
	ds_read_b128 v[178:181], v154 offset:2048
	ds_read_b128 v[182:185], v154 offset:3072
	s_add_u32 s36, s34, 0xfffc0080
	s_addc_u32 s37, s35, -1
	s_cmp_eq_u32 s73, 12
	s_cselect_b32 s39, s27, s37
	s_cselect_b32 s38, s63, s36
	s_cselect_b32 s37, s25, s72
	s_cselect_b32 s36, s70, s71
	s_add_i32 m0, s51, 0xc000
	ds_read_b128 v[186:189], v155
	ds_read_b128 v[190:193], v155 offset:1024
	ds_read_b128 v[196:199], v155 offset:2048
	ds_read_b128 v[200:203], v155 offset:3072
	ds_read_b128 v[204:207], v155 offset:4096
	ds_read_b128 v[208:211], v155 offset:5120
	ds_read_b128 v[212:215], v155 offset:6144
	ds_read_b128 v[216:219], v155 offset:7168
	global_load_lds_dwordx4 v136, s[34:35]
	s_add_i32 m0, s51, 0xe000
	s_nop 0
	global_load_lds_dwordx4 v138, s[34:35]
	s_waitcnt vmcnt(8)
	s_waitcnt lgkmcnt(0)
	s_barrier
	s_setprio 1
	s_waitcnt lgkmcnt(0)
	v_mfma_f32_16x16x32_bf16 v[124:127], v[144:147], v[186:189], v[124:127]
	v_mfma_f32_16x16x32_bf16 v[120:123], v[162:165], v[186:189], v[120:123]
	v_mfma_f32_16x16x32_bf16 v[108:111], v[144:147], v[196:199], v[108:111]
	v_mfma_f32_16x16x32_bf16 v[104:107], v[162:165], v[196:199], v[104:107]
	v_mfma_f32_16x16x32_bf16 v[92:95], v[144:147], v[204:207], v[92:95]
	v_mfma_f32_16x16x32_bf16 v[88:91], v[162:165], v[204:207], v[88:91]
	v_mfma_f32_16x16x32_bf16 v[76:79], v[144:147], v[212:215], v[76:79]
	v_mfma_f32_16x16x32_bf16 v[72:75], v[162:165], v[212:215], v[72:75]
	v_mfma_f32_16x16x32_bf16 v[124:127], v[158:161], v[190:193], v[124:127]
	v_mfma_f32_16x16x32_bf16 v[120:123], v[166:169], v[190:193], v[120:123]
	v_mfma_f32_16x16x32_bf16 v[108:111], v[158:161], v[200:203], v[108:111]
	v_mfma_f32_16x16x32_bf16 v[104:107], v[166:169], v[200:203], v[104:107]
	v_mfma_f32_16x16x32_bf16 v[92:95], v[158:161], v[208:211], v[92:95]
	v_mfma_f32_16x16x32_bf16 v[88:91], v[166:169], v[208:211], v[88:91]
	v_mfma_f32_16x16x32_bf16 v[76:79], v[158:161], v[216:219], v[76:79]
	v_mfma_f32_16x16x32_bf16 v[72:75], v[166:169], v[216:219], v[72:75]
	s_setprio 0
	s_setprio 1
	v_mfma_f32_16x16x32_bf16 v[116:119], v[170:173], v[186:189], v[116:119]
	v_mfma_f32_16x16x32_bf16 v[112:115], v[178:181], v[186:189], v[112:115]
	v_mfma_f32_16x16x32_bf16 v[100:103], v[170:173], v[196:199], v[100:103]
	v_mfma_f32_16x16x32_bf16 v[96:99], v[178:181], v[196:199], v[96:99]
	v_mfma_f32_16x16x32_bf16 v[84:87], v[170:173], v[204:207], v[84:87]
	v_mfma_f32_16x16x32_bf16 v[80:83], v[178:181], v[204:207], v[80:83]
	v_mfma_f32_16x16x32_bf16 v[68:71], v[170:173], v[212:215], v[68:71]
	v_mfma_f32_16x16x32_bf16 v[64:67], v[178:181], v[212:215], v[64:67]
	v_mfma_f32_16x16x32_bf16 v[116:119], v[174:177], v[190:193], v[116:119]
	v_mfma_f32_16x16x32_bf16 v[112:115], v[182:185], v[190:193], v[112:115]
	v_mfma_f32_16x16x32_bf16 v[100:103], v[174:177], v[200:203], v[100:103]
	v_mfma_f32_16x16x32_bf16 v[96:99], v[182:185], v[200:203], v[96:99]
	v_mfma_f32_16x16x32_bf16 v[84:87], v[174:177], v[208:211], v[84:87]
	v_mfma_f32_16x16x32_bf16 v[80:83], v[182:185], v[208:211], v[80:83]
	v_mfma_f32_16x16x32_bf16 v[68:71], v[174:177], v[216:219], v[68:71]
	v_mfma_f32_16x16x32_bf16 v[64:67], v[182:185], v[216:219], v[64:67]
	s_setprio 0
	s_barrier
	s_add_i32 s77, s59, s49
	v_lshl_add_u64 v[148:149], s[36:37], 0, v[130:131]
	s_mov_b32 m0, s77
	ds_read_b128 v[186:189], v155 offset:16384
	ds_read_b128 v[190:193], v155 offset:17408
	ds_read_b128 v[196:199], v155 offset:18432
	ds_read_b128 v[200:203], v155 offset:19456
	ds_read_b128 v[204:207], v155 offset:20480
	ds_read_b128 v[208:211], v155 offset:21504
	ds_read_b128 v[212:215], v155 offset:22528
	ds_read_b128 v[216:219], v155 offset:23552
	global_load_lds_dwordx4 v[148:149], off
	s_add_i32 m0, s77, 0x2000
	s_add_u32 s78, s36, 0x40000
	v_lshl_add_u64 v[220:221], s[36:37], 0, v[134:135]
	s_addc_u32 s79, s37, 0
	s_add_i32 s77, s60, s49
	global_load_lds_dwordx4 v[220:221], off
	s_mov_b32 m0, s77
	v_lshl_add_u64 v[224:225], s[38:39], 0, v[132:133]
	global_load_lds_dwordx4 v130, s[78:79]
	s_add_i32 m0, s77, 0x2000
	s_nop 0
	global_load_lds_dwordx4 v134, s[78:79]
	v_lshl_add_u64 v[222:223], s[38:39], 0, v[128:129]
	s_waitcnt vmcnt(6)
	s_waitcnt lgkmcnt(0)
	s_barrier
	s_setprio 1
	s_waitcnt lgkmcnt(0)
	v_mfma_f32_16x16x32_bf16 v[60:63], v[144:147], v[186:189], v[60:63]
	v_mfma_f32_16x16x32_bf16 v[56:59], v[162:165], v[186:189], v[56:59]
	v_mfma_f32_16x16x32_bf16 v[44:47], v[144:147], v[196:199], v[44:47]
	v_mfma_f32_16x16x32_bf16 v[40:43], v[162:165], v[196:199], v[40:43]
	v_mfma_f32_16x16x32_bf16 v[28:31], v[144:147], v[204:207], v[28:31]
	v_mfma_f32_16x16x32_bf16 v[24:27], v[162:165], v[204:207], v[24:27]
	v_mfma_f32_16x16x32_bf16 v[12:15], v[144:147], v[212:215], v[12:15]
	v_mfma_f32_16x16x32_bf16 v[8:11], v[162:165], v[212:215], v[8:11]
	v_mfma_f32_16x16x32_bf16 v[60:63], v[158:161], v[190:193], v[60:63]
	v_mfma_f32_16x16x32_bf16 v[56:59], v[166:169], v[190:193], v[56:59]
	v_mfma_f32_16x16x32_bf16 v[44:47], v[158:161], v[200:203], v[44:47]
	v_mfma_f32_16x16x32_bf16 v[40:43], v[166:169], v[200:203], v[40:43]
	v_mfma_f32_16x16x32_bf16 v[28:31], v[158:161], v[208:211], v[28:31]
	v_mfma_f32_16x16x32_bf16 v[24:27], v[166:169], v[208:211], v[24:27]
	v_mfma_f32_16x16x32_bf16 v[12:15], v[158:161], v[216:219], v[12:15]
	v_mfma_f32_16x16x32_bf16 v[8:11], v[166:169], v[216:219], v[8:11]
	s_setprio 0
	s_setprio 1
	v_mfma_f32_16x16x32_bf16 v[52:55], v[170:173], v[186:189], v[52:55]
	v_mfma_f32_16x16x32_bf16 v[48:51], v[178:181], v[186:189], v[48:51]
	v_mfma_f32_16x16x32_bf16 v[36:39], v[170:173], v[196:199], v[36:39]
	v_mfma_f32_16x16x32_bf16 v[32:35], v[178:181], v[196:199], v[32:35]
	v_mfma_f32_16x16x32_bf16 v[20:23], v[170:173], v[204:207], v[20:23]
	v_mfma_f32_16x16x32_bf16 v[16:19], v[178:181], v[204:207], v[16:19]
	v_mfma_f32_16x16x32_bf16 v[4:7], v[170:173], v[212:215], v[4:7]
	v_mfma_f32_16x16x32_bf16 v[0:3], v[178:181], v[212:215], v[0:3]
	v_mfma_f32_16x16x32_bf16 v[52:55], v[174:177], v[190:193], v[52:55]
	v_mfma_f32_16x16x32_bf16 v[48:51], v[182:185], v[190:193], v[48:51]
	v_mfma_f32_16x16x32_bf16 v[36:39], v[174:177], v[200:203], v[36:39]
	v_mfma_f32_16x16x32_bf16 v[32:35], v[182:185], v[200:203], v[32:35]
	v_mfma_f32_16x16x32_bf16 v[20:23], v[174:177], v[208:211], v[20:23]
	v_mfma_f32_16x16x32_bf16 v[16:19], v[182:185], v[208:211], v[16:19]
	v_mfma_f32_16x16x32_bf16 v[4:7], v[174:177], v[216:219], v[4:7]
	v_mfma_f32_16x16x32_bf16 v[0:3], v[182:185], v[216:219], v[0:3]
	s_setprio 0
	s_barrier
	s_add_i32 s77, 0, 0x18000
	v_add_u32_e32 v157, s77, v151
	s_add_i32 s78, 0, 0x1c000
	ds_read_b128 v[144:147], v157
	ds_read_b128 v[158:161], v157 offset:1024
	ds_read_b128 v[162:165], v157 offset:2048
	ds_read_b128 v[166:169], v157 offset:3072
	v_add_u32_e32 v157, s78, v151
	ds_read_b128 v[170:173], v157
	ds_read_b128 v[174:177], v157 offset:1024
	ds_read_b128 v[178:181], v157 offset:2048
	ds_read_b128 v[182:185], v157 offset:3072
	s_add_u32 s38, s38, 0x40000
	s_addc_u32 s39, s39, 0
	ds_read_b128 v[186:189], v155 offset:32768
	ds_read_b128 v[190:193], v155 offset:33792
	ds_read_b128 v[196:199], v155 offset:34816
	ds_read_b128 v[200:203], v155 offset:35840
	ds_read_b128 v[204:207], v155 offset:36864
	ds_read_b128 v[208:211], v155 offset:37888
	ds_read_b128 v[212:215], v155 offset:38912
	ds_read_b128 v[216:219], v155 offset:39936
	s_mov_b32 m0, s51
	s_nop 0
	global_load_lds_dwordx4 v[222:223], off
	s_mov_b32 m0, s52
	s_nop 0
	global_load_lds_dwordx4 v[224:225], off
	s_mov_b32 m0, s53
	s_nop 0
	global_load_lds_dwordx4 v128, s[38:39]
	s_mov_b32 m0, s54
	s_nop 0
	global_load_lds_dwordx4 v132, s[38:39]
	s_waitcnt vmcnt(8)
	s_waitcnt lgkmcnt(0)
	s_barrier
	s_setprio 1
	s_waitcnt lgkmcnt(0)
	v_mfma_f32_16x16x32_bf16 v[124:127], v[144:147], v[186:189], v[124:127]
	v_mfma_f32_16x16x32_bf16 v[120:123], v[162:165], v[186:189], v[120:123]
	v_mfma_f32_16x16x32_bf16 v[108:111], v[144:147], v[196:199], v[108:111]
	v_mfma_f32_16x16x32_bf16 v[104:107], v[162:165], v[196:199], v[104:107]
	v_mfma_f32_16x16x32_bf16 v[92:95], v[144:147], v[204:207], v[92:95]
	v_mfma_f32_16x16x32_bf16 v[88:91], v[162:165], v[204:207], v[88:91]
	v_mfma_f32_16x16x32_bf16 v[76:79], v[144:147], v[212:215], v[76:79]
	v_mfma_f32_16x16x32_bf16 v[72:75], v[162:165], v[212:215], v[72:75]
	v_mfma_f32_16x16x32_bf16 v[124:127], v[158:161], v[190:193], v[124:127]
	v_mfma_f32_16x16x32_bf16 v[120:123], v[166:169], v[190:193], v[120:123]
	v_mfma_f32_16x16x32_bf16 v[108:111], v[158:161], v[200:203], v[108:111]
	v_mfma_f32_16x16x32_bf16 v[104:107], v[166:169], v[200:203], v[104:107]
	v_mfma_f32_16x16x32_bf16 v[92:95], v[158:161], v[208:211], v[92:95]
	v_mfma_f32_16x16x32_bf16 v[88:91], v[166:169], v[208:211], v[88:91]
	v_mfma_f32_16x16x32_bf16 v[76:79], v[158:161], v[216:219], v[76:79]
	v_mfma_f32_16x16x32_bf16 v[72:75], v[166:169], v[216:219], v[72:75]
	s_setprio 0
	s_setprio 1
	v_mfma_f32_16x16x32_bf16 v[116:119], v[170:173], v[186:189], v[116:119]
	v_mfma_f32_16x16x32_bf16 v[112:115], v[178:181], v[186:189], v[112:115]
	v_mfma_f32_16x16x32_bf16 v[100:103], v[170:173], v[196:199], v[100:103]
	v_mfma_f32_16x16x32_bf16 v[96:99], v[178:181], v[196:199], v[96:99]
	v_mfma_f32_16x16x32_bf16 v[84:87], v[170:173], v[204:207], v[84:87]
	v_mfma_f32_16x16x32_bf16 v[80:83], v[178:181], v[204:207], v[80:83]
	v_mfma_f32_16x16x32_bf16 v[68:71], v[170:173], v[212:215], v[68:71]
	v_mfma_f32_16x16x32_bf16 v[64:67], v[178:181], v[212:215], v[64:67]
	v_mfma_f32_16x16x32_bf16 v[116:119], v[174:177], v[190:193], v[116:119]
	v_mfma_f32_16x16x32_bf16 v[112:115], v[182:185], v[190:193], v[112:115]
	v_mfma_f32_16x16x32_bf16 v[100:103], v[174:177], v[200:203], v[100:103]
	v_mfma_f32_16x16x32_bf16 v[96:99], v[182:185], v[200:203], v[96:99]
	v_mfma_f32_16x16x32_bf16 v[84:87], v[174:177], v[208:211], v[84:87]
	v_mfma_f32_16x16x32_bf16 v[80:83], v[182:185], v[208:211], v[80:83]
	v_mfma_f32_16x16x32_bf16 v[68:71], v[174:177], v[216:219], v[68:71]
	v_mfma_f32_16x16x32_bf16 v[64:67], v[182:185], v[216:219], v[64:67]
	s_setprio 0
	s_barrier
	s_add_i32 s38, s77, s49
	v_lshl_add_u64 v[148:149], v[148:149], 0, s[20:21]
	s_mov_b32 m0, s38
	ds_read_b128 v[186:189], v155 offset:49152
	ds_read_b128 v[190:193], v155 offset:50176
	ds_read_b128 v[196:199], v155 offset:51200
	ds_read_b128 v[200:203], v155 offset:52224
	ds_read_b128 v[204:207], v155 offset:53248
	ds_read_b128 v[208:211], v155 offset:54272
	ds_read_b128 v[212:215], v155 offset:55296
	ds_read_b128 v[216:219], v155 offset:56320
	global_load_lds_dwordx4 v[148:149], off
	s_add_i32 m0, s38, 0x2000
	s_add_u32 s36, s36, 0x40080
	v_lshl_add_u64 v[148:149], v[220:221], 0, s[20:21]
	s_addc_u32 s37, s37, 0
	s_add_i32 s38, s78, s49
	global_load_lds_dwordx4 v[148:149], off
	s_mov_b32 m0, s38
	s_nop 0
	global_load_lds_dwordx4 v130, s[36:37]
	s_add_i32 m0, s38, 0x2000
	s_nop 0
	global_load_lds_dwordx4 v134, s[36:37]
	s_waitcnt vmcnt(6)
	s_waitcnt lgkmcnt(0)
	s_barrier
	s_setprio 1
	s_waitcnt lgkmcnt(0)
	v_mfma_f32_16x16x32_bf16 v[60:63], v[144:147], v[186:189], v[60:63]
	v_mfma_f32_16x16x32_bf16 v[56:59], v[162:165], v[186:189], v[56:59]
	v_mfma_f32_16x16x32_bf16 v[44:47], v[144:147], v[196:199], v[44:47]
	v_mfma_f32_16x16x32_bf16 v[40:43], v[162:165], v[196:199], v[40:43]
	v_mfma_f32_16x16x32_bf16 v[28:31], v[144:147], v[204:207], v[28:31]
	v_mfma_f32_16x16x32_bf16 v[24:27], v[162:165], v[204:207], v[24:27]
	v_mfma_f32_16x16x32_bf16 v[12:15], v[144:147], v[212:215], v[12:15]
	v_mfma_f32_16x16x32_bf16 v[8:11], v[162:165], v[212:215], v[8:11]
	v_mfma_f32_16x16x32_bf16 v[60:63], v[158:161], v[190:193], v[60:63]
	v_mfma_f32_16x16x32_bf16 v[56:59], v[166:169], v[190:193], v[56:59]
	v_mfma_f32_16x16x32_bf16 v[44:47], v[158:161], v[200:203], v[44:47]
	v_mfma_f32_16x16x32_bf16 v[40:43], v[166:169], v[200:203], v[40:43]
	v_mfma_f32_16x16x32_bf16 v[28:31], v[158:161], v[208:211], v[28:31]
	v_mfma_f32_16x16x32_bf16 v[24:27], v[166:169], v[208:211], v[24:27]
	v_mfma_f32_16x16x32_bf16 v[12:15], v[158:161], v[216:219], v[12:15]
	v_mfma_f32_16x16x32_bf16 v[8:11], v[166:169], v[216:219], v[8:11]
	s_setprio 0
	s_setprio 1
	v_mfma_f32_16x16x32_bf16 v[52:55], v[170:173], v[186:189], v[52:55]
	v_mfma_f32_16x16x32_bf16 v[48:51], v[178:181], v[186:189], v[48:51]
	v_mfma_f32_16x16x32_bf16 v[36:39], v[170:173], v[196:199], v[36:39]
	v_mfma_f32_16x16x32_bf16 v[32:35], v[178:181], v[196:199], v[32:35]
	v_mfma_f32_16x16x32_bf16 v[20:23], v[170:173], v[204:207], v[20:23]
	v_mfma_f32_16x16x32_bf16 v[16:19], v[178:181], v[204:207], v[16:19]
	v_mfma_f32_16x16x32_bf16 v[4:7], v[170:173], v[212:215], v[4:7]
	v_mfma_f32_16x16x32_bf16 v[0:3], v[178:181], v[212:215], v[0:3]
	v_mfma_f32_16x16x32_bf16 v[52:55], v[174:177], v[190:193], v[52:55]
	v_mfma_f32_16x16x32_bf16 v[48:51], v[182:185], v[190:193], v[48:51]
	v_mfma_f32_16x16x32_bf16 v[36:39], v[174:177], v[200:203], v[36:39]
	v_mfma_f32_16x16x32_bf16 v[32:35], v[182:185], v[200:203], v[32:35]
	v_mfma_f32_16x16x32_bf16 v[20:23], v[174:177], v[208:211], v[20:23]
	v_mfma_f32_16x16x32_bf16 v[16:19], v[182:185], v[208:211], v[16:19]
	v_mfma_f32_16x16x32_bf16 v[4:7], v[174:177], v[216:219], v[4:7]
	v_mfma_f32_16x16x32_bf16 v[0:3], v[182:185], v[216:219], v[0:3]
	s_setprio 0
	s_barrier
	v_lshl_add_u64 v[222:223], v[222:223], 0, s[20:21]
	s_mov_b32 m0, s56
	s_nop 0
	global_load_lds_dwordx4 v[222:223], off
	v_lshl_add_u64 v[224:225], v[224:225], 0, s[20:21]
	s_mov_b32 m0, s57
	s_nop 0
	global_load_lds_dwordx4 v[224:225], off
	s_add_i32 s73, s73, 2
	s_add_u32 s34, s34, 0x100
	s_addc_u32 s35, s35, 0
	s_add_u32 s71, s71, 0x100
	s_addc_u32 s72, s72, 0
	s_cmp_gt_u32 s73, 13
	s_cbranch_scc0 .LBB0_2557
	s_and_b64 vcc, exec, s[22:23]
	s_cbranch_vccz .LBB0_2560
	s_barrier

.LBB0_2633:
	ds_read_b128 v[144:147], v153
	ds_read_b128 v[156:159], v153 offset:1024
	ds_read_b128 v[160:163], v153 offset:2048
	ds_read_b128 v[164:167], v153 offset:3072
	ds_read_b128 v[168:171], v154
	ds_read_b128 v[172:175], v154 offset:1024
	ds_read_b128 v[176:179], v154 offset:2048
	ds_read_b128 v[180:183], v154 offset:3072
	s_add_u32 s42, s40, 0xfffe0080
	s_addc_u32 s43, s41, -1
	s_cmp_eq_u32 s73, 4
	s_cselect_b32 s45, s31, s43
	s_cselect_b32 s44, s63, s42
	s_cselect_b32 s43, s29, s72
	s_cselect_b32 s42, s70, s71
	s_add_i32 m0, s39, 0xc000
	ds_read_b128 v[184:187], v155
	ds_read_b128 v[188:191], v155 offset:1024
	ds_read_b128 v[196:199], v155 offset:2048
	ds_read_b128 v[200:203], v155 offset:3072
	ds_read_b128 v[204:207], v155 offset:4096
	ds_read_b128 v[208:211], v155 offset:5120
	ds_read_b128 v[212:215], v155 offset:6144
	ds_read_b128 v[216:219], v155 offset:7168
	global_load_lds_dwordx4 v136, s[40:41]
	s_add_i32 m0, s39, 0xe000
	s_nop 0
	global_load_lds_dwordx4 v138, s[40:41]
	s_waitcnt vmcnt(8)
	s_waitcnt lgkmcnt(0)
	s_barrier
	s_setprio 1
	s_waitcnt lgkmcnt(0)
	v_mfma_f32_16x16x32_bf16 v[124:127], v[144:147], v[184:187], v[124:127]
	v_mfma_f32_16x16x32_bf16 v[120:123], v[160:163], v[184:187], v[120:123]
	v_mfma_f32_16x16x32_bf16 v[108:111], v[144:147], v[196:199], v[108:111]
	v_mfma_f32_16x16x32_bf16 v[104:107], v[160:163], v[196:199], v[104:107]
	v_mfma_f32_16x16x32_bf16 v[92:95], v[144:147], v[204:207], v[92:95]
	v_mfma_f32_16x16x32_bf16 v[88:91], v[160:163], v[204:207], v[88:91]
	v_mfma_f32_16x16x32_bf16 v[76:79], v[144:147], v[212:215], v[76:79]
	v_mfma_f32_16x16x32_bf16 v[72:75], v[160:163], v[212:215], v[72:75]
	v_mfma_f32_16x16x32_bf16 v[124:127], v[156:159], v[188:191], v[124:127]
	v_mfma_f32_16x16x32_bf16 v[120:123], v[164:167], v[188:191], v[120:123]
	v_mfma_f32_16x16x32_bf16 v[108:111], v[156:159], v[200:203], v[108:111]
	v_mfma_f32_16x16x32_bf16 v[104:107], v[164:167], v[200:203], v[104:107]
	v_mfma_f32_16x16x32_bf16 v[92:95], v[156:159], v[208:211], v[92:95]
	v_mfma_f32_16x16x32_bf16 v[88:91], v[164:167], v[208:211], v[88:91]
	v_mfma_f32_16x16x32_bf16 v[76:79], v[156:159], v[216:219], v[76:79]
	v_mfma_f32_16x16x32_bf16 v[72:75], v[164:167], v[216:219], v[72:75]
	s_setprio 0
	s_setprio 1
	v_mfma_f32_16x16x32_bf16 v[116:119], v[168:171], v[184:187], v[116:119]
	v_mfma_f32_16x16x32_bf16 v[112:115], v[176:179], v[184:187], v[112:115]
	v_mfma_f32_16x16x32_bf16 v[100:103], v[168:171], v[196:199], v[100:103]
	v_mfma_f32_16x16x32_bf16 v[96:99], v[176:179], v[196:199], v[96:99]
	v_mfma_f32_16x16x32_bf16 v[84:87], v[168:171], v[204:207], v[84:87]
	v_mfma_f32_16x16x32_bf16 v[80:83], v[176:179], v[204:207], v[80:83]
	v_mfma_f32_16x16x32_bf16 v[68:71], v[168:171], v[212:215], v[68:71]
	v_mfma_f32_16x16x32_bf16 v[64:67], v[176:179], v[212:215], v[64:67]
	v_mfma_f32_16x16x32_bf16 v[116:119], v[172:175], v[188:191], v[116:119]
	v_mfma_f32_16x16x32_bf16 v[112:115], v[180:183], v[188:191], v[112:115]
	v_mfma_f32_16x16x32_bf16 v[100:103], v[172:175], v[200:203], v[100:103]
	v_mfma_f32_16x16x32_bf16 v[96:99], v[180:183], v[200:203], v[96:99]
	v_mfma_f32_16x16x32_bf16 v[84:87], v[172:175], v[208:211], v[84:87]
	v_mfma_f32_16x16x32_bf16 v[80:83], v[180:183], v[208:211], v[80:83]
	v_mfma_f32_16x16x32_bf16 v[68:71], v[172:175], v[216:219], v[68:71]
	v_mfma_f32_16x16x32_bf16 v[64:67], v[180:183], v[216:219], v[64:67]
	s_setprio 0
	s_barrier
	s_add_i32 s77, s60, s52
	v_lshl_add_u64 v[148:149], s[42:43], 0, v[130:131]
	s_mov_b32 m0, s77
	ds_read_b128 v[184:187], v155 offset:16384
	ds_read_b128 v[188:191], v155 offset:17408
	ds_read_b128 v[196:199], v155 offset:18432
	ds_read_b128 v[200:203], v155 offset:19456
	ds_read_b128 v[204:207], v155 offset:20480
	ds_read_b128 v[208:211], v155 offset:21504
	ds_read_b128 v[212:215], v155 offset:22528
	ds_read_b128 v[216:219], v155 offset:23552
	global_load_lds_dwordx4 v[148:149], off
	s_add_i32 m0, s77, 0x2000
	s_add_u32 s78, s42, 0x20000
	v_lshl_add_u64 v[192:193], s[42:43], 0, v[134:135]
	s_addc_u32 s79, s43, 0
	s_add_i32 s77, s61, s52
	global_load_lds_dwordx4 v[192:193], off
	s_mov_b32 m0, s77
	v_lshl_add_u64 v[222:223], s[44:45], 0, v[132:133]
	global_load_lds_dwordx4 v130, s[78:79]
	s_add_i32 m0, s77, 0x2000
	s_nop 0
	global_load_lds_dwordx4 v134, s[78:79]
	v_lshl_add_u64 v[220:221], s[44:45], 0, v[128:129]
	s_waitcnt vmcnt(6)
	s_waitcnt lgkmcnt(0)
	s_barrier
	s_setprio 1
	s_waitcnt lgkmcnt(0)
	v_mfma_f32_16x16x32_bf16 v[60:63], v[144:147], v[184:187], v[60:63]
	v_mfma_f32_16x16x32_bf16 v[56:59], v[160:163], v[184:187], v[56:59]
	v_mfma_f32_16x16x32_bf16 v[44:47], v[144:147], v[196:199], v[44:47]
	v_mfma_f32_16x16x32_bf16 v[40:43], v[160:163], v[196:199], v[40:43]
	v_mfma_f32_16x16x32_bf16 v[28:31], v[144:147], v[204:207], v[28:31]
	v_mfma_f32_16x16x32_bf16 v[24:27], v[160:163], v[204:207], v[24:27]
	v_mfma_f32_16x16x32_bf16 v[12:15], v[144:147], v[212:215], v[12:15]
	v_mfma_f32_16x16x32_bf16 v[8:11], v[160:163], v[212:215], v[8:11]
	v_mfma_f32_16x16x32_bf16 v[60:63], v[156:159], v[188:191], v[60:63]
	v_mfma_f32_16x16x32_bf16 v[56:59], v[164:167], v[188:191], v[56:59]
	v_mfma_f32_16x16x32_bf16 v[44:47], v[156:159], v[200:203], v[44:47]
	v_mfma_f32_16x16x32_bf16 v[40:43], v[164:167], v[200:203], v[40:43]
	v_mfma_f32_16x16x32_bf16 v[28:31], v[156:159], v[208:211], v[28:31]
	v_mfma_f32_16x16x32_bf16 v[24:27], v[164:167], v[208:211], v[24:27]
	v_mfma_f32_16x16x32_bf16 v[12:15], v[156:159], v[216:219], v[12:15]
	v_mfma_f32_16x16x32_bf16 v[8:11], v[164:167], v[216:219], v[8:11]
	s_setprio 0
	s_setprio 1
	v_mfma_f32_16x16x32_bf16 v[52:55], v[168:171], v[184:187], v[52:55]
	v_mfma_f32_16x16x32_bf16 v[48:51], v[176:179], v[184:187], v[48:51]
	v_mfma_f32_16x16x32_bf16 v[36:39], v[168:171], v[196:199], v[36:39]
	v_mfma_f32_16x16x32_bf16 v[32:35], v[176:179], v[196:199], v[32:35]
	v_mfma_f32_16x16x32_bf16 v[20:23], v[168:171], v[204:207], v[20:23]
	v_mfma_f32_16x16x32_bf16 v[16:19], v[176:179], v[204:207], v[16:19]
	v_mfma_f32_16x16x32_bf16 v[4:7], v[168:171], v[212:215], v[4:7]
	v_mfma_f32_16x16x32_bf16 v[0:3], v[176:179], v[212:215], v[0:3]
	v_mfma_f32_16x16x32_bf16 v[52:55], v[172:175], v[188:191], v[52:55]
	v_mfma_f32_16x16x32_bf16 v[48:51], v[180:183], v[188:191], v[48:51]
	v_mfma_f32_16x16x32_bf16 v[36:39], v[172:175], v[200:203], v[36:39]
	v_mfma_f32_16x16x32_bf16 v[32:35], v[180:183], v[200:203], v[32:35]
	v_mfma_f32_16x16x32_bf16 v[20:23], v[172:175], v[208:211], v[20:23]
	v_mfma_f32_16x16x32_bf16 v[16:19], v[180:183], v[208:211], v[16:19]
	v_mfma_f32_16x16x32_bf16 v[4:7], v[172:175], v[216:219], v[4:7]
	v_mfma_f32_16x16x32_bf16 v[0:3], v[180:183], v[216:219], v[0:3]
	s_setprio 0
	s_barrier
	s_add_i32 s77, 0, 0x18000
	s_add_i32 s78, 0, 0x1c000
	v_add_u32_e32 v164, s77, v151
	v_add_u32_e32 v180, s78, v151
	ds_read_b128 v[144:147], v164
	ds_read_b128 v[156:159], v164 offset:1024
	ds_read_b128 v[160:163], v164 offset:2048
	ds_read_b128 v[164:167], v164 offset:3072
	ds_read_b128 v[168:171], v180
	ds_read_b128 v[172:175], v180 offset:1024
	ds_read_b128 v[176:179], v180 offset:2048
	ds_read_b128 v[180:183], v180 offset:3072
	s_add_u32 s44, s44, 0x20000
	s_addc_u32 s45, s45, 0
	ds_read_b128 v[184:187], v155 offset:32768
	ds_read_b128 v[188:191], v155 offset:33792
	ds_read_b128 v[196:199], v155 offset:34816
	ds_read_b128 v[200:203], v155 offset:35840
	ds_read_b128 v[204:207], v155 offset:36864
	ds_read_b128 v[208:211], v155 offset:37888
	ds_read_b128 v[212:215], v155 offset:38912
	ds_read_b128 v[216:219], v155 offset:39936
	s_mov_b32 m0, s39
	s_nop 0
	global_load_lds_dwordx4 v[220:221], off
	s_mov_b32 m0, s53
	s_nop 0
	global_load_lds_dwordx4 v[222:223], off
	s_mov_b32 m0, s54
	s_nop 0
	global_load_lds_dwordx4 v128, s[44:45]
	s_mov_b32 m0, s55
	s_nop 0
	global_load_lds_dwordx4 v132, s[44:45]
	s_waitcnt vmcnt(8)
	s_waitcnt lgkmcnt(0)
	s_barrier
	s_setprio 1
	s_waitcnt lgkmcnt(0)
	v_mfma_f32_16x16x32_bf16 v[124:127], v[144:147], v[184:187], v[124:127]
	v_mfma_f32_16x16x32_bf16 v[120:123], v[160:163], v[184:187], v[120:123]
	v_mfma_f32_16x16x32_bf16 v[108:111], v[144:147], v[196:199], v[108:111]
	v_mfma_f32_16x16x32_bf16 v[104:107], v[160:163], v[196:199], v[104:107]
	v_mfma_f32_16x16x32_bf16 v[92:95], v[144:147], v[204:207], v[92:95]
	v_mfma_f32_16x16x32_bf16 v[88:91], v[160:163], v[204:207], v[88:91]
	v_mfma_f32_16x16x32_bf16 v[76:79], v[144:147], v[212:215], v[76:79]
	v_mfma_f32_16x16x32_bf16 v[72:75], v[160:163], v[212:215], v[72:75]
	v_mfma_f32_16x16x32_bf16 v[124:127], v[156:159], v[188:191], v[124:127]
	v_mfma_f32_16x16x32_bf16 v[120:123], v[164:167], v[188:191], v[120:123]
	v_mfma_f32_16x16x32_bf16 v[108:111], v[156:159], v[200:203], v[108:111]
	v_mfma_f32_16x16x32_bf16 v[104:107], v[164:167], v[200:203], v[104:107]
	v_mfma_f32_16x16x32_bf16 v[92:95], v[156:159], v[208:211], v[92:95]
	v_mfma_f32_16x16x32_bf16 v[88:91], v[164:167], v[208:211], v[88:91]
	v_mfma_f32_16x16x32_bf16 v[76:79], v[156:159], v[216:219], v[76:79]
	v_mfma_f32_16x16x32_bf16 v[72:75], v[164:167], v[216:219], v[72:75]
	s_setprio 0
	s_setprio 1
	v_mfma_f32_16x16x32_bf16 v[116:119], v[168:171], v[184:187], v[116:119]
	v_mfma_f32_16x16x32_bf16 v[112:115], v[176:179], v[184:187], v[112:115]
	v_mfma_f32_16x16x32_bf16 v[100:103], v[168:171], v[196:199], v[100:103]
	v_mfma_f32_16x16x32_bf16 v[96:99], v[176:179], v[196:199], v[96:99]
	v_mfma_f32_16x16x32_bf16 v[84:87], v[168:171], v[204:207], v[84:87]
	v_mfma_f32_16x16x32_bf16 v[80:83], v[176:179], v[204:207], v[80:83]
	v_mfma_f32_16x16x32_bf16 v[68:71], v[168:171], v[212:215], v[68:71]
	v_mfma_f32_16x16x32_bf16 v[64:67], v[176:179], v[212:215], v[64:67]
	v_mfma_f32_16x16x32_bf16 v[116:119], v[172:175], v[188:191], v[116:119]
	v_mfma_f32_16x16x32_bf16 v[112:115], v[180:183], v[188:191], v[112:115]
	v_mfma_f32_16x16x32_bf16 v[100:103], v[172:175], v[200:203], v[100:103]
	v_mfma_f32_16x16x32_bf16 v[96:99], v[180:183], v[200:203], v[96:99]
	v_mfma_f32_16x16x32_bf16 v[84:87], v[172:175], v[208:211], v[84:87]
	v_mfma_f32_16x16x32_bf16 v[80:83], v[180:183], v[208:211], v[80:83]
	v_mfma_f32_16x16x32_bf16 v[68:71], v[172:175], v[216:219], v[68:71]
	v_mfma_f32_16x16x32_bf16 v[64:67], v[180:183], v[216:219], v[64:67]
	s_setprio 0
	s_barrier
	s_add_i32 s44, s77, s52
	v_lshl_add_u64 v[148:149], v[148:149], 0, s[18:19]
	s_mov_b32 m0, s44
	ds_read_b128 v[184:187], v155 offset:49152
	ds_read_b128 v[188:191], v155 offset:50176
	ds_read_b128 v[196:199], v155 offset:51200
	ds_read_b128 v[200:203], v155 offset:52224
	ds_read_b128 v[204:207], v155 offset:53248
	ds_read_b128 v[208:211], v155 offset:54272
	ds_read_b128 v[212:215], v155 offset:55296
	ds_read_b128 v[216:219], v155 offset:56320
	global_load_lds_dwordx4 v[148:149], off
	s_add_i32 m0, s44, 0x2000
	s_add_u32 s42, s42, 0x20080
	v_lshl_add_u64 v[148:149], v[192:193], 0, s[18:19]
	s_addc_u32 s43, s43, 0
	s_add_i32 s44, s78, s52
	global_load_lds_dwordx4 v[148:149], off
	s_mov_b32 m0, s44
	s_nop 0
	global_load_lds_dwordx4 v130, s[42:43]
	s_add_i32 m0, s44, 0x2000
	s_nop 0
	global_load_lds_dwordx4 v134, s[42:43]
	s_waitcnt vmcnt(6)
	s_waitcnt lgkmcnt(0)
	s_barrier
	s_setprio 1
	s_waitcnt lgkmcnt(0)
	v_mfma_f32_16x16x32_bf16 v[60:63], v[144:147], v[184:187], v[60:63]
	v_mfma_f32_16x16x32_bf16 v[56:59], v[160:163], v[184:187], v[56:59]
	v_mfma_f32_16x16x32_bf16 v[44:47], v[144:147], v[196:199], v[44:47]
	v_mfma_f32_16x16x32_bf16 v[40:43], v[160:163], v[196:199], v[40:43]
	v_mfma_f32_16x16x32_bf16 v[28:31], v[144:147], v[204:207], v[28:31]
	v_mfma_f32_16x16x32_bf16 v[24:27], v[160:163], v[204:207], v[24:27]
	v_mfma_f32_16x16x32_bf16 v[12:15], v[144:147], v[212:215], v[12:15]
	v_mfma_f32_16x16x32_bf16 v[8:11], v[160:163], v[212:215], v[8:11]
	v_mfma_f32_16x16x32_bf16 v[60:63], v[156:159], v[188:191], v[60:63]
	v_mfma_f32_16x16x32_bf16 v[56:59], v[164:167], v[188:191], v[56:59]
	v_mfma_f32_16x16x32_bf16 v[44:47], v[156:159], v[200:203], v[44:47]
	v_mfma_f32_16x16x32_bf16 v[40:43], v[164:167], v[200:203], v[40:43]
	v_mfma_f32_16x16x32_bf16 v[28:31], v[156:159], v[208:211], v[28:31]
	v_mfma_f32_16x16x32_bf16 v[24:27], v[164:167], v[208:211], v[24:27]
	v_mfma_f32_16x16x32_bf16 v[12:15], v[156:159], v[216:219], v[12:15]
	v_mfma_f32_16x16x32_bf16 v[8:11], v[164:167], v[216:219], v[8:11]
	s_setprio 0
	s_setprio 1
	v_mfma_f32_16x16x32_bf16 v[52:55], v[168:171], v[184:187], v[52:55]
	v_mfma_f32_16x16x32_bf16 v[48:51], v[176:179], v[184:187], v[48:51]
	v_mfma_f32_16x16x32_bf16 v[36:39], v[168:171], v[196:199], v[36:39]
	v_mfma_f32_16x16x32_bf16 v[32:35], v[176:179], v[196:199], v[32:35]
	v_mfma_f32_16x16x32_bf16 v[20:23], v[168:171], v[204:207], v[20:23]
	v_mfma_f32_16x16x32_bf16 v[16:19], v[176:179], v[204:207], v[16:19]
	v_mfma_f32_16x16x32_bf16 v[4:7], v[168:171], v[212:215], v[4:7]
	v_mfma_f32_16x16x32_bf16 v[0:3], v[176:179], v[212:215], v[0:3]
	v_mfma_f32_16x16x32_bf16 v[52:55], v[172:175], v[188:191], v[52:55]
	v_mfma_f32_16x16x32_bf16 v[48:51], v[180:183], v[188:191], v[48:51]
	v_mfma_f32_16x16x32_bf16 v[36:39], v[172:175], v[200:203], v[36:39]
	v_mfma_f32_16x16x32_bf16 v[32:35], v[180:183], v[200:203], v[32:35]
	v_mfma_f32_16x16x32_bf16 v[20:23], v[172:175], v[208:211], v[20:23]
	v_mfma_f32_16x16x32_bf16 v[16:19], v[180:183], v[208:211], v[16:19]
	v_mfma_f32_16x16x32_bf16 v[4:7], v[172:175], v[216:219], v[4:7]
	v_mfma_f32_16x16x32_bf16 v[0:3], v[180:183], v[216:219], v[0:3]
	s_setprio 0
	s_barrier
	v_lshl_add_u64 v[220:221], v[220:221], 0, s[18:19]
	s_mov_b32 m0, s57
	s_nop 0
	global_load_lds_dwordx4 v[220:221], off
	v_lshl_add_u64 v[222:223], v[222:223], 0, s[18:19]
	s_mov_b32 m0, s58
	s_nop 0
	global_load_lds_dwordx4 v[222:223], off
	s_add_i32 s73, s73, 2
	s_add_u32 s40, s40, 0x100
	s_addc_u32 s41, s41, 0
	s_add_u32 s71, s71, 0x100
	s_addc_u32 s72, s72, 0
	s_cmp_gt_u32 s73, 5
	s_cbranch_scc0 .LBB0_2633
	s_and_b64 vcc, exec, s[20:21]
	s_cbranch_vccz .LBB0_2636
	s_barrier

.LBB0_2657:
	ds_read_b128 v[144:147], v153
	ds_read_b128 v[158:161], v153 offset:1024
	ds_read_b128 v[162:165], v153 offset:2048
	ds_read_b128 v[166:169], v153 offset:3072
	ds_read_b128 v[170:173], v154
	ds_read_b128 v[174:177], v154 offset:1024
	ds_read_b128 v[178:181], v154 offset:2048
	ds_read_b128 v[182:185], v154 offset:3072
	s_add_u32 s34, s30, 0xfffc0080
	s_addc_u32 s35, s31, -1
	s_cmp_eq_u32 s70, 12
	s_cselect_b32 s37, s25, s35
	s_cselect_b32 s36, s60, s34
	s_cselect_b32 s35, s23, s63
	s_cselect_b32 s34, s61, s62
	s_add_i32 m0, s48, 0xc000
	ds_read_b128 v[186:189], v155
	ds_read_b128 v[190:193], v155 offset:1024
	ds_read_b128 v[196:199], v155 offset:2048
	ds_read_b128 v[200:203], v155 offset:3072
	ds_read_b128 v[204:207], v155 offset:4096
	ds_read_b128 v[208:211], v155 offset:5120
	ds_read_b128 v[212:215], v155 offset:6144
	ds_read_b128 v[216:219], v155 offset:7168
	global_load_lds_dwordx4 v136, s[30:31]
	s_add_i32 m0, s48, 0xe000
	s_nop 0
	global_load_lds_dwordx4 v138, s[30:31]
	s_waitcnt vmcnt(8)
	s_waitcnt lgkmcnt(0)
	s_barrier
	s_setprio 1
	s_waitcnt lgkmcnt(0)
	v_mfma_f32_16x16x32_bf16 v[124:127], v[144:147], v[186:189], v[124:127]
	v_mfma_f32_16x16x32_bf16 v[120:123], v[162:165], v[186:189], v[120:123]
	v_mfma_f32_16x16x32_bf16 v[108:111], v[144:147], v[196:199], v[108:111]
	v_mfma_f32_16x16x32_bf16 v[104:107], v[162:165], v[196:199], v[104:107]
	v_mfma_f32_16x16x32_bf16 v[92:95], v[144:147], v[204:207], v[92:95]
	v_mfma_f32_16x16x32_bf16 v[88:91], v[162:165], v[204:207], v[88:91]
	v_mfma_f32_16x16x32_bf16 v[76:79], v[144:147], v[212:215], v[76:79]
	v_mfma_f32_16x16x32_bf16 v[72:75], v[162:165], v[212:215], v[72:75]
	v_mfma_f32_16x16x32_bf16 v[124:127], v[158:161], v[190:193], v[124:127]
	v_mfma_f32_16x16x32_bf16 v[120:123], v[166:169], v[190:193], v[120:123]
	v_mfma_f32_16x16x32_bf16 v[108:111], v[158:161], v[200:203], v[108:111]
	v_mfma_f32_16x16x32_bf16 v[104:107], v[166:169], v[200:203], v[104:107]
	v_mfma_f32_16x16x32_bf16 v[92:95], v[158:161], v[208:211], v[92:95]
	v_mfma_f32_16x16x32_bf16 v[88:91], v[166:169], v[208:211], v[88:91]
	v_mfma_f32_16x16x32_bf16 v[76:79], v[158:161], v[216:219], v[76:79]
	v_mfma_f32_16x16x32_bf16 v[72:75], v[166:169], v[216:219], v[72:75]
	s_setprio 0
	s_setprio 1
	v_mfma_f32_16x16x32_bf16 v[116:119], v[170:173], v[186:189], v[116:119]
	v_mfma_f32_16x16x32_bf16 v[112:115], v[178:181], v[186:189], v[112:115]
	v_mfma_f32_16x16x32_bf16 v[100:103], v[170:173], v[196:199], v[100:103]
	v_mfma_f32_16x16x32_bf16 v[96:99], v[178:181], v[196:199], v[96:99]
	v_mfma_f32_16x16x32_bf16 v[84:87], v[170:173], v[204:207], v[84:87]
	v_mfma_f32_16x16x32_bf16 v[80:83], v[178:181], v[204:207], v[80:83]
	v_mfma_f32_16x16x32_bf16 v[68:71], v[170:173], v[212:215], v[68:71]
	v_mfma_f32_16x16x32_bf16 v[64:67], v[178:181], v[212:215], v[64:67]
	v_mfma_f32_16x16x32_bf16 v[116:119], v[174:177], v[190:193], v[116:119]
	v_mfma_f32_16x16x32_bf16 v[112:115], v[182:185], v[190:193], v[112:115]
	v_mfma_f32_16x16x32_bf16 v[100:103], v[174:177], v[200:203], v[100:103]
	v_mfma_f32_16x16x32_bf16 v[96:99], v[182:185], v[200:203], v[96:99]
	v_mfma_f32_16x16x32_bf16 v[84:87], v[174:177], v[208:211], v[84:87]
	v_mfma_f32_16x16x32_bf16 v[80:83], v[182:185], v[208:211], v[80:83]
	v_mfma_f32_16x16x32_bf16 v[68:71], v[174:177], v[216:219], v[68:71]
	v_mfma_f32_16x16x32_bf16 v[64:67], v[182:185], v[216:219], v[64:67]
	s_setprio 0
	s_barrier
	s_add_i32 s71, s56, s45
	v_lshl_add_u64 v[148:149], s[34:35], 0, v[130:131]
	s_mov_b32 m0, s71
	ds_read_b128 v[186:189], v155 offset:16384
	ds_read_b128 v[190:193], v155 offset:17408
	ds_read_b128 v[196:199], v155 offset:18432
	ds_read_b128 v[200:203], v155 offset:19456
	ds_read_b128 v[204:207], v155 offset:20480
	ds_read_b128 v[208:211], v155 offset:21504
	ds_read_b128 v[212:215], v155 offset:22528
	ds_read_b128 v[216:219], v155 offset:23552
	global_load_lds_dwordx4 v[148:149], off
	s_add_i32 m0, s71, 0x2000
	s_add_u32 s72, s34, 0x40000
	v_lshl_add_u64 v[220:221], s[34:35], 0, v[134:135]
	s_addc_u32 s73, s35, 0
	s_add_i32 s71, s57, s45
	global_load_lds_dwordx4 v[220:221], off
	s_mov_b32 m0, s71
	v_lshl_add_u64 v[224:225], s[36:37], 0, v[132:133]
	global_load_lds_dwordx4 v130, s[72:73]
	s_add_i32 m0, s71, 0x2000
	s_nop 0
	global_load_lds_dwordx4 v134, s[72:73]
	v_lshl_add_u64 v[222:223], s[36:37], 0, v[128:129]
	s_waitcnt vmcnt(6)
	s_waitcnt lgkmcnt(0)
	s_barrier
	s_setprio 1
	s_waitcnt lgkmcnt(0)
	v_mfma_f32_16x16x32_bf16 v[60:63], v[144:147], v[186:189], v[60:63]
	v_mfma_f32_16x16x32_bf16 v[56:59], v[162:165], v[186:189], v[56:59]
	v_mfma_f32_16x16x32_bf16 v[44:47], v[144:147], v[196:199], v[44:47]
	v_mfma_f32_16x16x32_bf16 v[40:43], v[162:165], v[196:199], v[40:43]
	v_mfma_f32_16x16x32_bf16 v[28:31], v[144:147], v[204:207], v[28:31]
	v_mfma_f32_16x16x32_bf16 v[24:27], v[162:165], v[204:207], v[24:27]
	v_mfma_f32_16x16x32_bf16 v[12:15], v[144:147], v[212:215], v[12:15]
	v_mfma_f32_16x16x32_bf16 v[8:11], v[162:165], v[212:215], v[8:11]
	v_mfma_f32_16x16x32_bf16 v[60:63], v[158:161], v[190:193], v[60:63]
	v_mfma_f32_16x16x32_bf16 v[56:59], v[166:169], v[190:193], v[56:59]
	v_mfma_f32_16x16x32_bf16 v[44:47], v[158:161], v[200:203], v[44:47]
	v_mfma_f32_16x16x32_bf16 v[40:43], v[166:169], v[200:203], v[40:43]
	v_mfma_f32_16x16x32_bf16 v[28:31], v[158:161], v[208:211], v[28:31]
	v_mfma_f32_16x16x32_bf16 v[24:27], v[166:169], v[208:211], v[24:27]
	v_mfma_f32_16x16x32_bf16 v[12:15], v[158:161], v[216:219], v[12:15]
	v_mfma_f32_16x16x32_bf16 v[8:11], v[166:169], v[216:219], v[8:11]
	s_setprio 0
	s_setprio 1
	v_mfma_f32_16x16x32_bf16 v[52:55], v[170:173], v[186:189], v[52:55]
	v_mfma_f32_16x16x32_bf16 v[48:51], v[178:181], v[186:189], v[48:51]
	v_mfma_f32_16x16x32_bf16 v[36:39], v[170:173], v[196:199], v[36:39]
	v_mfma_f32_16x16x32_bf16 v[32:35], v[178:181], v[196:199], v[32:35]
	v_mfma_f32_16x16x32_bf16 v[20:23], v[170:173], v[204:207], v[20:23]
	v_mfma_f32_16x16x32_bf16 v[16:19], v[178:181], v[204:207], v[16:19]
	v_mfma_f32_16x16x32_bf16 v[4:7], v[170:173], v[212:215], v[4:7]
	v_mfma_f32_16x16x32_bf16 v[0:3], v[178:181], v[212:215], v[0:3]
	v_mfma_f32_16x16x32_bf16 v[52:55], v[174:177], v[190:193], v[52:55]
	v_mfma_f32_16x16x32_bf16 v[48:51], v[182:185], v[190:193], v[48:51]
	v_mfma_f32_16x16x32_bf16 v[36:39], v[174:177], v[200:203], v[36:39]
	v_mfma_f32_16x16x32_bf16 v[32:35], v[182:185], v[200:203], v[32:35]
	v_mfma_f32_16x16x32_bf16 v[20:23], v[174:177], v[208:211], v[20:23]
	v_mfma_f32_16x16x32_bf16 v[16:19], v[182:185], v[208:211], v[16:19]
	v_mfma_f32_16x16x32_bf16 v[4:7], v[174:177], v[216:219], v[4:7]
	v_mfma_f32_16x16x32_bf16 v[0:3], v[182:185], v[216:219], v[0:3]
	s_setprio 0
	s_barrier
	s_add_i32 s71, 0, 0x18000
	v_add_u32_e32 v157, s71, v151
	s_add_i32 s72, 0, 0x1c000
	ds_read_b128 v[144:147], v157
	ds_read_b128 v[158:161], v157 offset:1024
	ds_read_b128 v[162:165], v157 offset:2048
	ds_read_b128 v[166:169], v157 offset:3072
	v_add_u32_e32 v157, s72, v151
	ds_read_b128 v[170:173], v157
	ds_read_b128 v[174:177], v157 offset:1024
	ds_read_b128 v[178:181], v157 offset:2048
	ds_read_b128 v[182:185], v157 offset:3072
	s_add_u32 s36, s36, 0x40000
	s_addc_u32 s37, s37, 0
	ds_read_b128 v[186:189], v155 offset:32768
	ds_read_b128 v[190:193], v155 offset:33792
	ds_read_b128 v[196:199], v155 offset:34816
	ds_read_b128 v[200:203], v155 offset:35840
	ds_read_b128 v[204:207], v155 offset:36864
	ds_read_b128 v[208:211], v155 offset:37888
	ds_read_b128 v[212:215], v155 offset:38912
	ds_read_b128 v[216:219], v155 offset:39936
	s_mov_b32 m0, s48
	s_nop 0
	global_load_lds_dwordx4 v[222:223], off
	s_mov_b32 m0, s49
	s_nop 0
	global_load_lds_dwordx4 v[224:225], off
	s_mov_b32 m0, s50
	s_nop 0
	global_load_lds_dwordx4 v128, s[36:37]
	s_mov_b32 m0, s51
	s_nop 0
	global_load_lds_dwordx4 v132, s[36:37]
	s_waitcnt vmcnt(8)
	s_waitcnt lgkmcnt(0)
	s_barrier
	s_setprio 1
	s_waitcnt lgkmcnt(0)
	v_mfma_f32_16x16x32_bf16 v[124:127], v[144:147], v[186:189], v[124:127]
	v_mfma_f32_16x16x32_bf16 v[120:123], v[162:165], v[186:189], v[120:123]
	v_mfma_f32_16x16x32_bf16 v[108:111], v[144:147], v[196:199], v[108:111]
	v_mfma_f32_16x16x32_bf16 v[104:107], v[162:165], v[196:199], v[104:107]
	v_mfma_f32_16x16x32_bf16 v[92:95], v[144:147], v[204:207], v[92:95]
	v_mfma_f32_16x16x32_bf16 v[88:91], v[162:165], v[204:207], v[88:91]
	v_mfma_f32_16x16x32_bf16 v[76:79], v[144:147], v[212:215], v[76:79]
	v_mfma_f32_16x16x32_bf16 v[72:75], v[162:165], v[212:215], v[72:75]
	v_mfma_f32_16x16x32_bf16 v[124:127], v[158:161], v[190:193], v[124:127]
	v_mfma_f32_16x16x32_bf16 v[120:123], v[166:169], v[190:193], v[120:123]
	v_mfma_f32_16x16x32_bf16 v[108:111], v[158:161], v[200:203], v[108:111]
	v_mfma_f32_16x16x32_bf16 v[104:107], v[166:169], v[200:203], v[104:107]
	v_mfma_f32_16x16x32_bf16 v[92:95], v[158:161], v[208:211], v[92:95]
	v_mfma_f32_16x16x32_bf16 v[88:91], v[166:169], v[208:211], v[88:91]
	v_mfma_f32_16x16x32_bf16 v[76:79], v[158:161], v[216:219], v[76:79]
	v_mfma_f32_16x16x32_bf16 v[72:75], v[166:169], v[216:219], v[72:75]
	s_setprio 0
	s_setprio 1
	v_mfma_f32_16x16x32_bf16 v[116:119], v[170:173], v[186:189], v[116:119]
	v_mfma_f32_16x16x32_bf16 v[112:115], v[178:181], v[186:189], v[112:115]
	v_mfma_f32_16x16x32_bf16 v[100:103], v[170:173], v[196:199], v[100:103]
	v_mfma_f32_16x16x32_bf16 v[96:99], v[178:181], v[196:199], v[96:99]
	v_mfma_f32_16x16x32_bf16 v[84:87], v[170:173], v[204:207], v[84:87]
	v_mfma_f32_16x16x32_bf16 v[80:83], v[178:181], v[204:207], v[80:83]
	v_mfma_f32_16x16x32_bf16 v[68:71], v[170:173], v[212:215], v[68:71]
	v_mfma_f32_16x16x32_bf16 v[64:67], v[178:181], v[212:215], v[64:67]
	v_mfma_f32_16x16x32_bf16 v[116:119], v[174:177], v[190:193], v[116:119]
	v_mfma_f32_16x16x32_bf16 v[112:115], v[182:185], v[190:193], v[112:115]
	v_mfma_f32_16x16x32_bf16 v[100:103], v[174:177], v[200:203], v[100:103]
	v_mfma_f32_16x16x32_bf16 v[96:99], v[182:185], v[200:203], v[96:99]
	v_mfma_f32_16x16x32_bf16 v[84:87], v[174:177], v[208:211], v[84:87]
	v_mfma_f32_16x16x32_bf16 v[80:83], v[182:185], v[208:211], v[80:83]
	v_mfma_f32_16x16x32_bf16 v[68:71], v[174:177], v[216:219], v[68:71]
	v_mfma_f32_16x16x32_bf16 v[64:67], v[182:185], v[216:219], v[64:67]
	s_setprio 0
	s_barrier
	s_add_i32 s36, s71, s45
	v_lshl_add_u64 v[148:149], v[148:149], 0, s[18:19]
	s_mov_b32 m0, s36
	ds_read_b128 v[186:189], v155 offset:49152
	ds_read_b128 v[190:193], v155 offset:50176
	ds_read_b128 v[196:199], v155 offset:51200
	ds_read_b128 v[200:203], v155 offset:52224
	ds_read_b128 v[204:207], v155 offset:53248
	ds_read_b128 v[208:211], v155 offset:54272
	ds_read_b128 v[212:215], v155 offset:55296
	ds_read_b128 v[216:219], v155 offset:56320
	global_load_lds_dwordx4 v[148:149], off
	s_add_i32 m0, s36, 0x2000
	s_add_u32 s34, s34, 0x40080
	v_lshl_add_u64 v[148:149], v[220:221], 0, s[18:19]
	s_addc_u32 s35, s35, 0
	s_add_i32 s36, s72, s45
	global_load_lds_dwordx4 v[148:149], off
	s_mov_b32 m0, s36
	s_nop 0
	global_load_lds_dwordx4 v130, s[34:35]
	s_add_i32 m0, s36, 0x2000
	s_nop 0
	global_load_lds_dwordx4 v134, s[34:35]
	s_waitcnt vmcnt(6)
	s_waitcnt lgkmcnt(0)
	s_barrier
	s_setprio 1
	s_waitcnt lgkmcnt(0)
	v_mfma_f32_16x16x32_bf16 v[60:63], v[144:147], v[186:189], v[60:63]
	v_mfma_f32_16x16x32_bf16 v[56:59], v[162:165], v[186:189], v[56:59]
	v_mfma_f32_16x16x32_bf16 v[44:47], v[144:147], v[196:199], v[44:47]
	v_mfma_f32_16x16x32_bf16 v[40:43], v[162:165], v[196:199], v[40:43]
	v_mfma_f32_16x16x32_bf16 v[28:31], v[144:147], v[204:207], v[28:31]
	v_mfma_f32_16x16x32_bf16 v[24:27], v[162:165], v[204:207], v[24:27]
	v_mfma_f32_16x16x32_bf16 v[12:15], v[144:147], v[212:215], v[12:15]
	v_mfma_f32_16x16x32_bf16 v[8:11], v[162:165], v[212:215], v[8:11]
	v_mfma_f32_16x16x32_bf16 v[60:63], v[158:161], v[190:193], v[60:63]
	v_mfma_f32_16x16x32_bf16 v[56:59], v[166:169], v[190:193], v[56:59]
	v_mfma_f32_16x16x32_bf16 v[44:47], v[158:161], v[200:203], v[44:47]
	v_mfma_f32_16x16x32_bf16 v[40:43], v[166:169], v[200:203], v[40:43]
	v_mfma_f32_16x16x32_bf16 v[28:31], v[158:161], v[208:211], v[28:31]
	v_mfma_f32_16x16x32_bf16 v[24:27], v[166:169], v[208:211], v[24:27]
	v_mfma_f32_16x16x32_bf16 v[12:15], v[158:161], v[216:219], v[12:15]
	v_mfma_f32_16x16x32_bf16 v[8:11], v[166:169], v[216:219], v[8:11]
	s_setprio 0
	s_setprio 1
	v_mfma_f32_16x16x32_bf16 v[52:55], v[170:173], v[186:189], v[52:55]
	v_mfma_f32_16x16x32_bf16 v[48:51], v[178:181], v[186:189], v[48:51]
	v_mfma_f32_16x16x32_bf16 v[36:39], v[170:173], v[196:199], v[36:39]
	v_mfma_f32_16x16x32_bf16 v[32:35], v[178:181], v[196:199], v[32:35]
	v_mfma_f32_16x16x32_bf16 v[20:23], v[170:173], v[204:207], v[20:23]
	v_mfma_f32_16x16x32_bf16 v[16:19], v[178:181], v[204:207], v[16:19]
	v_mfma_f32_16x16x32_bf16 v[4:7], v[170:173], v[212:215], v[4:7]
	v_mfma_f32_16x16x32_bf16 v[0:3], v[178:181], v[212:215], v[0:3]
	v_mfma_f32_16x16x32_bf16 v[52:55], v[174:177], v[190:193], v[52:55]
	v_mfma_f32_16x16x32_bf16 v[48:51], v[182:185], v[190:193], v[48:51]
	v_mfma_f32_16x16x32_bf16 v[36:39], v[174:177], v[200:203], v[36:39]
	v_mfma_f32_16x16x32_bf16 v[32:35], v[182:185], v[200:203], v[32:35]
	v_mfma_f32_16x16x32_bf16 v[20:23], v[174:177], v[208:211], v[20:23]
	v_mfma_f32_16x16x32_bf16 v[16:19], v[182:185], v[208:211], v[16:19]
	v_mfma_f32_16x16x32_bf16 v[4:7], v[174:177], v[216:219], v[4:7]
	v_mfma_f32_16x16x32_bf16 v[0:3], v[182:185], v[216:219], v[0:3]
	s_setprio 0
	s_barrier
	v_lshl_add_u64 v[222:223], v[222:223], 0, s[18:19]
	s_mov_b32 m0, s53
	s_nop 0
	global_load_lds_dwordx4 v[222:223], off
	v_lshl_add_u64 v[224:225], v[224:225], 0, s[18:19]
	s_mov_b32 m0, s54
	s_nop 0
	global_load_lds_dwordx4 v[224:225], off
	s_add_i32 s70, s70, 2
	s_add_u32 s30, s30, 0x100
	s_addc_u32 s31, s31, 0
	s_add_u32 s62, s62, 0x100
	s_addc_u32 s63, s63, 0
	s_cmp_gt_u32 s70, 13
	s_cbranch_scc0 .LBB0_2657
	s_and_b64 vcc, exec, s[20:21]
	s_cbranch_vccz .LBB0_2660
	s_barrier

.LBB0_3031:
	ds_read_b128 v[146:149], v155
	ds_read_b128 v[160:163], v155 offset:1024
	ds_read_b128 v[164:167], v155 offset:2048
	ds_read_b128 v[168:171], v155 offset:3072
	ds_read_b128 v[172:175], v156
	ds_read_b128 v[176:179], v156 offset:1024
	ds_read_b128 v[180:183], v156 offset:2048
	ds_read_b128 v[184:187], v156 offset:3072
	s_add_u32 s36, s0, 0xfffc0080
	s_addc_u32 s37, s1, -1
	s_cmp_eq_u32 s60, 12
	s_cselect_b32 s39, s21, s37
	s_cselect_b32 s38, s23, s36
	s_cselect_b32 s37, s27, s59
	s_cselect_b32 s36, s26, s25
	s_add_i32 m0, s35, 0xc000
	ds_read_b128 v[188:191], v157
	ds_read_b128 v[196:199], v157 offset:1024
	ds_read_b128 v[200:203], v157 offset:2048
	ds_read_b128 v[204:207], v157 offset:3072
	ds_read_b128 v[208:211], v157 offset:4096
	ds_read_b128 v[212:215], v157 offset:5120
	ds_read_b128 v[216:219], v157 offset:6144
	ds_read_b128 v[220:223], v157 offset:7168
	global_load_lds_dwordx4 v138, s[0:1]
	s_add_i32 m0, s35, 0xe000
	s_nop 0
	global_load_lds_dwordx4 v140, s[0:1]
	s_waitcnt vmcnt(8)
	s_waitcnt lgkmcnt(0)
	s_barrier
	s_setprio 1
	s_waitcnt lgkmcnt(0)
	v_mfma_f32_16x16x32_bf16 v[124:127], v[146:149], v[188:191], v[124:127]
	v_mfma_f32_16x16x32_bf16 v[120:123], v[164:167], v[188:191], v[120:123]
	v_mfma_f32_16x16x32_bf16 v[108:111], v[146:149], v[200:203], v[108:111]
	v_mfma_f32_16x16x32_bf16 v[104:107], v[164:167], v[200:203], v[104:107]
	v_mfma_f32_16x16x32_bf16 v[92:95], v[146:149], v[208:211], v[92:95]
	v_mfma_f32_16x16x32_bf16 v[88:91], v[164:167], v[208:211], v[88:91]
	v_mfma_f32_16x16x32_bf16 v[76:79], v[146:149], v[216:219], v[76:79]
	v_mfma_f32_16x16x32_bf16 v[72:75], v[164:167], v[216:219], v[72:75]
	v_mfma_f32_16x16x32_bf16 v[124:127], v[160:163], v[196:199], v[124:127]
	v_mfma_f32_16x16x32_bf16 v[120:123], v[168:171], v[196:199], v[120:123]
	v_mfma_f32_16x16x32_bf16 v[108:111], v[160:163], v[204:207], v[108:111]
	v_mfma_f32_16x16x32_bf16 v[104:107], v[168:171], v[204:207], v[104:107]
	v_mfma_f32_16x16x32_bf16 v[92:95], v[160:163], v[212:215], v[92:95]
	v_mfma_f32_16x16x32_bf16 v[88:91], v[168:171], v[212:215], v[88:91]
	v_mfma_f32_16x16x32_bf16 v[76:79], v[160:163], v[220:223], v[76:79]
	v_mfma_f32_16x16x32_bf16 v[72:75], v[168:171], v[220:223], v[72:75]
	s_setprio 0
	s_setprio 1
	v_mfma_f32_16x16x32_bf16 v[116:119], v[172:175], v[188:191], v[116:119]
	v_mfma_f32_16x16x32_bf16 v[112:115], v[180:183], v[188:191], v[112:115]
	v_mfma_f32_16x16x32_bf16 v[100:103], v[172:175], v[200:203], v[100:103]
	v_mfma_f32_16x16x32_bf16 v[96:99], v[180:183], v[200:203], v[96:99]
	v_mfma_f32_16x16x32_bf16 v[84:87], v[172:175], v[208:211], v[84:87]
	v_mfma_f32_16x16x32_bf16 v[80:83], v[180:183], v[208:211], v[80:83]
	v_mfma_f32_16x16x32_bf16 v[68:71], v[172:175], v[216:219], v[68:71]
	v_mfma_f32_16x16x32_bf16 v[64:67], v[180:183], v[216:219], v[64:67]
	v_mfma_f32_16x16x32_bf16 v[116:119], v[176:179], v[196:199], v[116:119]
	v_mfma_f32_16x16x32_bf16 v[112:115], v[184:187], v[196:199], v[112:115]
	v_mfma_f32_16x16x32_bf16 v[100:103], v[176:179], v[204:207], v[100:103]
	v_mfma_f32_16x16x32_bf16 v[96:99], v[184:187], v[204:207], v[96:99]
	v_mfma_f32_16x16x32_bf16 v[84:87], v[176:179], v[212:215], v[84:87]
	v_mfma_f32_16x16x32_bf16 v[80:83], v[184:187], v[212:215], v[80:83]
	v_mfma_f32_16x16x32_bf16 v[68:71], v[176:179], v[220:223], v[68:71]
	v_mfma_f32_16x16x32_bf16 v[64:67], v[184:187], v[220:223], v[64:67]
	s_setprio 0
	s_barrier
	s_add_i32 s61, s55, s44
	v_lshl_add_u64 v[150:151], s[36:37], 0, v[130:131]
	s_mov_b32 m0, s61
	ds_read_b128 v[188:191], v157 offset:16384
	ds_read_b128 v[196:199], v157 offset:17408
	ds_read_b128 v[200:203], v157 offset:18432
	ds_read_b128 v[204:207], v157 offset:19456
	ds_read_b128 v[208:211], v157 offset:20480
	ds_read_b128 v[212:215], v157 offset:21504
	ds_read_b128 v[216:219], v157 offset:22528
	ds_read_b128 v[220:223], v157 offset:23552
	global_load_lds_dwordx4 v[150:151], off
	s_add_i32 m0, s61, 0x2000
	s_add_u32 s62, s36, 0x40000
	v_lshl_add_u64 v[192:193], s[36:37], 0, v[134:135]
	s_addc_u32 s63, s37, 0
	s_add_i32 s61, s56, s44
	global_load_lds_dwordx4 v[192:193], off
	s_mov_b32 m0, s61
	v_lshl_add_u64 v[226:227], s[38:39], 0, v[132:133]
	global_load_lds_dwordx4 v130, s[62:63]
	s_add_i32 m0, s61, 0x2000
	s_nop 0
	global_load_lds_dwordx4 v134, s[62:63]
	v_lshl_add_u64 v[224:225], s[38:39], 0, v[128:129]
	s_waitcnt vmcnt(6)
	s_waitcnt lgkmcnt(0)
	s_barrier
	s_setprio 1
	s_waitcnt lgkmcnt(0)
	v_mfma_f32_16x16x32_bf16 v[60:63], v[146:149], v[188:191], v[60:63]
	v_mfma_f32_16x16x32_bf16 v[56:59], v[164:167], v[188:191], v[56:59]
	v_mfma_f32_16x16x32_bf16 v[44:47], v[146:149], v[200:203], v[44:47]
	v_mfma_f32_16x16x32_bf16 v[40:43], v[164:167], v[200:203], v[40:43]
	v_mfma_f32_16x16x32_bf16 v[28:31], v[146:149], v[208:211], v[28:31]
	v_mfma_f32_16x16x32_bf16 v[24:27], v[164:167], v[208:211], v[24:27]
	v_mfma_f32_16x16x32_bf16 v[12:15], v[146:149], v[216:219], v[12:15]
	v_mfma_f32_16x16x32_bf16 v[8:11], v[164:167], v[216:219], v[8:11]
	v_mfma_f32_16x16x32_bf16 v[60:63], v[160:163], v[196:199], v[60:63]
	v_mfma_f32_16x16x32_bf16 v[56:59], v[168:171], v[196:199], v[56:59]
	v_mfma_f32_16x16x32_bf16 v[44:47], v[160:163], v[204:207], v[44:47]
	v_mfma_f32_16x16x32_bf16 v[40:43], v[168:171], v[204:207], v[40:43]
	v_mfma_f32_16x16x32_bf16 v[28:31], v[160:163], v[212:215], v[28:31]
	v_mfma_f32_16x16x32_bf16 v[24:27], v[168:171], v[212:215], v[24:27]
	v_mfma_f32_16x16x32_bf16 v[12:15], v[160:163], v[220:223], v[12:15]
	v_mfma_f32_16x16x32_bf16 v[8:11], v[168:171], v[220:223], v[8:11]
	s_setprio 0
	s_setprio 1
	v_mfma_f32_16x16x32_bf16 v[52:55], v[172:175], v[188:191], v[52:55]
	v_mfma_f32_16x16x32_bf16 v[48:51], v[180:183], v[188:191], v[48:51]
	v_mfma_f32_16x16x32_bf16 v[36:39], v[172:175], v[200:203], v[36:39]
	v_mfma_f32_16x16x32_bf16 v[32:35], v[180:183], v[200:203], v[32:35]
	v_mfma_f32_16x16x32_bf16 v[20:23], v[172:175], v[208:211], v[20:23]
	v_mfma_f32_16x16x32_bf16 v[16:19], v[180:183], v[208:211], v[16:19]
	v_mfma_f32_16x16x32_bf16 v[4:7], v[172:175], v[216:219], v[4:7]
	v_mfma_f32_16x16x32_bf16 v[0:3], v[180:183], v[216:219], v[0:3]
	v_mfma_f32_16x16x32_bf16 v[52:55], v[176:179], v[196:199], v[52:55]
	v_mfma_f32_16x16x32_bf16 v[48:51], v[184:187], v[196:199], v[48:51]
	v_mfma_f32_16x16x32_bf16 v[36:39], v[176:179], v[204:207], v[36:39]
	v_mfma_f32_16x16x32_bf16 v[32:35], v[184:187], v[204:207], v[32:35]
	v_mfma_f32_16x16x32_bf16 v[20:23], v[176:179], v[212:215], v[20:23]
	v_mfma_f32_16x16x32_bf16 v[16:19], v[184:187], v[212:215], v[16:19]
	v_mfma_f32_16x16x32_bf16 v[4:7], v[176:179], v[220:223], v[4:7]
	v_mfma_f32_16x16x32_bf16 v[0:3], v[184:187], v[220:223], v[0:3]
	s_setprio 0
	s_barrier
	s_add_i32 s61, 0, 0x18000
	v_add_u32_e32 v159, s61, v153
	s_add_i32 s62, 0, 0x1c000
	ds_read_b128 v[146:149], v159
	ds_read_b128 v[160:163], v159 offset:1024
	ds_read_b128 v[164:167], v159 offset:2048
	ds_read_b128 v[168:171], v159 offset:3072
	v_add_u32_e32 v159, s62, v153
	ds_read_b128 v[172:175], v159
	ds_read_b128 v[176:179], v159 offset:1024
	ds_read_b128 v[180:183], v159 offset:2048
	ds_read_b128 v[184:187], v159 offset:3072
	s_add_u32 s38, s38, 0x40000
	s_addc_u32 s39, s39, 0
	ds_read_b128 v[188:191], v157 offset:32768
	ds_read_b128 v[196:199], v157 offset:33792
	ds_read_b128 v[200:203], v157 offset:34816
	ds_read_b128 v[204:207], v157 offset:35840
	ds_read_b128 v[208:211], v157 offset:36864
	ds_read_b128 v[212:215], v157 offset:37888
	ds_read_b128 v[216:219], v157 offset:38912
	ds_read_b128 v[220:223], v157 offset:39936
	s_mov_b32 m0, s35
	s_nop 0
	global_load_lds_dwordx4 v[224:225], off
	s_mov_b32 m0, s45
	s_nop 0
	global_load_lds_dwordx4 v[226:227], off
	s_mov_b32 m0, s48
	s_nop 0
	global_load_lds_dwordx4 v128, s[38:39]
	s_mov_b32 m0, s49
	s_nop 0
	global_load_lds_dwordx4 v132, s[38:39]
	s_waitcnt vmcnt(8)
	s_waitcnt lgkmcnt(0)
	s_barrier
	s_setprio 1
	s_waitcnt lgkmcnt(0)
	v_mfma_f32_16x16x32_bf16 v[124:127], v[146:149], v[188:191], v[124:127]
	v_mfma_f32_16x16x32_bf16 v[120:123], v[164:167], v[188:191], v[120:123]
	v_mfma_f32_16x16x32_bf16 v[108:111], v[146:149], v[200:203], v[108:111]
	v_mfma_f32_16x16x32_bf16 v[104:107], v[164:167], v[200:203], v[104:107]
	v_mfma_f32_16x16x32_bf16 v[92:95], v[146:149], v[208:211], v[92:95]
	v_mfma_f32_16x16x32_bf16 v[88:91], v[164:167], v[208:211], v[88:91]
	v_mfma_f32_16x16x32_bf16 v[76:79], v[146:149], v[216:219], v[76:79]
	v_mfma_f32_16x16x32_bf16 v[72:75], v[164:167], v[216:219], v[72:75]
	v_mfma_f32_16x16x32_bf16 v[124:127], v[160:163], v[196:199], v[124:127]
	v_mfma_f32_16x16x32_bf16 v[120:123], v[168:171], v[196:199], v[120:123]
	v_mfma_f32_16x16x32_bf16 v[108:111], v[160:163], v[204:207], v[108:111]
	v_mfma_f32_16x16x32_bf16 v[104:107], v[168:171], v[204:207], v[104:107]
	v_mfma_f32_16x16x32_bf16 v[92:95], v[160:163], v[212:215], v[92:95]
	v_mfma_f32_16x16x32_bf16 v[88:91], v[168:171], v[212:215], v[88:91]
	v_mfma_f32_16x16x32_bf16 v[76:79], v[160:163], v[220:223], v[76:79]
	v_mfma_f32_16x16x32_bf16 v[72:75], v[168:171], v[220:223], v[72:75]
	s_setprio 0
	s_setprio 1
	v_mfma_f32_16x16x32_bf16 v[116:119], v[172:175], v[188:191], v[116:119]
	v_mfma_f32_16x16x32_bf16 v[112:115], v[180:183], v[188:191], v[112:115]
	v_mfma_f32_16x16x32_bf16 v[100:103], v[172:175], v[200:203], v[100:103]
	v_mfma_f32_16x16x32_bf16 v[96:99], v[180:183], v[200:203], v[96:99]
	v_mfma_f32_16x16x32_bf16 v[84:87], v[172:175], v[208:211], v[84:87]
	v_mfma_f32_16x16x32_bf16 v[80:83], v[180:183], v[208:211], v[80:83]
	v_mfma_f32_16x16x32_bf16 v[68:71], v[172:175], v[216:219], v[68:71]
	v_mfma_f32_16x16x32_bf16 v[64:67], v[180:183], v[216:219], v[64:67]
	v_mfma_f32_16x16x32_bf16 v[116:119], v[176:179], v[196:199], v[116:119]
	v_mfma_f32_16x16x32_bf16 v[112:115], v[184:187], v[196:199], v[112:115]
	v_mfma_f32_16x16x32_bf16 v[100:103], v[176:179], v[204:207], v[100:103]
	v_mfma_f32_16x16x32_bf16 v[96:99], v[184:187], v[204:207], v[96:99]
	v_mfma_f32_16x16x32_bf16 v[84:87], v[176:179], v[212:215], v[84:87]
	v_mfma_f32_16x16x32_bf16 v[80:83], v[184:187], v[212:215], v[80:83]
	v_mfma_f32_16x16x32_bf16 v[68:71], v[176:179], v[220:223], v[68:71]
	v_mfma_f32_16x16x32_bf16 v[64:67], v[184:187], v[220:223], v[64:67]
	s_setprio 0
	s_barrier
	s_add_i32 s38, s61, s44
	v_lshl_add_u64 v[150:151], v[150:151], 0, s[16:17]
	s_mov_b32 m0, s38
	ds_read_b128 v[188:191], v157 offset:49152
	ds_read_b128 v[196:199], v157 offset:50176
	ds_read_b128 v[200:203], v157 offset:51200
	ds_read_b128 v[204:207], v157 offset:52224
	ds_read_b128 v[208:211], v157 offset:53248
	ds_read_b128 v[212:215], v157 offset:54272
	ds_read_b128 v[216:219], v157 offset:55296
	ds_read_b128 v[220:223], v157 offset:56320
	global_load_lds_dwordx4 v[150:151], off
	s_add_i32 m0, s38, 0x2000
	s_add_u32 s36, s36, 0x40080
	v_lshl_add_u64 v[150:151], v[192:193], 0, s[16:17]
	s_addc_u32 s37, s37, 0
	s_add_i32 s38, s62, s44
	global_load_lds_dwordx4 v[150:151], off
	s_mov_b32 m0, s38
	s_nop 0
	global_load_lds_dwordx4 v130, s[36:37]
	s_add_i32 m0, s38, 0x2000
	s_nop 0
	global_load_lds_dwordx4 v134, s[36:37]
	s_waitcnt vmcnt(6)
	s_waitcnt lgkmcnt(0)
	s_barrier
	s_setprio 1
	s_waitcnt lgkmcnt(0)
	v_mfma_f32_16x16x32_bf16 v[60:63], v[146:149], v[188:191], v[60:63]
	v_mfma_f32_16x16x32_bf16 v[56:59], v[164:167], v[188:191], v[56:59]
	v_mfma_f32_16x16x32_bf16 v[44:47], v[146:149], v[200:203], v[44:47]
	v_mfma_f32_16x16x32_bf16 v[40:43], v[164:167], v[200:203], v[40:43]
	v_mfma_f32_16x16x32_bf16 v[28:31], v[146:149], v[208:211], v[28:31]
	v_mfma_f32_16x16x32_bf16 v[24:27], v[164:167], v[208:211], v[24:27]
	v_mfma_f32_16x16x32_bf16 v[12:15], v[146:149], v[216:219], v[12:15]
	v_mfma_f32_16x16x32_bf16 v[8:11], v[164:167], v[216:219], v[8:11]
	v_mfma_f32_16x16x32_bf16 v[60:63], v[160:163], v[196:199], v[60:63]
	v_mfma_f32_16x16x32_bf16 v[56:59], v[168:171], v[196:199], v[56:59]
	v_mfma_f32_16x16x32_bf16 v[44:47], v[160:163], v[204:207], v[44:47]
	v_mfma_f32_16x16x32_bf16 v[40:43], v[168:171], v[204:207], v[40:43]
	v_mfma_f32_16x16x32_bf16 v[28:31], v[160:163], v[212:215], v[28:31]
	v_mfma_f32_16x16x32_bf16 v[24:27], v[168:171], v[212:215], v[24:27]
	v_mfma_f32_16x16x32_bf16 v[12:15], v[160:163], v[220:223], v[12:15]
	v_mfma_f32_16x16x32_bf16 v[8:11], v[168:171], v[220:223], v[8:11]
	s_setprio 0
	s_setprio 1
	v_mfma_f32_16x16x32_bf16 v[52:55], v[172:175], v[188:191], v[52:55]
	v_mfma_f32_16x16x32_bf16 v[48:51], v[180:183], v[188:191], v[48:51]
	v_mfma_f32_16x16x32_bf16 v[36:39], v[172:175], v[200:203], v[36:39]
	v_mfma_f32_16x16x32_bf16 v[32:35], v[180:183], v[200:203], v[32:35]
	v_mfma_f32_16x16x32_bf16 v[20:23], v[172:175], v[208:211], v[20:23]
	v_mfma_f32_16x16x32_bf16 v[16:19], v[180:183], v[208:211], v[16:19]
	v_mfma_f32_16x16x32_bf16 v[4:7], v[172:175], v[216:219], v[4:7]
	v_mfma_f32_16x16x32_bf16 v[0:3], v[180:183], v[216:219], v[0:3]
	v_mfma_f32_16x16x32_bf16 v[52:55], v[176:179], v[196:199], v[52:55]
	v_mfma_f32_16x16x32_bf16 v[48:51], v[184:187], v[196:199], v[48:51]
	v_mfma_f32_16x16x32_bf16 v[36:39], v[176:179], v[204:207], v[36:39]
	v_mfma_f32_16x16x32_bf16 v[32:35], v[184:187], v[204:207], v[32:35]
	v_mfma_f32_16x16x32_bf16 v[20:23], v[176:179], v[212:215], v[20:23]
	v_mfma_f32_16x16x32_bf16 v[16:19], v[184:187], v[212:215], v[16:19]
	v_mfma_f32_16x16x32_bf16 v[4:7], v[176:179], v[220:223], v[4:7]
	v_mfma_f32_16x16x32_bf16 v[0:3], v[184:187], v[220:223], v[0:3]
	s_setprio 0
	s_barrier
	v_lshl_add_u64 v[224:225], v[224:225], 0, s[16:17]
	s_mov_b32 m0, s50
	s_nop 0
	global_load_lds_dwordx4 v[224:225], off
	v_lshl_add_u64 v[226:227], v[226:227], 0, s[16:17]
	s_mov_b32 m0, s51
	s_nop 0
	global_load_lds_dwordx4 v[226:227], off
	s_add_i32 s60, s60, 2
	s_add_u32 s0, s0, 0x100
	s_addc_u32 s1, s1, 0
	s_add_u32 s25, s25, 0x100
	s_addc_u32 s59, s59, 0
	s_cmp_gt_u32 s60, 13
	s_cbranch_scc0 .LBB0_3031
	s_and_b64 vcc, exec, s[18:19]
	s_cbranch_vccz .LBB0_3034
	s_barrier

.LBB0_3061:
	ds_read_b128 v[144:147], v159
	ds_read_b128 v[148:151], v159 offset:1024
	ds_read_b128 v[152:155], v159 offset:2048
	ds_read_b128 v[162:165], v159 offset:3072
	ds_read_b128 v[166:169], v160
	ds_read_b128 v[170:173], v160 offset:1024
	ds_read_b128 v[174:177], v160 offset:2048
	ds_read_b128 v[178:181], v160 offset:3072
	s_add_u32 s37, s42, 0xfffe0080
	s_addc_u32 s39, s43, -1
	s_cmp_eq_u32 s35, 4
	s_cselect_b32 s51, s1, s39
	s_cselect_b32 s50, s0, s37
	s_cselect_b32 s49, s41, s13
	s_cselect_b32 s48, s40, s11
	s_add_i32 m0, s60, 0xc000
	ds_read_b128 v[182:185], v161
	ds_read_b128 v[186:189], v161 offset:1024
	ds_read_b128 v[190:193], v161 offset:2048
	ds_read_b128 v[196:199], v161 offset:3072
	ds_read_b128 v[200:203], v161 offset:4096
	ds_read_b128 v[204:207], v161 offset:5120
	ds_read_b128 v[208:211], v161 offset:6144
	ds_read_b128 v[212:215], v161 offset:7168
	global_load_lds_dwordx4 v136, s[42:43]
	s_add_i32 m0, s60, 0xe000
	s_nop 0
	global_load_lds_dwordx4 v138, s[42:43]
	s_waitcnt vmcnt(8)
	s_waitcnt lgkmcnt(0)
	s_barrier
	s_setprio 1
	s_waitcnt lgkmcnt(0)
	v_mfma_f32_16x16x32_bf16 v[124:127], v[144:147], v[182:185], v[124:127]
	v_mfma_f32_16x16x32_bf16 v[120:123], v[152:155], v[182:185], v[120:123]
	v_mfma_f32_16x16x32_bf16 v[108:111], v[144:147], v[190:193], v[108:111]
	v_mfma_f32_16x16x32_bf16 v[104:107], v[152:155], v[190:193], v[104:107]
	v_mfma_f32_16x16x32_bf16 v[92:95], v[144:147], v[200:203], v[92:95]
	v_mfma_f32_16x16x32_bf16 v[88:91], v[152:155], v[200:203], v[88:91]
	v_mfma_f32_16x16x32_bf16 v[76:79], v[144:147], v[208:211], v[76:79]
	v_mfma_f32_16x16x32_bf16 v[72:75], v[152:155], v[208:211], v[72:75]
	v_mfma_f32_16x16x32_bf16 v[124:127], v[148:151], v[186:189], v[124:127]
	v_mfma_f32_16x16x32_bf16 v[120:123], v[162:165], v[186:189], v[120:123]
	v_mfma_f32_16x16x32_bf16 v[108:111], v[148:151], v[196:199], v[108:111]
	v_mfma_f32_16x16x32_bf16 v[104:107], v[162:165], v[196:199], v[104:107]
	v_mfma_f32_16x16x32_bf16 v[92:95], v[148:151], v[204:207], v[92:95]
	v_mfma_f32_16x16x32_bf16 v[88:91], v[162:165], v[204:207], v[88:91]
	v_mfma_f32_16x16x32_bf16 v[76:79], v[148:151], v[212:215], v[76:79]
	v_mfma_f32_16x16x32_bf16 v[72:75], v[162:165], v[212:215], v[72:75]
	s_setprio 0
	s_setprio 1
	v_mfma_f32_16x16x32_bf16 v[116:119], v[166:169], v[182:185], v[116:119]
	v_mfma_f32_16x16x32_bf16 v[112:115], v[174:177], v[182:185], v[112:115]
	v_mfma_f32_16x16x32_bf16 v[100:103], v[166:169], v[190:193], v[100:103]
	v_mfma_f32_16x16x32_bf16 v[96:99], v[174:177], v[190:193], v[96:99]
	v_mfma_f32_16x16x32_bf16 v[84:87], v[166:169], v[200:203], v[84:87]
	v_mfma_f32_16x16x32_bf16 v[80:83], v[174:177], v[200:203], v[80:83]
	v_mfma_f32_16x16x32_bf16 v[68:71], v[166:169], v[208:211], v[68:71]
	v_mfma_f32_16x16x32_bf16 v[64:67], v[174:177], v[208:211], v[64:67]
	v_mfma_f32_16x16x32_bf16 v[116:119], v[170:173], v[186:189], v[116:119]
	v_mfma_f32_16x16x32_bf16 v[112:115], v[178:181], v[186:189], v[112:115]
	v_mfma_f32_16x16x32_bf16 v[100:103], v[170:173], v[196:199], v[100:103]
	v_mfma_f32_16x16x32_bf16 v[96:99], v[178:181], v[196:199], v[96:99]
	v_mfma_f32_16x16x32_bf16 v[84:87], v[170:173], v[204:207], v[84:87]
	v_mfma_f32_16x16x32_bf16 v[80:83], v[178:181], v[204:207], v[80:83]
	v_mfma_f32_16x16x32_bf16 v[68:71], v[170:173], v[212:215], v[68:71]
	v_mfma_f32_16x16x32_bf16 v[64:67], v[178:181], v[212:215], v[64:67]
	s_setprio 0
	s_barrier
	s_add_i32 s37, s73, s57
	v_lshl_add_u64 v[216:217], s[48:49], 0, v[130:131]
	s_mov_b32 m0, s37
	ds_read_b128 v[182:185], v161 offset:16384
	ds_read_b128 v[186:189], v161 offset:17408
	ds_read_b128 v[190:193], v161 offset:18432
	ds_read_b128 v[196:199], v161 offset:19456
	ds_read_b128 v[200:203], v161 offset:20480
	ds_read_b128 v[204:207], v161 offset:21504
	ds_read_b128 v[208:211], v161 offset:22528
	ds_read_b128 v[212:215], v161 offset:23552
	global_load_lds_dwordx4 v[216:217], off
	s_add_i32 m0, s37, 0x2000
	s_add_u32 s80, s48, 0x20000
	v_lshl_add_u64 v[218:219], s[48:49], 0, v[134:135]
	s_addc_u32 s81, s49, 0
	s_add_i32 s37, s77, s57
	global_load_lds_dwordx4 v[218:219], off
	s_mov_b32 m0, s37
	v_lshl_add_u64 v[222:223], s[50:51], 0, v[132:133]
	global_load_lds_dwordx4 v130, s[80:81]
	s_add_i32 m0, s37, 0x2000
	s_nop 0
	global_load_lds_dwordx4 v134, s[80:81]
	v_lshl_add_u64 v[220:221], s[50:51], 0, v[128:129]
	s_waitcnt vmcnt(6)
	s_waitcnt lgkmcnt(0)
	s_barrier
	s_setprio 1
	s_waitcnt lgkmcnt(0)
	v_mfma_f32_16x16x32_bf16 v[60:63], v[144:147], v[182:185], v[60:63]
	v_mfma_f32_16x16x32_bf16 v[56:59], v[152:155], v[182:185], v[56:59]
	v_mfma_f32_16x16x32_bf16 v[44:47], v[144:147], v[190:193], v[44:47]
	v_mfma_f32_16x16x32_bf16 v[40:43], v[152:155], v[190:193], v[40:43]
	v_mfma_f32_16x16x32_bf16 v[28:31], v[144:147], v[200:203], v[28:31]
	v_mfma_f32_16x16x32_bf16 v[24:27], v[152:155], v[200:203], v[24:27]
	v_mfma_f32_16x16x32_bf16 v[12:15], v[144:147], v[208:211], v[12:15]
	v_mfma_f32_16x16x32_bf16 v[8:11], v[152:155], v[208:211], v[8:11]
	v_mfma_f32_16x16x32_bf16 v[60:63], v[148:151], v[186:189], v[60:63]
	v_mfma_f32_16x16x32_bf16 v[56:59], v[162:165], v[186:189], v[56:59]
	v_mfma_f32_16x16x32_bf16 v[44:47], v[148:151], v[196:199], v[44:47]
	v_mfma_f32_16x16x32_bf16 v[40:43], v[162:165], v[196:199], v[40:43]
	v_mfma_f32_16x16x32_bf16 v[28:31], v[148:151], v[204:207], v[28:31]
	v_mfma_f32_16x16x32_bf16 v[24:27], v[162:165], v[204:207], v[24:27]
	v_mfma_f32_16x16x32_bf16 v[12:15], v[148:151], v[212:215], v[12:15]
	v_mfma_f32_16x16x32_bf16 v[8:11], v[162:165], v[212:215], v[8:11]
	s_setprio 0
	s_setprio 1
	v_mfma_f32_16x16x32_bf16 v[52:55], v[166:169], v[182:185], v[52:55]
	v_mfma_f32_16x16x32_bf16 v[48:51], v[174:177], v[182:185], v[48:51]
	v_mfma_f32_16x16x32_bf16 v[36:39], v[166:169], v[190:193], v[36:39]
	v_mfma_f32_16x16x32_bf16 v[32:35], v[174:177], v[190:193], v[32:35]
	v_mfma_f32_16x16x32_bf16 v[20:23], v[166:169], v[200:203], v[20:23]
	v_mfma_f32_16x16x32_bf16 v[16:19], v[174:177], v[200:203], v[16:19]
	v_mfma_f32_16x16x32_bf16 v[4:7], v[166:169], v[208:211], v[4:7]
	v_mfma_f32_16x16x32_bf16 v[0:3], v[174:177], v[208:211], v[0:3]
	v_mfma_f32_16x16x32_bf16 v[52:55], v[170:173], v[186:189], v[52:55]
	v_mfma_f32_16x16x32_bf16 v[48:51], v[178:181], v[186:189], v[48:51]
	v_mfma_f32_16x16x32_bf16 v[36:39], v[170:173], v[196:199], v[36:39]
	v_mfma_f32_16x16x32_bf16 v[32:35], v[178:181], v[196:199], v[32:35]
	v_mfma_f32_16x16x32_bf16 v[20:23], v[170:173], v[204:207], v[20:23]
	v_mfma_f32_16x16x32_bf16 v[16:19], v[178:181], v[204:207], v[16:19]
	v_mfma_f32_16x16x32_bf16 v[4:7], v[170:173], v[212:215], v[4:7]
	v_mfma_f32_16x16x32_bf16 v[0:3], v[178:181], v[212:215], v[0:3]
	s_setprio 0
	s_barrier
	s_add_i32 s37, 0, 0x18000
	s_add_i32 s39, 0, 0x1c000
	v_add_u32_e32 v162, s37, v157
	v_add_u32_e32 v178, s39, v157
	ds_read_b128 v[144:147], v162
	ds_read_b128 v[148:151], v162 offset:1024
	ds_read_b128 v[152:155], v162 offset:2048
	ds_read_b128 v[162:165], v162 offset:3072
	ds_read_b128 v[166:169], v178
	ds_read_b128 v[170:173], v178 offset:1024
	ds_read_b128 v[174:177], v178 offset:2048
	ds_read_b128 v[178:181], v178 offset:3072
	s_add_u32 s50, s50, 0x20000
	s_addc_u32 s51, s51, 0
	ds_read_b128 v[182:185], v161 offset:32768
	ds_read_b128 v[186:189], v161 offset:33792
	ds_read_b128 v[190:193], v161 offset:34816
	ds_read_b128 v[196:199], v161 offset:35840
	ds_read_b128 v[200:203], v161 offset:36864
	ds_read_b128 v[204:207], v161 offset:37888
	ds_read_b128 v[208:211], v161 offset:38912
	ds_read_b128 v[212:215], v161 offset:39936
	s_mov_b32 m0, s60
	s_nop 0
	global_load_lds_dwordx4 v[220:221], off
	s_mov_b32 m0, s61
	s_nop 0
	global_load_lds_dwordx4 v[222:223], off
	s_mov_b32 m0, s62
	s_nop 0
	global_load_lds_dwordx4 v128, s[50:51]
	s_mov_b32 m0, s63
	s_nop 0
	global_load_lds_dwordx4 v132, s[50:51]
	s_waitcnt vmcnt(8)
	s_waitcnt lgkmcnt(0)
	s_barrier
	s_setprio 1
	s_waitcnt lgkmcnt(0)
	v_mfma_f32_16x16x32_bf16 v[124:127], v[144:147], v[182:185], v[124:127]
	v_mfma_f32_16x16x32_bf16 v[120:123], v[152:155], v[182:185], v[120:123]
	v_mfma_f32_16x16x32_bf16 v[108:111], v[144:147], v[190:193], v[108:111]
	v_mfma_f32_16x16x32_bf16 v[104:107], v[152:155], v[190:193], v[104:107]
	v_mfma_f32_16x16x32_bf16 v[92:95], v[144:147], v[200:203], v[92:95]
	v_mfma_f32_16x16x32_bf16 v[88:91], v[152:155], v[200:203], v[88:91]
	v_mfma_f32_16x16x32_bf16 v[76:79], v[144:147], v[208:211], v[76:79]
	v_mfma_f32_16x16x32_bf16 v[72:75], v[152:155], v[208:211], v[72:75]
	v_mfma_f32_16x16x32_bf16 v[124:127], v[148:151], v[186:189], v[124:127]
	v_mfma_f32_16x16x32_bf16 v[120:123], v[162:165], v[186:189], v[120:123]
	v_mfma_f32_16x16x32_bf16 v[108:111], v[148:151], v[196:199], v[108:111]
	v_mfma_f32_16x16x32_bf16 v[104:107], v[162:165], v[196:199], v[104:107]
	v_mfma_f32_16x16x32_bf16 v[92:95], v[148:151], v[204:207], v[92:95]
	v_mfma_f32_16x16x32_bf16 v[88:91], v[162:165], v[204:207], v[88:91]
	v_mfma_f32_16x16x32_bf16 v[76:79], v[148:151], v[212:215], v[76:79]
	v_mfma_f32_16x16x32_bf16 v[72:75], v[162:165], v[212:215], v[72:75]
	s_setprio 0
	s_setprio 1
	v_mfma_f32_16x16x32_bf16 v[116:119], v[166:169], v[182:185], v[116:119]
	v_mfma_f32_16x16x32_bf16 v[112:115], v[174:177], v[182:185], v[112:115]
	v_mfma_f32_16x16x32_bf16 v[100:103], v[166:169], v[190:193], v[100:103]
	v_mfma_f32_16x16x32_bf16 v[96:99], v[174:177], v[190:193], v[96:99]
	v_mfma_f32_16x16x32_bf16 v[84:87], v[166:169], v[200:203], v[84:87]
	v_mfma_f32_16x16x32_bf16 v[80:83], v[174:177], v[200:203], v[80:83]
	v_mfma_f32_16x16x32_bf16 v[68:71], v[166:169], v[208:211], v[68:71]
	v_mfma_f32_16x16x32_bf16 v[64:67], v[174:177], v[208:211], v[64:67]
	v_mfma_f32_16x16x32_bf16 v[116:119], v[170:173], v[186:189], v[116:119]
	v_mfma_f32_16x16x32_bf16 v[112:115], v[178:181], v[186:189], v[112:115]
	v_mfma_f32_16x16x32_bf16 v[100:103], v[170:173], v[196:199], v[100:103]
	v_mfma_f32_16x16x32_bf16 v[96:99], v[178:181], v[196:199], v[96:99]
	v_mfma_f32_16x16x32_bf16 v[84:87], v[170:173], v[204:207], v[84:87]
	v_mfma_f32_16x16x32_bf16 v[80:83], v[178:181], v[204:207], v[80:83]
	v_mfma_f32_16x16x32_bf16 v[68:71], v[170:173], v[212:215], v[68:71]
	v_mfma_f32_16x16x32_bf16 v[64:67], v[178:181], v[212:215], v[64:67]
	s_setprio 0
	s_barrier
	s_add_i32 s37, s37, s57
	v_lshl_add_u64 v[216:217], v[216:217], 0, s[22:23]
	s_mov_b32 m0, s37
	ds_read_b128 v[182:185], v161 offset:49152
	ds_read_b128 v[186:189], v161 offset:50176
	ds_read_b128 v[190:193], v161 offset:51200
	ds_read_b128 v[196:199], v161 offset:52224
	ds_read_b128 v[200:203], v161 offset:53248
	ds_read_b128 v[204:207], v161 offset:54272
	ds_read_b128 v[208:211], v161 offset:55296
	ds_read_b128 v[212:215], v161 offset:56320
	global_load_lds_dwordx4 v[216:217], off
	s_add_i32 m0, s37, 0x2000
	s_add_u32 s48, s48, 0x20080
	v_lshl_add_u64 v[216:217], v[218:219], 0, s[22:23]
	s_addc_u32 s49, s49, 0
	s_add_i32 s37, s39, s57
	global_load_lds_dwordx4 v[216:217], off
	s_mov_b32 m0, s37
	s_nop 0
	global_load_lds_dwordx4 v130, s[48:49]
	s_add_i32 m0, s37, 0x2000
	s_nop 0
	global_load_lds_dwordx4 v134, s[48:49]
	s_waitcnt vmcnt(6)
	s_waitcnt lgkmcnt(0)
	s_barrier
	s_setprio 1
	s_waitcnt lgkmcnt(0)
	v_mfma_f32_16x16x32_bf16 v[60:63], v[144:147], v[182:185], v[60:63]
	v_mfma_f32_16x16x32_bf16 v[56:59], v[152:155], v[182:185], v[56:59]
	v_mfma_f32_16x16x32_bf16 v[44:47], v[144:147], v[190:193], v[44:47]
	v_mfma_f32_16x16x32_bf16 v[40:43], v[152:155], v[190:193], v[40:43]
	v_mfma_f32_16x16x32_bf16 v[28:31], v[144:147], v[200:203], v[28:31]
	v_mfma_f32_16x16x32_bf16 v[24:27], v[152:155], v[200:203], v[24:27]
	v_mfma_f32_16x16x32_bf16 v[12:15], v[144:147], v[208:211], v[12:15]
	v_mfma_f32_16x16x32_bf16 v[8:11], v[152:155], v[208:211], v[8:11]
	v_mfma_f32_16x16x32_bf16 v[60:63], v[148:151], v[186:189], v[60:63]
	v_mfma_f32_16x16x32_bf16 v[56:59], v[162:165], v[186:189], v[56:59]
	v_mfma_f32_16x16x32_bf16 v[44:47], v[148:151], v[196:199], v[44:47]
	v_mfma_f32_16x16x32_bf16 v[40:43], v[162:165], v[196:199], v[40:43]
	v_mfma_f32_16x16x32_bf16 v[28:31], v[148:151], v[204:207], v[28:31]
	v_mfma_f32_16x16x32_bf16 v[24:27], v[162:165], v[204:207], v[24:27]
	v_mfma_f32_16x16x32_bf16 v[12:15], v[148:151], v[212:215], v[12:15]
	v_mfma_f32_16x16x32_bf16 v[8:11], v[162:165], v[212:215], v[8:11]
	s_setprio 0
	s_setprio 1
	v_mfma_f32_16x16x32_bf16 v[52:55], v[166:169], v[182:185], v[52:55]
	v_mfma_f32_16x16x32_bf16 v[48:51], v[174:177], v[182:185], v[48:51]
	v_mfma_f32_16x16x32_bf16 v[36:39], v[166:169], v[190:193], v[36:39]
	v_mfma_f32_16x16x32_bf16 v[32:35], v[174:177], v[190:193], v[32:35]
	v_mfma_f32_16x16x32_bf16 v[20:23], v[166:169], v[200:203], v[20:23]
	v_mfma_f32_16x16x32_bf16 v[16:19], v[174:177], v[200:203], v[16:19]
	v_mfma_f32_16x16x32_bf16 v[4:7], v[166:169], v[208:211], v[4:7]
	v_mfma_f32_16x16x32_bf16 v[0:3], v[174:177], v[208:211], v[0:3]
	v_mfma_f32_16x16x32_bf16 v[52:55], v[170:173], v[186:189], v[52:55]
	v_mfma_f32_16x16x32_bf16 v[48:51], v[178:181], v[186:189], v[48:51]
	v_mfma_f32_16x16x32_bf16 v[36:39], v[170:173], v[196:199], v[36:39]
	v_mfma_f32_16x16x32_bf16 v[32:35], v[178:181], v[196:199], v[32:35]
	v_mfma_f32_16x16x32_bf16 v[20:23], v[170:173], v[204:207], v[20:23]
	v_mfma_f32_16x16x32_bf16 v[16:19], v[178:181], v[204:207], v[16:19]
	v_mfma_f32_16x16x32_bf16 v[4:7], v[170:173], v[212:215], v[4:7]
	v_mfma_f32_16x16x32_bf16 v[0:3], v[178:181], v[212:215], v[0:3]
	s_setprio 0
	s_barrier
	v_lshl_add_u64 v[220:221], v[220:221], 0, s[22:23]
	s_mov_b32 m0, s70
	s_nop 0
	global_load_lds_dwordx4 v[220:221], off
	v_lshl_add_u64 v[222:223], v[222:223], 0, s[22:23]
	s_mov_b32 m0, s71
	s_nop 0
	global_load_lds_dwordx4 v[222:223], off
	s_add_i32 s35, s35, 2
	s_add_u32 s42, s42, 0x100
	s_addc_u32 s43, s43, 0
	s_add_u32 s11, s11, 0x100
	s_addc_u32 s13, s13, 0
	s_cmp_gt_u32 s35, 5
	s_cbranch_scc0 .LBB0_3061
	s_and_b64 vcc, exec, s[24:25]
	s_cbranch_vccz .LBB0_3064
	s_barrier

.LBB0_3235:
	ds_read_b128 v[144:147], v151
	ds_read_b128 v[156:159], v151 offset:1024
	ds_read_b128 v[160:163], v151 offset:2048
	ds_read_b128 v[164:167], v151 offset:3072
	ds_read_b128 v[168:171], v152
	ds_read_b128 v[172:175], v152 offset:1024
	ds_read_b128 v[176:179], v152 offset:2048
	ds_read_b128 v[180:183], v152 offset:3072
	s_add_u32 s38, s36, 0xfffc0080
	s_addc_u32 s39, s37, -1
	s_cmp_eq_u32 s70, 12
	s_cselect_b32 s41, s27, s39
	s_cselect_b32 s40, s35, s38
	s_cselect_b32 s39, s25, s63
	s_cselect_b32 s38, s61, s62
	s_add_i32 m0, s50, 0xc000
	ds_read_b128 v[184:187], v153
	ds_read_b128 v[188:191], v153 offset:1024
	ds_read_b128 v[196:199], v153 offset:2048
	ds_read_b128 v[200:203], v153 offset:3072
	ds_read_b128 v[204:207], v153 offset:4096
	ds_read_b128 v[208:211], v153 offset:5120
	ds_read_b128 v[212:215], v153 offset:6144
	ds_read_b128 v[216:219], v153 offset:7168
	global_load_lds_dwordx4 v136, s[36:37]
	s_add_i32 m0, s50, 0xe000
	s_nop 0
	global_load_lds_dwordx4 v138, s[36:37]
	s_waitcnt vmcnt(8)
	s_waitcnt lgkmcnt(0)
	s_barrier
	s_setprio 1
	s_waitcnt lgkmcnt(0)
	v_mfma_f32_16x16x32_bf16 v[124:127], v[144:147], v[184:187], v[124:127]
	v_mfma_f32_16x16x32_bf16 v[120:123], v[160:163], v[184:187], v[120:123]
	v_mfma_f32_16x16x32_bf16 v[108:111], v[144:147], v[196:199], v[108:111]
	v_mfma_f32_16x16x32_bf16 v[104:107], v[160:163], v[196:199], v[104:107]
	v_mfma_f32_16x16x32_bf16 v[92:95], v[144:147], v[204:207], v[92:95]
	v_mfma_f32_16x16x32_bf16 v[88:91], v[160:163], v[204:207], v[88:91]
	v_mfma_f32_16x16x32_bf16 v[76:79], v[144:147], v[212:215], v[76:79]
	v_mfma_f32_16x16x32_bf16 v[72:75], v[160:163], v[212:215], v[72:75]
	v_mfma_f32_16x16x32_bf16 v[124:127], v[156:159], v[188:191], v[124:127]
	v_mfma_f32_16x16x32_bf16 v[120:123], v[164:167], v[188:191], v[120:123]
	v_mfma_f32_16x16x32_bf16 v[108:111], v[156:159], v[200:203], v[108:111]
	v_mfma_f32_16x16x32_bf16 v[104:107], v[164:167], v[200:203], v[104:107]
	v_mfma_f32_16x16x32_bf16 v[92:95], v[156:159], v[208:211], v[92:95]
	v_mfma_f32_16x16x32_bf16 v[88:91], v[164:167], v[208:211], v[88:91]
	v_mfma_f32_16x16x32_bf16 v[76:79], v[156:159], v[216:219], v[76:79]
	v_mfma_f32_16x16x32_bf16 v[72:75], v[164:167], v[216:219], v[72:75]
	s_setprio 0
	s_setprio 1
	v_mfma_f32_16x16x32_bf16 v[116:119], v[168:171], v[184:187], v[116:119]
	v_mfma_f32_16x16x32_bf16 v[112:115], v[176:179], v[184:187], v[112:115]
	v_mfma_f32_16x16x32_bf16 v[100:103], v[168:171], v[196:199], v[100:103]
	v_mfma_f32_16x16x32_bf16 v[96:99], v[176:179], v[196:199], v[96:99]
	v_mfma_f32_16x16x32_bf16 v[84:87], v[168:171], v[204:207], v[84:87]
	v_mfma_f32_16x16x32_bf16 v[80:83], v[176:179], v[204:207], v[80:83]
	v_mfma_f32_16x16x32_bf16 v[68:71], v[168:171], v[212:215], v[68:71]
	v_mfma_f32_16x16x32_bf16 v[64:67], v[176:179], v[212:215], v[64:67]
	v_mfma_f32_16x16x32_bf16 v[116:119], v[172:175], v[188:191], v[116:119]
	v_mfma_f32_16x16x32_bf16 v[112:115], v[180:183], v[188:191], v[112:115]
	v_mfma_f32_16x16x32_bf16 v[100:103], v[172:175], v[200:203], v[100:103]
	v_mfma_f32_16x16x32_bf16 v[96:99], v[180:183], v[200:203], v[96:99]
	v_mfma_f32_16x16x32_bf16 v[84:87], v[172:175], v[208:211], v[84:87]
	v_mfma_f32_16x16x32_bf16 v[80:83], v[180:183], v[208:211], v[80:83]
	v_mfma_f32_16x16x32_bf16 v[68:71], v[172:175], v[216:219], v[68:71]
	v_mfma_f32_16x16x32_bf16 v[64:67], v[180:183], v[216:219], v[64:67]
	s_setprio 0
	s_barrier
	s_add_i32 s71, s58, s49
	v_lshl_add_u64 v[192:193], s[38:39], 0, v[130:131]
	s_mov_b32 m0, s71
	ds_read_b128 v[184:187], v153 offset:16384
	ds_read_b128 v[188:191], v153 offset:17408
	ds_read_b128 v[196:199], v153 offset:18432
	ds_read_b128 v[200:203], v153 offset:19456
	ds_read_b128 v[204:207], v153 offset:20480
	ds_read_b128 v[208:211], v153 offset:21504
	ds_read_b128 v[212:215], v153 offset:22528
	ds_read_b128 v[216:219], v153 offset:23552
	global_load_lds_dwordx4 v[192:193], off
	s_add_i32 m0, s71, 0x2000
	s_add_u32 s72, s38, 0x40000
	v_lshl_add_u64 v[220:221], s[38:39], 0, v[134:135]
	s_addc_u32 s73, s39, 0
	s_add_i32 s71, s59, s49
	global_load_lds_dwordx4 v[220:221], off
	s_mov_b32 m0, s71
	v_lshl_add_u64 v[224:225], s[40:41], 0, v[132:133]
	global_load_lds_dwordx4 v130, s[72:73]
	s_add_i32 m0, s71, 0x2000
	s_nop 0
	global_load_lds_dwordx4 v134, s[72:73]
	v_lshl_add_u64 v[222:223], s[40:41], 0, v[128:129]
	s_waitcnt vmcnt(6)
	s_waitcnt lgkmcnt(0)
	s_barrier
	s_setprio 1
	s_waitcnt lgkmcnt(0)
	v_mfma_f32_16x16x32_bf16 v[60:63], v[144:147], v[184:187], v[60:63]
	v_mfma_f32_16x16x32_bf16 v[56:59], v[160:163], v[184:187], v[56:59]
	v_mfma_f32_16x16x32_bf16 v[44:47], v[144:147], v[196:199], v[44:47]
	v_mfma_f32_16x16x32_bf16 v[40:43], v[160:163], v[196:199], v[40:43]
	v_mfma_f32_16x16x32_bf16 v[28:31], v[144:147], v[204:207], v[28:31]
	v_mfma_f32_16x16x32_bf16 v[24:27], v[160:163], v[204:207], v[24:27]
	v_mfma_f32_16x16x32_bf16 v[12:15], v[144:147], v[212:215], v[12:15]
	v_mfma_f32_16x16x32_bf16 v[8:11], v[160:163], v[212:215], v[8:11]
	v_mfma_f32_16x16x32_bf16 v[60:63], v[156:159], v[188:191], v[60:63]
	v_mfma_f32_16x16x32_bf16 v[56:59], v[164:167], v[188:191], v[56:59]
	v_mfma_f32_16x16x32_bf16 v[44:47], v[156:159], v[200:203], v[44:47]
	v_mfma_f32_16x16x32_bf16 v[40:43], v[164:167], v[200:203], v[40:43]
	v_mfma_f32_16x16x32_bf16 v[28:31], v[156:159], v[208:211], v[28:31]
	v_mfma_f32_16x16x32_bf16 v[24:27], v[164:167], v[208:211], v[24:27]
	v_mfma_f32_16x16x32_bf16 v[12:15], v[156:159], v[216:219], v[12:15]
	v_mfma_f32_16x16x32_bf16 v[8:11], v[164:167], v[216:219], v[8:11]
	s_setprio 0
	s_setprio 1
	v_mfma_f32_16x16x32_bf16 v[52:55], v[168:171], v[184:187], v[52:55]
	v_mfma_f32_16x16x32_bf16 v[48:51], v[176:179], v[184:187], v[48:51]
	v_mfma_f32_16x16x32_bf16 v[36:39], v[168:171], v[196:199], v[36:39]
	v_mfma_f32_16x16x32_bf16 v[32:35], v[176:179], v[196:199], v[32:35]
	v_mfma_f32_16x16x32_bf16 v[20:23], v[168:171], v[204:207], v[20:23]
	v_mfma_f32_16x16x32_bf16 v[16:19], v[176:179], v[204:207], v[16:19]
	v_mfma_f32_16x16x32_bf16 v[4:7], v[168:171], v[212:215], v[4:7]
	v_mfma_f32_16x16x32_bf16 v[0:3], v[176:179], v[212:215], v[0:3]
	v_mfma_f32_16x16x32_bf16 v[52:55], v[172:175], v[188:191], v[52:55]
	v_mfma_f32_16x16x32_bf16 v[48:51], v[180:183], v[188:191], v[48:51]
	v_mfma_f32_16x16x32_bf16 v[36:39], v[172:175], v[200:203], v[36:39]
	v_mfma_f32_16x16x32_bf16 v[32:35], v[180:183], v[200:203], v[32:35]
	v_mfma_f32_16x16x32_bf16 v[20:23], v[172:175], v[208:211], v[20:23]
	v_mfma_f32_16x16x32_bf16 v[16:19], v[180:183], v[208:211], v[16:19]
	v_mfma_f32_16x16x32_bf16 v[4:7], v[172:175], v[216:219], v[4:7]
	v_mfma_f32_16x16x32_bf16 v[0:3], v[180:183], v[216:219], v[0:3]
	s_setprio 0
	s_barrier
	s_add_i32 s71, 0, 0x18000
	v_add_u32_e32 v155, s71, v149
	s_add_i32 s72, 0, 0x1c000
	ds_read_b128 v[144:147], v155
	ds_read_b128 v[156:159], v155 offset:1024
	ds_read_b128 v[160:163], v155 offset:2048
	ds_read_b128 v[164:167], v155 offset:3072
	v_add_u32_e32 v155, s72, v149
	ds_read_b128 v[168:171], v155
	ds_read_b128 v[172:175], v155 offset:1024
	ds_read_b128 v[176:179], v155 offset:2048
	ds_read_b128 v[180:183], v155 offset:3072
	s_add_u32 s40, s40, 0x40000
	s_addc_u32 s41, s41, 0
	ds_read_b128 v[184:187], v153 offset:32768
	ds_read_b128 v[188:191], v153 offset:33792
	ds_read_b128 v[196:199], v153 offset:34816
	ds_read_b128 v[200:203], v153 offset:35840
	ds_read_b128 v[204:207], v153 offset:36864
	ds_read_b128 v[208:211], v153 offset:37888
	ds_read_b128 v[212:215], v153 offset:38912
	ds_read_b128 v[216:219], v153 offset:39936
	s_mov_b32 m0, s50
	s_nop 0
	global_load_lds_dwordx4 v[222:223], off
	s_mov_b32 m0, s51
	s_nop 0
	global_load_lds_dwordx4 v[224:225], off
	s_mov_b32 m0, s52
	s_nop 0
	global_load_lds_dwordx4 v128, s[40:41]
	s_mov_b32 m0, s53
	s_nop 0
	global_load_lds_dwordx4 v132, s[40:41]
	s_waitcnt vmcnt(8)
	s_waitcnt lgkmcnt(0)
	s_barrier
	s_setprio 1
	s_waitcnt lgkmcnt(0)
	v_mfma_f32_16x16x32_bf16 v[124:127], v[144:147], v[184:187], v[124:127]
	v_mfma_f32_16x16x32_bf16 v[120:123], v[160:163], v[184:187], v[120:123]
	v_mfma_f32_16x16x32_bf16 v[108:111], v[144:147], v[196:199], v[108:111]
	v_mfma_f32_16x16x32_bf16 v[104:107], v[160:163], v[196:199], v[104:107]
	v_mfma_f32_16x16x32_bf16 v[92:95], v[144:147], v[204:207], v[92:95]
	v_mfma_f32_16x16x32_bf16 v[88:91], v[160:163], v[204:207], v[88:91]
	v_mfma_f32_16x16x32_bf16 v[76:79], v[144:147], v[212:215], v[76:79]
	v_mfma_f32_16x16x32_bf16 v[72:75], v[160:163], v[212:215], v[72:75]
	v_mfma_f32_16x16x32_bf16 v[124:127], v[156:159], v[188:191], v[124:127]
	v_mfma_f32_16x16x32_bf16 v[120:123], v[164:167], v[188:191], v[120:123]
	v_mfma_f32_16x16x32_bf16 v[108:111], v[156:159], v[200:203], v[108:111]
	v_mfma_f32_16x16x32_bf16 v[104:107], v[164:167], v[200:203], v[104:107]
	v_mfma_f32_16x16x32_bf16 v[92:95], v[156:159], v[208:211], v[92:95]
	v_mfma_f32_16x16x32_bf16 v[88:91], v[164:167], v[208:211], v[88:91]
	v_mfma_f32_16x16x32_bf16 v[76:79], v[156:159], v[216:219], v[76:79]
	v_mfma_f32_16x16x32_bf16 v[72:75], v[164:167], v[216:219], v[72:75]
	s_setprio 0
	s_setprio 1
	v_mfma_f32_16x16x32_bf16 v[116:119], v[168:171], v[184:187], v[116:119]
	v_mfma_f32_16x16x32_bf16 v[112:115], v[176:179], v[184:187], v[112:115]
	v_mfma_f32_16x16x32_bf16 v[100:103], v[168:171], v[196:199], v[100:103]
	v_mfma_f32_16x16x32_bf16 v[96:99], v[176:179], v[196:199], v[96:99]
	v_mfma_f32_16x16x32_bf16 v[84:87], v[168:171], v[204:207], v[84:87]
	v_mfma_f32_16x16x32_bf16 v[80:83], v[176:179], v[204:207], v[80:83]
	v_mfma_f32_16x16x32_bf16 v[68:71], v[168:171], v[212:215], v[68:71]
	v_mfma_f32_16x16x32_bf16 v[64:67], v[176:179], v[212:215], v[64:67]
	v_mfma_f32_16x16x32_bf16 v[116:119], v[172:175], v[188:191], v[116:119]
	v_mfma_f32_16x16x32_bf16 v[112:115], v[180:183], v[188:191], v[112:115]
	v_mfma_f32_16x16x32_bf16 v[100:103], v[172:175], v[200:203], v[100:103]
	v_mfma_f32_16x16x32_bf16 v[96:99], v[180:183], v[200:203], v[96:99]
	v_mfma_f32_16x16x32_bf16 v[84:87], v[172:175], v[208:211], v[84:87]
	v_mfma_f32_16x16x32_bf16 v[80:83], v[180:183], v[208:211], v[80:83]
	v_mfma_f32_16x16x32_bf16 v[68:71], v[172:175], v[216:219], v[68:71]
	v_mfma_f32_16x16x32_bf16 v[64:67], v[180:183], v[216:219], v[64:67]
	s_setprio 0
	s_barrier
	s_add_i32 s40, s71, s49
	v_lshl_add_u64 v[192:193], v[192:193], 0, s[20:21]
	s_mov_b32 m0, s40
	ds_read_b128 v[184:187], v153 offset:49152
	ds_read_b128 v[188:191], v153 offset:50176
	ds_read_b128 v[196:199], v153 offset:51200
	ds_read_b128 v[200:203], v153 offset:52224
	ds_read_b128 v[204:207], v153 offset:53248
	ds_read_b128 v[208:211], v153 offset:54272
	ds_read_b128 v[212:215], v153 offset:55296
	ds_read_b128 v[216:219], v153 offset:56320
	global_load_lds_dwordx4 v[192:193], off
	s_add_i32 m0, s40, 0x2000
	s_add_u32 s38, s38, 0x40080
	v_lshl_add_u64 v[192:193], v[220:221], 0, s[20:21]
	s_addc_u32 s39, s39, 0
	s_add_i32 s40, s72, s49
	global_load_lds_dwordx4 v[192:193], off
	s_mov_b32 m0, s40
	s_nop 0
	global_load_lds_dwordx4 v130, s[38:39]
	s_add_i32 m0, s40, 0x2000
	s_nop 0
	global_load_lds_dwordx4 v134, s[38:39]
	s_waitcnt vmcnt(6)
	s_waitcnt lgkmcnt(0)
	s_barrier
	s_setprio 1
	s_waitcnt lgkmcnt(0)
	v_mfma_f32_16x16x32_bf16 v[60:63], v[144:147], v[184:187], v[60:63]
	v_mfma_f32_16x16x32_bf16 v[56:59], v[160:163], v[184:187], v[56:59]
	v_mfma_f32_16x16x32_bf16 v[44:47], v[144:147], v[196:199], v[44:47]
	v_mfma_f32_16x16x32_bf16 v[40:43], v[160:163], v[196:199], v[40:43]
	v_mfma_f32_16x16x32_bf16 v[28:31], v[144:147], v[204:207], v[28:31]
	v_mfma_f32_16x16x32_bf16 v[24:27], v[160:163], v[204:207], v[24:27]
	v_mfma_f32_16x16x32_bf16 v[12:15], v[144:147], v[212:215], v[12:15]
	v_mfma_f32_16x16x32_bf16 v[8:11], v[160:163], v[212:215], v[8:11]
	v_mfma_f32_16x16x32_bf16 v[60:63], v[156:159], v[188:191], v[60:63]
	v_mfma_f32_16x16x32_bf16 v[56:59], v[164:167], v[188:191], v[56:59]
	v_mfma_f32_16x16x32_bf16 v[44:47], v[156:159], v[200:203], v[44:47]
	v_mfma_f32_16x16x32_bf16 v[40:43], v[164:167], v[200:203], v[40:43]
	v_mfma_f32_16x16x32_bf16 v[28:31], v[156:159], v[208:211], v[28:31]
	v_mfma_f32_16x16x32_bf16 v[24:27], v[164:167], v[208:211], v[24:27]
	v_mfma_f32_16x16x32_bf16 v[12:15], v[156:159], v[216:219], v[12:15]
	v_mfma_f32_16x16x32_bf16 v[8:11], v[164:167], v[216:219], v[8:11]
	s_setprio 0
	s_setprio 1
	v_mfma_f32_16x16x32_bf16 v[52:55], v[168:171], v[184:187], v[52:55]
	v_mfma_f32_16x16x32_bf16 v[48:51], v[176:179], v[184:187], v[48:51]
	v_mfma_f32_16x16x32_bf16 v[36:39], v[168:171], v[196:199], v[36:39]
	v_mfma_f32_16x16x32_bf16 v[32:35], v[176:179], v[196:199], v[32:35]
	v_mfma_f32_16x16x32_bf16 v[20:23], v[168:171], v[204:207], v[20:23]
	v_mfma_f32_16x16x32_bf16 v[16:19], v[176:179], v[204:207], v[16:19]
	v_mfma_f32_16x16x32_bf16 v[4:7], v[168:171], v[212:215], v[4:7]
	v_mfma_f32_16x16x32_bf16 v[0:3], v[176:179], v[212:215], v[0:3]
	v_mfma_f32_16x16x32_bf16 v[52:55], v[172:175], v[188:191], v[52:55]
	v_mfma_f32_16x16x32_bf16 v[48:51], v[180:183], v[188:191], v[48:51]
	v_mfma_f32_16x16x32_bf16 v[36:39], v[172:175], v[200:203], v[36:39]
	v_mfma_f32_16x16x32_bf16 v[32:35], v[180:183], v[200:203], v[32:35]
	v_mfma_f32_16x16x32_bf16 v[20:23], v[172:175], v[208:211], v[20:23]
	v_mfma_f32_16x16x32_bf16 v[16:19], v[180:183], v[208:211], v[16:19]
	v_mfma_f32_16x16x32_bf16 v[4:7], v[172:175], v[216:219], v[4:7]
	v_mfma_f32_16x16x32_bf16 v[0:3], v[180:183], v[216:219], v[0:3]
	s_setprio 0
	s_barrier
	v_lshl_add_u64 v[222:223], v[222:223], 0, s[20:21]
	s_mov_b32 m0, s55
	s_nop 0
	global_load_lds_dwordx4 v[222:223], off
	v_lshl_add_u64 v[224:225], v[224:225], 0, s[20:21]
	s_mov_b32 m0, s56
	s_nop 0
	global_load_lds_dwordx4 v[224:225], off
	s_add_i32 s70, s70, 2
	s_add_u32 s36, s36, 0x100
	s_addc_u32 s37, s37, 0
	s_add_u32 s62, s62, 0x100
	s_addc_u32 s63, s63, 0
	s_cmp_gt_u32 s70, 13
	s_cbranch_scc0 .LBB0_3235
	s_and_b64 vcc, exec, s[22:23]
	s_cbranch_vccz .LBB0_3238
	s_barrier

.LBB0_3319:
	ds_read_b128 v[154:157], v149
	ds_read_b128 v[158:161], v149 offset:1024
	ds_read_b128 v[162:165], v149 offset:2048
	ds_read_b128 v[166:169], v149 offset:3072
	ds_read_b128 v[170:173], v150
	ds_read_b128 v[174:177], v150 offset:1024
	ds_read_b128 v[178:181], v150 offset:2048
	ds_read_b128 v[182:185], v150 offset:3072
	s_add_u32 s28, s26, 0xfffc0080
	s_addc_u32 s29, s27, -1
	s_cmp_eq_u32 s59, 12
	s_cselect_b32 s31, s19, s29
	s_cselect_b32 s30, s55, s28
	s_cselect_b32 s29, s17, s58
	s_cselect_b32 s28, s56, s57
	s_add_i32 m0, s25, 0xc000
	ds_read_b128 v[186:189], v151
	ds_read_b128 v[190:193], v151 offset:1024
	ds_read_b128 v[196:199], v151 offset:2048
	ds_read_b128 v[200:203], v151 offset:3072
	ds_read_b128 v[204:207], v151 offset:4096
	ds_read_b128 v[208:211], v151 offset:5120
	ds_read_b128 v[212:215], v151 offset:6144
	ds_read_b128 v[216:219], v151 offset:7168
	global_load_lds_dwordx4 v136, s[26:27]
	s_add_i32 m0, s25, 0xe000
	s_nop 0
	global_load_lds_dwordx4 v138, s[26:27]
	s_waitcnt vmcnt(8)
	s_waitcnt lgkmcnt(0)
	s_barrier
	s_setprio 1
	s_waitcnt lgkmcnt(0)
	v_mfma_f32_16x16x32_bf16 v[116:119], v[154:157], v[186:189], v[116:119]
	v_mfma_f32_16x16x32_bf16 v[112:115], v[162:165], v[186:189], v[112:115]
	v_mfma_f32_16x16x32_bf16 v[100:103], v[154:157], v[196:199], v[100:103]
	v_mfma_f32_16x16x32_bf16 v[96:99], v[162:165], v[196:199], v[96:99]
	v_mfma_f32_16x16x32_bf16 v[84:87], v[154:157], v[204:207], v[84:87]
	v_mfma_f32_16x16x32_bf16 v[80:83], v[162:165], v[204:207], v[80:83]
	v_mfma_f32_16x16x32_bf16 v[68:71], v[154:157], v[212:215], v[68:71]
	v_mfma_f32_16x16x32_bf16 v[64:67], v[162:165], v[212:215], v[64:67]
	v_mfma_f32_16x16x32_bf16 v[116:119], v[158:161], v[190:193], v[116:119]
	v_mfma_f32_16x16x32_bf16 v[112:115], v[166:169], v[190:193], v[112:115]
	v_mfma_f32_16x16x32_bf16 v[100:103], v[158:161], v[200:203], v[100:103]
	v_mfma_f32_16x16x32_bf16 v[96:99], v[166:169], v[200:203], v[96:99]
	v_mfma_f32_16x16x32_bf16 v[84:87], v[158:161], v[208:211], v[84:87]
	v_mfma_f32_16x16x32_bf16 v[80:83], v[166:169], v[208:211], v[80:83]
	v_mfma_f32_16x16x32_bf16 v[68:71], v[158:161], v[216:219], v[68:71]
	v_mfma_f32_16x16x32_bf16 v[64:67], v[166:169], v[216:219], v[64:67]
	s_setprio 0
	s_setprio 1
	v_mfma_f32_16x16x32_bf16 v[124:127], v[170:173], v[186:189], v[124:127]
	v_mfma_f32_16x16x32_bf16 v[120:123], v[178:181], v[186:189], v[120:123]
	v_mfma_f32_16x16x32_bf16 v[108:111], v[170:173], v[196:199], v[108:111]
	v_mfma_f32_16x16x32_bf16 v[104:107], v[178:181], v[196:199], v[104:107]
	v_mfma_f32_16x16x32_bf16 v[92:95], v[170:173], v[204:207], v[92:95]
	v_mfma_f32_16x16x32_bf16 v[88:91], v[178:181], v[204:207], v[88:91]
	v_mfma_f32_16x16x32_bf16 v[76:79], v[170:173], v[212:215], v[76:79]
	v_mfma_f32_16x16x32_bf16 v[72:75], v[178:181], v[212:215], v[72:75]
	v_mfma_f32_16x16x32_bf16 v[124:127], v[174:177], v[190:193], v[124:127]
	v_mfma_f32_16x16x32_bf16 v[120:123], v[182:185], v[190:193], v[120:123]
	v_mfma_f32_16x16x32_bf16 v[108:111], v[174:177], v[200:203], v[108:111]
	v_mfma_f32_16x16x32_bf16 v[104:107], v[182:185], v[200:203], v[104:107]
	v_mfma_f32_16x16x32_bf16 v[92:95], v[174:177], v[208:211], v[92:95]
	v_mfma_f32_16x16x32_bf16 v[88:91], v[182:185], v[208:211], v[88:91]
	v_mfma_f32_16x16x32_bf16 v[76:79], v[174:177], v[216:219], v[76:79]
	v_mfma_f32_16x16x32_bf16 v[72:75], v[182:185], v[216:219], v[72:75]
	s_setprio 0
	s_barrier
	s_add_i32 s60, s50, s39
	v_lshl_add_u64 v[144:145], s[28:29], 0, v[132:133]
	s_mov_b32 m0, s60
	ds_read_b128 v[186:189], v151 offset:16384
	ds_read_b128 v[190:193], v151 offset:17408
	ds_read_b128 v[196:199], v151 offset:18432
	ds_read_b128 v[200:203], v151 offset:19456
	ds_read_b128 v[204:207], v151 offset:20480
	ds_read_b128 v[208:211], v151 offset:21504
	ds_read_b128 v[212:215], v151 offset:22528
	ds_read_b128 v[216:219], v151 offset:23552
	global_load_lds_dwordx4 v[144:145], off
	s_add_i32 m0, s60, 0x2000
	s_add_u32 s60, s28, 0x40000
	v_lshl_add_u64 v[220:221], s[28:29], 0, v[128:129]
	s_addc_u32 s61, s29, 0
	s_add_i32 s62, s51, s39
	global_load_lds_dwordx4 v[220:221], off
	s_mov_b32 m0, s62
	v_lshl_add_u64 v[224:225], s[30:31], 0, v[130:131]
	global_load_lds_dwordx4 v132, s[60:61]
	s_add_i32 m0, s62, 0x2000
	s_nop 0
	global_load_lds_dwordx4 v128, s[60:61]
	v_lshl_add_u64 v[222:223], s[30:31], 0, v[134:135]
	s_waitcnt vmcnt(6)
	s_waitcnt lgkmcnt(0)
	s_barrier
	s_setprio 1
	s_waitcnt lgkmcnt(0)
	v_mfma_f32_16x16x32_bf16 v[52:55], v[154:157], v[186:189], v[52:55]
	v_mfma_f32_16x16x32_bf16 v[48:51], v[162:165], v[186:189], v[48:51]
	v_mfma_f32_16x16x32_bf16 v[36:39], v[154:157], v[196:199], v[36:39]
	v_mfma_f32_16x16x32_bf16 v[32:35], v[162:165], v[196:199], v[32:35]
	v_mfma_f32_16x16x32_bf16 v[20:23], v[154:157], v[204:207], v[20:23]
	v_mfma_f32_16x16x32_bf16 v[16:19], v[162:165], v[204:207], v[16:19]
	v_mfma_f32_16x16x32_bf16 v[4:7], v[154:157], v[212:215], v[4:7]
	v_mfma_f32_16x16x32_bf16 v[0:3], v[162:165], v[212:215], v[0:3]
	v_mfma_f32_16x16x32_bf16 v[52:55], v[158:161], v[190:193], v[52:55]
	v_mfma_f32_16x16x32_bf16 v[48:51], v[166:169], v[190:193], v[48:51]
	v_mfma_f32_16x16x32_bf16 v[36:39], v[158:161], v[200:203], v[36:39]
	v_mfma_f32_16x16x32_bf16 v[32:35], v[166:169], v[200:203], v[32:35]
	v_mfma_f32_16x16x32_bf16 v[20:23], v[158:161], v[208:211], v[20:23]
	v_mfma_f32_16x16x32_bf16 v[16:19], v[166:169], v[208:211], v[16:19]
	v_mfma_f32_16x16x32_bf16 v[4:7], v[158:161], v[216:219], v[4:7]
	v_mfma_f32_16x16x32_bf16 v[0:3], v[166:169], v[216:219], v[0:3]
	s_setprio 0
	s_setprio 1
	v_mfma_f32_16x16x32_bf16 v[60:63], v[170:173], v[186:189], v[60:63]
	v_mfma_f32_16x16x32_bf16 v[56:59], v[178:181], v[186:189], v[56:59]
	v_mfma_f32_16x16x32_bf16 v[44:47], v[170:173], v[196:199], v[44:47]
	v_mfma_f32_16x16x32_bf16 v[40:43], v[178:181], v[196:199], v[40:43]
	v_mfma_f32_16x16x32_bf16 v[28:31], v[170:173], v[204:207], v[28:31]
	v_mfma_f32_16x16x32_bf16 v[24:27], v[178:181], v[204:207], v[24:27]
	v_mfma_f32_16x16x32_bf16 v[12:15], v[170:173], v[212:215], v[12:15]
	v_mfma_f32_16x16x32_bf16 v[8:11], v[178:181], v[212:215], v[8:11]
	v_mfma_f32_16x16x32_bf16 v[60:63], v[174:177], v[190:193], v[60:63]
	v_mfma_f32_16x16x32_bf16 v[56:59], v[182:185], v[190:193], v[56:59]
	v_mfma_f32_16x16x32_bf16 v[44:47], v[174:177], v[200:203], v[44:47]
	v_mfma_f32_16x16x32_bf16 v[40:43], v[182:185], v[200:203], v[40:43]
	v_mfma_f32_16x16x32_bf16 v[28:31], v[174:177], v[208:211], v[28:31]
	v_mfma_f32_16x16x32_bf16 v[24:27], v[182:185], v[208:211], v[24:27]
	v_mfma_f32_16x16x32_bf16 v[12:15], v[174:177], v[216:219], v[12:15]
	v_mfma_f32_16x16x32_bf16 v[8:11], v[182:185], v[216:219], v[8:11]
	s_setprio 0
	s_barrier
	s_add_i32 s60, 0, 0x18000
	v_add_u32_e32 v153, s60, v147
	s_add_i32 s61, 0, 0x1c000
	ds_read_b128 v[154:157], v153
	ds_read_b128 v[158:161], v153 offset:1024
	ds_read_b128 v[162:165], v153 offset:2048
	ds_read_b128 v[166:169], v153 offset:3072
	v_add_u32_e32 v153, s61, v147
	ds_read_b128 v[170:173], v153
	ds_read_b128 v[174:177], v153 offset:1024
	ds_read_b128 v[178:181], v153 offset:2048
	ds_read_b128 v[182:185], v153 offset:3072
	s_add_u32 s30, s30, 0x40000
	s_addc_u32 s31, s31, 0
	ds_read_b128 v[186:189], v151 offset:32768
	ds_read_b128 v[190:193], v151 offset:33792
	ds_read_b128 v[196:199], v151 offset:34816
	ds_read_b128 v[200:203], v151 offset:35840
	ds_read_b128 v[204:207], v151 offset:36864
	ds_read_b128 v[208:211], v151 offset:37888
	ds_read_b128 v[212:215], v151 offset:38912
	ds_read_b128 v[216:219], v151 offset:39936
	s_mov_b32 m0, s25
	s_nop 0
	global_load_lds_dwordx4 v[222:223], off
	s_mov_b32 m0, s41
	s_nop 0
	global_load_lds_dwordx4 v[224:225], off
	s_mov_b32 m0, s42
	s_nop 0
	global_load_lds_dwordx4 v134, s[30:31]
	s_mov_b32 m0, s43
	s_nop 0
	global_load_lds_dwordx4 v130, s[30:31]
	s_waitcnt vmcnt(8)
	s_waitcnt lgkmcnt(0)
	s_barrier
	s_setprio 1
	s_waitcnt lgkmcnt(0)
	v_mfma_f32_16x16x32_bf16 v[116:119], v[154:157], v[186:189], v[116:119]
	v_mfma_f32_16x16x32_bf16 v[112:115], v[162:165], v[186:189], v[112:115]
	v_mfma_f32_16x16x32_bf16 v[100:103], v[154:157], v[196:199], v[100:103]
	v_mfma_f32_16x16x32_bf16 v[96:99], v[162:165], v[196:199], v[96:99]
	v_mfma_f32_16x16x32_bf16 v[84:87], v[154:157], v[204:207], v[84:87]
	v_mfma_f32_16x16x32_bf16 v[80:83], v[162:165], v[204:207], v[80:83]
	v_mfma_f32_16x16x32_bf16 v[68:71], v[154:157], v[212:215], v[68:71]
	v_mfma_f32_16x16x32_bf16 v[64:67], v[162:165], v[212:215], v[64:67]
	v_mfma_f32_16x16x32_bf16 v[116:119], v[158:161], v[190:193], v[116:119]
	v_mfma_f32_16x16x32_bf16 v[112:115], v[166:169], v[190:193], v[112:115]
	v_mfma_f32_16x16x32_bf16 v[100:103], v[158:161], v[200:203], v[100:103]
	v_mfma_f32_16x16x32_bf16 v[96:99], v[166:169], v[200:203], v[96:99]
	v_mfma_f32_16x16x32_bf16 v[84:87], v[158:161], v[208:211], v[84:87]
	v_mfma_f32_16x16x32_bf16 v[80:83], v[166:169], v[208:211], v[80:83]
	v_mfma_f32_16x16x32_bf16 v[68:71], v[158:161], v[216:219], v[68:71]
	v_mfma_f32_16x16x32_bf16 v[64:67], v[166:169], v[216:219], v[64:67]
	s_setprio 0
	s_setprio 1
	v_mfma_f32_16x16x32_bf16 v[124:127], v[170:173], v[186:189], v[124:127]
	v_mfma_f32_16x16x32_bf16 v[120:123], v[178:181], v[186:189], v[120:123]
	v_mfma_f32_16x16x32_bf16 v[108:111], v[170:173], v[196:199], v[108:111]
	v_mfma_f32_16x16x32_bf16 v[104:107], v[178:181], v[196:199], v[104:107]
	v_mfma_f32_16x16x32_bf16 v[92:95], v[170:173], v[204:207], v[92:95]
	v_mfma_f32_16x16x32_bf16 v[88:91], v[178:181], v[204:207], v[88:91]
	v_mfma_f32_16x16x32_bf16 v[76:79], v[170:173], v[212:215], v[76:79]
	v_mfma_f32_16x16x32_bf16 v[72:75], v[178:181], v[212:215], v[72:75]
	v_mfma_f32_16x16x32_bf16 v[124:127], v[174:177], v[190:193], v[124:127]
	v_mfma_f32_16x16x32_bf16 v[120:123], v[182:185], v[190:193], v[120:123]
	v_mfma_f32_16x16x32_bf16 v[108:111], v[174:177], v[200:203], v[108:111]
	v_mfma_f32_16x16x32_bf16 v[104:107], v[182:185], v[200:203], v[104:107]
	v_mfma_f32_16x16x32_bf16 v[92:95], v[174:177], v[208:211], v[92:95]
	v_mfma_f32_16x16x32_bf16 v[88:91], v[182:185], v[208:211], v[88:91]
	v_mfma_f32_16x16x32_bf16 v[76:79], v[174:177], v[216:219], v[76:79]
	v_mfma_f32_16x16x32_bf16 v[72:75], v[182:185], v[216:219], v[72:75]
	s_setprio 0
	s_barrier
	s_add_i32 s30, s60, s39
	v_lshl_add_u64 v[144:145], v[144:145], 0, s[12:13]
	s_mov_b32 m0, s30
	ds_read_b128 v[186:189], v151 offset:49152
	ds_read_b128 v[190:193], v151 offset:50176
	ds_read_b128 v[196:199], v151 offset:51200
	ds_read_b128 v[200:203], v151 offset:52224
	ds_read_b128 v[204:207], v151 offset:53248
	ds_read_b128 v[208:211], v151 offset:54272
	ds_read_b128 v[212:215], v151 offset:55296
	ds_read_b128 v[216:219], v151 offset:56320
	global_load_lds_dwordx4 v[144:145], off
	s_add_i32 m0, s30, 0x2000
	s_add_u32 s28, s28, 0x40080
	v_lshl_add_u64 v[144:145], v[220:221], 0, s[12:13]
	s_addc_u32 s29, s29, 0
	s_add_i32 s30, s61, s39
	global_load_lds_dwordx4 v[144:145], off
	s_mov_b32 m0, s30
	s_nop 0
	global_load_lds_dwordx4 v132, s[28:29]
	s_add_i32 m0, s30, 0x2000
	s_nop 0
	global_load_lds_dwordx4 v128, s[28:29]
	s_waitcnt vmcnt(6)
	s_waitcnt lgkmcnt(0)
	s_barrier
	s_setprio 1
	s_waitcnt lgkmcnt(0)
	v_mfma_f32_16x16x32_bf16 v[52:55], v[154:157], v[186:189], v[52:55]
	v_mfma_f32_16x16x32_bf16 v[48:51], v[162:165], v[186:189], v[48:51]
	v_mfma_f32_16x16x32_bf16 v[36:39], v[154:157], v[196:199], v[36:39]
	v_mfma_f32_16x16x32_bf16 v[32:35], v[162:165], v[196:199], v[32:35]
	v_mfma_f32_16x16x32_bf16 v[20:23], v[154:157], v[204:207], v[20:23]
	v_mfma_f32_16x16x32_bf16 v[16:19], v[162:165], v[204:207], v[16:19]
	v_mfma_f32_16x16x32_bf16 v[4:7], v[154:157], v[212:215], v[4:7]
	v_mfma_f32_16x16x32_bf16 v[0:3], v[162:165], v[212:215], v[0:3]
	v_mfma_f32_16x16x32_bf16 v[52:55], v[158:161], v[190:193], v[52:55]
	v_mfma_f32_16x16x32_bf16 v[48:51], v[166:169], v[190:193], v[48:51]
	v_mfma_f32_16x16x32_bf16 v[36:39], v[158:161], v[200:203], v[36:39]
	v_mfma_f32_16x16x32_bf16 v[32:35], v[166:169], v[200:203], v[32:35]
	v_mfma_f32_16x16x32_bf16 v[20:23], v[158:161], v[208:211], v[20:23]
	v_mfma_f32_16x16x32_bf16 v[16:19], v[166:169], v[208:211], v[16:19]
	v_mfma_f32_16x16x32_bf16 v[4:7], v[158:161], v[216:219], v[4:7]
	v_mfma_f32_16x16x32_bf16 v[0:3], v[166:169], v[216:219], v[0:3]
	s_setprio 0
	s_setprio 1
	v_mfma_f32_16x16x32_bf16 v[60:63], v[170:173], v[186:189], v[60:63]
	v_mfma_f32_16x16x32_bf16 v[56:59], v[178:181], v[186:189], v[56:59]
	v_mfma_f32_16x16x32_bf16 v[44:47], v[170:173], v[196:199], v[44:47]
	v_mfma_f32_16x16x32_bf16 v[40:43], v[178:181], v[196:199], v[40:43]
	v_mfma_f32_16x16x32_bf16 v[28:31], v[170:173], v[204:207], v[28:31]
	v_mfma_f32_16x16x32_bf16 v[24:27], v[178:181], v[204:207], v[24:27]
	v_mfma_f32_16x16x32_bf16 v[12:15], v[170:173], v[212:215], v[12:15]
	v_mfma_f32_16x16x32_bf16 v[8:11], v[178:181], v[212:215], v[8:11]
	v_mfma_f32_16x16x32_bf16 v[60:63], v[174:177], v[190:193], v[60:63]
	v_mfma_f32_16x16x32_bf16 v[56:59], v[182:185], v[190:193], v[56:59]
	v_mfma_f32_16x16x32_bf16 v[44:47], v[174:177], v[200:203], v[44:47]
	v_mfma_f32_16x16x32_bf16 v[40:43], v[182:185], v[200:203], v[40:43]
	v_mfma_f32_16x16x32_bf16 v[28:31], v[174:177], v[208:211], v[28:31]
	v_mfma_f32_16x16x32_bf16 v[24:27], v[182:185], v[208:211], v[24:27]
	v_mfma_f32_16x16x32_bf16 v[12:15], v[174:177], v[216:219], v[12:15]
	v_mfma_f32_16x16x32_bf16 v[8:11], v[182:185], v[216:219], v[8:11]
	s_setprio 0
	s_barrier
	v_lshl_add_u64 v[222:223], v[222:223], 0, s[12:13]
	s_mov_b32 m0, s45
	s_nop 0
	global_load_lds_dwordx4 v[222:223], off
	v_lshl_add_u64 v[224:225], v[224:225], 0, s[12:13]
	s_mov_b32 m0, s48
	s_nop 0
	global_load_lds_dwordx4 v[224:225], off
	s_add_i32 s59, s59, 2
	s_add_u32 s26, s26, 0x100
	s_addc_u32 s27, s27, 0
	s_add_u32 s57, s57, 0x100
	s_addc_u32 s58, s58, 0
	s_cmp_gt_u32 s59, 13
	s_cbranch_scc0 .LBB0_3319
	s_and_b64 vcc, exec, s[14:15]
	s_cbranch_vccz .LBB0_3322
	s_barrier

.LBB0_3401:
	ds_read_b128 v[144:147], v151
	ds_read_b128 v[156:159], v151 offset:1024
	ds_read_b128 v[160:163], v151 offset:2048
	ds_read_b128 v[164:167], v151 offset:3072
	ds_read_b128 v[168:171], v152
	ds_read_b128 v[172:175], v152 offset:1024
	ds_read_b128 v[176:179], v152 offset:2048
	ds_read_b128 v[180:183], v152 offset:3072
	s_add_u32 s24, s22, 0x100
	s_addc_u32 s25, s23, 0
	s_cmp_eq_u32 s56, 40
	s_cselect_b32 s29, s1, s25
	s_cselect_b32 s28, s0, s24
	s_cselect_b32 s27, s21, s55
	s_cselect_b32 s26, s20, s54
	v_lshl_add_u64 v[192:193], s[22:23], 0, v[136:137]
	s_add_i32 m0, s38, 0xc000
	ds_read_b128 v[184:187], v153
	ds_read_b128 v[188:191], v153 offset:1024
	ds_read_b128 v[196:199], v153 offset:2048
	ds_read_b128 v[200:203], v153 offset:3072
	ds_read_b128 v[204:207], v153 offset:4096
	ds_read_b128 v[208:211], v153 offset:5120
	ds_read_b128 v[212:215], v153 offset:6144
	ds_read_b128 v[216:219], v153 offset:7168
	global_load_lds_dwordx4 v[192:193], off
	v_lshl_add_u64 v[192:193], s[22:23], 0, v[138:139]
	s_add_i32 m0, s38, 0xe000
	s_nop 0
	global_load_lds_dwordx4 v[192:193], off
	s_waitcnt vmcnt(8)
	s_waitcnt lgkmcnt(0)
	s_barrier
	s_setprio 1
	s_waitcnt lgkmcnt(0)
	v_mfma_f32_16x16x32_bf16 v[124:127], v[144:147], v[184:187], v[124:127]
	v_mfma_f32_16x16x32_bf16 v[120:123], v[160:163], v[184:187], v[120:123]
	v_mfma_f32_16x16x32_bf16 v[108:111], v[144:147], v[196:199], v[108:111]
	v_mfma_f32_16x16x32_bf16 v[104:107], v[160:163], v[196:199], v[104:107]
	v_mfma_f32_16x16x32_bf16 v[92:95], v[144:147], v[204:207], v[92:95]
	v_mfma_f32_16x16x32_bf16 v[88:91], v[160:163], v[204:207], v[88:91]
	v_mfma_f32_16x16x32_bf16 v[76:79], v[144:147], v[212:215], v[76:79]
	v_mfma_f32_16x16x32_bf16 v[72:75], v[160:163], v[212:215], v[72:75]
	v_mfma_f32_16x16x32_bf16 v[124:127], v[156:159], v[188:191], v[124:127]
	v_mfma_f32_16x16x32_bf16 v[120:123], v[164:167], v[188:191], v[120:123]
	v_mfma_f32_16x16x32_bf16 v[108:111], v[156:159], v[200:203], v[108:111]
	v_mfma_f32_16x16x32_bf16 v[104:107], v[164:167], v[200:203], v[104:107]
	v_mfma_f32_16x16x32_bf16 v[92:95], v[156:159], v[208:211], v[92:95]
	v_mfma_f32_16x16x32_bf16 v[88:91], v[164:167], v[208:211], v[88:91]
	v_mfma_f32_16x16x32_bf16 v[76:79], v[156:159], v[216:219], v[76:79]
	v_mfma_f32_16x16x32_bf16 v[72:75], v[164:167], v[216:219], v[72:75]
	s_setprio 0
	s_setprio 1
	v_mfma_f32_16x16x32_bf16 v[116:119], v[168:171], v[184:187], v[116:119]
	v_mfma_f32_16x16x32_bf16 v[112:115], v[176:179], v[184:187], v[112:115]
	v_mfma_f32_16x16x32_bf16 v[100:103], v[168:171], v[196:199], v[100:103]
	v_mfma_f32_16x16x32_bf16 v[96:99], v[176:179], v[196:199], v[96:99]
	v_mfma_f32_16x16x32_bf16 v[84:87], v[168:171], v[204:207], v[84:87]
	v_mfma_f32_16x16x32_bf16 v[80:83], v[176:179], v[204:207], v[80:83]
	v_mfma_f32_16x16x32_bf16 v[68:71], v[168:171], v[212:215], v[68:71]
	v_mfma_f32_16x16x32_bf16 v[64:67], v[176:179], v[212:215], v[64:67]
	v_mfma_f32_16x16x32_bf16 v[116:119], v[172:175], v[188:191], v[116:119]
	v_mfma_f32_16x16x32_bf16 v[112:115], v[180:183], v[188:191], v[112:115]
	v_mfma_f32_16x16x32_bf16 v[100:103], v[172:175], v[200:203], v[100:103]
	v_mfma_f32_16x16x32_bf16 v[96:99], v[180:183], v[200:203], v[96:99]
	v_mfma_f32_16x16x32_bf16 v[84:87], v[172:175], v[208:211], v[84:87]
	v_mfma_f32_16x16x32_bf16 v[80:83], v[180:183], v[208:211], v[80:83]
	v_mfma_f32_16x16x32_bf16 v[68:71], v[172:175], v[216:219], v[68:71]
	v_mfma_f32_16x16x32_bf16 v[64:67], v[180:183], v[216:219], v[64:67]
	s_setprio 0
	s_barrier
	s_add_i32 s22, s48, s37
	v_lshl_add_u64 v[192:193], s[26:27], 0, v[130:131]
	s_mov_b32 m0, s22
	ds_read_b128 v[184:187], v153 offset:16384
	ds_read_b128 v[188:191], v153 offset:17408
	ds_read_b128 v[196:199], v153 offset:18432
	ds_read_b128 v[200:203], v153 offset:19456
	ds_read_b128 v[204:207], v153 offset:20480
	ds_read_b128 v[208:211], v153 offset:21504
	ds_read_b128 v[212:215], v153 offset:22528
	ds_read_b128 v[216:219], v153 offset:23552
	global_load_lds_dwordx4 v[192:193], off
	s_add_i32 m0, s22, 0x2000
	s_add_u32 s22, s26, 0xb0000
	v_lshl_add_u64 v[220:221], s[26:27], 0, v[134:135]
	s_addc_u32 s23, s27, 0
	s_add_i32 s57, s49, s37
	global_load_lds_dwordx4 v[220:221], off
	s_mov_b32 m0, s57
	v_lshl_add_u64 v[224:225], s[28:29], 0, v[132:133]
	global_load_lds_dwordx4 v130, s[22:23]
	s_add_i32 m0, s57, 0x2000
	s_nop 0
	global_load_lds_dwordx4 v134, s[22:23]
	v_lshl_add_u64 v[222:223], s[28:29], 0, v[128:129]
	s_waitcnt vmcnt(6)
	s_waitcnt lgkmcnt(0)
	s_barrier
	s_setprio 1
	s_waitcnt lgkmcnt(0)
	v_mfma_f32_16x16x32_bf16 v[60:63], v[144:147], v[184:187], v[60:63]
	v_mfma_f32_16x16x32_bf16 v[56:59], v[160:163], v[184:187], v[56:59]
	v_mfma_f32_16x16x32_bf16 v[44:47], v[144:147], v[196:199], v[44:47]
	v_mfma_f32_16x16x32_bf16 v[40:43], v[160:163], v[196:199], v[40:43]
	v_mfma_f32_16x16x32_bf16 v[28:31], v[144:147], v[204:207], v[28:31]
	v_mfma_f32_16x16x32_bf16 v[24:27], v[160:163], v[204:207], v[24:27]
	v_mfma_f32_16x16x32_bf16 v[12:15], v[144:147], v[212:215], v[12:15]
	v_mfma_f32_16x16x32_bf16 v[8:11], v[160:163], v[212:215], v[8:11]
	v_mfma_f32_16x16x32_bf16 v[60:63], v[156:159], v[188:191], v[60:63]
	v_mfma_f32_16x16x32_bf16 v[56:59], v[164:167], v[188:191], v[56:59]
	v_mfma_f32_16x16x32_bf16 v[44:47], v[156:159], v[200:203], v[44:47]
	v_mfma_f32_16x16x32_bf16 v[40:43], v[164:167], v[200:203], v[40:43]
	v_mfma_f32_16x16x32_bf16 v[28:31], v[156:159], v[208:211], v[28:31]
	v_mfma_f32_16x16x32_bf16 v[24:27], v[164:167], v[208:211], v[24:27]
	v_mfma_f32_16x16x32_bf16 v[12:15], v[156:159], v[216:219], v[12:15]
	v_mfma_f32_16x16x32_bf16 v[8:11], v[164:167], v[216:219], v[8:11]
	s_setprio 0
	s_setprio 1
	v_mfma_f32_16x16x32_bf16 v[52:55], v[168:171], v[184:187], v[52:55]
	v_mfma_f32_16x16x32_bf16 v[48:51], v[176:179], v[184:187], v[48:51]
	v_mfma_f32_16x16x32_bf16 v[36:39], v[168:171], v[196:199], v[36:39]
	v_mfma_f32_16x16x32_bf16 v[32:35], v[176:179], v[196:199], v[32:35]
	v_mfma_f32_16x16x32_bf16 v[20:23], v[168:171], v[204:207], v[20:23]
	v_mfma_f32_16x16x32_bf16 v[16:19], v[176:179], v[204:207], v[16:19]
	v_mfma_f32_16x16x32_bf16 v[4:7], v[168:171], v[212:215], v[4:7]
	v_mfma_f32_16x16x32_bf16 v[0:3], v[176:179], v[212:215], v[0:3]
	v_mfma_f32_16x16x32_bf16 v[52:55], v[172:175], v[188:191], v[52:55]
	v_mfma_f32_16x16x32_bf16 v[48:51], v[180:183], v[188:191], v[48:51]
	v_mfma_f32_16x16x32_bf16 v[36:39], v[172:175], v[200:203], v[36:39]
	v_mfma_f32_16x16x32_bf16 v[32:35], v[180:183], v[200:203], v[32:35]
	v_mfma_f32_16x16x32_bf16 v[20:23], v[172:175], v[208:211], v[20:23]
	v_mfma_f32_16x16x32_bf16 v[16:19], v[180:183], v[208:211], v[16:19]
	v_mfma_f32_16x16x32_bf16 v[4:7], v[172:175], v[216:219], v[4:7]
	v_mfma_f32_16x16x32_bf16 v[0:3], v[180:183], v[216:219], v[0:3]
	s_setprio 0
	s_barrier
	s_add_i32 s57, 0, 0x18000
	v_add_u32_e32 v155, s57, v149
	s_add_i32 s58, 0, 0x1c000
	ds_read_b128 v[144:147], v155
	ds_read_b128 v[156:159], v155 offset:1024
	ds_read_b128 v[160:163], v155 offset:2048
	ds_read_b128 v[164:167], v155 offset:3072
	v_add_u32_e32 v155, s58, v149
	ds_read_b128 v[168:171], v155
	ds_read_b128 v[172:175], v155 offset:1024
	ds_read_b128 v[176:179], v155 offset:2048
	ds_read_b128 v[180:183], v155 offset:3072
	s_add_u32 s22, s28, 0xb0000
	s_addc_u32 s23, s29, 0
	ds_read_b128 v[184:187], v153 offset:32768
	ds_read_b128 v[188:191], v153 offset:33792
	ds_read_b128 v[196:199], v153 offset:34816
	ds_read_b128 v[200:203], v153 offset:35840
	ds_read_b128 v[204:207], v153 offset:36864
	ds_read_b128 v[208:211], v153 offset:37888
	ds_read_b128 v[212:215], v153 offset:38912
	ds_read_b128 v[216:219], v153 offset:39936
	s_mov_b32 m0, s38
	s_nop 0
	global_load_lds_dwordx4 v[222:223], off
	s_mov_b32 m0, s39
	s_nop 0
	global_load_lds_dwordx4 v[224:225], off
	s_mov_b32 m0, s40
	s_nop 0
	global_load_lds_dwordx4 v128, s[22:23]
	s_mov_b32 m0, s41
	s_nop 0
	global_load_lds_dwordx4 v132, s[22:23]
	s_waitcnt vmcnt(8)
	s_waitcnt lgkmcnt(0)
	s_barrier
	s_setprio 1
	s_waitcnt lgkmcnt(0)
	v_mfma_f32_16x16x32_bf16 v[124:127], v[144:147], v[184:187], v[124:127]
	v_mfma_f32_16x16x32_bf16 v[120:123], v[160:163], v[184:187], v[120:123]
	v_mfma_f32_16x16x32_bf16 v[108:111], v[144:147], v[196:199], v[108:111]
	v_mfma_f32_16x16x32_bf16 v[104:107], v[160:163], v[196:199], v[104:107]
	v_mfma_f32_16x16x32_bf16 v[92:95], v[144:147], v[204:207], v[92:95]
	v_mfma_f32_16x16x32_bf16 v[88:91], v[160:163], v[204:207], v[88:91]
	v_mfma_f32_16x16x32_bf16 v[76:79], v[144:147], v[212:215], v[76:79]
	v_mfma_f32_16x16x32_bf16 v[72:75], v[160:163], v[212:215], v[72:75]
	v_mfma_f32_16x16x32_bf16 v[124:127], v[156:159], v[188:191], v[124:127]
	v_mfma_f32_16x16x32_bf16 v[120:123], v[164:167], v[188:191], v[120:123]
	v_mfma_f32_16x16x32_bf16 v[108:111], v[156:159], v[200:203], v[108:111]
	v_mfma_f32_16x16x32_bf16 v[104:107], v[164:167], v[200:203], v[104:107]
	v_mfma_f32_16x16x32_bf16 v[92:95], v[156:159], v[208:211], v[92:95]
	v_mfma_f32_16x16x32_bf16 v[88:91], v[164:167], v[208:211], v[88:91]
	v_mfma_f32_16x16x32_bf16 v[76:79], v[156:159], v[216:219], v[76:79]
	v_mfma_f32_16x16x32_bf16 v[72:75], v[164:167], v[216:219], v[72:75]
	s_setprio 0
	s_setprio 1
	v_mfma_f32_16x16x32_bf16 v[116:119], v[168:171], v[184:187], v[116:119]
	v_mfma_f32_16x16x32_bf16 v[112:115], v[176:179], v[184:187], v[112:115]
	v_mfma_f32_16x16x32_bf16 v[100:103], v[168:171], v[196:199], v[100:103]
	v_mfma_f32_16x16x32_bf16 v[96:99], v[176:179], v[196:199], v[96:99]
	v_mfma_f32_16x16x32_bf16 v[84:87], v[168:171], v[204:207], v[84:87]
	v_mfma_f32_16x16x32_bf16 v[80:83], v[176:179], v[204:207], v[80:83]
	v_mfma_f32_16x16x32_bf16 v[68:71], v[168:171], v[212:215], v[68:71]
	v_mfma_f32_16x16x32_bf16 v[64:67], v[176:179], v[212:215], v[64:67]
	v_mfma_f32_16x16x32_bf16 v[116:119], v[172:175], v[188:191], v[116:119]
	v_mfma_f32_16x16x32_bf16 v[112:115], v[180:183], v[188:191], v[112:115]
	v_mfma_f32_16x16x32_bf16 v[100:103], v[172:175], v[200:203], v[100:103]
	v_mfma_f32_16x16x32_bf16 v[96:99], v[180:183], v[200:203], v[96:99]
	v_mfma_f32_16x16x32_bf16 v[84:87], v[172:175], v[208:211], v[84:87]
	v_mfma_f32_16x16x32_bf16 v[80:83], v[180:183], v[208:211], v[80:83]
	v_mfma_f32_16x16x32_bf16 v[68:71], v[172:175], v[216:219], v[68:71]
	v_mfma_f32_16x16x32_bf16 v[64:67], v[180:183], v[216:219], v[64:67]
	s_setprio 0
	s_barrier
	s_add_i32 s22, s57, s37
	v_lshl_add_u64 v[192:193], v[192:193], 0, s[16:17]
	s_mov_b32 m0, s22
	ds_read_b128 v[184:187], v153 offset:49152
	ds_read_b128 v[188:191], v153 offset:50176
	ds_read_b128 v[196:199], v153 offset:51200
	ds_read_b128 v[200:203], v153 offset:52224
	ds_read_b128 v[204:207], v153 offset:53248
	ds_read_b128 v[208:211], v153 offset:54272
	ds_read_b128 v[212:215], v153 offset:55296
	ds_read_b128 v[216:219], v153 offset:56320
	global_load_lds_dwordx4 v[192:193], off
	s_add_i32 m0, s22, 0x2000
	s_add_u32 s22, s26, 0xb0080
	v_lshl_add_u64 v[192:193], v[220:221], 0, s[16:17]
	s_addc_u32 s23, s27, 0
	s_add_i32 s26, s58, s37
	global_load_lds_dwordx4 v[192:193], off
	s_mov_b32 m0, s26
	s_nop 0
	global_load_lds_dwordx4 v130, s[22:23]
	s_add_i32 m0, s26, 0x2000
	s_nop 0
	global_load_lds_dwordx4 v134, s[22:23]
	s_waitcnt vmcnt(6)
	s_waitcnt lgkmcnt(0)
	s_barrier
	s_setprio 1
	s_waitcnt lgkmcnt(0)
	v_mfma_f32_16x16x32_bf16 v[60:63], v[144:147], v[184:187], v[60:63]
	v_mfma_f32_16x16x32_bf16 v[56:59], v[160:163], v[184:187], v[56:59]
	v_mfma_f32_16x16x32_bf16 v[44:47], v[144:147], v[196:199], v[44:47]
	v_mfma_f32_16x16x32_bf16 v[40:43], v[160:163], v[196:199], v[40:43]
	v_mfma_f32_16x16x32_bf16 v[28:31], v[144:147], v[204:207], v[28:31]
	v_mfma_f32_16x16x32_bf16 v[24:27], v[160:163], v[204:207], v[24:27]
	v_mfma_f32_16x16x32_bf16 v[12:15], v[144:147], v[212:215], v[12:15]
	v_mfma_f32_16x16x32_bf16 v[8:11], v[160:163], v[212:215], v[8:11]
	v_mfma_f32_16x16x32_bf16 v[60:63], v[156:159], v[188:191], v[60:63]
	v_mfma_f32_16x16x32_bf16 v[56:59], v[164:167], v[188:191], v[56:59]
	v_mfma_f32_16x16x32_bf16 v[44:47], v[156:159], v[200:203], v[44:47]
	v_mfma_f32_16x16x32_bf16 v[40:43], v[164:167], v[200:203], v[40:43]
	v_mfma_f32_16x16x32_bf16 v[28:31], v[156:159], v[208:211], v[28:31]
	v_mfma_f32_16x16x32_bf16 v[24:27], v[164:167], v[208:211], v[24:27]
	v_mfma_f32_16x16x32_bf16 v[12:15], v[156:159], v[216:219], v[12:15]
	v_mfma_f32_16x16x32_bf16 v[8:11], v[164:167], v[216:219], v[8:11]
	s_setprio 0
	s_setprio 1
	v_mfma_f32_16x16x32_bf16 v[52:55], v[168:171], v[184:187], v[52:55]
	v_mfma_f32_16x16x32_bf16 v[48:51], v[176:179], v[184:187], v[48:51]
	v_mfma_f32_16x16x32_bf16 v[36:39], v[168:171], v[196:199], v[36:39]
	v_mfma_f32_16x16x32_bf16 v[32:35], v[176:179], v[196:199], v[32:35]
	v_mfma_f32_16x16x32_bf16 v[20:23], v[168:171], v[204:207], v[20:23]
	v_mfma_f32_16x16x32_bf16 v[16:19], v[176:179], v[204:207], v[16:19]
	v_mfma_f32_16x16x32_bf16 v[4:7], v[168:171], v[212:215], v[4:7]
	v_mfma_f32_16x16x32_bf16 v[0:3], v[176:179], v[212:215], v[0:3]
	v_mfma_f32_16x16x32_bf16 v[52:55], v[172:175], v[188:191], v[52:55]
	v_mfma_f32_16x16x32_bf16 v[48:51], v[180:183], v[188:191], v[48:51]
	v_mfma_f32_16x16x32_bf16 v[36:39], v[172:175], v[200:203], v[36:39]
	v_mfma_f32_16x16x32_bf16 v[32:35], v[180:183], v[200:203], v[32:35]
	v_mfma_f32_16x16x32_bf16 v[20:23], v[172:175], v[208:211], v[20:23]
	v_mfma_f32_16x16x32_bf16 v[16:19], v[180:183], v[208:211], v[16:19]
	v_mfma_f32_16x16x32_bf16 v[4:7], v[172:175], v[216:219], v[4:7]
	v_mfma_f32_16x16x32_bf16 v[0:3], v[180:183], v[216:219], v[0:3]
	s_setprio 0
	s_barrier
	v_lshl_add_u64 v[222:223], v[222:223], 0, s[16:17]
	s_mov_b32 m0, s43
	s_nop 0
	global_load_lds_dwordx4 v[222:223], off
	v_lshl_add_u64 v[224:225], v[224:225], 0, s[16:17]
	s_mov_b32 m0, s44
	s_nop 0
	global_load_lds_dwordx4 v[224:225], off
	s_add_i32 s56, s56, 2
	s_add_u32 s54, s54, 0x100
	s_addc_u32 s55, s55, 0
	s_cmp_gt_u32 s56, 41
	s_mov_b64 s[22:23], s[24:25]
	s_cbranch_scc0 .LBB0_3401
	s_and_b64 vcc, exec, s[18:19]
	s_cbranch_vccz .LBB0_3404
	s_barrier
